# v025 + counted LDS waits/hoisted K reads in attention + dead zero-init/canonical-max removal + mov_b64 zeroing + dead nop removal
# speedup vs baseline: 1.0034x; 1.0034x over previous
.LBB0_52:
	s_andn2_b64 vcc, exec, s[4:5]
	s_cbranch_vccnz .LBB0_33
	s_mul_hi_i32 s2, s15, 0x6e5478ad
	s_lshr_b32 s4, s2, 31
	s_ashr_i32 s2, s2, 8
	s_add_i32 s2, s2, s4
	s_mul_i32 s5, s2, 0xffffb5c0
	s_lshl_b32 s4, s2, 6
	s_add_i32 s6, s11, s5
	v_or_b32_e32 v2, s4, v28
	s_ashr_i32 s7, s6, 31
	v_lshl_add_u64 v[42:43], s[6:7], 2, v[22:23]
	v_or_b32_e32 v27, 2, v2
	v_mad_i64_i32 v[46:47], s[84:85], v27, s83, v[42:43]
	v_or_b32_e32 v27, 4, v2
	v_mad_i64_i32 v[48:49], s[84:85], v27, s83, v[42:43]
	v_or_b32_e32 v27, 6, v2
	v_mad_i64_i32 v[50:51], s[84:85], v27, s83, v[42:43]
	v_or_b32_e32 v27, 8, v2
	v_mad_i64_i32 v[52:53], s[84:85], v27, s83, v[42:43]
	v_or_b32_e32 v27, 10, v2
	v_mad_i64_i32 v[54:55], s[84:85], v27, s83, v[42:43]
	v_or_b32_e32 v27, 12, v2
	v_mad_i64_i32 v[44:45], s[84:85], v2, s83, v[42:43]
	v_mad_i64_i32 v[56:57], s[84:85], v27, s83, v[42:43]
	v_or_b32_e32 v27, 14, v2
	v_mad_i64_i32 v[58:59], s[84:85], v27, s83, v[42:43]
	global_load_dword v27, v[44:45], off nt
	global_load_dword v60, v[46:47], off nt
	global_load_dword v61, v[48:49], off nt
	global_load_dword v62, v[50:51], off nt
	global_load_dword v63, v[52:53], off nt
	global_load_dword v64, v[54:55], off nt
	global_load_dword v65, v[56:57], off nt
	global_load_dword v66, v[58:59], off nt
	v_or_b32_e32 v44, 16, v2
	v_mad_i64_i32 v[44:45], s[84:85], v44, s83, v[42:43]
	v_or_b32_e32 v46, 18, v2
	v_or_b32_e32 v48, 20, v2
	v_or_b32_e32 v50, 22, v2
	v_or_b32_e32 v52, 24, v2
	v_or_b32_e32 v54, 26, v2
	v_or_b32_e32 v56, 28, v2
	v_or_b32_e32 v58, 30, v2
	v_mad_i64_i32 v[46:47], s[84:85], v46, s83, v[42:43]
	v_mad_i64_i32 v[48:49], s[84:85], v48, s83, v[42:43]
	v_mad_i64_i32 v[50:51], s[84:85], v50, s83, v[42:43]
	v_mad_i64_i32 v[52:53], s[84:85], v52, s83, v[42:43]
	v_mad_i64_i32 v[54:55], s[84:85], v54, s83, v[42:43]
	v_mad_i64_i32 v[56:57], s[84:85], v56, s83, v[42:43]
	v_mad_i64_i32 v[58:59], s[84:85], v58, s83, v[42:43]
	global_load_dword v67, v[44:45], off nt
	global_load_dword v68, v[46:47], off nt
	global_load_dword v69, v[48:49], off nt
	global_load_dword v70, v[50:51], off nt
	global_load_dword v71, v[52:53], off nt
	global_load_dword v72, v[54:55], off nt
	global_load_dword v73, v[56:57], off nt
	global_load_dword v74, v[58:59], off nt
	v_or_b32_e32 v44, 32, v2
	v_or_b32_e32 v46, 34, v2
	v_or_b32_e32 v48, 36, v2
	v_or_b32_e32 v50, 38, v2
	v_or_b32_e32 v56, 44, v2
	v_mad_i64_i32 v[44:45], s[84:85], v44, s83, v[42:43]
	v_mad_i64_i32 v[46:47], s[84:85], v46, s83, v[42:43]
	v_mad_i64_i32 v[48:49], s[84:85], v48, s83, v[42:43]
	v_mad_i64_i32 v[50:51], s[84:85], v50, s83, v[42:43]
	v_or_b32_e32 v52, 40, v2
	v_or_b32_e32 v54, 42, v2
	v_mad_i64_i32 v[56:57], s[84:85], v56, s83, v[42:43]
	v_or_b32_e32 v58, 46, v2
	v_mad_i64_i32 v[52:53], s[84:85], v52, s83, v[42:43]
	v_mad_i64_i32 v[54:55], s[84:85], v54, s83, v[42:43]
	v_mad_i64_i32 v[58:59], s[84:85], v58, s83, v[42:43]
	global_load_dword v75, v[44:45], off nt
	global_load_dword v76, v[46:47], off nt
	global_load_dword v77, v[48:49], off nt
	global_load_dword v78, v[50:51], off nt
	global_load_dword v79, v[52:53], off nt
	global_load_dword v80, v[54:55], off nt
	s_nop 0
	global_load_dword v56, v[56:57], off nt
	s_nop 0
	global_load_dword v57, v[58:59], off nt
	v_or_b32_e32 v44, 48, v2
	v_or_b32_e32 v46, 50, v2
	v_or_b32_e32 v48, 52, v2
	v_or_b32_e32 v50, 54, v2
	v_mad_i64_i32 v[44:45], s[84:85], v44, s83, v[42:43]
	v_mad_i64_i32 v[46:47], s[84:85], v46, s83, v[42:43]
	v_mad_i64_i32 v[48:49], s[84:85], v48, s83, v[42:43]
	v_mad_i64_i32 v[50:51], s[84:85], v50, s83, v[42:43]
	v_or_b32_e32 v52, 56, v2
	v_or_b32_e32 v54, 58, v2
	v_mad_i64_i32 v[52:53], s[84:85], v52, s83, v[42:43]
	v_mad_i64_i32 v[54:55], s[84:85], v54, s83, v[42:43]
	global_load_dword v58, v[44:45], off nt
	s_nop 0
	global_load_dword v46, v[46:47], off nt
	s_nop 0
	global_load_dword v47, v[48:49], off nt
	s_nop 0
	global_load_dword v48, v[50:51], off nt
	global_load_dword v49, v[52:53], off nt
	s_nop 0
	global_load_dword v50, v[54:55], off nt
	v_or_b32_e32 v44, 60, v2
	v_or_b32_e32 v2, 62, v2
	v_mad_i64_i32 v[44:45], s[84:85], v44, s83, v[42:43]
	v_mad_i64_i32 v[42:43], s[84:85], v2, s83, v[42:43]
	global_load_dword v2, v[44:45], off nt
	s_nop 0
	global_load_dword v42, v[42:43], off nt
	s_waitcnt vmcnt(31)
	v_mul_f32_e32 v27, 0x42800000, v27
	s_waitcnt vmcnt(30)
	v_mul_f32_e32 v43, 0x42800000, v60
	ds_write2_b32 v29, v27, v43 offset1:66
	s_waitcnt vmcnt(29)
	v_mul_f32_e32 v27, 0x42800000, v61
	s_waitcnt vmcnt(28)
	v_mul_f32_e32 v43, 0x42800000, v62
	ds_write2_b32 v29, v27, v43 offset0:132 offset1:198
	s_waitcnt vmcnt(27)
	v_mul_f32_e32 v27, 0x42800000, v63
	s_waitcnt vmcnt(26)
	v_mul_f32_e32 v43, 0x42800000, v64
	ds_write2_b32 v35, v27, v43 offset0:8 offset1:74
	s_waitcnt vmcnt(25)
	v_mul_f32_e32 v27, 0x42800000, v65
	s_waitcnt vmcnt(24)
	v_mul_f32_e32 v43, 0x42800000, v66
	ds_write2_b32 v35, v27, v43 offset0:140 offset1:206
	s_lshl_b32 s2, s2, 1
	s_sub_i32 s2, s15, s2
	v_mov_b32_e32 v51, 0
	s_and_b32 s5, s13, 4
	s_bfe_u32 s2, s2, 0x20001
	s_or_b32 s2, s5, s2
	s_lshl_b32 s2, s2, 5
	s_and_b32 s5, s6, 0xffffff00
	s_or_b32 s2, s2, s5
	s_waitcnt vmcnt(23)
	v_mul_f32_e32 v27, 0x42800000, v67
	s_waitcnt vmcnt(22)
	v_mul_f32_e32 v43, 0x42800000, v68
	ds_write2_b32 v36, v27, v43 offset0:16 offset1:82
	s_waitcnt vmcnt(21)
	v_mul_f32_e32 v27, 0x42800000, v69
	s_waitcnt vmcnt(20)
	v_mul_f32_e32 v43, 0x42800000, v70
	ds_write2_b32 v36, v27, v43 offset0:148 offset1:214
	s_waitcnt vmcnt(19)
	v_mul_f32_e32 v27, 0x42800000, v71
	s_waitcnt vmcnt(18)
	v_mul_f32_e32 v43, 0x42800000, v72
	ds_write2_b32 v37, v27, v43 offset0:24 offset1:90
	s_waitcnt vmcnt(17)
	v_mul_f32_e32 v27, 0x42800000, v73
	s_waitcnt vmcnt(16)
	v_mul_f32_e32 v43, 0x42800000, v74
	ds_write2_b32 v37, v27, v43 offset0:156 offset1:222
	v_or_b32_e32 v62, s2, v30
	s_ashr_i32 s5, s4, 31
	v_ashrrev_i32_e32 v63, 31, v62
	v_lshl_add_u64 v[60:61], v[24:25], 0, s[4:5]
	v_lshlrev_b64 v[62:63], 11, v[62:63]
	s_waitcnt vmcnt(15)
	v_mul_f32_e32 v27, 0x42800000, v75
	s_waitcnt vmcnt(14)
	v_mul_f32_e32 v43, 0x42800000, v76
	ds_write2_b32 v38, v27, v43 offset0:32 offset1:98
	s_waitcnt vmcnt(13)
	v_mul_f32_e32 v27, 0x42800000, v77
	s_waitcnt vmcnt(12)
	v_mul_f32_e32 v43, 0x42800000, v78
	ds_write2_b32 v38, v27, v43 offset0:164 offset1:230
	s_waitcnt vmcnt(11)
	v_mul_f32_e32 v27, 0x42800000, v79
	s_waitcnt vmcnt(10)
	v_mul_f32_e32 v43, 0x42800000, v80
	ds_write2_b32 v39, v27, v43 offset0:40 offset1:106
	s_waitcnt vmcnt(9)
	v_mul_f32_e32 v27, 0x42800000, v56
	s_waitcnt vmcnt(8)
	v_mul_f32_e32 v43, 0x42800000, v57
	ds_write2_b32 v39, v27, v43 offset0:172 offset1:238
	s_waitcnt vmcnt(7)
	v_mul_f32_e32 v27, 0x42800000, v58
	s_waitcnt vmcnt(6)
	v_mul_f32_e32 v43, 0x42800000, v46
	ds_write2_b32 v40, v27, v43 offset0:48 offset1:114
	s_waitcnt vmcnt(5)
	v_mul_f32_e32 v27, 0x42800000, v47
	s_waitcnt vmcnt(4)
	v_mul_f32_e32 v43, 0x42800000, v48
	ds_write2_b32 v40, v27, v43 offset0:180 offset1:246
	s_waitcnt vmcnt(3)
	v_mul_f32_e32 v27, 0x42800000, v49
	s_waitcnt vmcnt(2)
	v_mul_f32_e32 v43, 0x42800000, v50
	ds_write2_b32 v41, v27, v43 offset0:56 offset1:122
	s_waitcnt vmcnt(1)
	v_mul_f32_e32 v2, 0x42800000, v2
	s_waitcnt vmcnt(0)
	v_mul_f32_e32 v27, 0x42800000, v42
	ds_write2_b32 v41, v2, v27 offset0:188 offset1:254
	s_waitcnt lgkmcnt(0)
	ds_read2_b32 v[42:43], v31 offset0:33 offset1:41
	ds_read2_b32 v[44:45], v31 offset0:66 offset1:74
	ds_read2_b32 v[46:47], v31 offset1:8
	ds_read2_b32 v[48:49], v31 offset0:99 offset1:107
	ds_read2_b32 v[52:53], v31 offset0:132 offset1:140
	ds_read2_b32 v[54:55], v31 offset0:165 offset1:173
	ds_read2_b32 v[56:57], v31 offset0:198 offset1:206
	ds_read2_b32 v[58:59], v31 offset0:231 offset1:239
	s_waitcnt lgkmcnt(5)
	v_cvt_pk_fp8_f32 v50, v46, v42
	s_waitcnt lgkmcnt(2)
	v_cvt_pk_fp8_f32 v51, v52, v54
	v_cvt_pk_fp8_f32 v42, v47, v43
	v_cvt_pk_fp8_f32 v50, v44, v48 op_sel:[0,0,1]
	s_waitcnt lgkmcnt(0)
	v_cvt_pk_fp8_f32 v51, v56, v58 op_sel:[0,0,1]
	v_cvt_pk_fp8_f32 v43, v53, v55
	v_lshl_add_u64 v[46:47], v[60:61], 0, v[62:63]
	v_cvt_pk_fp8_f32 v42, v45, v49 op_sel:[0,0,1]
	global_store_dwordx2 v[46:47], v[50:51], off
	v_cvt_pk_fp8_f32 v43, v57, v59 op_sel:[0,0,1]
	ds_read2_b32 v[46:47], v31 offset0:49 offset1:57
	ds_read2_b32 v[48:49], v31 offset0:82 offset1:90
	ds_read2_b32 v[50:51], v31 offset0:16 offset1:24
	ds_read2_b32 v[52:53], v31 offset0:115 offset1:123
	ds_read2_b32 v[56:57], v31 offset0:148 offset1:156
	ds_read2_b32 v[58:59], v31 offset0:181 offset1:189
	v_or_b32_e32 v44, s2, v32
	ds_read2_b32 v[62:63], v31 offset0:214 offset1:222
	ds_read2_b32 v[64:65], v31 offset0:247 offset1:255
	v_ashrrev_i32_e32 v45, 31, v44
	s_waitcnt lgkmcnt(5)
	v_cvt_pk_fp8_f32 v54, v50, v46
	s_waitcnt lgkmcnt(2)
	v_cvt_pk_fp8_f32 v55, v56, v58
	v_lshlrev_b64 v[44:45], 11, v[44:45]
	v_lshl_add_u64 v[44:45], v[60:61], 0, v[44:45]
	global_store_dwordx2 v[44:45], v[42:43], off
	v_cvt_pk_fp8_f32 v54, v48, v52 op_sel:[0,0,1]
	s_waitcnt lgkmcnt(0)
	v_cvt_pk_fp8_f32 v55, v62, v64 op_sel:[0,0,1]
	v_or_b32_e32 v42, s2, v33
	v_cvt_pk_fp8_f32 v44, v51, v47
	v_cvt_pk_fp8_f32 v45, v57, v59
	v_ashrrev_i32_e32 v43, 31, v42
	v_lshlrev_b64 v[42:43], 11, v[42:43]
	v_lshl_add_u64 v[42:43], v[60:61], 0, v[42:43]
	global_store_dwordx2 v[42:43], v[54:55], off
	v_cvt_pk_fp8_f32 v44, v49, v53 op_sel:[0,0,1]
	v_cvt_pk_fp8_f32 v45, v63, v65 op_sel:[0,0,1]
	v_or_b32_e32 v42, s2, v34
	v_ashrrev_i32_e32 v43, 31, v42
	v_lshlrev_b64 v[42:43], 11, v[42:43]
	v_lshl_add_u64 v[42:43], v[60:61], 0, v[42:43]
	global_store_dwordx2 v[42:43], v[44:45], off
	s_waitcnt lgkmcnt(0)
	s_branch .LBB0_33

.LBB0_260:
	v_lshl_or_b32 v4, s4, 8, v231
	v_cmp_gt_i32_e32 vcc, s67, v4
	v_add_u32_e32 v14, 0xffffcfc0, v4
	v_add_u32_e32 v2, 0xffffcdc0, v4
	v_cndmask_b32_e64 v3, 0, 1, vcc
	v_cmp_lt_i32_e32 vcc, s65, v4
	v_add_u32_e32 v13, 0xfffff1c0, v4
	v_cmp_gt_u32_e64 s[0:1], s70, v14
	v_cndmask_b32_e64 v5, 0, 1, vcc
	v_cmp_lt_i32_e32 vcc, s66, v4
	v_lshl_add_u32 v12, s77, 8, v1
	v_cmp_gt_u32_e64 s[4:5], s69, v13
	v_cndmask_b32_e32 v3, v5, v3, vcc
	v_and_b32_e32 v3, 1, v3
	v_cmp_eq_u32_e32 vcc, 1, v3
	s_or_b64 s[0:1], vcc, s[0:1]
	v_cmp_gt_u32_e64 s[6:7], s68, v2
	s_nor_b64 s[0:1], s[4:5], s[0:1]
	v_ashrrev_i32_e32 v5, 31, v4
	v_cndmask_b32_e64 v2, v236, v237, s[6:7]
	v_or_b32_e32 v11, 16, v12
	v_or_b32_e32 v10, 32, v12
	v_or_b32_e32 v9, 48, v12
	v_add_u32_e32 v8, 0x80, v12
	v_add_u32_e32 v7, 0x90, v12
	v_add_u32_e32 v6, 0xa0, v12
	v_add_u32_e32 v3, 0xb0, v12
	s_and_saveexec_b64 s[30:31], s[0:1]
	s_xor_b64 s[0:1], exec, s[30:31]
	s_cbranch_execz .LBB0_263
	v_pk_mul_f32 v[14:15], v[2:3], v[192:193] op_sel_hi:[0,1]
	v_pk_mul_f32 v[16:17], v[2:3], v[190:191] op_sel_hi:[0,1]
	v_pk_mul_f32 v[18:19], v[2:3], v[188:189] op_sel_hi:[0,1]
	v_pk_mul_f32 v[20:21], v[2:3], v[186:187] op_sel_hi:[0,1]
	v_cvt_pk_bf16_f32 v13, v16, v17
	v_cvt_pk_bf16_f32 v22, v14, v15
	v_cvt_pk_bf16_f32 v23, v20, v21
	v_cvt_pk_bf16_f32 v24, v18, v19
	v_pk_mul_f32 v[16:17], v[2:3], v[184:185] op_sel_hi:[0,1]
	v_pk_mul_f32 v[14:15], v[2:3], v[182:183] op_sel_hi:[0,1]
	v_pk_mul_f32 v[18:19], v[2:3], v[180:181] op_sel_hi:[0,1]
	v_pk_mul_f32 v[20:21], v[2:3], v[178:179] op_sel_hi:[0,1]
	v_cvt_pk_bf16_f32 v14, v14, v15
	v_cvt_pk_bf16_f32 v15, v16, v17
	v_cvt_pk_bf16_f32 v16, v20, v21
	v_cvt_pk_bf16_f32 v17, v18, v19
	v_mov_b32_e32 v18, v13
	v_lshl_add_u64 v[4:5], v[4:5], 1, v[208:209]
	v_mov_b32_e32 v19, v22
	v_mov_b32_dpp v18, v14 row_ror:8 row_mask:0xf bank_mask:0xc
	v_mov_b32_dpp v14, v13 row_ror:8 row_mask:0xf bank_mask:0x3
	v_ashrrev_i32_e32 v13, 31, v12
	v_sub_co_u32_e32 v12, vcc, v12, v204
	v_mov_b32_dpp v19, v15 row_ror:8 row_mask:0xf bank_mask:0xc
	v_mov_b32_dpp v15, v22 row_ror:8 row_mask:0xf bank_mask:0x3
	v_mov_b32_e32 v20, v23
	v_mov_b32_e32 v21, v24
	v_subbrev_co_u32_e32 v22, vcc, 0, v13, vcc
	v_mad_u64_u32 v[12:13], s[30:31], v12, s71, v[4:5]
	v_mov_b32_dpp v20, v16 row_ror:8 row_mask:0xf bank_mask:0xc
	v_mov_b32_dpp v21, v17 row_ror:8 row_mask:0xf bank_mask:0xc
	v_mad_i32_i24 v13, v22, s71, v13
	global_store_dwordx4 v[12:13], v[18:21], off
	v_add_co_u32_e32 v12, vcc, s63, v12
	v_mov_b32_dpp v16, v23 row_ror:8 row_mask:0xf bank_mask:0x3
	v_mov_b32_dpp v17, v24 row_ror:8 row_mask:0xf bank_mask:0x3
	v_addc_co_u32_e32 v13, vcc, 0, v13, vcc
	global_store_dwordx4 v[12:13], v[14:17], off
	v_pk_mul_f32 v[12:13], v[2:3], v[176:177] op_sel_hi:[0,1]
	v_pk_mul_f32 v[18:19], v[2:3], v[170:171] op_sel_hi:[0,1]
	v_pk_mul_f32 v[14:15], v[2:3], v[174:175] op_sel_hi:[0,1]
	v_pk_mul_f32 v[16:17], v[2:3], v[172:173] op_sel_hi:[0,1]
	v_cvt_pk_bf16_f32 v20, v14, v15
	v_cvt_pk_bf16_f32 v21, v12, v13
	v_cvt_pk_bf16_f32 v22, v18, v19
	v_cvt_pk_bf16_f32 v23, v16, v17
	v_pk_mul_f32 v[14:15], v[2:3], v[168:169] op_sel_hi:[0,1]
	v_pk_mul_f32 v[12:13], v[2:3], v[166:167] op_sel_hi:[0,1]
	v_pk_mul_f32 v[16:17], v[2:3], v[164:165] op_sel_hi:[0,1]
	v_pk_mul_f32 v[18:19], v[2:3], v[162:163] op_sel_hi:[0,1]
	v_cvt_pk_bf16_f32 v12, v12, v13
	v_cvt_pk_bf16_f32 v13, v14, v15
	v_cvt_pk_bf16_f32 v14, v18, v19
	v_cvt_pk_bf16_f32 v15, v16, v17
	v_mov_b32_e32 v16, v20
	v_mov_b32_e32 v17, v21
	v_mov_b32_e32 v18, v22
	v_mov_b32_dpp v16, v12 row_ror:8 row_mask:0xf bank_mask:0xc
	v_mov_b32_dpp v12, v20 row_ror:8 row_mask:0xf bank_mask:0x3
	v_ashrrev_i32_e32 v20, 31, v11
	v_sub_co_u32_e32 v11, vcc, v11, v204
	v_mov_b32_dpp v17, v13 row_ror:8 row_mask:0xf bank_mask:0xc
	v_mov_b32_dpp v13, v21 row_ror:8 row_mask:0xf bank_mask:0x3
	v_mov_b32_dpp v18, v14 row_ror:8 row_mask:0xf bank_mask:0xc
	v_mov_b32_dpp v14, v22 row_ror:8 row_mask:0xf bank_mask:0x3
	v_mov_b32_e32 v19, v23
	v_subbrev_co_u32_e32 v22, vcc, 0, v20, vcc
	v_mad_u64_u32 v[20:21], s[30:31], v11, s71, v[4:5]
	v_mov_b32_dpp v19, v15 row_ror:8 row_mask:0xf bank_mask:0xc
	v_mad_i32_i24 v21, v22, s71, v21
	global_store_dwordx4 v[20:21], v[16:19], off
	v_mov_b32_dpp v15, v23 row_ror:8 row_mask:0xf bank_mask:0x3
	s_nop 0
	v_add_co_u32_e32 v16, vcc, s63, v20
	v_pk_mul_f32 v[18:19], v[2:3], v[154:155] op_sel_hi:[0,1]
	s_nop 0
	v_addc_co_u32_e32 v17, vcc, 0, v21, vcc
	global_store_dwordx4 v[16:17], v[12:15], off
	v_pk_mul_f32 v[16:17], v[2:3], v[156:157] op_sel_hi:[0,1]
	s_nop 0
	v_pk_mul_f32 v[12:13], v[2:3], v[160:161] op_sel_hi:[0,1]
	v_pk_mul_f32 v[14:15], v[2:3], v[158:159] op_sel_hi:[0,1]
	v_cvt_pk_bf16_f32 v11, v14, v15
	v_cvt_pk_bf16_f32 v20, v12, v13
	v_cvt_pk_bf16_f32 v21, v18, v19
	v_cvt_pk_bf16_f32 v22, v16, v17
	v_pk_mul_f32 v[14:15], v[2:3], v[152:153] op_sel_hi:[0,1]
	v_pk_mul_f32 v[12:13], v[2:3], v[150:151] op_sel_hi:[0,1]
	v_pk_mul_f32 v[16:17], v[2:3], v[148:149] op_sel_hi:[0,1]
	v_pk_mul_f32 v[18:19], v[2:3], v[146:147] op_sel_hi:[0,1]
	v_cvt_pk_bf16_f32 v12, v12, v13
	v_cvt_pk_bf16_f32 v13, v14, v15
	v_cvt_pk_bf16_f32 v14, v18, v19
	v_cvt_pk_bf16_f32 v15, v16, v17
	v_mov_b32_e32 v16, v11
	v_mov_b32_e32 v17, v20
	v_mov_b32_e32 v18, v21
	v_mov_b32_dpp v16, v12 row_ror:8 row_mask:0xf bank_mask:0xc
	v_mov_b32_dpp v12, v11 row_ror:8 row_mask:0xf bank_mask:0x3
	v_ashrrev_i32_e32 v11, 31, v10
	v_sub_co_u32_e32 v10, vcc, v10, v204
	v_mov_b32_dpp v17, v13 row_ror:8 row_mask:0xf bank_mask:0xc
	v_mov_b32_dpp v13, v20 row_ror:8 row_mask:0xf bank_mask:0x3
	v_mov_b32_e32 v19, v22
	v_subbrev_co_u32_e32 v20, vcc, 0, v11, vcc
	v_mad_u64_u32 v[10:11], s[30:31], v10, s71, v[4:5]
	v_mov_b32_dpp v18, v14 row_ror:8 row_mask:0xf bank_mask:0xc
	v_mov_b32_dpp v19, v15 row_ror:8 row_mask:0xf bank_mask:0xc
	v_mad_i32_i24 v11, v20, s71, v11
	global_store_dwordx4 v[10:11], v[16:19], off
	v_add_co_u32_e32 v10, vcc, s63, v10
	v_mov_b32_dpp v14, v21 row_ror:8 row_mask:0xf bank_mask:0x3
	v_mov_b32_dpp v15, v22 row_ror:8 row_mask:0xf bank_mask:0x3
	v_addc_co_u32_e32 v11, vcc, 0, v11, vcc
	global_store_dwordx4 v[10:11], v[12:15], off
	v_pk_mul_f32 v[10:11], v[2:3], v[144:145] op_sel_hi:[0,1]
	v_pk_mul_f32 v[16:17], v[2:3], v[138:139] op_sel_hi:[0,1]
	v_pk_mul_f32 v[12:13], v[2:3], v[142:143] op_sel_hi:[0,1]
	v_pk_mul_f32 v[14:15], v[2:3], v[140:141] op_sel_hi:[0,1]
	v_cvt_pk_bf16_f32 v18, v12, v13
	v_cvt_pk_bf16_f32 v19, v10, v11
	v_cvt_pk_bf16_f32 v20, v16, v17
	v_cvt_pk_bf16_f32 v21, v14, v15
	v_pk_mul_f32 v[12:13], v[2:3], v[136:137] op_sel_hi:[0,1]
	v_pk_mul_f32 v[10:11], v[2:3], v[134:135] op_sel_hi:[0,1]
	v_pk_mul_f32 v[14:15], v[2:3], v[132:133] op_sel_hi:[0,1]
	v_pk_mul_f32 v[16:17], v[2:3], v[130:131] op_sel_hi:[0,1]
	v_cvt_pk_bf16_f32 v10, v10, v11
	v_cvt_pk_bf16_f32 v11, v12, v13
	v_cvt_pk_bf16_f32 v12, v16, v17
	v_cvt_pk_bf16_f32 v13, v14, v15
	v_mov_b32_e32 v14, v18
	v_mov_b32_e32 v15, v19
	v_mov_b32_e32 v16, v20
	v_mov_b32_dpp v14, v10 row_ror:8 row_mask:0xf bank_mask:0xc
	v_mov_b32_dpp v10, v18 row_ror:8 row_mask:0xf bank_mask:0x3
	v_ashrrev_i32_e32 v18, 31, v9
	v_sub_co_u32_e32 v9, vcc, v9, v204
	v_mov_b32_dpp v15, v11 row_ror:8 row_mask:0xf bank_mask:0xc
	v_mov_b32_dpp v11, v19 row_ror:8 row_mask:0xf bank_mask:0x3
	v_mov_b32_dpp v16, v12 row_ror:8 row_mask:0xf bank_mask:0xc
	v_mov_b32_dpp v12, v20 row_ror:8 row_mask:0xf bank_mask:0x3
	v_mov_b32_e32 v17, v21
	v_subbrev_co_u32_e32 v20, vcc, 0, v18, vcc
	v_mad_u64_u32 v[18:19], s[30:31], v9, s71, v[4:5]
	v_mov_b32_dpp v17, v13 row_ror:8 row_mask:0xf bank_mask:0xc
	v_mad_i32_i24 v19, v20, s71, v19
	global_store_dwordx4 v[18:19], v[14:17], off
	v_mov_b32_dpp v13, v21 row_ror:8 row_mask:0xf bank_mask:0x3
	s_nop 0
	v_add_co_u32_e32 v14, vcc, s63, v18
	v_pk_mul_f32 v[16:17], v[2:3], v[122:123] op_sel_hi:[0,1]
	s_nop 0
	v_addc_co_u32_e32 v15, vcc, 0, v19, vcc
	global_store_dwordx4 v[14:15], v[10:13], off
	v_pk_mul_f32 v[14:15], v[2:3], v[124:125] op_sel_hi:[0,1]
	s_nop 0
	v_pk_mul_f32 v[10:11], v[2:3], v[128:129] op_sel_hi:[0,1]
	v_pk_mul_f32 v[12:13], v[2:3], v[126:127] op_sel_hi:[0,1]
	v_cvt_pk_bf16_f32 v9, v12, v13
	v_cvt_pk_bf16_f32 v18, v10, v11
	v_cvt_pk_bf16_f32 v19, v16, v17
	v_cvt_pk_bf16_f32 v20, v14, v15
	v_pk_mul_f32 v[12:13], v[2:3], v[120:121] op_sel_hi:[0,1]
	v_pk_mul_f32 v[10:11], v[2:3], v[118:119] op_sel_hi:[0,1]
	v_pk_mul_f32 v[14:15], v[2:3], v[116:117] op_sel_hi:[0,1]
	v_pk_mul_f32 v[16:17], v[2:3], v[114:115] op_sel_hi:[0,1]
	v_cvt_pk_bf16_f32 v10, v10, v11
	v_cvt_pk_bf16_f32 v11, v12, v13
	v_cvt_pk_bf16_f32 v12, v16, v17
	v_cvt_pk_bf16_f32 v13, v14, v15
	v_mov_b32_e32 v14, v9
	v_mov_b32_e32 v15, v18
	v_mov_b32_e32 v16, v19
	v_mov_b32_dpp v14, v10 row_ror:8 row_mask:0xf bank_mask:0xc
	v_mov_b32_dpp v10, v9 row_ror:8 row_mask:0xf bank_mask:0x3
	v_ashrrev_i32_e32 v9, 31, v8
	v_sub_co_u32_e32 v8, vcc, v8, v204
	v_mov_b32_dpp v15, v11 row_ror:8 row_mask:0xf bank_mask:0xc
	v_mov_b32_dpp v11, v18 row_ror:8 row_mask:0xf bank_mask:0x3
	v_mov_b32_e32 v17, v20
	v_subbrev_co_u32_e32 v18, vcc, 0, v9, vcc
	v_mad_u64_u32 v[8:9], s[30:31], v8, s71, v[4:5]
	v_mov_b32_dpp v16, v12 row_ror:8 row_mask:0xf bank_mask:0xc
	v_mov_b32_dpp v17, v13 row_ror:8 row_mask:0xf bank_mask:0xc
	v_mad_i32_i24 v9, v18, s71, v9
	global_store_dwordx4 v[8:9], v[14:17], off
	v_add_co_u32_e32 v8, vcc, s63, v8
	v_mov_b32_dpp v12, v19 row_ror:8 row_mask:0xf bank_mask:0x3
	v_mov_b32_dpp v13, v20 row_ror:8 row_mask:0xf bank_mask:0x3
	v_addc_co_u32_e32 v9, vcc, 0, v9, vcc
	global_store_dwordx4 v[8:9], v[10:13], off
	v_pk_mul_f32 v[8:9], v[2:3], v[112:113] op_sel_hi:[0,1]
	v_pk_mul_f32 v[14:15], v[2:3], v[106:107] op_sel_hi:[0,1]
	v_pk_mul_f32 v[10:11], v[2:3], v[110:111] op_sel_hi:[0,1]
	v_pk_mul_f32 v[12:13], v[2:3], v[108:109] op_sel_hi:[0,1]
	v_cvt_pk_bf16_f32 v16, v10, v11
	v_cvt_pk_bf16_f32 v17, v8, v9
	v_cvt_pk_bf16_f32 v18, v14, v15
	v_cvt_pk_bf16_f32 v19, v12, v13
	v_pk_mul_f32 v[10:11], v[2:3], v[104:105] op_sel_hi:[0,1]
	v_pk_mul_f32 v[8:9], v[2:3], v[102:103] op_sel_hi:[0,1]
	v_pk_mul_f32 v[12:13], v[2:3], v[100:101] op_sel_hi:[0,1]
	v_pk_mul_f32 v[14:15], v[2:3], v[98:99] op_sel_hi:[0,1]
	v_cvt_pk_bf16_f32 v8, v8, v9
	v_cvt_pk_bf16_f32 v9, v10, v11
	v_cvt_pk_bf16_f32 v10, v14, v15
	v_cvt_pk_bf16_f32 v11, v12, v13
	v_mov_b32_e32 v12, v16
	v_mov_b32_e32 v13, v17
	v_mov_b32_e32 v14, v18
	v_mov_b32_dpp v12, v8 row_ror:8 row_mask:0xf bank_mask:0xc
	v_mov_b32_dpp v8, v16 row_ror:8 row_mask:0xf bank_mask:0x3
	v_ashrrev_i32_e32 v16, 31, v7
	v_sub_co_u32_e32 v7, vcc, v7, v204
	v_mov_b32_dpp v13, v9 row_ror:8 row_mask:0xf bank_mask:0xc
	v_mov_b32_dpp v9, v17 row_ror:8 row_mask:0xf bank_mask:0x3
	v_mov_b32_dpp v14, v10 row_ror:8 row_mask:0xf bank_mask:0xc
	v_mov_b32_dpp v10, v18 row_ror:8 row_mask:0xf bank_mask:0x3
	v_mov_b32_e32 v15, v19
	v_subbrev_co_u32_e32 v18, vcc, 0, v16, vcc
	v_mad_u64_u32 v[16:17], s[30:31], v7, s71, v[4:5]
	v_mov_b32_dpp v15, v11 row_ror:8 row_mask:0xf bank_mask:0xc
	v_mad_i32_i24 v17, v18, s71, v17
	global_store_dwordx4 v[16:17], v[12:15], off
	v_mov_b32_dpp v11, v19 row_ror:8 row_mask:0xf bank_mask:0x3
	s_nop 0
	v_add_co_u32_e32 v12, vcc, s63, v16
	v_pk_mul_f32 v[14:15], v[2:3], v[90:91] op_sel_hi:[0,1]
	s_nop 0
	v_addc_co_u32_e32 v13, vcc, 0, v17, vcc
	global_store_dwordx4 v[12:13], v[8:11], off
	v_pk_mul_f32 v[12:13], v[2:3], v[92:93] op_sel_hi:[0,1]
	s_nop 0
	v_pk_mul_f32 v[8:9], v[2:3], v[96:97] op_sel_hi:[0,1]
	v_pk_mul_f32 v[10:11], v[2:3], v[94:95] op_sel_hi:[0,1]
	v_cvt_pk_bf16_f32 v7, v10, v11
	v_cvt_pk_bf16_f32 v16, v8, v9
	v_cvt_pk_bf16_f32 v17, v14, v15
	v_cvt_pk_bf16_f32 v18, v12, v13
	v_pk_mul_f32 v[10:11], v[2:3], v[88:89] op_sel_hi:[0,1]
	v_pk_mul_f32 v[8:9], v[2:3], v[86:87] op_sel_hi:[0,1]
	v_pk_mul_f32 v[12:13], v[2:3], v[84:85] op_sel_hi:[0,1]
	v_pk_mul_f32 v[14:15], v[2:3], v[82:83] op_sel_hi:[0,1]
	v_cvt_pk_bf16_f32 v8, v8, v9
	v_cvt_pk_bf16_f32 v9, v10, v11
	v_cvt_pk_bf16_f32 v10, v14, v15
	v_cvt_pk_bf16_f32 v11, v12, v13
	v_mov_b32_e32 v12, v7
	v_mov_b32_e32 v13, v16
	v_mov_b32_e32 v14, v17
	v_mov_b32_dpp v12, v8 row_ror:8 row_mask:0xf bank_mask:0xc
	v_mov_b32_dpp v8, v7 row_ror:8 row_mask:0xf bank_mask:0x3
	v_ashrrev_i32_e32 v7, 31, v6
	v_sub_co_u32_e32 v6, vcc, v6, v204
	v_mov_b32_dpp v13, v9 row_ror:8 row_mask:0xf bank_mask:0xc
	v_mov_b32_dpp v9, v16 row_ror:8 row_mask:0xf bank_mask:0x3
	v_mov_b32_e32 v15, v18
	v_subbrev_co_u32_e32 v16, vcc, 0, v7, vcc
	v_mad_u64_u32 v[6:7], s[30:31], v6, s71, v[4:5]
	v_mov_b32_dpp v14, v10 row_ror:8 row_mask:0xf bank_mask:0xc
	v_mov_b32_dpp v15, v11 row_ror:8 row_mask:0xf bank_mask:0xc
	v_mad_i32_i24 v7, v16, s71, v7
	global_store_dwordx4 v[6:7], v[12:15], off
	v_add_co_u32_e32 v6, vcc, s63, v6
	v_mov_b32_dpp v10, v17 row_ror:8 row_mask:0xf bank_mask:0x3
	v_mov_b32_dpp v11, v18 row_ror:8 row_mask:0xf bank_mask:0x3
	v_addc_co_u32_e32 v7, vcc, 0, v7, vcc
	global_store_dwordx4 v[6:7], v[8:11], off
	v_pk_mul_f32 v[6:7], v[2:3], v[80:81] op_sel_hi:[0,1]
	v_pk_mul_f32 v[12:13], v[2:3], v[74:75] op_sel_hi:[0,1]
	v_pk_mul_f32 v[8:9], v[2:3], v[78:79] op_sel_hi:[0,1]
	v_pk_mul_f32 v[10:11], v[2:3], v[76:77] op_sel_hi:[0,1]
	v_cvt_pk_bf16_f32 v14, v8, v9
	v_cvt_pk_bf16_f32 v15, v6, v7
	v_cvt_pk_bf16_f32 v16, v12, v13
	v_cvt_pk_bf16_f32 v17, v10, v11
	v_pk_mul_f32 v[8:9], v[2:3], v[72:73] op_sel_hi:[0,1]
	v_pk_mul_f32 v[6:7], v[2:3], v[70:71] op_sel_hi:[0,1]
	v_pk_mul_f32 v[10:11], v[2:3], v[68:69] op_sel_hi:[0,1]
	v_pk_mul_f32 v[12:13], v[2:3], v[66:67] op_sel_hi:[0,1]
	v_cvt_pk_bf16_f32 v6, v6, v7
	v_cvt_pk_bf16_f32 v7, v8, v9
	v_cvt_pk_bf16_f32 v8, v12, v13
	v_cvt_pk_bf16_f32 v9, v10, v11
	v_mov_b32_e32 v10, v14
	v_ashrrev_i32_e32 v2, 31, v3
	v_sub_co_u32_e32 v3, vcc, v3, v204
	v_mov_b32_dpp v10, v6 row_ror:8 row_mask:0xf bank_mask:0xc
	v_mov_b32_dpp v6, v14 row_ror:8 row_mask:0xf bank_mask:0x3
	v_mov_b32_e32 v11, v15
	v_mov_b32_e32 v12, v16
	v_mov_b32_e32 v13, v17
	v_subbrev_co_u32_e32 v14, vcc, 0, v2, vcc
	v_mad_u64_u32 v[2:3], s[30:31], v3, s71, v[4:5]
	v_mov_b32_dpp v11, v7 row_ror:8 row_mask:0xf bank_mask:0xc
	v_mov_b32_dpp v12, v8 row_ror:8 row_mask:0xf bank_mask:0xc
	v_mov_b32_dpp v13, v9 row_ror:8 row_mask:0xf bank_mask:0xc
	v_mad_i32_i24 v3, v14, s71, v3
	global_store_dwordx4 v[2:3], v[10:13], off
	v_add_co_u32_e32 v2, vcc, 0x53000, v2
	v_mov_b32_dpp v7, v15 row_ror:8 row_mask:0xf bank_mask:0x3
	v_mov_b32_dpp v8, v16 row_ror:8 row_mask:0xf bank_mask:0x3
	v_mov_b32_dpp v9, v17 row_ror:8 row_mask:0xf bank_mask:0x3
	v_addc_co_u32_e32 v3, vcc, 0, v3, vcc
	global_store_dwordx4 v[2:3], v[6:9], off
	s_andn2_saveexec_b64 s[30:31], s[0:1]
	s_cbranch_execnz .LBB0_264

.LBB0_430:
	v_pk_mul_f32 v[4:5], v[170:171], s[22:23] op_sel_hi:[1,0]
	v_pk_mul_f32 v[12:13], v[174:175], s[22:23] op_sel_hi:[1,0]
	v_cvt_pk_fp8_f32 v2, v4, v5
	v_cvt_pk_fp8_f32 v3, v12, v13
	v_pk_mul_f32 v[4:5], v[172:173], s[22:23] op_sel_hi:[1,0]
	v_pk_mul_f32 v[12:13], v[176:177], s[22:23] op_sel_hi:[1,0]
	v_cvt_pk_fp8_f32 v2, v4, v5 op_sel:[0,0,1]
	v_cvt_pk_fp8_f32 v3, v12, v13 op_sel:[0,0,1]
	v_pk_mul_f32 v[12:13], v[154:155], s[22:23] op_sel_hi:[1,0]
	v_pk_mul_f32 v[14:15], v[158:159], s[22:23] op_sel_hi:[1,0]
	v_cvt_pk_fp8_f32 v4, v12, v13
	v_cvt_pk_fp8_f32 v5, v14, v15
	v_pk_mul_f32 v[12:13], v[156:157], s[22:23] op_sel_hi:[1,0]
	v_lshl_add_u32 v6, s34, 8, v214
	v_cvt_pk_fp8_f32 v4, v12, v13 op_sel:[0,0,1]
	v_pk_mul_f32 v[12:13], v[160:161], s[22:23] op_sel_hi:[1,0]
	v_lshl_add_u32 v8, s67, 7, v215
	v_cvt_pk_fp8_f32 v5, v12, v13 op_sel:[0,0,1]
	v_ashrrev_i32_e32 v9, 31, v8
	v_ashrrev_i32_e32 v7, 31, v6
	v_lshl_add_u64 v[10:11], s[8:9], 0, v[8:9]
	v_lshlrev_b64 v[12:13], 11, v[6:7]
	v_permlane16_swap_b32_e32 v2, v4
	v_permlane16_swap_b32_e32 v3, v5
	v_lshl_add_u64 v[14:15], v[10:11], 0, v[12:13]
	global_store_dwordx4 v[14:15], v[2:5], off
	v_pk_mul_f32 v[14:15], v[142:143], s[22:23] op_sel_hi:[1,0]
	v_pk_mul_f32 v[16:17], v[134:135], s[22:23] op_sel_hi:[1,0]
	v_pk_mul_f32 v[4:5], v[138:139], s[22:23] op_sel_hi:[1,0]
	v_cvt_pk_fp8_f32 v2, v4, v5
	v_cvt_pk_fp8_f32 v3, v14, v15
	v_pk_mul_f32 v[4:5], v[140:141], s[22:23] op_sel_hi:[1,0]
	v_pk_mul_f32 v[14:15], v[144:145], s[22:23] op_sel_hi:[1,0]
	v_cvt_pk_fp8_f32 v2, v4, v5 op_sel:[0,0,1]
	v_cvt_pk_fp8_f32 v3, v14, v15 op_sel:[0,0,1]
	v_pk_mul_f32 v[14:15], v[130:131], s[22:23] op_sel_hi:[1,0]
	v_cvt_pk_fp8_f32 v4, v14, v15
	v_cvt_pk_fp8_f32 v5, v16, v17
	v_pk_mul_f32 v[14:15], v[132:133], s[22:23] op_sel_hi:[1,0]
	v_or_b32_e32 v6, 32, v6
	v_cvt_pk_fp8_f32 v4, v14, v15 op_sel:[0,0,1]
	v_pk_mul_f32 v[14:15], v[136:137], s[22:23] op_sel_hi:[1,0]
	v_ashrrev_i32_e32 v7, 31, v6
	v_cvt_pk_fp8_f32 v5, v14, v15 op_sel:[0,0,1]
	v_lshlrev_b64 v[6:7], 11, v[6:7]
	v_permlane16_swap_b32_e32 v2, v4
	v_permlane16_swap_b32_e32 v3, v5
	v_lshl_add_u64 v[14:15], v[10:11], 0, v[6:7]
	global_store_dwordx4 v[14:15], v[2:5], off
	v_pk_mul_f32 v[14:15], v[190:191], s[22:23] op_sel_hi:[1,0]
	v_pk_mul_f32 v[16:17], v[182:183], s[22:23] op_sel_hi:[1,0]
	v_pk_mul_f32 v[4:5], v[186:187], s[22:23] op_sel_hi:[1,0]
	v_cvt_pk_fp8_f32 v2, v4, v5
	v_cvt_pk_fp8_f32 v3, v14, v15
	v_pk_mul_f32 v[4:5], v[188:189], s[22:23] op_sel_hi:[1,0]
	v_pk_mul_f32 v[14:15], v[192:193], s[22:23] op_sel_hi:[1,0]
	v_cvt_pk_fp8_f32 v2, v4, v5 op_sel:[0,0,1]
	v_cvt_pk_fp8_f32 v3, v14, v15 op_sel:[0,0,1]
	v_pk_mul_f32 v[14:15], v[178:179], s[22:23] op_sel_hi:[1,0]
	v_cvt_pk_fp8_f32 v4, v14, v15
	v_cvt_pk_fp8_f32 v5, v16, v17
	v_pk_mul_f32 v[14:15], v[180:181], s[22:23] op_sel_hi:[1,0]
	v_pk_mul_f32 v[18:19], v[150:151], s[22:23] op_sel_hi:[1,0]
	v_cvt_pk_fp8_f32 v4, v14, v15 op_sel:[0,0,1]
	v_pk_mul_f32 v[14:15], v[184:185], s[22:23] op_sel_hi:[1,0]
	v_lshl_add_u64 v[8:9], s[10:11], 0, v[8:9]
	v_cvt_pk_fp8_f32 v5, v14, v15 op_sel:[0,0,1]
	v_lshl_add_u64 v[14:15], v[12:13], 0, s[24:25]
	v_permlane16_swap_b32_e32 v2, v4
	v_permlane16_swap_b32_e32 v3, v5
	v_lshl_add_u64 v[16:17], v[10:11], 0, v[14:15]
	global_store_dwordx4 v[16:17], v[2:5], off
	v_pk_mul_f32 v[16:17], v[166:167], s[22:23] op_sel_hi:[1,0]
	v_lshl_add_u64 v[6:7], v[8:9], 0, v[6:7]
	v_pk_mul_f32 v[4:5], v[162:163], s[22:23] op_sel_hi:[1,0]
	v_cvt_pk_fp8_f32 v2, v4, v5
	v_cvt_pk_fp8_f32 v3, v16, v17
	v_pk_mul_f32 v[4:5], v[164:165], s[22:23] op_sel_hi:[1,0]
	v_pk_mul_f32 v[16:17], v[168:169], s[22:23] op_sel_hi:[1,0]
	v_cvt_pk_fp8_f32 v2, v4, v5 op_sel:[0,0,1]
	v_cvt_pk_fp8_f32 v3, v16, v17 op_sel:[0,0,1]
	v_pk_mul_f32 v[16:17], v[146:147], s[22:23] op_sel_hi:[1,0]
	v_cvt_pk_fp8_f32 v4, v16, v17
	v_cvt_pk_fp8_f32 v5, v18, v19
	v_pk_mul_f32 v[16:17], v[148:149], s[22:23] op_sel_hi:[1,0]
	v_pk_mul_f32 v[18:19], v[90:91], s[22:23] op_sel_hi:[1,0]
	v_cvt_pk_fp8_f32 v4, v16, v17 op_sel:[0,0,1]
	v_pk_mul_f32 v[16:17], v[152:153], s[22:23] op_sel_hi:[1,0]
	s_andn2_b64 vcc, exec, s[2:3]
	v_cvt_pk_fp8_f32 v5, v16, v17 op_sel:[0,0,1]
	v_lshl_add_u64 v[16:17], v[12:13], 0, s[26:27]
	v_permlane16_swap_b32_e32 v2, v4
	v_permlane16_swap_b32_e32 v3, v5
	v_lshl_add_u64 v[10:11], v[10:11], 0, v[16:17]
	global_store_dwordx4 v[10:11], v[2:5], off
	v_pk_mul_f32 v[10:11], v[102:103], s[22:23] op_sel_hi:[1,0]
	s_nop 0
	v_pk_mul_f32 v[4:5], v[98:99], s[22:23] op_sel_hi:[1,0]
	v_cvt_pk_fp8_f32 v2, v4, v5
	v_cvt_pk_fp8_f32 v3, v10, v11
	v_pk_mul_f32 v[4:5], v[100:101], s[22:23] op_sel_hi:[1,0]
	v_pk_mul_f32 v[10:11], v[104:105], s[22:23] op_sel_hi:[1,0]
	v_cvt_pk_fp8_f32 v2, v4, v5 op_sel:[0,0,1]
	v_cvt_pk_fp8_f32 v3, v10, v11 op_sel:[0,0,1]
	v_pk_mul_f32 v[10:11], v[86:87], s[22:23] op_sel_hi:[1,0]
	v_cvt_pk_fp8_f32 v4, v10, v11
	v_cvt_pk_fp8_f32 v5, v18, v19
	v_pk_mul_f32 v[10:11], v[88:89], s[22:23] op_sel_hi:[1,0]
	s_nop 0
	v_cvt_pk_fp8_f32 v4, v10, v11 op_sel:[0,0,1]
	v_pk_mul_f32 v[10:11], v[92:93], s[22:23] op_sel_hi:[1,0]
	s_nop 0
	v_permlane16_swap_b32_e32 v2, v4
	v_cvt_pk_fp8_f32 v5, v10, v11 op_sel:[0,0,1]
	v_lshl_add_u64 v[10:11], v[8:9], 0, v[12:13]
	v_pk_mul_f32 v[12:13], v[66:67], s[22:23] op_sel_hi:[1,0]
	v_permlane16_swap_b32_e32 v3, v5
	global_store_dwordx4 v[10:11], v[2:5], off
	v_pk_mul_f32 v[10:11], v[82:83], s[22:23] op_sel_hi:[1,0]
	s_nop 0
	v_pk_mul_f32 v[4:5], v[78:79], s[22:23] op_sel_hi:[1,0]
	v_cvt_pk_fp8_f32 v2, v4, v5
	v_cvt_pk_fp8_f32 v3, v10, v11
	v_pk_mul_f32 v[4:5], v[80:81], s[22:23] op_sel_hi:[1,0]
	v_pk_mul_f32 v[10:11], v[84:85], s[22:23] op_sel_hi:[1,0]
	v_cvt_pk_fp8_f32 v2, v4, v5 op_sel:[0,0,1]
	v_cvt_pk_fp8_f32 v3, v10, v11 op_sel:[0,0,1]
	v_pk_mul_f32 v[10:11], v[74:75], s[22:23] op_sel_hi:[1,0]
	v_cvt_pk_fp8_f32 v4, v10, v11
	v_cvt_pk_fp8_f32 v5, v12, v13
	v_pk_mul_f32 v[10:11], v[76:77], s[22:23] op_sel_hi:[1,0]
	s_nop 0
	v_cvt_pk_fp8_f32 v4, v10, v11 op_sel:[0,0,1]
	v_pk_mul_f32 v[10:11], v[68:69], s[22:23] op_sel_hi:[1,0]
	s_nop 0
	v_permlane16_swap_b32_e32 v2, v4
	v_cvt_pk_fp8_f32 v5, v10, v11 op_sel:[0,0,1]
	v_pk_mul_f32 v[10:11], v[118:119], s[22:23] op_sel_hi:[1,0]
	s_nop 0
	v_permlane16_swap_b32_e32 v3, v5
	global_store_dwordx4 v[6:7], v[2:5], off
	v_pk_mul_f32 v[6:7], v[126:127], s[22:23] op_sel_hi:[1,0]
	s_nop 0
	v_pk_mul_f32 v[4:5], v[122:123], s[22:23] op_sel_hi:[1,0]
	v_cvt_pk_fp8_f32 v2, v4, v5
	v_cvt_pk_fp8_f32 v3, v6, v7
	v_pk_mul_f32 v[4:5], v[124:125], s[22:23] op_sel_hi:[1,0]
	v_pk_mul_f32 v[6:7], v[128:129], s[22:23] op_sel_hi:[1,0]
	v_cvt_pk_fp8_f32 v2, v4, v5 op_sel:[0,0,1]
	v_cvt_pk_fp8_f32 v3, v6, v7 op_sel:[0,0,1]
	v_pk_mul_f32 v[6:7], v[114:115], s[22:23] op_sel_hi:[1,0]
	v_cvt_pk_fp8_f32 v4, v6, v7
	v_cvt_pk_fp8_f32 v5, v10, v11
	v_pk_mul_f32 v[6:7], v[116:117], s[22:23] op_sel_hi:[1,0]
	v_pk_mul_f32 v[10:11], v[70:71], s[22:23] op_sel_hi:[1,0]
	v_cvt_pk_fp8_f32 v4, v6, v7 op_sel:[0,0,1]
	v_pk_mul_f32 v[6:7], v[120:121], s[22:23] op_sel_hi:[1,0]
	s_nop 0
	v_permlane16_swap_b32_e32 v2, v4
	v_cvt_pk_fp8_f32 v5, v6, v7 op_sel:[0,0,1]
	v_lshl_add_u64 v[6:7], v[8:9], 0, v[14:15]
	s_nop 0
	v_permlane16_swap_b32_e32 v3, v5
	global_store_dwordx4 v[6:7], v[2:5], off
	v_pk_mul_f32 v[6:7], v[110:111], s[22:23] op_sel_hi:[1,0]
	s_nop 0
	v_pk_mul_f32 v[4:5], v[106:107], s[22:23] op_sel_hi:[1,0]
	v_cvt_pk_fp8_f32 v2, v4, v5
	v_cvt_pk_fp8_f32 v3, v6, v7
	v_pk_mul_f32 v[4:5], v[108:109], s[22:23] op_sel_hi:[1,0]
	v_pk_mul_f32 v[6:7], v[112:113], s[22:23] op_sel_hi:[1,0]
	v_cvt_pk_fp8_f32 v2, v4, v5 op_sel:[0,0,1]
	v_cvt_pk_fp8_f32 v3, v6, v7 op_sel:[0,0,1]
	v_pk_mul_f32 v[6:7], v[94:95], s[22:23] op_sel_hi:[1,0]
	v_cvt_pk_fp8_f32 v4, v6, v7
	v_cvt_pk_fp8_f32 v5, v10, v11
	v_pk_mul_f32 v[6:7], v[96:97], s[22:23] op_sel_hi:[1,0]
	s_nop 0
	v_cvt_pk_fp8_f32 v4, v6, v7 op_sel:[0,0,1]
	v_pk_mul_f32 v[6:7], v[72:73], s[22:23] op_sel_hi:[1,0]
	s_nop 0
	v_permlane16_swap_b32_e32 v2, v4
	v_cvt_pk_fp8_f32 v5, v6, v7 op_sel:[0,0,1]
	v_lshl_add_u64 v[6:7], v[8:9], 0, v[16:17]
	s_nop 0
	v_permlane16_swap_b32_e32 v3, v5
	global_store_dwordx4 v[6:7], v[2:5], off
	s_cbranch_vccnz .LBB0_433
	s_andn2_b64 vcc, exec, s[0:1]
	s_cbranch_vccnz .LBB0_409
	s_barrier
	s_branch .LBB0_409

.LBB0_506:
	s_waitcnt vmcnt(0)
	v_lshlrev_b32_e32 v58, 16, v46
	v_and_b32_e32 v46, 0xffff0000, v46
	v_mov_b32_e32 v146, v171
	v_cvt_pk_fp8_f32 v146, v58, v46
	v_lshlrev_b32_e32 v58, 16, v48
	v_and_b32_e32 v48, 0xffff0000, v48
	v_mov_b32_e32 v147, v171
	v_cvt_pk_fp8_f32 v147, v58, v48
	v_lshlrev_b32_e32 v46, 16, v47
	v_and_b32_e32 v47, 0xffff0000, v47
	v_cvt_pk_fp8_f32 v146, v46, v47 op_sel:[0,0,1]
	v_lshlrev_b32_e32 v46, 16, v49
	v_and_b32_e32 v47, 0xffff0000, v49
	v_cvt_pk_fp8_f32 v147, v46, v47 op_sel:[0,0,1]
	v_lshlrev_b32_e32 v46, 16, v42
	v_and_b32_e32 v42, 0xffff0000, v42
	v_mov_b32_e32 v148, v171
	v_cvt_pk_fp8_f32 v148, v46, v42
	v_lshlrev_b32_e32 v46, 16, v44
	v_and_b32_e32 v44, 0xffff0000, v44
	v_mov_b32_e32 v149, v171
	v_cvt_pk_fp8_f32 v149, v46, v44
	v_lshlrev_b32_e32 v42, 16, v43
	v_and_b32_e32 v43, 0xffff0000, v43
	v_cvt_pk_fp8_f32 v148, v42, v43 op_sel:[0,0,1]
	v_lshlrev_b32_e32 v42, 16, v45
	v_and_b32_e32 v43, 0xffff0000, v45
	v_cvt_pk_fp8_f32 v149, v42, v43 op_sel:[0,0,1]
	v_lshlrev_b32_e32 v42, 16, v38
	v_and_b32_e32 v38, 0xffff0000, v38
	v_mov_b32_e32 v150, v171
	v_cvt_pk_fp8_f32 v150, v42, v38
	v_lshlrev_b32_e32 v42, 16, v40
	v_and_b32_e32 v40, 0xffff0000, v40
	v_mov_b32_e32 v151, v171
	v_cvt_pk_fp8_f32 v151, v42, v40
	v_lshlrev_b32_e32 v38, 16, v39
	v_and_b32_e32 v39, 0xffff0000, v39
	v_cvt_pk_fp8_f32 v150, v38, v39 op_sel:[0,0,1]
	v_lshlrev_b32_e32 v38, 16, v41
	v_and_b32_e32 v39, 0xffff0000, v41
	v_cvt_pk_fp8_f32 v151, v38, v39 op_sel:[0,0,1]
	v_lshlrev_b32_e32 v38, 16, v34
	v_and_b32_e32 v34, 0xffff0000, v34
	v_mov_b32_e32 v152, v171
	v_cvt_pk_fp8_f32 v152, v38, v34
	v_lshlrev_b32_e32 v38, 16, v36
	v_and_b32_e32 v36, 0xffff0000, v36
	v_mov_b32_e32 v153, v171
	v_cvt_pk_fp8_f32 v153, v38, v36
	v_lshlrev_b32_e32 v34, 16, v35
	v_and_b32_e32 v35, 0xffff0000, v35
	v_cvt_pk_fp8_f32 v152, v34, v35 op_sel:[0,0,1]
	v_lshlrev_b32_e32 v34, 16, v37
	v_and_b32_e32 v35, 0xffff0000, v37
	v_cvt_pk_fp8_f32 v153, v34, v35 op_sel:[0,0,1]
	v_lshlrev_b32_e32 v34, 16, v30
	v_and_b32_e32 v30, 0xffff0000, v30
	v_mov_b32_e32 v154, v171
	v_cvt_pk_fp8_f32 v154, v34, v30
	v_lshlrev_b32_e32 v34, 16, v32
	v_and_b32_e32 v32, 0xffff0000, v32
	v_mov_b32_e32 v155, v171
	v_cvt_pk_fp8_f32 v155, v34, v32
	v_lshlrev_b32_e32 v30, 16, v31
	v_and_b32_e32 v31, 0xffff0000, v31
	v_cvt_pk_fp8_f32 v154, v30, v31 op_sel:[0,0,1]
	v_lshlrev_b32_e32 v30, 16, v33
	v_and_b32_e32 v31, 0xffff0000, v33
	v_cvt_pk_fp8_f32 v155, v30, v31 op_sel:[0,0,1]
	v_lshlrev_b32_e32 v30, 16, v26
	v_and_b32_e32 v26, 0xffff0000, v26
	v_mov_b32_e32 v156, v171
	v_cvt_pk_fp8_f32 v156, v30, v26
	v_lshlrev_b32_e32 v30, 16, v28
	v_and_b32_e32 v28, 0xffff0000, v28
	v_mov_b32_e32 v157, v171
	v_cvt_pk_fp8_f32 v157, v30, v28
	v_lshlrev_b32_e32 v26, 16, v27
	v_and_b32_e32 v27, 0xffff0000, v27
	v_cvt_pk_fp8_f32 v156, v26, v27 op_sel:[0,0,1]
	v_lshlrev_b32_e32 v26, 16, v29
	v_and_b32_e32 v27, 0xffff0000, v29
	v_cvt_pk_fp8_f32 v157, v26, v27 op_sel:[0,0,1]
	v_lshlrev_b32_e32 v26, 16, v22
	v_and_b32_e32 v22, 0xffff0000, v22
	v_mov_b32_e32 v158, v171
	v_cvt_pk_fp8_f32 v158, v26, v22
	v_lshlrev_b32_e32 v26, 16, v24
	v_and_b32_e32 v24, 0xffff0000, v24
	v_mov_b32_e32 v159, v171
	v_cvt_pk_fp8_f32 v159, v26, v24
	v_lshlrev_b32_e32 v22, 16, v23
	v_and_b32_e32 v23, 0xffff0000, v23
	v_cvt_pk_fp8_f32 v158, v22, v23 op_sel:[0,0,1]
	v_lshlrev_b32_e32 v22, 16, v25
	v_and_b32_e32 v23, 0xffff0000, v25
	v_cvt_pk_fp8_f32 v159, v22, v23 op_sel:[0,0,1]
	v_lshlrev_b32_e32 v22, 16, v18
	v_and_b32_e32 v18, 0xffff0000, v18
	v_mov_b32_e32 v160, v171
	v_cvt_pk_fp8_f32 v160, v22, v18
	v_lshlrev_b32_e32 v22, 16, v20
	v_and_b32_e32 v20, 0xffff0000, v20
	v_mov_b32_e32 v161, v171
	v_cvt_pk_fp8_f32 v161, v22, v20
	v_lshlrev_b32_e32 v18, 16, v19
	v_and_b32_e32 v19, 0xffff0000, v19
	v_cvt_pk_fp8_f32 v160, v18, v19 op_sel:[0,0,1]
	v_lshlrev_b32_e32 v18, 16, v21
	v_and_b32_e32 v19, 0xffff0000, v21
	v_cvt_pk_fp8_f32 v161, v18, v19 op_sel:[0,0,1]
	v_lshlrev_b32_e32 v18, 16, v14
	v_and_b32_e32 v14, 0xffff0000, v14
	v_mov_b32_e32 v162, v171
	v_cvt_pk_fp8_f32 v162, v18, v14
	v_lshlrev_b32_e32 v18, 16, v16
	v_and_b32_e32 v16, 0xffff0000, v16
	v_mov_b32_e32 v163, v171
	v_cvt_pk_fp8_f32 v163, v18, v16
	v_lshlrev_b32_e32 v14, 16, v15
	v_and_b32_e32 v15, 0xffff0000, v15
	v_cvt_pk_fp8_f32 v162, v14, v15 op_sel:[0,0,1]
	v_lshlrev_b32_e32 v14, 16, v17
	v_and_b32_e32 v15, 0xffff0000, v17
	v_cvt_pk_fp8_f32 v163, v14, v15 op_sel:[0,0,1]
	v_lshlrev_b32_e32 v14, 16, v10
	v_and_b32_e32 v10, 0xffff0000, v10
	v_mov_b32_e32 v164, v171
	v_cvt_pk_fp8_f32 v164, v14, v10
	v_lshlrev_b32_e32 v14, 16, v12
	v_and_b32_e32 v12, 0xffff0000, v12
	v_mov_b32_e32 v165, v171
	v_cvt_pk_fp8_f32 v165, v14, v12
	v_lshlrev_b32_e32 v10, 16, v11
	v_and_b32_e32 v11, 0xffff0000, v11
	v_cvt_pk_fp8_f32 v164, v10, v11 op_sel:[0,0,1]
	v_lshlrev_b32_e32 v10, 16, v13
	v_and_b32_e32 v11, 0xffff0000, v13
	v_cvt_pk_fp8_f32 v165, v10, v11 op_sel:[0,0,1]
	v_lshlrev_b32_e32 v10, 16, v6
	v_and_b32_e32 v6, 0xffff0000, v6
	v_mov_b32_e32 v166, v171
	v_cvt_pk_fp8_f32 v166, v10, v6
	v_lshlrev_b32_e32 v10, 16, v8
	v_and_b32_e32 v8, 0xffff0000, v8
	v_mov_b32_e32 v167, v171
	v_cvt_pk_fp8_f32 v167, v10, v8
	v_lshlrev_b32_e32 v6, 16, v7
	v_and_b32_e32 v7, 0xffff0000, v7
	v_cvt_pk_fp8_f32 v166, v6, v7 op_sel:[0,0,1]
	v_lshlrev_b32_e32 v6, 16, v9
	v_and_b32_e32 v7, 0xffff0000, v9
	v_cvt_pk_fp8_f32 v167, v6, v7 op_sel:[0,0,1]
	v_lshlrev_b32_e32 v6, 16, v2
	v_and_b32_e32 v2, 0xffff0000, v2
	v_mov_b32_e32 v168, v171
	v_cvt_pk_fp8_f32 v168, v6, v2
	v_lshlrev_b32_e32 v6, 16, v4
	v_and_b32_e32 v4, 0xffff0000, v4
	v_mov_b32_e32 v169, v171
	v_cvt_pk_fp8_f32 v169, v6, v4
	v_lshlrev_b32_e32 v2, 16, v3
	v_and_b32_e32 v3, 0xffff0000, v3
	v_cvt_pk_fp8_f32 v168, v2, v3 op_sel:[0,0,1]
	v_lshlrev_b32_e32 v2, 16, v5
	v_and_b32_e32 v3, 0xffff0000, v5
	v_cvt_pk_fp8_f32 v169, v2, v3 op_sel:[0,0,1]
	v_lshrrev_b32_e32 v2, 1, v55
	v_and_b32_e32 v3, 8, v55
	v_and_or_b32 v2, v2, 3, v3
	v_bfe_u32 v58, v55, 5, 1
	v_lshlrev_b32_e32 v2, 7, v2
	v_lshl_or_b32 v10, v58, 9, v2
	v_lshlrev_b32_e32 v2, 3, v55
	v_lshlrev_b32_e32 v42, 3, v52
	v_or_b32_e32 v61, 32, v52
	v_and_b32_e32 v11, 8, v2
	s_waitcnt lgkmcnt(0)
	v_bitop3_b32 v12, v42, v56, s45 bitop3:0x6c
	v_lshl_add_u32 v43, v52, 7, s63
	v_or_b32_e32 v2, 16, v56
	v_lshl_add_u32 v44, v61, 7, s63
	s_barrier
	v_add_u32_e32 v213, v43, v12
	v_bitop3_b32 v13, v42, v2, s45 bitop3:0x6c
	v_add_u32_e32 v215, v44, v12
	v_add_u32_e32 v214, v43, v13
	ds_read_b128 v[2:5], v213 offset:32768
	ds_read_b128 v[6:9], v214 offset:32768
	v_add_u32_e32 v216, v44, v13
	ds_read_b128 v[34:37], v215 offset:32768
	ds_read_b128 v[38:41], v216 offset:32768
	v_bfe_u32 v59, v55, 1, 3
	v_add3_u32 v62, v11, s63, v10
	v_bitop3_b32 v10, v57, v59, 1 bitop3:0x6c
	v_lshl_add_u32 v208, v10, 4, v62
	s_waitcnt lgkmcnt(0)
	v_mfma_f32_32x32x64_f8f6f4 v[18:33], v[2:9], v[146:153], 0
	v_mfma_f32_32x32x64_f8f6f4 v[2:17], v[34:41], v[146:153], 0
	v_or_b32_e32 v34, 64, v56
	v_bitop3_b32 v45, v42, v34, s45 bitop3:0x6c
	v_or_b32_e32 v34, 0x50, v56
	v_add_u32_e32 v217, v43, v45
	v_bitop3_b32 v42, v42, v34, s45 bitop3:0x6c
	v_add_u32_e32 v218, v43, v42
	ds_read_b128 v[34:37], v217 offset:32768
	ds_read_b128 v[38:41], v218 offset:32768
	v_add_u32_e32 v211, v44, v45
	v_add_u32_e32 v212, v44, v42
	ds_read_b128 v[42:45], v211 offset:32768
	ds_read_b128 v[46:49], v212 offset:32768
	s_waitcnt lgkmcnt(2)
	v_mfma_f32_32x32x64_f8f6f4 v[18:33], v[34:41], v[154:161], v[18:33]
	v_lshlrev_b32_e32 v34, 1, v58
	v_lshrrev_b32_e32 v35, 2, v55
	v_and_b32_e32 v199, 63, v55
	v_and_b32_e32 v60, 1, v57
	v_lshlrev_b32_e32 v57, 6, v52
	v_bfe_u32 v36, v55, 2, 2
	v_bitop3_b32 v35, v34, v35, 3 bitop3:0x78
	v_lshlrev_b32_e32 v55, 6, v61
	s_waitcnt lgkmcnt(0)
	v_mfma_f32_32x32x64_f8f6f4 v[2:17], v[42:49], v[154:161], v[2:17]
	v_lshlrev_b32_e32 v219, 4, v35
	v_add_u32_e32 v35, s37, v57
	v_bitop3_b32 v34, v34, v36, 1 bitop3:0x36
	v_add_u32_e32 v42, s37, v55
	v_add_u32_e32 v220, v35, v219
	v_lshlrev_b32_e32 v221, 4, v34
	v_add_u32_e32 v223, v42, v219
	v_add_u32_e32 v222, v35, v221
	ds_read_b128 v[34:37], v220
	ds_read_b128 v[38:41], v222
	v_add_u32_e32 v224, v42, v221
	ds_read_b128 v[42:45], v223
	ds_read_b128 v[46:49], v224
	s_waitcnt lgkmcnt(2)
	v_mfma_f32_32x32x64_f8f6f4 v[18:33], v[34:41], v[162:169], v[18:33]
	s_waitcnt lgkmcnt(0)
	v_mfma_f32_32x32x64_f8f6f4 v[2:17], v[42:49], v[162:169], v[2:17]
	s_nop 0
	s_nop 15
	s_nop 7
	s_and_b32 s2, s54, 0x3fffffc0
	v_max_f32_e32 v34, v18, v19
	v_max3_f32 v34, v34, v20, v21
	v_max3_f32 v34, v34, v22, v23
	v_max3_f32 v34, v34, v24, v25
	v_max3_f32 v34, v34, v26, v27
	v_max3_f32 v34, v34, v28, v29
	v_max3_f32 v34, v34, v30, v31
	v_max3_f32 v34, v34, v32, v33
	v_max3_f32 v34, v34, v2, v3
	v_max3_f32 v34, v34, v4, v5
	v_max3_f32 v34, v34, v6, v7
	v_max3_f32 v34, v34, v8, v9
	v_max3_f32 v34, v34, v10, v11
	v_max3_f32 v34, v34, v12, v13
	v_max3_f32 v34, v34, v14, v15
	v_max3_f32 v34, v34, v16, v17
	v_mov_b32_e32 v35, v34
	s_nop 1
	v_permlane32_swap_b32_e32 v34, v35
	v_max_f32_e32 v34, v34, v35
	s_lshl_b32 s2, s2, 2
	v_add_f32_e32 v35, 0x7149f2ca, v34
	s_add_i32 s54, s36, s2
	v_cmp_ge_f32_e32 vcc, s46, v35
	s_cmp_eq_u64 vcc, exec
	v_max_f32_e32 v34, 0xf149f2ca, v34
	s_cselect_b64 vcc, -1, 0
	v_cndmask_b32_e32 v233, v34, v198, vcc
	v_sub_f32_e32 v36, 0xf149f2ca, v34
	v_fma_f32 v34, v233, s47, 4.0
	v_mov_b32_e32 v35, v34
	s_add_u32 s2, s26, s28
	v_fmac_f32_e32 v35, 0x3dd53b94, v33
	s_addc_u32 s3, s27, s29
	s_add_i32 s55, s63, s55
	v_pk_fma_f32 v[66:67], v[2:3], s[6:7], v[34:35] op_sel_hi:[1,0,0]
	v_lshl_add_u64 v[2:3], s[2:3], 0, v[174:175]
	s_add_i32 s58, s55, 0x4000
	v_lshl_add_u64 v[2:3], v[2:3], 0, s[8:9]
	s_mov_b32 m0, s58
	v_lshl_add_u64 v[176:177], s[24:25], 0, v[172:173]
	global_load_lds_dwordx4 v[2:3], off
	s_add_u32 s24, s40, s53
	s_addc_u32 s25, s41, 0
	s_add_u32 s24, s24, s28
	v_mul_f32_e32 v36, 0x3dd53b94, v36
	s_addc_u32 s25, s25, s29
	v_bitop3_b32 v56, v60, v59, 2 bitop3:0x36
	v_exp_f32_e32 v36, v36
	v_fmamk_f32 v18, v18, 0x3dd53b94, v34
	v_fmamk_f32 v19, v19, 0x3dd53b94, v34
	v_fmamk_f32 v20, v20, 0x3dd53b94, v34
	v_fmamk_f32 v21, v21, 0x3dd53b94, v34
	v_fmamk_f32 v22, v22, 0x3dd53b94, v34
	v_fmamk_f32 v23, v23, 0x3dd53b94, v34
	v_fmamk_f32 v24, v24, 0x3dd53b94, v34
	v_fmamk_f32 v25, v25, 0x3dd53b94, v34
	v_fmamk_f32 v26, v26, 0x3dd53b94, v34
	v_fmamk_f32 v27, v27, 0x3dd53b94, v34
	v_fmamk_f32 v28, v28, 0x3dd53b94, v34
	v_fmamk_f32 v29, v29, 0x3dd53b94, v34
	v_fmamk_f32 v30, v30, 0x3dd53b94, v34
	v_fmamk_f32 v31, v31, 0x3dd53b94, v34
	v_fmamk_f32 v32, v32, 0x3dd53b94, v34
	v_lshl_add_u64 v[184:185], s[24:25], 0, v[174:175]
	s_add_u32 s24, s28, s53
	v_lshl_add_u32 v210, v56, 4, v62
	v_bitop3_b32 v56, v60, v59, 4 bitop3:0x36
	v_exp_f32_e32 v82, v18
	v_exp_f32_e32 v83, v19
	v_exp_f32_e32 v84, v20
	v_exp_f32_e32 v85, v21
	v_exp_f32_e32 v190, v22
	v_exp_f32_e32 v191, v23
	v_exp_f32_e32 v188, v24
	v_exp_f32_e32 v189, v25
	v_exp_f32_e32 v144, v26
	v_exp_f32_e32 v145, v27
	v_exp_f32_e32 v138, v28
	v_exp_f32_e32 v139, v29
	v_exp_f32_e32 v142, v30
	v_exp_f32_e32 v143, v31
	v_exp_f32_e32 v140, v32
	v_exp_f32_e32 v141, v35
	s_waitcnt vmcnt(1)
	v_lshl_add_u64 v[2:3], s[4:5], 0, v[50:51]
	s_addc_u32 s25, s29, 0
	v_lshl_add_u32 v209, v56, 4, v62
	v_bitop3_b32 v56, v60, v59, 6 bitop3:0x36
	s_barrier
	v_lshl_add_u64 v[182:183], v[2:3], 0, v[170:171]
	v_add_u32_e32 v2, v54, v53
	s_add_u32 s24, s42, s24
	v_lshl_add_u32 v206, v56, 4, v62
	v_ashrrev_i32_e32 v3, 31, v2
	s_addc_u32 s25, s43, s25
	v_mov_b32_e32 v200, 0
	s_mov_b32 s23, 2
	v_cndmask_b32_e64 v225, v36, 1.0, vcc
	v_pk_fma_f32 v[80:81], v[16:17], s[6:7], v[34:35] op_sel_hi:[1,0,0]
	v_pk_fma_f32 v[78:79], v[14:15], s[6:7], v[34:35] op_sel_hi:[1,0,0]
	v_pk_fma_f32 v[76:77], v[12:13], s[6:7], v[34:35] op_sel_hi:[1,0,0]
	v_pk_fma_f32 v[74:75], v[10:11], s[6:7], v[34:35] op_sel_hi:[1,0,0]
	v_pk_fma_f32 v[72:73], v[8:9], s[6:7], v[34:35] op_sel_hi:[1,0,0]
	v_pk_fma_f32 v[70:71], v[6:7], s[6:7], v[34:35] op_sel_hi:[1,0,0]
	v_pk_fma_f32 v[68:69], v[4:5], s[6:7], v[34:35] op_sel_hi:[1,0,0]
	v_add_u32_e32 v226, s38, v57
	v_add_u32_e32 v227, s38, v55
	v_cmp_gt_u32_e64 s[2:3], 32, v199
	v_lshl_add_u32 v207, v52, 2, s54
	v_lshl_add_u32 v205, v58, 4, s54
	v_add_u32_e32 v204, 0x4000, v208
	v_add_u32_e32 v203, 0x4000, v210
	v_add_u32_e32 v202, 0x4000, v209
	v_add_u32_e32 v201, 0x4000, v206
	v_lshl_add_u64 v[178:179], s[0:1], 0, v[170:171]
	v_lshl_add_u64 v[180:181], s[26:27], 0, v[174:175]
	v_lshl_add_u64 v[186:187], s[24:25], 0, v[2:3]
	s_movk_i32 s28, 0xc0
	v_mov_b32_e32 v2, 0
	v_mov_b32_e32 v3, v200
	v_mov_b32_e32 v4, v200
	v_mov_b32_e32 v5, v200
	v_mov_b32_e32 v6, v200
	v_mov_b32_e32 v7, v200
	v_mov_b32_e32 v8, v200
	v_mov_b32_e32 v9, v200
	v_mov_b32_e32 v10, v200
	v_mov_b32_e32 v11, v200
	v_mov_b32_e32 v12, v200
	v_mov_b32_e32 v13, v200
	v_mov_b32_e32 v14, v200
	v_mov_b32_e32 v15, v200
	v_mov_b32_e32 v16, v200
	v_mov_b32_e32 v17, v200
	v_mov_b32_e32 v18, 0
	v_mov_b32_e32 v19, v200
	v_mov_b32_e32 v20, v200
	v_mov_b32_e32 v21, v200
	v_mov_b32_e32 v22, v200
	v_mov_b32_e32 v23, v200
	v_mov_b32_e32 v24, v200
	v_mov_b32_e32 v25, v200
	v_mov_b32_e32 v26, v200
	v_mov_b32_e32 v27, v200
	v_mov_b32_e32 v28, v200
	v_mov_b32_e32 v29, v200
	v_mov_b32_e32 v30, v200
	v_mov_b32_e32 v31, v200
	v_mov_b32_e32 v32, v200
	v_mov_b32_e32 v33, v200
	v_mov_b32_e32 v34, 0
	v_mov_b32_e32 v35, v200
	v_mov_b32_e32 v36, v200
	v_mov_b32_e32 v37, v200
	v_mov_b32_e32 v38, v200
	v_mov_b32_e32 v39, v200
	v_mov_b32_e32 v40, v200
	v_mov_b32_e32 v41, v200
	v_mov_b32_e32 v42, v200
	v_mov_b32_e32 v43, v200
	v_mov_b32_e32 v44, v200
	v_mov_b32_e32 v45, v200
	v_mov_b32_e32 v46, v200
	v_mov_b32_e32 v47, v200
	v_mov_b32_e32 v48, v200
	v_mov_b32_e32 v49, v200
	v_mov_b32_e32 v50, 0
	v_mov_b32_e32 v51, v200
	v_mov_b32_e32 v52, v200
	v_mov_b32_e32 v53, v200
	v_mov_b32_e32 v54, v200
	v_mov_b32_e32 v55, v200
	v_mov_b32_e32 v56, v200
	v_mov_b32_e32 v57, v200
	v_mov_b32_e32 v58, v200
	v_mov_b32_e32 v59, v200
	v_mov_b32_e32 v60, v200
	v_mov_b32_e32 v61, v200
	v_mov_b32_e32 v62, v200
	v_mov_b32_e32 v63, v200
	v_mov_b32_e32 v64, v200
	v_mov_b32_e32 v65, v200
.LBB0_507:
	ds_read_b128 v[102:105], v213 offset:49152
	ds_read_b128 v[106:109], v214 offset:49152
	ds_read_b128 v[130:133], v215 offset:49152
	ds_read_b128 v[134:137], v216 offset:49152
	s_add_i32 s27, s55, 0x8000
	s_mov_b32 m0, s27
	s_add_i32 s26, s37, s57
	global_load_lds_dwordx4 v[186:187], off
	s_mov_b32 m0, s26
	s_nop 0
	global_load_lds_dwordx4 v[182:183], off
	v_add_u32_e32 v228, v226, v219
	v_add_u32_e32 v229, v226, v221
	s_waitcnt lgkmcnt(2)
	v_mfma_f32_32x32x64_f8f6f4 v[86:101], v[102:109], v[146:153], 0
	ds_read_b128 v[102:105], v217 offset:49152
	ds_read_b128 v[106:109], v218 offset:49152
	v_exp_f32_e32 v66, v66
	v_exp_f32_e32 v67, v67
	v_exp_f32_e32 v68, v68
	s_waitcnt lgkmcnt(2)
	v_mfma_f32_32x32x64_f8f6f4 v[114:129], v[130:137], v[146:153], 0
	ds_read_b128 v[234:237], v211 offset:49152
	ds_read_b128 v[238:241], v212 offset:49152
	v_exp_f32_e32 v69, v69
	v_exp_f32_e32 v70, v70
	v_exp_f32_e32 v71, v71
	s_waitcnt lgkmcnt(2)
	v_mfma_f32_32x32x64_f8f6f4 v[86:101], v[102:109], v[154:161], v[86:101]
	ds_read_b128 v[102:105], v228
	ds_read_b128 v[106:109], v229
	v_exp_f32_e32 v72, v72
	v_exp_f32_e32 v73, v73
	v_exp_f32_e32 v74, v74
	v_add_u32_e32 v231, v227, v219
	s_waitcnt lgkmcnt(2)
	v_mfma_f32_32x32x64_f8f6f4 v[114:129], v[234:241], v[154:161], v[114:129]
	v_add_u32_e32 v232, v227, v221
	ds_read_b128 v[234:237], v231
	ds_read_b128 v[238:241], v232
	v_exp_f32_e32 v75, v75
	v_exp_f32_e32 v76, v76
	v_exp_f32_e32 v77, v77
	s_waitcnt lgkmcnt(2)
	v_mfma_f32_32x32x64_f8f6f4 v[86:101], v[102:109], v[162:169], v[86:101]
	v_exp_f32_e32 v78, v78
	v_exp_f32_e32 v79, v79
	s_waitcnt lgkmcnt(0)
	v_mfma_f32_32x32x64_f8f6f4 v[114:129], v[234:241], v[162:169], v[114:129]
	ds_read_b64_tr_b8 v[102:103], v208 offset:0
	ds_read_b64_tr_b8 v[104:105], v208 offset:0x800
	ds_read_b64_tr_b8 v[106:107], v208 offset:0x1000
	ds_read_b64_tr_b8 v[108:109], v208 offset:0x1800
	v_cvt_pk_fp8_f32 v130, v82, v83
	v_cvt_pk_fp8_f32 v131, v190, v191
	v_cvt_pk_fp8_f32 v132, v144, v145
	v_cvt_pk_fp8_f32 v134, v66, v67
	v_cvt_pk_fp8_f32 v135, v70, v71
	v_exp_f32_e32 v80, v80
	v_exp_f32_e32 v81, v81
	v_cvt_pk_fp8_f32 v136, v74, v75
	v_cvt_pk_fp8_f32 v133, v142, v143
	v_cvt_pk_fp8_f32 v137, v78, v79
	ds_read_b64_tr_b8 v[236:237], v210 offset:0
	ds_read_b64_tr_b8 v[238:239], v210 offset:0x800
	ds_read_b64_tr_b8 v[240:241], v210 offset:0x1000
	ds_read_b64_tr_b8 v[242:243], v210 offset:0x1800
	v_cvt_pk_fp8_f32 v130, v84, v85 op_sel:[0,0,1]
	v_cvt_pk_fp8_f32 v131, v188, v189 op_sel:[0,0,1]
	v_cvt_pk_fp8_f32 v134, v68, v69 op_sel:[0,0,1]
	v_cvt_pk_fp8_f32 v135, v72, v73 op_sel:[0,0,1]
	v_cvt_pk_fp8_f32 v132, v138, v139 op_sel:[0,0,1]
	v_cvt_pk_fp8_f32 v136, v76, v77 op_sel:[0,0,1]
	v_cvt_pk_fp8_f32 v133, v140, v141 op_sel:[0,0,1]
	v_cvt_pk_fp8_f32 v137, v80, v81 op_sel:[0,0,1]
	s_waitcnt lgkmcnt(4)
	s_mov_b32 m0, s55
	v_mfma_f32_32x32x64_f8f6f4 v[2:17], v[130:137], v[102:109], v[2:17]
	ds_read_b64_tr_b8 v[244:245], v209 offset:0
	ds_read_b64_tr_b8 v[246:247], v209 offset:0x800
	ds_read_b64_tr_b8 v[248:249], v209 offset:0x1000
	ds_read_b64_tr_b8 v[250:251], v209 offset:0x1800
	s_waitcnt lgkmcnt(4)
	s_nop 0
	v_max_f32_e32 v102, v86, v87
	v_max3_f32 v102, v102, v88, v89
	v_max3_f32 v102, v102, v90, v91
	v_max3_f32 v102, v102, v92, v93
	v_max3_f32 v102, v102, v94, v95
	v_max3_f32 v102, v102, v96, v97
	v_max3_f32 v102, v102, v98, v99
	v_max3_f32 v102, v102, v100, v101
	v_max3_f32 v102, v102, v114, v115
	v_max3_f32 v102, v102, v116, v117
	v_max3_f32 v102, v102, v118, v119
	v_max3_f32 v102, v102, v120, v121
	v_max3_f32 v102, v102, v122, v123
	v_max3_f32 v102, v102, v124, v125
	v_max3_f32 v102, v102, v126, v127
	v_max3_f32 v102, v102, v128, v129
	v_mov_b32_e32 v103, v102
	s_nop 1
	v_permlane32_swap_b32_e32 v102, v103
	v_max_f32_e32 v102, v102, v103
	v_sub_f32_e32 v103, v102, v233
	v_cmp_ge_f32_e32 vcc, s46, v103
	s_cmp_eq_u64 vcc, exec
	v_max_f32_e32 v103, v233, v233
	v_max_f32_e32 v193, v103, v102
	s_cselect_b64 vcc, -1, 0
	v_cndmask_b32_e32 v235, v193, v233, vcc
	v_fma_f32 v192, v235, s47, 4.0
	v_mfma_f32_32x32x64_f8f6f4 v[18:33], v[130:137], v[236:243], v[18:33]
	v_pk_add_f32 v[82:83], v[82:83], v[84:85]
	v_pk_fma_f32 v[110:111], v[98:99], s[6:7], v[192:193] op_sel_hi:[1,0,0]
	v_pk_fma_f32 v[98:99], v[86:87], s[6:7], v[192:193] op_sel_hi:[1,0,0]
	ds_read_b64_tr_b8 v[86:87], v206 offset:0
	v_pk_fma_f32 v[112:113], v[100:101], s[6:7], v[192:193] op_sel_hi:[1,0,0]
	v_pk_fma_f32 v[100:101], v[88:89], s[6:7], v[192:193] op_sel_hi:[1,0,0]
	ds_read_b64_tr_b8 v[88:89], v206 offset:0x800
	v_pk_fma_f32 v[102:103], v[90:91], s[6:7], v[192:193] op_sel_hi:[1,0,0]
	ds_read_b64_tr_b8 v[90:91], v206 offset:0x1000
	v_pk_fma_f32 v[108:109], v[96:97], s[6:7], v[192:193] op_sel_hi:[1,0,0]
	v_pk_fma_f32 v[106:107], v[94:95], s[6:7], v[192:193] op_sel_hi:[1,0,0]
	v_pk_fma_f32 v[104:105], v[92:93], s[6:7], v[192:193] op_sel_hi:[1,0,0]
	v_pk_fma_f32 v[128:129], v[128:129], s[6:7], v[192:193] op_sel_hi:[1,0,0]
	v_pk_fma_f32 v[126:127], v[126:127], s[6:7], v[192:193] op_sel_hi:[1,0,0]
	v_pk_fma_f32 v[124:125], v[124:125], s[6:7], v[192:193] op_sel_hi:[1,0,0]
	v_pk_fma_f32 v[122:123], v[122:123], s[6:7], v[192:193] op_sel_hi:[1,0,0]
	v_pk_fma_f32 v[120:121], v[120:121], s[6:7], v[192:193] op_sel_hi:[1,0,0]
	v_pk_fma_f32 v[118:119], v[118:119], s[6:7], v[192:193] op_sel_hi:[1,0,0]
	v_pk_fma_f32 v[116:117], v[116:117], s[6:7], v[192:193] op_sel_hi:[1,0,0]
	v_pk_fma_f32 v[114:115], v[114:115], s[6:7], v[192:193] op_sel_hi:[1,0,0]
	ds_read_b64_tr_b8 v[92:93], v206 offset:0x1800
	s_waitcnt lgkmcnt(4)
	v_pk_add_f32 v[82:83], v[190:191], v[82:83]
	v_mfma_f32_32x32x64_f8f6f4 v[34:49], v[130:137], v[244:251], v[34:49]
	s_waitcnt lgkmcnt(0)
	s_nop 0
	v_exp_f32_e32 v98, v98
	v_exp_f32_e32 v99, v99
	v_exp_f32_e32 v100, v100
	v_exp_f32_e32 v101, v101
	v_mfma_f32_32x32x64_f8f6f4 v[50:65], v[130:137], v[86:93], v[50:65]
	s_barrier
	global_load_lds_dwordx4 v[184:185], off
	v_pk_add_f32 v[82:83], v[188:189], v[82:83]
	s_nop 0
	v_pk_add_f32 v[82:83], v[144:145], v[82:83]
	s_nop 0
	v_pk_add_f32 v[82:83], v[138:139], v[82:83]
	s_nop 0
	v_pk_add_f32 v[82:83], v[142:143], v[82:83]
	s_nop 0
	v_pk_add_f32 v[82:83], v[140:141], v[82:83]
	s_nop 0
	v_pk_add_f32 v[66:67], v[82:83], v[66:67]
	s_nop 0
	v_pk_add_f32 v[66:67], v[68:69], v[66:67]
	s_nop 0
	v_pk_add_f32 v[66:67], v[70:71], v[66:67]
	s_nop 0
	v_pk_add_f32 v[66:67], v[72:73], v[66:67]
	s_nop 0
	v_pk_add_f32 v[66:67], v[74:75], v[66:67]
	s_nop 0
	v_pk_add_f32 v[66:67], v[76:77], v[66:67]
	s_nop 0
	v_pk_add_f32 v[66:67], v[78:79], v[66:67]
	s_nop 0
	v_pk_add_f32 v[66:67], v[80:81], v[66:67]
	s_nop 0
	v_pk_add_f32 v[188:189], v[66:67], v[66:67] op_sel:[0,1] op_sel_hi:[1,0]
	v_sub_f32_e32 v66, v233, v193
	v_mul_f32_e32 v66, 0x3dd53b94, v66
	v_exp_f32_e32 v66, v66
	v_mov_b32_e32 v234, v188
	s_nop 1
	v_permlane32_swap_b32_e32 v188, v234
	v_cndmask_b32_e64 v189, v66, 1.0, vcc
	v_cmp_gt_f32_e32 vcc, 1.0, v189
	s_cbranch_vccz .LBB0_511
	s_and_saveexec_b64 s[24:25], s[2:3]
	ds_write_b32 v207, v189 offset:128
	s_or_b64 exec, exec, s[24:25]
	s_waitcnt lgkmcnt(0)
	s_nop 15
	s_nop 7
	ds_read2_b32 v[66:67], v205 offset0:32 offset1:33
	ds_read2_b32 v[68:69], v205 offset0:34 offset1:35
	ds_read2_b32 v[70:71], v205 offset0:40 offset1:41
	ds_read2_b32 v[72:73], v205 offset0:42 offset1:43
	s_waitcnt lgkmcnt(0)
	v_pk_mul_f32 v[2:3], v[66:67], v[2:3]
	v_pk_mul_f32 v[18:19], v[66:67], v[18:19]
	v_pk_mul_f32 v[34:35], v[66:67], v[34:35]
	v_pk_mul_f32 v[50:51], v[66:67], v[50:51]
	v_pk_mul_f32 v[4:5], v[4:5], v[68:69]
	v_pk_mul_f32 v[20:21], v[20:21], v[68:69]
	v_pk_mul_f32 v[36:37], v[36:37], v[68:69]
	v_pk_mul_f32 v[52:53], v[52:53], v[68:69]
	v_pk_mul_f32 v[6:7], v[6:7], v[70:71]
	v_pk_mul_f32 v[22:23], v[22:23], v[70:71]
	v_pk_mul_f32 v[38:39], v[38:39], v[70:71]
	v_pk_mul_f32 v[54:55], v[54:55], v[70:71]
	v_pk_mul_f32 v[8:9], v[8:9], v[72:73]
	v_pk_mul_f32 v[24:25], v[24:25], v[72:73]
	v_pk_mul_f32 v[40:41], v[40:41], v[72:73]
	ds_read2_b32 v[66:67], v205 offset0:48 offset1:49
	v_pk_mul_f32 v[56:57], v[56:57], v[72:73]
	ds_read2_b32 v[68:69], v205 offset0:50 offset1:51
	ds_read2_b32 v[70:71], v205 offset0:56 offset1:57
	ds_read2_b32 v[72:73], v205 offset0:58 offset1:59
	s_waitcnt lgkmcnt(0)
	v_pk_mul_f32 v[10:11], v[10:11], v[66:67]
	v_pk_mul_f32 v[26:27], v[26:27], v[66:67]
	v_pk_mul_f32 v[42:43], v[42:43], v[66:67]
	v_pk_mul_f32 v[58:59], v[58:59], v[66:67]
	v_pk_mul_f32 v[12:13], v[12:13], v[68:69]
	v_pk_mul_f32 v[28:29], v[28:29], v[68:69]
	v_pk_mul_f32 v[44:45], v[44:45], v[68:69]
	v_pk_mul_f32 v[60:61], v[60:61], v[68:69]
	v_pk_mul_f32 v[14:15], v[14:15], v[70:71]
	v_pk_mul_f32 v[30:31], v[30:31], v[70:71]
	v_pk_mul_f32 v[46:47], v[46:47], v[70:71]
	v_pk_mul_f32 v[62:63], v[62:63], v[70:71]
	v_pk_mul_f32 v[16:17], v[16:17], v[72:73]
	v_pk_mul_f32 v[32:33], v[32:33], v[72:73]
	v_pk_mul_f32 v[48:49], v[48:49], v[72:73]
	v_pk_mul_f32 v[64:65], v[64:65], v[72:73]
.LBB0_511:
	s_add_i32 s24, s23, 1
	s_cmp_lt_u32 s24, s56
	s_cselect_b32 s24, 0, s56
	s_cselect_b32 s25, s22, 0
	s_lshl_b32 s24, s24, 6
	s_ashr_i32 s29, s25, 31
	s_sub_i32 s24, s28, s24
	s_add_u32 s60, s24, s25
	s_addc_u32 s61, 0, s29
	s_waitcnt vmcnt(1)
	s_lshl_b64 s[24:25], s[60:61], 11
	s_add_i32 s59, s55, 0xc000
	s_barrier
	ds_read_b128 v[82:85], v213 offset:32768
	ds_read_b128 v[86:89], v214 offset:32768
	ds_read_b128 v[90:93], v215 offset:32768
	ds_read_b128 v[94:97], v216 offset:32768
	v_lshl_add_u64 v[66:67], v[176:177], 0, s[24:25]
	s_mov_b32 m0, s59
	s_lshl_b64 s[60:61], s[60:61], 6
	s_add_i32 s29, s38, s57
	global_load_lds_dwordx4 v[66:67], off
	v_lshl_add_u64 v[66:67], v[178:179], 0, s[60:61]
	s_mov_b32 m0, s29
	v_exp_f32_e32 v190, v102
	global_load_lds_dwordx4 v[66:67], off
	v_exp_f32_e32 v191, v103
	v_exp_f32_e32 v192, v104
	v_exp_f32_e32 v193, v105
	v_exp_f32_e32 v194, v106
	v_exp_f32_e32 v195, v107
	v_exp_f32_e32 v196, v108
	v_exp_f32_e32 v197, v109
	v_exp_f32_e32 v110, v110
	v_exp_f32_e32 v111, v111
	v_exp_f32_e32 v112, v112
	v_exp_f32_e32 v113, v113
	v_mov_b32_e32 v102, 0
	v_mov_b32_e32 v103, 0
	s_waitcnt lgkmcnt(2)
	v_mfma_f32_32x32x64_f8f6f4 v[66:81], v[82:89], v[146:153], 0
	ds_read_b128 v[82:85], v217 offset:32768
	ds_read_b128 v[86:89], v218 offset:32768
	v_exp_f32_e32 v114, v114
	v_exp_f32_e32 v115, v115
	v_exp_f32_e32 v116, v116
	s_waitcnt lgkmcnt(2)
	v_mfma_f32_32x32x64_f8f6f4 v[130:145], v[90:97], v[146:153], 0
	ds_read_b128 v[90:93], v211 offset:32768
	ds_read_b128 v[94:97], v212 offset:32768
	v_exp_f32_e32 v117, v117
	v_exp_f32_e32 v118, v118
	v_exp_f32_e32 v119, v119
	s_waitcnt lgkmcnt(2)
	v_mfma_f32_32x32x64_f8f6f4 v[66:81], v[82:89], v[154:161], v[66:81]
	ds_read_b128 v[82:85], v220
	ds_read_b128 v[86:89], v222
	v_exp_f32_e32 v120, v120
	v_exp_f32_e32 v121, v121
	v_exp_f32_e32 v122, v122
	s_waitcnt lgkmcnt(2)
	v_mfma_f32_32x32x64_f8f6f4 v[130:145], v[90:97], v[154:161], v[130:145]
	ds_read_b128 v[90:93], v223
	ds_read_b128 v[94:97], v224
	v_exp_f32_e32 v123, v123
	v_exp_f32_e32 v124, v124
	v_exp_f32_e32 v125, v125
	s_waitcnt lgkmcnt(2)
	v_mfma_f32_32x32x64_f8f6f4 v[66:81], v[82:89], v[162:169], v[66:81]
	v_exp_f32_e32 v126, v126
	v_exp_f32_e32 v127, v127
	s_waitcnt lgkmcnt(0)
	v_mfma_f32_32x32x64_f8f6f4 v[130:145], v[90:97], v[162:169], v[130:145]
	ds_read_b64_tr_b8 v[82:83], v204 offset:0
	ds_read_b64_tr_b8 v[84:85], v204 offset:0x800
	ds_read_b64_tr_b8 v[86:87], v204 offset:0x1000
	ds_read_b64_tr_b8 v[88:89], v204 offset:0x1800
	v_cvt_pk_fp8_f32 v102, v98, v99
	v_cvt_pk_fp8_f32 v103, v190, v191
	v_cvt_pk_fp8_f32 v104, v194, v195
	v_cvt_pk_fp8_f32 v105, v110, v111
	v_exp_f32_e32 v128, v128
	v_cvt_pk_fp8_f32 v106, v114, v115
	v_cvt_pk_fp8_f32 v107, v118, v119
	v_exp_f32_e32 v129, v129
	v_cvt_pk_fp8_f32 v108, v122, v123
	v_cvt_pk_fp8_f32 v109, v126, v127
	ds_read_b64_tr_b8 v[90:91], v203 offset:0
	ds_read_b64_tr_b8 v[92:93], v203 offset:0x800
	ds_read_b64_tr_b8 v[94:95], v203 offset:0x1000
	ds_read_b64_tr_b8 v[96:97], v203 offset:0x1800
	v_cvt_pk_fp8_f32 v102, v100, v101 op_sel:[0,0,1]
	v_cvt_pk_fp8_f32 v103, v192, v193 op_sel:[0,0,1]
	v_cvt_pk_fp8_f32 v106, v116, v117 op_sel:[0,0,1]
	v_cvt_pk_fp8_f32 v107, v120, v121 op_sel:[0,0,1]
	v_cvt_pk_fp8_f32 v104, v196, v197 op_sel:[0,0,1]
	v_cvt_pk_fp8_f32 v108, v124, v125 op_sel:[0,0,1]
	v_cvt_pk_fp8_f32 v105, v112, v113 op_sel:[0,0,1]
	v_cvt_pk_fp8_f32 v109, v128, v129 op_sel:[0,0,1]
	s_waitcnt lgkmcnt(4)
	s_mov_b32 m0, s58
	v_mfma_f32_32x32x64_f8f6f4 v[2:17], v[102:109], v[82:89], v[2:17]
	ds_read_b64_tr_b8 v[236:237], v202 offset:0
	ds_read_b64_tr_b8 v[238:239], v202 offset:0x800
	ds_read_b64_tr_b8 v[240:241], v202 offset:0x1000
	ds_read_b64_tr_b8 v[242:243], v202 offset:0x1800
	s_waitcnt lgkmcnt(4)
	s_nop 0
	v_max_f32_e32 v82, v66, v67
	v_max3_f32 v82, v82, v68, v69
	v_max3_f32 v82, v82, v70, v71
	v_max3_f32 v82, v82, v72, v73
	v_max3_f32 v82, v82, v74, v75
	v_max3_f32 v82, v82, v76, v77
	v_max3_f32 v82, v82, v78, v79
	v_max3_f32 v82, v82, v80, v81
	v_max3_f32 v82, v82, v130, v131
	v_max3_f32 v82, v82, v132, v133
	v_max3_f32 v82, v82, v134, v135
	v_max3_f32 v82, v82, v136, v137
	v_max3_f32 v82, v82, v138, v139
	v_max3_f32 v82, v82, v140, v141
	v_max3_f32 v82, v82, v142, v143
	v_max3_f32 v82, v82, v144, v145
	v_mov_b32_e32 v83, v82
	s_nop 1
	v_permlane32_swap_b32_e32 v82, v83
	v_max_f32_e32 v82, v82, v83
	v_sub_f32_e32 v83, v82, v235
	v_cmp_ge_f32_e32 vcc, s46, v83
	s_cmp_eq_u64 vcc, exec
	v_max_f32_e32 v83, v235, v235
	v_max_f32_e32 v245, v83, v82
	s_cselect_b64 vcc, -1, 0
	v_cndmask_b32_e32 v233, v245, v235, vcc
	v_fma_f32 v244, v233, s47, 4.0
	v_mfma_f32_32x32x64_f8f6f4 v[18:33], v[102:109], v[90:97], v[18:33]
	v_pk_add_f32 v[98:99], v[98:99], v[100:101]
	v_pk_fma_f32 v[82:83], v[66:67], s[6:7], v[244:245] op_sel_hi:[1,0,0]
	v_pk_fma_f32 v[66:67], v[130:131], s[6:7], v[244:245] op_sel_hi:[1,0,0]
	ds_read_b64_tr_b8 v[130:131], v201 offset:0
	v_pk_fma_f32 v[84:85], v[68:69], s[6:7], v[244:245] op_sel_hi:[1,0,0]
	v_pk_fma_f32 v[68:69], v[132:133], s[6:7], v[244:245] op_sel_hi:[1,0,0]
	ds_read_b64_tr_b8 v[132:133], v201 offset:0x800
	v_pk_fma_f32 v[86:87], v[70:71], s[6:7], v[244:245] op_sel_hi:[1,0,0]
	v_pk_fma_f32 v[70:71], v[134:135], s[6:7], v[244:245] op_sel_hi:[1,0,0]
	ds_read_b64_tr_b8 v[134:135], v201 offset:0x1000
	v_pk_fma_f32 v[96:97], v[80:81], s[6:7], v[244:245] op_sel_hi:[1,0,0]
	v_pk_fma_f32 v[94:95], v[78:79], s[6:7], v[244:245] op_sel_hi:[1,0,0]
	v_pk_fma_f32 v[92:93], v[76:77], s[6:7], v[244:245] op_sel_hi:[1,0,0]
	v_pk_fma_f32 v[90:91], v[74:75], s[6:7], v[244:245] op_sel_hi:[1,0,0]
	v_pk_fma_f32 v[88:89], v[72:73], s[6:7], v[244:245] op_sel_hi:[1,0,0]
	v_pk_fma_f32 v[80:81], v[144:145], s[6:7], v[244:245] op_sel_hi:[1,0,0]
	v_pk_fma_f32 v[78:79], v[142:143], s[6:7], v[244:245] op_sel_hi:[1,0,0]
	v_pk_fma_f32 v[76:77], v[140:141], s[6:7], v[244:245] op_sel_hi:[1,0,0]
	v_pk_fma_f32 v[74:75], v[138:139], s[6:7], v[244:245] op_sel_hi:[1,0,0]
	v_pk_fma_f32 v[72:73], v[136:137], s[6:7], v[244:245] op_sel_hi:[1,0,0]
	ds_read_b64_tr_b8 v[136:137], v201 offset:0x1800
	s_waitcnt lgkmcnt(4)
	v_pk_add_f32 v[98:99], v[98:99], v[190:191]
	v_mfma_f32_32x32x64_f8f6f4 v[34:49], v[102:109], v[236:243], v[34:49]
	s_waitcnt lgkmcnt(0)
	s_nop 0
	v_exp_f32_e32 v82, v82
	v_exp_f32_e32 v83, v83
	v_exp_f32_e32 v84, v84
	v_exp_f32_e32 v85, v85
	v_mfma_f32_32x32x64_f8f6f4 v[50:65], v[102:109], v[130:137], v[50:65]
	s_barrier
	v_lshl_add_u64 v[102:103], v[180:181], 0, s[24:25]
	global_load_lds_dwordx4 v[102:103], off
	v_pk_add_f32 v[98:99], v[192:193], v[98:99]
	s_nop 0
	v_pk_add_f32 v[98:99], v[194:195], v[98:99]
	s_nop 0
	v_pk_add_f32 v[98:99], v[196:197], v[98:99]
	s_nop 0
	v_pk_add_f32 v[98:99], v[110:111], v[98:99]
	s_nop 0
	v_pk_add_f32 v[98:99], v[112:113], v[98:99]
	s_nop 0
	v_pk_add_f32 v[98:99], v[98:99], v[114:115]
	s_nop 0
	v_pk_add_f32 v[98:99], v[116:117], v[98:99]
	s_nop 0
	v_pk_add_f32 v[98:99], v[118:119], v[98:99]
	s_nop 0
	v_pk_add_f32 v[98:99], v[120:121], v[98:99]
	s_nop 0
	v_pk_add_f32 v[98:99], v[122:123], v[98:99]
	s_nop 0
	v_pk_add_f32 v[98:99], v[124:125], v[98:99]
	s_nop 0
	v_pk_add_f32 v[98:99], v[126:127], v[98:99]
	s_nop 0
	v_pk_add_f32 v[98:99], v[128:129], v[98:99]
	s_nop 0
	v_pk_add_f32 v[98:99], v[98:99], v[98:99] op_sel:[0,1] op_sel_hi:[1,0]
	s_nop 0
	v_sub_f32_e32 v99, v235, v245
	v_mul_f32_e32 v99, 0x3dd53b94, v99
	v_exp_f32_e32 v100, v99
	v_mov_b32_e32 v99, v98
	s_nop 1
	v_permlane32_swap_b32_e32 v98, v99
	v_cndmask_b32_e64 v128, v100, 1.0, vcc
	v_cmp_gt_f32_e32 vcc, 1.0, v128
	s_cbranch_vccz .LBB0_515
	s_and_saveexec_b64 s[24:25], s[2:3]
	ds_write_b32 v207, v128 offset:128
	s_or_b64 exec, exec, s[24:25]
	s_waitcnt lgkmcnt(0)
	s_nop 15
	s_nop 7
	ds_read2_b32 v[100:101], v205 offset0:32 offset1:33
	ds_read2_b32 v[102:103], v205 offset0:34 offset1:35
	ds_read2_b32 v[104:105], v205 offset0:40 offset1:41
	ds_read2_b32 v[106:107], v205 offset0:42 offset1:43
	s_waitcnt lgkmcnt(0)
	v_pk_mul_f32 v[2:3], v[100:101], v[2:3]
	v_pk_mul_f32 v[18:19], v[100:101], v[18:19]
	v_pk_mul_f32 v[34:35], v[100:101], v[34:35]
	v_pk_mul_f32 v[50:51], v[100:101], v[50:51]
	v_pk_mul_f32 v[4:5], v[4:5], v[102:103]
	v_pk_mul_f32 v[20:21], v[20:21], v[102:103]
	v_pk_mul_f32 v[36:37], v[36:37], v[102:103]
	v_pk_mul_f32 v[52:53], v[52:53], v[102:103]
	v_pk_mul_f32 v[6:7], v[6:7], v[104:105]
	v_pk_mul_f32 v[22:23], v[22:23], v[104:105]
	v_pk_mul_f32 v[38:39], v[38:39], v[104:105]
	v_pk_mul_f32 v[54:55], v[54:55], v[104:105]
	v_pk_mul_f32 v[8:9], v[8:9], v[106:107]
	v_pk_mul_f32 v[24:25], v[24:25], v[106:107]
	v_pk_mul_f32 v[40:41], v[40:41], v[106:107]
	ds_read2_b32 v[100:101], v205 offset0:48 offset1:49
	v_pk_mul_f32 v[56:57], v[56:57], v[106:107]
	ds_read2_b32 v[102:103], v205 offset0:50 offset1:51
	ds_read2_b32 v[104:105], v205 offset0:56 offset1:57
	ds_read2_b32 v[106:107], v205 offset0:58 offset1:59
	s_waitcnt lgkmcnt(0)
	v_pk_mul_f32 v[10:11], v[10:11], v[100:101]
	v_pk_mul_f32 v[26:27], v[26:27], v[100:101]
	v_pk_mul_f32 v[42:43], v[42:43], v[100:101]
	v_pk_mul_f32 v[58:59], v[58:59], v[100:101]
	v_pk_mul_f32 v[12:13], v[12:13], v[102:103]
	v_pk_mul_f32 v[28:29], v[28:29], v[102:103]
	v_pk_mul_f32 v[44:45], v[44:45], v[102:103]
	v_pk_mul_f32 v[60:61], v[60:61], v[102:103]
	v_pk_mul_f32 v[14:15], v[14:15], v[104:105]
	v_pk_mul_f32 v[30:31], v[30:31], v[104:105]
	v_pk_mul_f32 v[46:47], v[46:47], v[104:105]
	v_pk_mul_f32 v[62:63], v[62:63], v[104:105]
	v_pk_mul_f32 v[16:17], v[16:17], v[106:107]
	v_pk_mul_f32 v[32:33], v[32:33], v[106:107]
	v_pk_mul_f32 v[48:49], v[48:49], v[106:107]
	v_pk_mul_f32 v[64:65], v[64:65], v[106:107]

.LBB0_517:
	ds_read_b128 v[102:105], v213 offset:49152
	ds_read_b128 v[106:109], v214 offset:49152
	ds_read_b128 v[120:123], v215 offset:49152
	ds_read_b128 v[124:127], v216 offset:49152
	v_mov_b32_e32 v118, v171
	v_cvt_pk_fp8_f32 v118, v82, v83
	s_waitcnt lgkmcnt(2)
	v_mfma_f32_32x32x64_f8f6f4 v[86:101], v[102:109], v[146:153], 0
	ds_read_b128 v[130:133], v217 offset:49152
	ds_read_b128 v[134:137], v218 offset:49152
	v_exp_f32_e32 v66, v66
	v_exp_f32_e32 v67, v67
	v_exp_f32_e32 v68, v68
	v_pk_add_f32 v[102:103], v[82:83], v[84:85]
	v_mov_b32_e32 v119, v171
	v_pk_add_f32 v[176:177], v[102:103], v[190:191]
	s_waitcnt lgkmcnt(2)
	v_mfma_f32_32x32x64_f8f6f4 v[102:117], v[120:127], v[146:153], 0
	ds_read_b128 v[120:123], v211 offset:49152
	ds_read_b128 v[124:127], v212 offset:49152
	v_exp_f32_e32 v69, v69
	v_exp_f32_e32 v70, v70
	v_exp_f32_e32 v71, v71
	s_waitcnt lgkmcnt(2)
	v_mfma_f32_32x32x64_f8f6f4 v[86:101], v[130:137], v[154:161], v[86:101]
	ds_read_b128 v[130:133], v228
	ds_read_b128 v[134:137], v229
	v_exp_f32_e32 v72, v72
	v_exp_f32_e32 v73, v73
	v_exp_f32_e32 v74, v74
	s_waitcnt lgkmcnt(2)
	v_mfma_f32_32x32x64_f8f6f4 v[102:117], v[120:127], v[154:161], v[102:117]
	v_pk_add_f32 v[82:83], v[176:177], v[188:189]
	ds_read_b128 v[146:149], v231
	ds_read_b128 v[150:153], v232
	v_pk_add_f32 v[82:83], v[82:83], v[144:145]
	v_exp_f32_e32 v75, v75
	v_exp_f32_e32 v76, v76
	v_exp_f32_e32 v77, v77
	v_pk_add_f32 v[82:83], v[82:83], v[138:139]
	s_waitcnt lgkmcnt(2)
	v_mfma_f32_32x32x64_f8f6f4 v[86:101], v[130:137], v[162:169], v[86:101]
	v_mov_b32_e32 v122, v171
	v_pk_add_f32 v[82:83], v[82:83], v[142:143]
	v_exp_f32_e32 v78, v78
	v_exp_f32_e32 v79, v79
	v_pk_add_f32 v[82:83], v[82:83], v[140:141]
	s_waitcnt lgkmcnt(0)
	v_mfma_f32_32x32x64_f8f6f4 v[102:117], v[146:153], v[162:169], v[102:117]
	v_mov_b32_e32 v123, v171
	v_pk_add_f32 v[82:83], v[82:83], v[66:67]
	v_cvt_pk_fp8_f32 v122, v66, v67
	v_pk_add_f32 v[66:67], v[68:69], v[82:83]
	v_exp_f32_e32 v80, v80
	v_pk_add_f32 v[66:67], v[70:71], v[66:67]
	v_exp_f32_e32 v81, v81
	v_pk_add_f32 v[66:67], v[72:73], v[66:67]
	v_cvt_pk_fp8_f32 v123, v70, v71
	v_pk_add_f32 v[66:67], v[74:75], v[66:67]
	v_mov_b32_e32 v124, v171
	v_pk_add_f32 v[66:67], v[76:77], v[66:67]
	v_cvt_pk_fp8_f32 v122, v68, v69 op_sel:[0,0,1]
	v_pk_add_f32 v[66:67], v[78:79], v[66:67]
	v_cvt_pk_fp8_f32 v124, v74, v75
	v_pk_add_f32 v[66:67], v[80:81], v[66:67]
	v_mov_b32_e32 v125, v171
	v_pk_add_f32 v[126:127], v[66:67], v[66:67] op_sel:[0,1] op_sel_hi:[1,0]
	ds_read_b64_tr_b8 v[66:67], v208 offset:0
	ds_read_b64_tr_b8 v[68:69], v208 offset:0x800
	ds_read_b64_tr_b8 v[70:71], v208 offset:0x1000
	v_cvt_pk_fp8_f32 v123, v72, v73 op_sel:[0,0,1]
	v_mov_b32_e32 v120, v171
	v_mov_b32_e32 v121, v171
	v_cvt_pk_fp8_f32 v125, v78, v79
	ds_read_b64_tr_b8 v[72:73], v208 offset:0x1800
	v_cvt_pk_fp8_f32 v119, v190, v191
	v_cvt_pk_fp8_f32 v120, v144, v145
	v_cvt_pk_fp8_f32 v121, v142, v143
	ds_read_b64_tr_b8 v[74:75], v210 offset:0
	v_cvt_pk_fp8_f32 v124, v76, v77 op_sel:[0,0,1]
	ds_read_b64_tr_b8 v[76:77], v210 offset:0x800
	ds_read_b64_tr_b8 v[78:79], v210 offset:0x1000
	v_cvt_pk_fp8_f32 v125, v80, v81 op_sel:[0,0,1]
	ds_read_b64_tr_b8 v[80:81], v210 offset:0x1800
	v_cvt_pk_fp8_f32 v118, v84, v85 op_sel:[0,0,1]
	v_cvt_pk_fp8_f32 v119, v188, v189 op_sel:[0,0,1]
	v_cvt_pk_fp8_f32 v120, v138, v139 op_sel:[0,0,1]
	v_cvt_pk_fp8_f32 v121, v140, v141 op_sel:[0,0,1]
	s_waitcnt lgkmcnt(4)
	v_mov_b32_e32 v127, v126
	v_mfma_f32_32x32x64_f8f6f4 v[2:17], v[118:125], v[66:73], v[2:17]
	ds_read_b64_tr_b8 v[130:131], v209 offset:0
	ds_read_b64_tr_b8 v[132:133], v209 offset:0x800
	ds_read_b64_tr_b8 v[134:135], v209 offset:0x1000
	ds_read_b64_tr_b8 v[136:137], v209 offset:0x1800
	s_waitcnt lgkmcnt(4)
	s_nop 0
	v_max_f32_e32 v66, v86, v87
	v_max3_f32 v66, v66, v88, v89
	v_max3_f32 v66, v66, v90, v91
	v_max3_f32 v66, v66, v92, v93
	v_max3_f32 v66, v66, v94, v95
	v_max3_f32 v66, v66, v96, v97
	v_max3_f32 v66, v66, v98, v99
	v_max3_f32 v66, v66, v100, v101
	v_max3_f32 v66, v66, v102, v103
	v_max3_f32 v66, v66, v104, v105
	v_max3_f32 v66, v66, v106, v107
	v_max3_f32 v66, v66, v108, v109
	v_max3_f32 v66, v66, v110, v111
	v_max3_f32 v66, v66, v112, v113
	v_max3_f32 v66, v66, v114, v115
	v_max3_f32 v66, v66, v116, v117
	v_mov_b32_e32 v67, v66
	s_nop 1
	v_permlane32_swap_b32_e32 v66, v67
	v_max_f32_e32 v66, v66, v67
	v_sub_f32_e32 v67, v66, v233
	v_cmp_ge_f32_e32 vcc, s46, v67
	s_cmp_eq_u64 vcc, exec
	v_max_f32_e32 v66, v233, v66
	s_cselect_b64 vcc, -1, 0
	v_sub_f32_e32 v67, v233, v66
	v_cndmask_b32_e32 v66, v66, v233, vcc
	v_mul_f32_e32 v83, 0x3dd53b94, v67
	v_fma_f32 v82, v66, s47, 4.0
	v_mfma_f32_32x32x64_f8f6f4 v[18:33], v[118:125], v[74:81], v[18:33]
	v_permlane32_swap_b32_e32 v126, v127
	v_pk_fma_f32 v[80:81], v[100:101], s[6:7], v[82:83] op_sel_hi:[1,0,0]
	ds_read_b64_tr_b8 v[100:101], v206 offset:0
	v_pk_fma_f32 v[78:79], v[98:99], s[6:7], v[82:83] op_sel_hi:[1,0,0]
	v_pk_fma_f32 v[76:77], v[96:97], s[6:7], v[82:83] op_sel_hi:[1,0,0]
	v_pk_fma_f32 v[74:75], v[94:95], s[6:7], v[82:83] op_sel_hi:[1,0,0]
	v_pk_fma_f32 v[72:73], v[92:93], s[6:7], v[82:83] op_sel_hi:[1,0,0]
	v_pk_fma_f32 v[70:71], v[90:91], s[6:7], v[82:83] op_sel_hi:[1,0,0]
	v_pk_fma_f32 v[68:69], v[88:89], s[6:7], v[82:83] op_sel_hi:[1,0,0]
	v_pk_fma_f32 v[66:67], v[86:87], s[6:7], v[82:83] op_sel_hi:[1,0,0]
	v_exp_f32_e32 v98, v83
	v_pk_fma_f32 v[96:97], v[116:117], s[6:7], v[82:83] op_sel_hi:[1,0,0]
	v_pk_fma_f32 v[94:95], v[114:115], s[6:7], v[82:83] op_sel_hi:[1,0,0]
	v_pk_fma_f32 v[92:93], v[112:113], s[6:7], v[82:83] op_sel_hi:[1,0,0]
	v_pk_fma_f32 v[90:91], v[110:111], s[6:7], v[82:83] op_sel_hi:[1,0,0]
	v_pk_fma_f32 v[88:89], v[108:109], s[6:7], v[82:83] op_sel_hi:[1,0,0]
	v_pk_fma_f32 v[86:87], v[106:107], s[6:7], v[82:83] op_sel_hi:[1,0,0]
	v_pk_fma_f32 v[84:85], v[104:105], s[6:7], v[82:83] op_sel_hi:[1,0,0]
	v_pk_fma_f32 v[82:83], v[102:103], s[6:7], v[82:83] op_sel_hi:[1,0,0]
	ds_read_b64_tr_b8 v[102:103], v206 offset:0x800
	ds_read_b64_tr_b8 v[104:105], v206 offset:0x1000
	ds_read_b64_tr_b8 v[106:107], v206 offset:0x1800
	s_waitcnt lgkmcnt(4)
	v_cndmask_b32_e64 v98, v98, 1.0, vcc
	v_mfma_f32_32x32x64_f8f6f4 v[34:49], v[118:125], v[130:137], v[34:49]
	s_waitcnt lgkmcnt(0)
	v_cmp_gt_f32_e32 vcc, 1.0, v98
	v_exp_f32_e32 v66, v66
	v_exp_f32_e32 v67, v67
	v_exp_f32_e32 v68, v68
	v_exp_f32_e32 v69, v69
	v_mfma_f32_32x32x64_f8f6f4 v[50:65], v[118:125], v[100:107], v[50:65]
	s_cbranch_vccz .LBB0_521
	s_and_saveexec_b64 s[22:23], s[2:3]
	ds_write_b32 v207, v98 offset:128
	s_or_b64 exec, exec, s[22:23]
	s_waitcnt lgkmcnt(0)
	s_nop 15
	s_nop 7
	ds_read2_b32 v[100:101], v205 offset0:32 offset1:33
	ds_read2_b32 v[102:103], v205 offset0:34 offset1:35
	ds_read2_b32 v[104:105], v205 offset0:40 offset1:41
	ds_read2_b32 v[106:107], v205 offset0:42 offset1:43
	s_waitcnt lgkmcnt(0)
	v_pk_mul_f32 v[2:3], v[100:101], v[2:3]
	v_pk_mul_f32 v[18:19], v[100:101], v[18:19]
	v_pk_mul_f32 v[34:35], v[100:101], v[34:35]
	v_pk_mul_f32 v[50:51], v[100:101], v[50:51]
	v_pk_mul_f32 v[4:5], v[4:5], v[102:103]
	v_pk_mul_f32 v[20:21], v[20:21], v[102:103]
	v_pk_mul_f32 v[36:37], v[36:37], v[102:103]
	v_pk_mul_f32 v[52:53], v[52:53], v[102:103]
	v_pk_mul_f32 v[6:7], v[6:7], v[104:105]
	v_pk_mul_f32 v[22:23], v[22:23], v[104:105]
	v_pk_mul_f32 v[38:39], v[38:39], v[104:105]
	v_pk_mul_f32 v[54:55], v[54:55], v[104:105]
	v_pk_mul_f32 v[8:9], v[8:9], v[106:107]
	v_pk_mul_f32 v[24:25], v[24:25], v[106:107]
	v_pk_mul_f32 v[40:41], v[40:41], v[106:107]
	ds_read2_b32 v[100:101], v205 offset0:48 offset1:49
	v_pk_mul_f32 v[56:57], v[56:57], v[106:107]
	ds_read2_b32 v[102:103], v205 offset0:50 offset1:51
	ds_read2_b32 v[104:105], v205 offset0:56 offset1:57
	ds_read2_b32 v[106:107], v205 offset0:58 offset1:59
	s_waitcnt lgkmcnt(0)
	v_pk_mul_f32 v[10:11], v[10:11], v[100:101]
	v_pk_mul_f32 v[26:27], v[26:27], v[100:101]
	v_pk_mul_f32 v[42:43], v[42:43], v[100:101]
	v_pk_mul_f32 v[58:59], v[58:59], v[100:101]
	v_pk_mul_f32 v[12:13], v[12:13], v[102:103]
	v_pk_mul_f32 v[28:29], v[28:29], v[102:103]
	v_pk_mul_f32 v[44:45], v[44:45], v[102:103]
	v_pk_mul_f32 v[60:61], v[60:61], v[102:103]
	v_pk_mul_f32 v[14:15], v[14:15], v[104:105]
	v_pk_mul_f32 v[30:31], v[30:31], v[104:105]
	v_pk_mul_f32 v[46:47], v[46:47], v[104:105]
	v_pk_mul_f32 v[62:63], v[62:63], v[104:105]
	v_pk_mul_f32 v[16:17], v[16:17], v[106:107]
	v_pk_mul_f32 v[32:33], v[32:33], v[106:107]
	v_pk_mul_f32 v[48:49], v[48:49], v[106:107]
	v_pk_mul_f32 v[64:65], v[64:65], v[106:107]

.LBB0_550:
	v_lshrrev_b32_e32 v4, 3, v39
	v_and_b32_e32 v3, 8, v39
	v_and_b32_e32 v58, 4, v4
	v_bfe_u32 v4, v39, 1, 2
	v_or3_b32 v3, v4, v3, v58
	v_lshlrev_b32_e32 v4, 3, v39
	v_bfe_u32 v56, v39, 1, 3
	v_lshlrev_b32_e32 v3, 7, v3
	v_and_b32_e32 v4, 8, v4
	v_and_b32_e32 v57, 1, v2
	v_add3_u32 v59, v4, s63, v3
	v_bitop3_b32 v2, v2, v56, 1 bitop3:0x6c
	v_lshlrev_b32_e32 v48, 3, v38
	v_lshl_add_u32 v195, v2, 4, v59
	v_bitop3_b32 v2, v48, v162, s28 bitop3:0x6c
	v_lshl_add_u32 v49, v38, 7, s63
	s_waitcnt lgkmcnt(0)
	v_add_u32_e32 v199, v49, v2
	v_or_b32_e32 v2, 16, v162
	s_barrier
	v_bitop3_b32 v2, v48, v2, s28 bitop3:0x6c
	v_add_u32_e32 v200, v49, v2
	ds_read_b128 v[2:5], v199 offset:32768
	ds_read_b128 v[40:43], v199 offset:36864
	ds_read_b128 v[6:9], v200 offset:32768
	ds_read_b128 v[44:47], v200 offset:36864
	v_bitop3_b32 v10, v57, v56, 2 bitop3:0x36
	v_lshl_add_u32 v196, v10, 4, v59
	v_bitop3_b32 v10, v57, v56, 4 bitop3:0x36
	v_lshl_add_u32 v194, v10, 4, v59
	s_waitcnt vmcnt(0) lgkmcnt(0)
	v_mfma_f32_32x32x64_f8f6f4 v[18:33], v[2:9], v[154:161], 0
	v_mfma_f32_32x32x64_f8f6f4 v[2:17], v[40:47], v[154:161], 0
	v_or_b32_e32 v40, 64, v162
	v_bitop3_b32 v40, v48, v40, s28 bitop3:0x6c
	v_add_u32_e32 v197, v49, v40
	v_or_b32_e32 v40, 0x50, v162
	v_bitop3_b32 v40, v48, v40, s28 bitop3:0x6c
	v_add_u32_e32 v198, v49, v40
	ds_read_b128 v[40:43], v197 offset:32768
	ds_read_b128 v[48:51], v197 offset:36864
	ds_read_b128 v[44:47], v198 offset:32768
	ds_read_b128 v[52:55], v198 offset:36864
	s_waitcnt lgkmcnt(1)
	v_mfma_f32_32x32x64_f8f6f4 v[18:33], v[40:47], v[146:153], v[18:33]
	s_waitcnt lgkmcnt(0)
	v_mfma_f32_32x32x64_f8f6f4 v[2:17], v[48:55], v[146:153], v[2:17]
	v_and_b32_e32 v183, 63, v39
	s_nop 15
	s_nop 7
	s_and_b32 s24, s42, 0x3fffffc0
	v_max_f32_e32 v39, v18, v19
	v_max3_f32 v39, v39, v20, v21
	v_max3_f32 v39, v39, v22, v23
	v_max3_f32 v39, v39, v24, v25
	v_max3_f32 v39, v39, v26, v27
	v_max3_f32 v39, v39, v28, v29
	v_max3_f32 v39, v39, v30, v31
	v_max3_f32 v39, v39, v32, v33
	v_max3_f32 v39, v39, v2, v3
	v_max3_f32 v39, v39, v4, v5
	v_max3_f32 v39, v39, v6, v7
	v_max3_f32 v39, v39, v8, v9
	v_max3_f32 v39, v39, v10, v11
	v_max3_f32 v39, v39, v12, v13
	v_max3_f32 v39, v39, v14, v15
	v_max3_f32 v39, v39, v16, v17
	v_mov_b32_e32 v40, v39
	s_nop 1
	v_permlane32_swap_b32_e32 v39, v40
	v_max_f32_e32 v39, v39, v40
	v_add_f32_e32 v40, 0x7149f2ca, v39
	v_max_f32_e32 v39, 0xf149f2ca, v39
	s_lshl_b32 s24, s24, 2
	v_sub_f32_e32 v41, 0xf149f2ca, v39
	s_add_i32 s24, s5, s24
	v_mul_f32_e32 v41, 0x3e0293ee, v41
	v_cmp_ge_f32_e32 vcc, s29, v40
	v_exp_f32_e32 v41, v41
	s_cmp_eq_u64 vcc, exec
	s_cselect_b64 vcc, -1, 0
	s_add_u32 s2, s22, s2
	v_cndmask_b32_e32 v202, v39, v182, vcc
	s_addc_u32 s3, s23, s3
	s_add_i32 s25, s63, s43
	v_fma_f32 v40, v202, s33, 4.0
	s_add_i32 s43, s25, 0x4000
	v_pk_fma_f32 v[66:67], v[2:3], s[4:5], v[40:41] op_sel_hi:[1,0,0]
	v_lshl_add_u64 v[2:3], s[2:3], 0, v[36:37]
	s_mov_b32 m0, s43
	v_lshl_add_u64 v[168:169], v[36:37], 0, s[16:17]
	global_load_lds_dwordx4 v[2:3], off
	s_add_u32 s16, s39, 0x80
	s_addc_u32 s17, s45, 0
	v_mov_b32_e32 v39, v40
	v_lshl_add_u64 v[164:165], s[20:21], 0, v[34:35]
	s_mul_i32 s17, s41, s17
	s_mul_hi_u32 s20, s41, s16
	v_fmamk_f32 v18, v18, 0x3e0293ee, v40
	v_fmamk_f32 v19, v19, 0x3e0293ee, v40
	v_fmamk_f32 v20, v20, 0x3e0293ee, v40
	v_fmamk_f32 v21, v21, 0x3e0293ee, v40
	v_fmamk_f32 v22, v22, 0x3e0293ee, v40
	v_fmamk_f32 v23, v23, 0x3e0293ee, v40
	v_fmamk_f32 v24, v24, 0x3e0293ee, v40
	v_fmamk_f32 v25, v25, 0x3e0293ee, v40
	v_fmamk_f32 v26, v26, 0x3e0293ee, v40
	v_fmamk_f32 v27, v27, 0x3e0293ee, v40
	v_fmamk_f32 v28, v28, 0x3e0293ee, v40
	v_fmamk_f32 v29, v29, 0x3e0293ee, v40
	v_fmamk_f32 v30, v30, 0x3e0293ee, v40
	v_fmamk_f32 v31, v31, 0x3e0293ee, v40
	v_fmamk_f32 v32, v32, 0x3e0293ee, v40
	v_fmac_f32_e32 v39, 0x3e0293ee, v33
	s_add_i32 s20, s20, s17
	s_mul_i32 s16, s41, s16
	v_exp_f32_e32 v82, v18
	v_exp_f32_e32 v83, v19
	v_exp_f32_e32 v84, v20
	v_exp_f32_e32 v85, v21
	v_exp_f32_e32 v176, v22
	v_exp_f32_e32 v177, v23
	v_exp_f32_e32 v174, v24
	v_exp_f32_e32 v175, v25
	v_exp_f32_e32 v172, v26
	v_exp_f32_e32 v173, v27
	v_exp_f32_e32 v140, v28
	v_exp_f32_e32 v141, v29
	v_exp_f32_e32 v144, v30
	v_exp_f32_e32 v145, v31
	v_exp_f32_e32 v142, v32
	v_exp_f32_e32 v143, v39
	s_waitcnt vmcnt(1)
	s_add_u32 s16, s16, s44
	v_bitop3_b32 v56, v57, v56, 6 bitop3:0x36
	s_barrier
	s_addc_u32 s17, s20, 0
	v_lshl_add_u32 v192, v56, 4, v59
	s_add_u32 s16, s30, s16
	v_mov_b32_e32 v162, 0
	s_mov_b32 s42, 2
	v_cndmask_b32_e64 v201, v41, 1.0, vcc
	v_pk_fma_f32 v[80:81], v[16:17], s[4:5], v[40:41] op_sel_hi:[1,0,0]
	v_pk_fma_f32 v[78:79], v[14:15], s[4:5], v[40:41] op_sel_hi:[1,0,0]
	v_pk_fma_f32 v[76:77], v[12:13], s[4:5], v[40:41] op_sel_hi:[1,0,0]
	v_pk_fma_f32 v[74:75], v[10:11], s[4:5], v[40:41] op_sel_hi:[1,0,0]
	v_pk_fma_f32 v[72:73], v[8:9], s[4:5], v[40:41] op_sel_hi:[1,0,0]
	v_pk_fma_f32 v[70:71], v[6:7], s[4:5], v[40:41] op_sel_hi:[1,0,0]
	v_pk_fma_f32 v[68:69], v[4:5], s[4:5], v[40:41] op_sel_hi:[1,0,0]
	v_cmp_gt_u32_e64 s[2:3], 32, v183
	v_lshl_add_u32 v193, v38, 2, s24
	v_lshl_add_u32 v191, v58, 2, s24
	v_add_u32_e32 v190, 0x4000, v195
	v_add_u32_e32 v189, 0x4000, v196
	v_add_u32_e32 v188, 0x4000, v194
	v_add_u32_e32 v187, 0x4000, v192
	v_lshl_add_u64 v[166:167], s[22:23], 0, v[36:37]
	s_addc_u32 s17, s31, s17
	s_lshl_b32 s21, s41, 7
	v_lshl_add_u64 v[170:171], v[34:35], 0, s[18:19]
	s_movk_i32 s22, 0xc0
	v_mov_b32_e32 v2, 0
	v_mov_b32_e32 v3, v162
	v_mov_b32_e32 v4, v162
	v_mov_b32_e32 v5, v162
	v_mov_b32_e32 v6, v162
	v_mov_b32_e32 v7, v162
	v_mov_b32_e32 v8, v162
	v_mov_b32_e32 v9, v162
	v_mov_b32_e32 v10, v162
	v_mov_b32_e32 v11, v162
	v_mov_b32_e32 v12, v162
	v_mov_b32_e32 v13, v162
	v_mov_b32_e32 v14, v162
	v_mov_b32_e32 v15, v162
	v_mov_b32_e32 v16, v162
	v_mov_b32_e32 v17, v162
	v_mov_b32_e32 v18, 0
	v_mov_b32_e32 v19, v162
	v_mov_b32_e32 v20, v162
	v_mov_b32_e32 v21, v162
	v_mov_b32_e32 v22, v162
	v_mov_b32_e32 v23, v162
	v_mov_b32_e32 v24, v162
	v_mov_b32_e32 v25, v162
	v_mov_b32_e32 v26, v162
	v_mov_b32_e32 v27, v162
	v_mov_b32_e32 v28, v162
	v_mov_b32_e32 v29, v162
	v_mov_b32_e32 v30, v162
	v_mov_b32_e32 v31, v162
	v_mov_b32_e32 v32, v162
	v_mov_b32_e32 v33, v162
	v_mov_b32_e32 v34, 0
	v_mov_b32_e32 v35, v162
	v_mov_b32_e32 v36, v162
	v_mov_b32_e32 v37, v162
	v_mov_b32_e32 v38, v162
	v_mov_b32_e32 v39, v162
	v_mov_b32_e32 v40, v162
	v_mov_b32_e32 v41, v162
	v_mov_b32_e32 v42, v162
	v_mov_b32_e32 v43, v162
	v_mov_b32_e32 v44, v162
	v_mov_b32_e32 v45, v162
	v_mov_b32_e32 v46, v162
	v_mov_b32_e32 v47, v162
	v_mov_b32_e32 v48, v162
	v_mov_b32_e32 v49, v162
	v_mov_b32_e32 v50, 0
	v_mov_b32_e32 v51, v162
	v_mov_b32_e32 v52, v162
	v_mov_b32_e32 v53, v162
	v_mov_b32_e32 v54, v162
	v_mov_b32_e32 v55, v162
	v_mov_b32_e32 v56, v162
	v_mov_b32_e32 v57, v162
	v_mov_b32_e32 v58, v162
	v_mov_b32_e32 v59, v162
	v_mov_b32_e32 v60, v162
	v_mov_b32_e32 v61, v162
	v_mov_b32_e32 v62, v162
	v_mov_b32_e32 v63, v162
	v_mov_b32_e32 v64, v162
	v_mov_b32_e32 v65, v162
.LBB0_551:
	ds_read_b128 v[106:109], v200 offset:49152
	ds_read_b128 v[102:105], v199 offset:49152
	ds_read_b128 v[130:133], v199 offset:53248
	ds_read_b128 v[134:137], v200 offset:53248
	s_add_i32 s20, s25, 0x8000
	v_lshl_add_u64 v[86:87], s[16:17], 0, v[170:171]
	s_mov_b32 m0, s20
	s_nop 0
	global_load_lds_dwordx4 v[86:87], off
	s_mov_b32 m0, s25
	s_waitcnt lgkmcnt(2)
	v_mfma_f32_32x32x64_f8f6f4 v[86:101], v[102:109], v[154:161], 0
	s_nop 0
	v_exp_f32_e32 v66, v66
	v_exp_f32_e32 v67, v67
	v_exp_f32_e32 v68, v68
	v_exp_f32_e32 v69, v69
	ds_read_b128 v[102:105], v197 offset:49152
	ds_read_b128 v[106:109], v198 offset:49152
	s_waitcnt lgkmcnt(2)
	v_mfma_f32_32x32x64_f8f6f4 v[114:129], v[130:137], v[154:161], 0
	ds_read_b128 v[204:207], v197 offset:53248
	ds_read_b128 v[208:211], v198 offset:53248
	v_exp_f32_e32 v70, v70
	v_exp_f32_e32 v71, v71
	v_exp_f32_e32 v72, v72
	v_exp_f32_e32 v73, v73
	s_waitcnt lgkmcnt(2)
	v_mfma_f32_32x32x64_f8f6f4 v[86:101], v[102:109], v[146:153], v[86:101]
	v_exp_f32_e32 v74, v74
	v_exp_f32_e32 v75, v75
	v_exp_f32_e32 v76, v76
	v_exp_f32_e32 v77, v77
	s_waitcnt lgkmcnt(0)
	v_mfma_f32_32x32x64_f8f6f4 v[114:129], v[204:211], v[146:153], v[114:129]
	ds_read_b64_tr_b8 v[102:103], v195 offset:0
	ds_read_b64_tr_b8 v[104:105], v195 offset:0x800
	ds_read_b64_tr_b8 v[106:107], v195 offset:0x1000
	v_exp_f32_e32 v78, v78
	v_exp_f32_e32 v79, v79
	ds_read_b64_tr_b8 v[108:109], v195 offset:0x1800
	v_cvt_pk_fp8_f32 v130, v82, v83
	v_exp_f32_e32 v80, v80
	v_exp_f32_e32 v81, v81
	v_cvt_pk_fp8_f32 v134, v66, v67
	v_cvt_pk_fp8_f32 v131, v176, v177
	v_cvt_pk_fp8_f32 v135, v70, v71
	v_cvt_pk_fp8_f32 v132, v172, v173
	v_cvt_pk_fp8_f32 v136, v74, v75
	v_cvt_pk_fp8_f32 v133, v144, v145
	v_cvt_pk_fp8_f32 v137, v78, v79
	ds_read_b64_tr_b8 v[206:207], v196 offset:0
	ds_read_b64_tr_b8 v[208:209], v196 offset:0x800
	ds_read_b64_tr_b8 v[210:211], v196 offset:0x1000
	ds_read_b64_tr_b8 v[212:213], v196 offset:0x1800
	v_cvt_pk_fp8_f32 v130, v84, v85 op_sel:[0,0,1]
	v_cvt_pk_fp8_f32 v134, v68, v69 op_sel:[0,0,1]
	v_cvt_pk_fp8_f32 v131, v174, v175 op_sel:[0,0,1]
	v_cvt_pk_fp8_f32 v135, v72, v73 op_sel:[0,0,1]
	v_cvt_pk_fp8_f32 v132, v140, v141 op_sel:[0,0,1]
	v_cvt_pk_fp8_f32 v136, v76, v77 op_sel:[0,0,1]
	v_cvt_pk_fp8_f32 v133, v142, v143 op_sel:[0,0,1]
	v_cvt_pk_fp8_f32 v137, v80, v81 op_sel:[0,0,1]
	s_waitcnt lgkmcnt(4)
	v_pk_add_f32 v[82:83], v[82:83], v[84:85]
	v_mfma_f32_32x32x64_f8f6f4 v[2:17], v[130:137], v[102:109], v[2:17]
	ds_read_b64_tr_b8 v[214:215], v194 offset:0
	ds_read_b64_tr_b8 v[216:217], v194 offset:0x800
	ds_read_b64_tr_b8 v[218:219], v194 offset:0x1000
	ds_read_b64_tr_b8 v[220:221], v194 offset:0x1800
	s_waitcnt lgkmcnt(4)
	s_nop 0
	v_max_f32_e32 v102, v86, v87
	v_max3_f32 v102, v102, v88, v89
	v_max3_f32 v102, v102, v90, v91
	v_max3_f32 v102, v102, v92, v93
	v_max3_f32 v102, v102, v94, v95
	v_max3_f32 v102, v102, v96, v97
	v_max3_f32 v102, v102, v98, v99
	v_max3_f32 v102, v102, v100, v101
	v_max3_f32 v102, v102, v114, v115
	v_max3_f32 v102, v102, v116, v117
	v_max3_f32 v102, v102, v118, v119
	v_max3_f32 v102, v102, v120, v121
	v_max3_f32 v102, v102, v122, v123
	v_max3_f32 v102, v102, v124, v125
	v_max3_f32 v102, v102, v126, v127
	v_max3_f32 v102, v102, v128, v129
	v_mov_b32_e32 v103, v102
	s_nop 1
	v_permlane32_swap_b32_e32 v102, v103
	v_max_f32_e32 v102, v102, v103
	v_sub_f32_e32 v103, v102, v202
	v_cmp_ge_f32_e32 vcc, s29, v103
	s_cmp_eq_u64 vcc, exec
	v_max_f32_e32 v103, v202, v202
	v_max_f32_e32 v139, v103, v102
	s_cselect_b64 vcc, -1, 0
	v_cndmask_b32_e32 v204, v139, v202, vcc
	v_fma_f32 v138, v204, s33, 4.0
	v_mfma_f32_32x32x64_f8f6f4 v[18:33], v[130:137], v[206:213], v[18:33]
	v_pk_add_f32 v[82:83], v[176:177], v[82:83]
	v_pk_fma_f32 v[110:111], v[98:99], s[4:5], v[138:139] op_sel_hi:[1,0,0]
	v_pk_fma_f32 v[98:99], v[86:87], s[4:5], v[138:139] op_sel_hi:[1,0,0]
	ds_read_b64_tr_b8 v[86:87], v192 offset:0
	v_pk_fma_f32 v[112:113], v[100:101], s[4:5], v[138:139] op_sel_hi:[1,0,0]
	v_pk_fma_f32 v[100:101], v[88:89], s[4:5], v[138:139] op_sel_hi:[1,0,0]
	ds_read_b64_tr_b8 v[88:89], v192 offset:0x800
	v_pk_fma_f32 v[102:103], v[90:91], s[4:5], v[138:139] op_sel_hi:[1,0,0]
	ds_read_b64_tr_b8 v[90:91], v192 offset:0x1000
	v_pk_fma_f32 v[108:109], v[96:97], s[4:5], v[138:139] op_sel_hi:[1,0,0]
	v_pk_fma_f32 v[106:107], v[94:95], s[4:5], v[138:139] op_sel_hi:[1,0,0]
	v_pk_fma_f32 v[104:105], v[92:93], s[4:5], v[138:139] op_sel_hi:[1,0,0]
	v_pk_fma_f32 v[128:129], v[128:129], s[4:5], v[138:139] op_sel_hi:[1,0,0]
	v_pk_fma_f32 v[126:127], v[126:127], s[4:5], v[138:139] op_sel_hi:[1,0,0]
	v_pk_fma_f32 v[124:125], v[124:125], s[4:5], v[138:139] op_sel_hi:[1,0,0]
	v_pk_fma_f32 v[122:123], v[122:123], s[4:5], v[138:139] op_sel_hi:[1,0,0]
	v_pk_fma_f32 v[120:121], v[120:121], s[4:5], v[138:139] op_sel_hi:[1,0,0]
	v_pk_fma_f32 v[118:119], v[118:119], s[4:5], v[138:139] op_sel_hi:[1,0,0]
	v_pk_fma_f32 v[116:117], v[116:117], s[4:5], v[138:139] op_sel_hi:[1,0,0]
	v_pk_fma_f32 v[114:115], v[114:115], s[4:5], v[138:139] op_sel_hi:[1,0,0]
	ds_read_b64_tr_b8 v[92:93], v192 offset:0x1800
	s_waitcnt lgkmcnt(4)
	v_pk_add_f32 v[82:83], v[174:175], v[82:83]
	v_mfma_f32_32x32x64_f8f6f4 v[34:49], v[130:137], v[214:221], v[34:49]
	s_waitcnt lgkmcnt(0)
	s_nop 0
	v_exp_f32_e32 v98, v98
	v_exp_f32_e32 v99, v99
	v_exp_f32_e32 v100, v100
	v_exp_f32_e32 v101, v101
	v_mfma_f32_32x32x64_f8f6f4 v[50:65], v[130:137], v[86:93], v[50:65]
	s_barrier
	v_lshl_add_u64 v[86:87], s[16:17], 0, v[168:169]
	global_load_lds_dwordx4 v[86:87], off
	v_pk_add_f32 v[82:83], v[172:173], v[82:83]
	s_nop 0
	v_pk_add_f32 v[82:83], v[140:141], v[82:83]
	s_nop 0
	v_pk_add_f32 v[82:83], v[144:145], v[82:83]
	s_nop 0
	v_pk_add_f32 v[82:83], v[142:143], v[82:83]
	s_nop 0
	v_pk_add_f32 v[66:67], v[82:83], v[66:67]
	s_nop 0
	v_pk_add_f32 v[66:67], v[68:69], v[66:67]
	s_nop 0
	v_pk_add_f32 v[66:67], v[70:71], v[66:67]
	s_nop 0
	v_pk_add_f32 v[66:67], v[72:73], v[66:67]
	s_nop 0
	v_pk_add_f32 v[66:67], v[74:75], v[66:67]
	s_nop 0
	v_pk_add_f32 v[66:67], v[76:77], v[66:67]
	s_nop 0
	v_pk_add_f32 v[66:67], v[78:79], v[66:67]
	s_nop 0
	v_pk_add_f32 v[66:67], v[80:81], v[66:67]
	s_nop 0
	v_pk_add_f32 v[172:173], v[66:67], v[66:67] op_sel:[0,1] op_sel_hi:[1,0]
	v_sub_f32_e32 v66, v202, v139
	v_mul_f32_e32 v66, 0x3e0293ee, v66
	v_exp_f32_e32 v66, v66
	v_mov_b32_e32 v203, v172
	s_nop 1
	v_permlane32_swap_b32_e32 v172, v203
	v_cndmask_b32_e64 v173, v66, 1.0, vcc
	v_cmp_gt_f32_e32 vcc, 1.0, v173
	s_cbranch_vccz .LBB0_555
	s_and_saveexec_b64 s[18:19], s[2:3]
	ds_write_b32 v193, v173 offset:128
	s_or_b64 exec, exec, s[18:19]
	s_waitcnt lgkmcnt(0)
	s_nop 15
	s_nop 7
	ds_read2_b32 v[66:67], v191 offset0:32 offset1:33
	ds_read2_b32 v[68:69], v191 offset0:34 offset1:35
	ds_read2_b32 v[70:71], v191 offset0:40 offset1:41
	ds_read2_b32 v[72:73], v191 offset0:42 offset1:43
	s_waitcnt lgkmcnt(0)
	v_pk_mul_f32 v[2:3], v[66:67], v[2:3]
	v_pk_mul_f32 v[18:19], v[66:67], v[18:19]
	v_pk_mul_f32 v[34:35], v[66:67], v[34:35]
	v_pk_mul_f32 v[50:51], v[66:67], v[50:51]
	v_pk_mul_f32 v[4:5], v[4:5], v[68:69]
	v_pk_mul_f32 v[20:21], v[20:21], v[68:69]
	v_pk_mul_f32 v[36:37], v[36:37], v[68:69]
	v_pk_mul_f32 v[52:53], v[52:53], v[68:69]
	v_pk_mul_f32 v[6:7], v[6:7], v[70:71]
	v_pk_mul_f32 v[22:23], v[22:23], v[70:71]
	v_pk_mul_f32 v[38:39], v[38:39], v[70:71]
	v_pk_mul_f32 v[54:55], v[54:55], v[70:71]
	v_pk_mul_f32 v[8:9], v[8:9], v[72:73]
	v_pk_mul_f32 v[24:25], v[24:25], v[72:73]
	v_pk_mul_f32 v[40:41], v[40:41], v[72:73]
	ds_read2_b32 v[66:67], v191 offset0:48 offset1:49
	v_pk_mul_f32 v[56:57], v[56:57], v[72:73]
	ds_read2_b32 v[68:69], v191 offset0:50 offset1:51
	ds_read2_b32 v[70:71], v191 offset0:56 offset1:57
	ds_read2_b32 v[72:73], v191 offset0:58 offset1:59
	s_waitcnt lgkmcnt(0)
	v_pk_mul_f32 v[10:11], v[10:11], v[66:67]
	v_pk_mul_f32 v[26:27], v[26:27], v[66:67]
	v_pk_mul_f32 v[42:43], v[42:43], v[66:67]
	v_pk_mul_f32 v[58:59], v[58:59], v[66:67]
	v_pk_mul_f32 v[12:13], v[12:13], v[68:69]
	v_pk_mul_f32 v[28:29], v[28:29], v[68:69]
	v_pk_mul_f32 v[44:45], v[44:45], v[68:69]
	v_pk_mul_f32 v[60:61], v[60:61], v[68:69]
	v_pk_mul_f32 v[14:15], v[14:15], v[70:71]
	v_pk_mul_f32 v[30:31], v[30:31], v[70:71]
	v_pk_mul_f32 v[46:47], v[46:47], v[70:71]
	v_pk_mul_f32 v[62:63], v[62:63], v[70:71]
	v_pk_mul_f32 v[16:17], v[16:17], v[72:73]
	v_pk_mul_f32 v[32:33], v[32:33], v[72:73]
	v_pk_mul_f32 v[48:49], v[48:49], v[72:73]
	v_pk_mul_f32 v[64:65], v[64:65], v[72:73]
.LBB0_555:
	s_add_i32 s18, s42, 1
	s_cmp_lt_u32 s18, s40
	s_cselect_b32 s18, 0, s40
	s_cselect_b32 s19, s39, 0
	s_lshl_b32 s18, s18, 6
	s_ashr_i32 s23, s19, 31
	s_sub_i32 s18, s22, s18
	s_add_u32 s18, s18, s19
	s_addc_u32 s19, 0, s23
	v_mov_b32_e32 v205, s41
	s_waitcnt vmcnt(1)
	v_mad_u64_u32 v[66:67], s[44:45], s18, v205, v[164:165]
	s_mul_i32 s19, s19, s41
	s_add_i32 s23, s25, 0xc000
	s_barrier
	ds_read_b128 v[86:89], v200 offset:32768
	ds_read_b128 v[82:85], v199 offset:32768
	ds_read_b128 v[90:93], v199 offset:36864
	ds_read_b128 v[94:97], v200 offset:36864
	v_add_u32_e32 v67, s19, v67
	s_mov_b32 m0, s23
	v_exp_f32_e32 v178, v106
	global_load_lds_dwordx4 v[66:67], off
	v_exp_f32_e32 v174, v102
	v_exp_f32_e32 v175, v103
	v_exp_f32_e32 v176, v104
	v_exp_f32_e32 v177, v105
	v_exp_f32_e32 v179, v107
	v_exp_f32_e32 v180, v108
	v_exp_f32_e32 v181, v109
	v_exp_f32_e32 v110, v110
	v_exp_f32_e32 v111, v111
	v_exp_f32_e32 v112, v112
	v_exp_f32_e32 v113, v113
	s_waitcnt lgkmcnt(2)
	v_mfma_f32_32x32x64_f8f6f4 v[66:81], v[82:89], v[154:161], 0
	ds_read_b128 v[82:85], v197 offset:32768
	ds_read_b128 v[86:89], v198 offset:32768
	v_exp_f32_e32 v114, v114
	v_exp_f32_e32 v115, v115
	v_exp_f32_e32 v116, v116
	v_exp_f32_e32 v117, v117
	s_waitcnt lgkmcnt(2)
	v_mfma_f32_32x32x64_f8f6f4 v[130:145], v[90:97], v[154:161], 0
	ds_read_b128 v[90:93], v197 offset:36864
	ds_read_b128 v[94:97], v198 offset:36864
	v_exp_f32_e32 v118, v118
	v_exp_f32_e32 v119, v119
	v_exp_f32_e32 v120, v120
	v_exp_f32_e32 v121, v121
	s_waitcnt lgkmcnt(2)
	v_mfma_f32_32x32x64_f8f6f4 v[66:81], v[82:89], v[146:153], v[66:81]
	v_exp_f32_e32 v122, v122
	v_exp_f32_e32 v123, v123
	v_exp_f32_e32 v124, v124
	v_exp_f32_e32 v125, v125
	s_waitcnt lgkmcnt(0)
	v_mfma_f32_32x32x64_f8f6f4 v[130:145], v[90:97], v[146:153], v[130:145]
	ds_read_b64_tr_b8 v[82:83], v190 offset:0
	ds_read_b64_tr_b8 v[84:85], v190 offset:0x800
	ds_read_b64_tr_b8 v[86:87], v190 offset:0x1000
	v_exp_f32_e32 v126, v126
	v_exp_f32_e32 v127, v127
	ds_read_b64_tr_b8 v[88:89], v190 offset:0x1800
	v_cvt_pk_fp8_f32 v102, v98, v99
	v_exp_f32_e32 v128, v128
	v_exp_f32_e32 v129, v129
	v_cvt_pk_fp8_f32 v106, v114, v115
	v_cvt_pk_fp8_f32 v103, v174, v175
	v_cvt_pk_fp8_f32 v107, v118, v119
	v_cvt_pk_fp8_f32 v104, v178, v179
	v_cvt_pk_fp8_f32 v108, v122, v123
	v_cvt_pk_fp8_f32 v105, v110, v111
	v_cvt_pk_fp8_f32 v109, v126, v127
	ds_read_b64_tr_b8 v[90:91], v189 offset:0
	ds_read_b64_tr_b8 v[92:93], v189 offset:0x800
	ds_read_b64_tr_b8 v[94:95], v189 offset:0x1000
	ds_read_b64_tr_b8 v[96:97], v189 offset:0x1800
	v_cvt_pk_fp8_f32 v102, v100, v101 op_sel:[0,0,1]
	v_cvt_pk_fp8_f32 v106, v116, v117 op_sel:[0,0,1]
	v_cvt_pk_fp8_f32 v103, v176, v177 op_sel:[0,0,1]
	v_cvt_pk_fp8_f32 v107, v120, v121 op_sel:[0,0,1]
	v_cvt_pk_fp8_f32 v104, v180, v181 op_sel:[0,0,1]
	v_cvt_pk_fp8_f32 v108, v124, v125 op_sel:[0,0,1]
	v_cvt_pk_fp8_f32 v105, v112, v113 op_sel:[0,0,1]
	v_cvt_pk_fp8_f32 v109, v128, v129 op_sel:[0,0,1]
	s_waitcnt lgkmcnt(4)
	s_mov_b32 m0, s43
	v_mfma_f32_32x32x64_f8f6f4 v[2:17], v[102:109], v[82:89], v[2:17]
	ds_read_b64_tr_b8 v[206:207], v188 offset:0
	ds_read_b64_tr_b8 v[208:209], v188 offset:0x800
	ds_read_b64_tr_b8 v[210:211], v188 offset:0x1000
	ds_read_b64_tr_b8 v[212:213], v188 offset:0x1800
	s_waitcnt lgkmcnt(4)
	s_nop 0
	v_max_f32_e32 v82, v66, v67
	v_max3_f32 v82, v82, v68, v69
	v_max3_f32 v82, v82, v70, v71
	v_max3_f32 v82, v82, v72, v73
	v_max3_f32 v82, v82, v74, v75
	v_max3_f32 v82, v82, v76, v77
	v_max3_f32 v82, v82, v78, v79
	v_max3_f32 v82, v82, v80, v81
	v_max3_f32 v82, v82, v130, v131
	v_max3_f32 v82, v82, v132, v133
	v_max3_f32 v82, v82, v134, v135
	v_max3_f32 v82, v82, v136, v137
	v_max3_f32 v82, v82, v138, v139
	v_max3_f32 v82, v82, v140, v141
	v_max3_f32 v82, v82, v142, v143
	v_max3_f32 v82, v82, v144, v145
	v_mov_b32_e32 v83, v82
	s_nop 1
	v_permlane32_swap_b32_e32 v82, v83
	v_max_f32_e32 v82, v82, v83
	v_sub_f32_e32 v83, v82, v204
	v_cmp_ge_f32_e32 vcc, s29, v83
	s_cmp_eq_u64 vcc, exec
	v_max_f32_e32 v83, v204, v204
	v_max_f32_e32 v215, v83, v82
	s_cselect_b64 vcc, -1, 0
	v_cndmask_b32_e32 v202, v215, v204, vcc
	v_fma_f32 v214, v202, s33, 4.0
	v_mfma_f32_32x32x64_f8f6f4 v[18:33], v[102:109], v[90:97], v[18:33]
	v_pk_add_f32 v[98:99], v[98:99], v[100:101]
	v_pk_fma_f32 v[82:83], v[66:67], s[4:5], v[214:215] op_sel_hi:[1,0,0]
	v_pk_fma_f32 v[66:67], v[130:131], s[4:5], v[214:215] op_sel_hi:[1,0,0]
	ds_read_b64_tr_b8 v[130:131], v187 offset:0
	v_pk_fma_f32 v[84:85], v[68:69], s[4:5], v[214:215] op_sel_hi:[1,0,0]
	v_pk_fma_f32 v[68:69], v[132:133], s[4:5], v[214:215] op_sel_hi:[1,0,0]
	ds_read_b64_tr_b8 v[132:133], v187 offset:0x800
	v_pk_fma_f32 v[86:87], v[70:71], s[4:5], v[214:215] op_sel_hi:[1,0,0]
	v_pk_fma_f32 v[70:71], v[134:135], s[4:5], v[214:215] op_sel_hi:[1,0,0]
	ds_read_b64_tr_b8 v[134:135], v187 offset:0x1000
	v_pk_fma_f32 v[96:97], v[80:81], s[4:5], v[214:215] op_sel_hi:[1,0,0]
	v_pk_fma_f32 v[94:95], v[78:79], s[4:5], v[214:215] op_sel_hi:[1,0,0]
	v_pk_fma_f32 v[92:93], v[76:77], s[4:5], v[214:215] op_sel_hi:[1,0,0]
	v_pk_fma_f32 v[90:91], v[74:75], s[4:5], v[214:215] op_sel_hi:[1,0,0]
	v_pk_fma_f32 v[88:89], v[72:73], s[4:5], v[214:215] op_sel_hi:[1,0,0]
	v_pk_fma_f32 v[80:81], v[144:145], s[4:5], v[214:215] op_sel_hi:[1,0,0]
	v_pk_fma_f32 v[78:79], v[142:143], s[4:5], v[214:215] op_sel_hi:[1,0,0]
	v_pk_fma_f32 v[76:77], v[140:141], s[4:5], v[214:215] op_sel_hi:[1,0,0]
	v_pk_fma_f32 v[74:75], v[138:139], s[4:5], v[214:215] op_sel_hi:[1,0,0]
	v_pk_fma_f32 v[72:73], v[136:137], s[4:5], v[214:215] op_sel_hi:[1,0,0]
	ds_read_b64_tr_b8 v[136:137], v187 offset:0x1800
	s_waitcnt lgkmcnt(4)
	v_pk_add_f32 v[98:99], v[98:99], v[174:175]
	v_mfma_f32_32x32x64_f8f6f4 v[34:49], v[102:109], v[206:213], v[34:49]
	s_waitcnt lgkmcnt(0)
	s_nop 0
	v_exp_f32_e32 v82, v82
	v_exp_f32_e32 v83, v83
	v_exp_f32_e32 v84, v84
	v_exp_f32_e32 v85, v85
	v_mfma_f32_32x32x64_f8f6f4 v[50:65], v[102:109], v[130:137], v[50:65]
	v_mad_u64_u32 v[102:103], s[44:45], s18, v205, v[166:167]
	s_barrier
	v_add_u32_e32 v103, s19, v103
	global_load_lds_dwordx4 v[102:103], off
	v_pk_add_f32 v[98:99], v[176:177], v[98:99]
	s_nop 0
	v_pk_add_f32 v[98:99], v[178:179], v[98:99]
	s_nop 0
	v_pk_add_f32 v[98:99], v[180:181], v[98:99]
	s_nop 0
	v_pk_add_f32 v[98:99], v[110:111], v[98:99]
	s_nop 0
	v_pk_add_f32 v[98:99], v[112:113], v[98:99]
	s_nop 0
	v_pk_add_f32 v[98:99], v[98:99], v[114:115]
	s_nop 0
	v_pk_add_f32 v[98:99], v[116:117], v[98:99]
	s_nop 0
	v_pk_add_f32 v[98:99], v[118:119], v[98:99]
	s_nop 0
	v_pk_add_f32 v[98:99], v[120:121], v[98:99]
	s_nop 0
	v_pk_add_f32 v[98:99], v[122:123], v[98:99]
	s_nop 0
	v_pk_add_f32 v[98:99], v[124:125], v[98:99]
	s_nop 0
	v_pk_add_f32 v[98:99], v[126:127], v[98:99]
	s_nop 0
	v_pk_add_f32 v[98:99], v[128:129], v[98:99]
	s_nop 0
	v_pk_add_f32 v[98:99], v[98:99], v[98:99] op_sel:[0,1] op_sel_hi:[1,0]
	s_nop 0
	v_sub_f32_e32 v99, v204, v215
	v_mul_f32_e32 v99, 0x3e0293ee, v99
	v_exp_f32_e32 v100, v99
	v_mov_b32_e32 v99, v98
	s_nop 1
	v_permlane32_swap_b32_e32 v98, v99
	v_cndmask_b32_e64 v178, v100, 1.0, vcc
	v_cmp_gt_f32_e32 vcc, 1.0, v178
	s_cbranch_vccz .LBB0_559
	s_and_saveexec_b64 s[18:19], s[2:3]
	ds_write_b32 v193, v178 offset:128
	s_or_b64 exec, exec, s[18:19]
	s_waitcnt lgkmcnt(0)
	s_nop 15
	s_nop 7
	ds_read2_b32 v[100:101], v191 offset0:32 offset1:33
	ds_read2_b32 v[102:103], v191 offset0:34 offset1:35
	ds_read2_b32 v[104:105], v191 offset0:40 offset1:41
	ds_read2_b32 v[106:107], v191 offset0:42 offset1:43
	s_waitcnt lgkmcnt(0)
	v_pk_mul_f32 v[2:3], v[100:101], v[2:3]
	v_pk_mul_f32 v[18:19], v[100:101], v[18:19]
	v_pk_mul_f32 v[34:35], v[100:101], v[34:35]
	v_pk_mul_f32 v[50:51], v[100:101], v[50:51]
	v_pk_mul_f32 v[4:5], v[4:5], v[102:103]
	v_pk_mul_f32 v[20:21], v[20:21], v[102:103]
	v_pk_mul_f32 v[36:37], v[36:37], v[102:103]
	v_pk_mul_f32 v[52:53], v[52:53], v[102:103]
	v_pk_mul_f32 v[6:7], v[6:7], v[104:105]
	v_pk_mul_f32 v[22:23], v[22:23], v[104:105]
	v_pk_mul_f32 v[38:39], v[38:39], v[104:105]
	v_pk_mul_f32 v[54:55], v[54:55], v[104:105]
	v_pk_mul_f32 v[8:9], v[8:9], v[106:107]
	v_pk_mul_f32 v[24:25], v[24:25], v[106:107]
	v_pk_mul_f32 v[40:41], v[40:41], v[106:107]
	ds_read2_b32 v[100:101], v191 offset0:48 offset1:49
	v_pk_mul_f32 v[56:57], v[56:57], v[106:107]
	ds_read2_b32 v[102:103], v191 offset0:50 offset1:51
	ds_read2_b32 v[104:105], v191 offset0:56 offset1:57
	ds_read2_b32 v[106:107], v191 offset0:58 offset1:59
	s_waitcnt lgkmcnt(0)
	v_pk_mul_f32 v[10:11], v[10:11], v[100:101]
	v_pk_mul_f32 v[26:27], v[26:27], v[100:101]
	v_pk_mul_f32 v[42:43], v[42:43], v[100:101]
	v_pk_mul_f32 v[58:59], v[58:59], v[100:101]
	v_pk_mul_f32 v[12:13], v[12:13], v[102:103]
	v_pk_mul_f32 v[28:29], v[28:29], v[102:103]
	v_pk_mul_f32 v[44:45], v[44:45], v[102:103]
	v_pk_mul_f32 v[60:61], v[60:61], v[102:103]
	v_pk_mul_f32 v[14:15], v[14:15], v[104:105]
	v_pk_mul_f32 v[30:31], v[30:31], v[104:105]
	v_pk_mul_f32 v[46:47], v[46:47], v[104:105]
	v_pk_mul_f32 v[62:63], v[62:63], v[104:105]
	v_pk_mul_f32 v[16:17], v[16:17], v[106:107]
	v_pk_mul_f32 v[32:33], v[32:33], v[106:107]
	v_pk_mul_f32 v[48:49], v[48:49], v[106:107]
	v_pk_mul_f32 v[64:65], v[64:65], v[106:107]

.LBB0_561:
	ds_read_b128 v[90:93], v200 offset:49152
	ds_read_b128 v[86:89], v199 offset:49152
	ds_read_b128 v[130:133], v199 offset:53248
	ds_read_b128 v[134:137], v200 offset:53248
	v_pk_add_f32 v[94:95], v[82:83], v[84:85]
	s_waitcnt lgkmcnt(2)
	v_mfma_f32_32x32x64_f8f6f4 v[114:129], v[86:93], v[154:161], 0
	s_nop 0
	v_exp_f32_e32 v66, v66
	v_exp_f32_e32 v67, v67
	v_exp_f32_e32 v68, v68
	v_exp_f32_e32 v69, v69
	ds_read_b128 v[86:89], v197 offset:49152
	ds_read_b128 v[90:93], v198 offset:49152
	s_waitcnt lgkmcnt(2)
	v_mfma_f32_32x32x64_f8f6f4 v[98:113], v[130:137], v[154:161], 0
	ds_read_b128 v[130:133], v197 offset:53248
	ds_read_b128 v[134:137], v198 offset:53248
	v_exp_f32_e32 v70, v70
	v_exp_f32_e32 v71, v71
	v_exp_f32_e32 v72, v72
	v_exp_f32_e32 v73, v73
	v_pk_add_f32 v[94:95], v[94:95], v[176:177]
	s_waitcnt lgkmcnt(2)
	v_mfma_f32_32x32x64_f8f6f4 v[114:129], v[86:93], v[146:153], v[114:129]
	v_pk_add_f32 v[94:95], v[94:95], v[174:175]
	v_exp_f32_e32 v74, v74
	v_exp_f32_e32 v75, v75
	v_exp_f32_e32 v76, v76
	v_exp_f32_e32 v77, v77
	v_pk_add_f32 v[86:87], v[94:95], v[172:173]
	s_waitcnt lgkmcnt(0)
	v_mfma_f32_32x32x64_f8f6f4 v[98:113], v[130:137], v[146:153], v[98:113]
	v_mov_b32_e32 v134, v163
	v_pk_add_f32 v[86:87], v[86:87], v[140:141]
	v_cvt_pk_fp8_f32 v134, v66, v67
	v_pk_add_f32 v[86:87], v[86:87], v[144:145]
	v_mov_b32_e32 v135, v163
	v_exp_f32_e32 v78, v78
	v_exp_f32_e32 v79, v79
	v_pk_add_f32 v[86:87], v[86:87], v[142:143]
	v_cvt_pk_fp8_f32 v135, v70, v71
	v_pk_add_f32 v[86:87], v[86:87], v[66:67]
	v_mov_b32_e32 v136, v163
	ds_read_b64_tr_b8 v[66:67], v195 offset:0
	v_pk_add_f32 v[86:87], v[68:69], v[86:87]
	v_cvt_pk_fp8_f32 v134, v68, v69 op_sel:[0,0,1]
	v_cvt_pk_fp8_f32 v136, v74, v75
	ds_read_b64_tr_b8 v[68:69], v195 offset:0x800
	v_pk_add_f32 v[86:87], v[70:71], v[86:87]
	v_mov_b32_e32 v137, v163
	ds_read_b64_tr_b8 v[70:71], v195 offset:0x1000
	v_exp_f32_e32 v80, v80
	v_exp_f32_e32 v81, v81
	v_pk_add_f32 v[86:87], v[72:73], v[86:87]
	v_mov_b32_e32 v130, v163
	v_mov_b32_e32 v131, v163
	v_cvt_pk_fp8_f32 v135, v72, v73 op_sel:[0,0,1]
	v_mov_b32_e32 v132, v163
	v_mov_b32_e32 v133, v163
	v_cvt_pk_fp8_f32 v137, v78, v79
	ds_read_b64_tr_b8 v[72:73], v195 offset:0x1800
	v_pk_add_f32 v[86:87], v[74:75], v[86:87]
	v_cvt_pk_fp8_f32 v130, v82, v83
	v_cvt_pk_fp8_f32 v131, v176, v177
	v_cvt_pk_fp8_f32 v132, v172, v173
	v_cvt_pk_fp8_f32 v133, v144, v145
	ds_read_b64_tr_b8 v[74:75], v196 offset:0
	v_pk_add_f32 v[86:87], v[76:77], v[86:87]
	v_cvt_pk_fp8_f32 v136, v76, v77 op_sel:[0,0,1]
	ds_read_b64_tr_b8 v[76:77], v196 offset:0x800
	v_pk_add_f32 v[86:87], v[78:79], v[86:87]
	ds_read_b64_tr_b8 v[78:79], v196 offset:0x1000
	v_cvt_pk_fp8_f32 v137, v80, v81 op_sel:[0,0,1]
	v_pk_add_f32 v[86:87], v[80:81], v[86:87]
	ds_read_b64_tr_b8 v[80:81], v196 offset:0x1800
	v_cvt_pk_fp8_f32 v130, v84, v85 op_sel:[0,0,1]
	v_cvt_pk_fp8_f32 v131, v174, v175 op_sel:[0,0,1]
	v_cvt_pk_fp8_f32 v132, v140, v141 op_sel:[0,0,1]
	v_cvt_pk_fp8_f32 v133, v142, v143 op_sel:[0,0,1]
	s_waitcnt lgkmcnt(4)
	v_pk_add_f32 v[138:139], v[86:87], v[86:87] op_sel:[0,1] op_sel_hi:[1,0]
	v_mfma_f32_32x32x64_f8f6f4 v[2:17], v[130:137], v[66:73], v[2:17]
	ds_read_b64_tr_b8 v[140:141], v194 offset:0
	ds_read_b64_tr_b8 v[142:143], v194 offset:0x800
	ds_read_b64_tr_b8 v[144:145], v194 offset:0x1000
	ds_read_b64_tr_b8 v[146:147], v194 offset:0x1800
	s_waitcnt lgkmcnt(4)
	s_nop 0
	v_max_f32_e32 v66, v114, v115
	v_max3_f32 v66, v66, v116, v117
	v_max3_f32 v66, v66, v118, v119
	v_max3_f32 v66, v66, v120, v121
	v_max3_f32 v66, v66, v122, v123
	v_max3_f32 v66, v66, v124, v125
	v_max3_f32 v66, v66, v126, v127
	v_max3_f32 v66, v66, v128, v129
	v_max3_f32 v66, v66, v98, v99
	v_max3_f32 v66, v66, v100, v101
	v_max3_f32 v66, v66, v102, v103
	v_max3_f32 v66, v66, v104, v105
	v_max3_f32 v66, v66, v106, v107
	v_max3_f32 v66, v66, v108, v109
	v_max3_f32 v66, v66, v110, v111
	v_max3_f32 v66, v66, v112, v113
	v_mov_b32_e32 v67, v66
	s_nop 1
	v_permlane32_swap_b32_e32 v66, v67
	v_max_f32_e32 v66, v66, v67
	v_sub_f32_e32 v67, v66, v202
	v_cmp_ge_f32_e32 vcc, s29, v67
	s_cmp_eq_u64 vcc, exec
	v_max_f32_e32 v66, v202, v66
	s_cselect_b64 vcc, -1, 0
	v_sub_f32_e32 v67, v202, v66
	v_cndmask_b32_e32 v66, v66, v202, vcc
	v_mul_f32_e32 v83, 0x3e0293ee, v67
	v_fma_f32 v82, v66, s33, 4.0
	v_mfma_f32_32x32x64_f8f6f4 v[18:33], v[130:137], v[74:81], v[18:33]
	v_mov_b32_e32 v139, v138
	v_pk_fma_f32 v[84:85], v[100:101], s[4:5], v[82:83] op_sel_hi:[1,0,0]
	ds_read_b64_tr_b8 v[100:101], v192 offset:0
	v_pk_fma_f32 v[66:67], v[114:115], s[4:5], v[82:83] op_sel_hi:[1,0,0]
	v_exp_f32_e32 v114, v83
	v_pk_fma_f32 v[86:87], v[102:103], s[4:5], v[82:83] op_sel_hi:[1,0,0]
	ds_read_b64_tr_b8 v[102:103], v192 offset:0x800
	v_pk_fma_f32 v[88:89], v[104:105], s[4:5], v[82:83] op_sel_hi:[1,0,0]
	ds_read_b64_tr_b8 v[104:105], v192 offset:0x1000
	v_pk_fma_f32 v[80:81], v[128:129], s[4:5], v[82:83] op_sel_hi:[1,0,0]
	v_pk_fma_f32 v[78:79], v[126:127], s[4:5], v[82:83] op_sel_hi:[1,0,0]
	v_pk_fma_f32 v[76:77], v[124:125], s[4:5], v[82:83] op_sel_hi:[1,0,0]
	v_pk_fma_f32 v[74:75], v[122:123], s[4:5], v[82:83] op_sel_hi:[1,0,0]
	v_pk_fma_f32 v[72:73], v[120:121], s[4:5], v[82:83] op_sel_hi:[1,0,0]
	v_pk_fma_f32 v[70:71], v[118:119], s[4:5], v[82:83] op_sel_hi:[1,0,0]
	v_pk_fma_f32 v[68:69], v[116:117], s[4:5], v[82:83] op_sel_hi:[1,0,0]
	v_pk_fma_f32 v[96:97], v[112:113], s[4:5], v[82:83] op_sel_hi:[1,0,0]
	v_pk_fma_f32 v[94:95], v[110:111], s[4:5], v[82:83] op_sel_hi:[1,0,0]
	v_pk_fma_f32 v[92:93], v[108:109], s[4:5], v[82:83] op_sel_hi:[1,0,0]
	v_pk_fma_f32 v[90:91], v[106:107], s[4:5], v[82:83] op_sel_hi:[1,0,0]
	v_pk_fma_f32 v[82:83], v[98:99], s[4:5], v[82:83] op_sel_hi:[1,0,0]
	ds_read_b64_tr_b8 v[106:107], v192 offset:0x1800
	s_waitcnt lgkmcnt(4)
	v_cndmask_b32_e64 v98, v114, 1.0, vcc
	v_mfma_f32_32x32x64_f8f6f4 v[34:49], v[130:137], v[140:147], v[34:49]
	s_waitcnt lgkmcnt(0)
	v_permlane32_swap_b32_e32 v138, v139
	v_exp_f32_e32 v66, v66
	v_exp_f32_e32 v67, v67
	v_exp_f32_e32 v68, v68
	v_exp_f32_e32 v69, v69
	v_cmp_gt_f32_e32 vcc, 1.0, v98
	v_mfma_f32_32x32x64_f8f6f4 v[50:65], v[130:137], v[100:107], v[50:65]
	s_cbranch_vccz .LBB0_565
	s_and_saveexec_b64 s[16:17], s[2:3]
	ds_write_b32 v193, v98 offset:128
	s_or_b64 exec, exec, s[16:17]
	s_waitcnt lgkmcnt(0)
	s_nop 15
	s_nop 7
	ds_read2_b32 v[100:101], v191 offset0:32 offset1:33
	ds_read2_b32 v[102:103], v191 offset0:34 offset1:35
	ds_read2_b32 v[104:105], v191 offset0:40 offset1:41
	ds_read2_b32 v[106:107], v191 offset0:42 offset1:43
	s_waitcnt lgkmcnt(0)
	v_pk_mul_f32 v[2:3], v[100:101], v[2:3]
	v_pk_mul_f32 v[18:19], v[100:101], v[18:19]
	v_pk_mul_f32 v[34:35], v[100:101], v[34:35]
	v_pk_mul_f32 v[50:51], v[100:101], v[50:51]
	v_pk_mul_f32 v[4:5], v[4:5], v[102:103]
	v_pk_mul_f32 v[20:21], v[20:21], v[102:103]
	v_pk_mul_f32 v[36:37], v[36:37], v[102:103]
	v_pk_mul_f32 v[52:53], v[52:53], v[102:103]
	v_pk_mul_f32 v[6:7], v[6:7], v[104:105]
	v_pk_mul_f32 v[22:23], v[22:23], v[104:105]
	v_pk_mul_f32 v[38:39], v[38:39], v[104:105]
	v_pk_mul_f32 v[54:55], v[54:55], v[104:105]
	v_pk_mul_f32 v[8:9], v[8:9], v[106:107]
	v_pk_mul_f32 v[24:25], v[24:25], v[106:107]
	v_pk_mul_f32 v[40:41], v[40:41], v[106:107]
	ds_read2_b32 v[100:101], v191 offset0:48 offset1:49
	v_pk_mul_f32 v[56:57], v[56:57], v[106:107]
	ds_read2_b32 v[102:103], v191 offset0:50 offset1:51
	ds_read2_b32 v[104:105], v191 offset0:56 offset1:57
	ds_read2_b32 v[106:107], v191 offset0:58 offset1:59
	s_waitcnt lgkmcnt(0)
	v_pk_mul_f32 v[10:11], v[10:11], v[100:101]
	v_pk_mul_f32 v[26:27], v[26:27], v[100:101]
	v_pk_mul_f32 v[42:43], v[42:43], v[100:101]
	v_pk_mul_f32 v[58:59], v[58:59], v[100:101]
	v_pk_mul_f32 v[12:13], v[12:13], v[102:103]
	v_pk_mul_f32 v[28:29], v[28:29], v[102:103]
	v_pk_mul_f32 v[44:45], v[44:45], v[102:103]
	v_pk_mul_f32 v[60:61], v[60:61], v[102:103]
	v_pk_mul_f32 v[14:15], v[14:15], v[104:105]
	v_pk_mul_f32 v[30:31], v[30:31], v[104:105]
	v_pk_mul_f32 v[46:47], v[46:47], v[104:105]
	v_pk_mul_f32 v[62:63], v[62:63], v[104:105]
	v_pk_mul_f32 v[16:17], v[16:17], v[106:107]
	v_pk_mul_f32 v[32:33], v[32:33], v[106:107]
	v_pk_mul_f32 v[48:49], v[48:49], v[106:107]
	v_pk_mul_f32 v[64:65], v[64:65], v[106:107]

.LBB0_582:
	v_lshrrev_b32_e32 v4, 3, v39
	v_and_b32_e32 v37, 4, v4
	v_and_or_b32 v4, s16, 32, v38
	v_med3_i32 v5, v4, 8, 56
	v_sub_u32_e32 v56, v5, v37
	v_xad_u32 v198, v4, 63, v37
	v_and_b32_e32 v4, 8, v39
	v_bfe_u32 v5, v39, 1, 2
	v_or3_b32 v4, v5, v4, v37
	v_lshlrev_b32_e32 v5, 3, v39
	v_lshlrev_b32_e32 v4, 7, v4
	v_and_b32_e32 v5, 8, v5
	v_lshlrev_b32_e32 v48, 3, v38
	s_lshl_b32 s1, s14, 2
	s_ashr_i32 s70, s15, 7
	v_bfe_u32 v57, v39, 1, 3
	v_add3_u32 v59, v5, s63, v4
	v_bitop3_b32 v4, v48, v36, s68 bitop3:0x6c
	v_lshl_add_u32 v49, v38, 7, s63
	s_add_i32 s7, s70, s1
	v_and_b32_e32 v58, 1, v2
	v_bitop3_b32 v2, v2, v57, 1 bitop3:0x6c
	s_waitcnt lgkmcnt(0)
	v_add_u32_e32 v203, v49, v4
	v_or_b32_e32 v4, 16, v36
	v_med3_i32 v6, s7, 4, 28
	v_lshl_add_u32 v200, v2, 4, v59
	v_bitop3_b32 v2, v58, v57, 2 bitop3:0x36
	s_barrier
	v_bitop3_b32 v4, v48, v4, s68 bitop3:0x6c
	v_readfirstlane_b32 s96, v6
	v_add_u32_e32 v204, v49, v4
	ds_read_b128 v[4:7], v203 offset:32768
	ds_read_b128 v[40:43], v203 offset:36864
	ds_read_b128 v[8:11], v204 offset:32768
	ds_read_b128 v[44:47], v204 offset:36864
	v_lshl_add_u32 v202, v2, 4, v59
	v_bitop3_b32 v2, v58, v57, 4 bitop3:0x36
	v_lshl_add_u32 v199, v2, 4, v59
	v_or_b32_e32 v2, 64, v36
	v_bitop3_b32 v2, v48, v2, s68 bitop3:0x6c
	v_add_u32_e32 v205, v49, v2
	v_or_b32_e32 v2, 0x50, v36
	v_bitop3_b32 v2, v48, v2, s68 bitop3:0x6c
	s_waitcnt vmcnt(0) lgkmcnt(0)
	v_mfma_f32_32x32x64_f8f6f4 v[20:35], v[4:11], v[172:179], 0
	v_mfma_f32_32x32x64_f8f6f4 v[4:19], v[40:47], v[172:179], 0
	v_add_u32_e32 v206, v49, v2
	ds_read_b128 v[40:43], v205 offset:32768
	ds_read_b128 v[48:51], v205 offset:36864
	ds_read_b128 v[44:47], v206 offset:32768
	ds_read_b128 v[52:55], v206 offset:36864
	v_bitop3_b32 v2, v58, v57, 6 bitop3:0x36
	s_waitcnt lgkmcnt(1)
	v_mfma_f32_32x32x64_f8f6f4 v[20:35], v[40:47], v[164:171], v[20:35]
	s_waitcnt lgkmcnt(0)
	v_mfma_f32_32x32x64_f8f6f4 v[4:19], v[48:55], v[164:171], v[4:19]
	v_lshl_add_u32 v201, v2, 4, v59
	s_nop 15
	s_nop 7
	v_writelane_b32 v252, s16, 24
	v_max_f32_e32 v2, v20, v21
	v_max3_f32 v2, v2, v22, v23
	v_max3_f32 v2, v2, v24, v25
	v_max3_f32 v2, v2, v26, v27
	v_max3_f32 v2, v2, v28, v29
	v_max3_f32 v2, v2, v30, v31
	v_max3_f32 v2, v2, v32, v33
	v_max3_f32 v2, v2, v34, v35
	v_max3_f32 v2, v2, v4, v5
	v_writelane_b32 v252, s7, 25
	s_and_b32 s7, s74, 7
	v_max3_f32 v2, v2, v6, v7
	s_add_i32 s94, s96, -4
	s_lshl_b32 s71, s7, 2
	s_add_i32 s1, s1, -4
	v_max3_f32 v2, v2, v8, v9
	s_cmp_eq_u32 s14, 0
	v_max3_f32 v2, v2, v10, v11
	s_cselect_b64 s[8:9], -1, 0
	v_max3_f32 v2, v2, v12, v13
	s_and_b64 s[16:17], s[8:9], exec
	v_max3_f32 v2, v2, v14, v15
	s_cselect_b32 s1, 0, s1
	s_cmp_eq_u32 s14, 7
	v_max3_f32 v2, v2, v16, v17
	s_cselect_b64 s[16:17], -1, 0
	v_max3_f32 v2, v2, v18, v19
	s_or_b64 s[8:9], s[8:9], s[16:17]
	v_mov_b32_e32 v36, v2
	s_and_b64 s[8:9], s[8:9], exec
	s_nop 0
	v_permlane32_swap_b32_e32 v2, v36
	s_cselect_b32 s78, 12, 16
	s_lshl_b32 s79, s1, 6
	v_max_f32_e32 v36, v36, v36
	v_max_f32_e32 v2, v2, v2
	s_add_i32 s79, s79, s6
	s_and_b32 s6, s15, 0x3fffffc0
	v_max_f32_e32 v2, v2, v36
	s_lshl_b32 s6, s6, 2
	v_readlane_b32 s7, v252, 13
	v_add_f32_e32 v36, 0x7149f2ca, v2
	s_add_i32 s6, s7, s6
	v_cmp_ge_f32_e32 vcc, s76, v36
	s_cmp_eq_u64 vcc, exec
	v_max_f32_e32 v2, 0xf149f2ca, v2
	s_cselect_b64 vcc, -1, 0
	v_cndmask_b32_e32 v196, v2, v188, vcc
	s_add_u32 s2, s12, s2
	v_and_b32_e32 v189, 63, v39
	v_sub_f32_e32 v39, 0xf149f2ca, v2
	v_fma_f32 v2, v196, s33, 4.0
	s_addc_u32 s3, s13, s3
	s_add_i32 s92, s63, s10
	v_pk_fma_f32 v[114:115], v[18:19], s[80:81], v[2:3] op_sel_hi:[1,0,0]
	v_pk_fma_f32 v[112:113], v[16:17], s[80:81], v[2:3] op_sel_hi:[1,0,0]
	v_pk_fma_f32 v[110:111], v[14:15], s[80:81], v[2:3] op_sel_hi:[1,0,0]
	v_pk_fma_f32 v[108:109], v[12:13], s[80:81], v[2:3] op_sel_hi:[1,0,0]
	v_pk_fma_f32 v[106:107], v[10:11], s[80:81], v[2:3] op_sel_hi:[1,0,0]
	v_pk_fma_f32 v[104:105], v[8:9], s[80:81], v[2:3] op_sel_hi:[1,0,0]
	v_pk_fma_f32 v[102:103], v[6:7], s[80:81], v[2:3] op_sel_hi:[1,0,0]
	v_pk_fma_f32 v[100:101], v[4:5], s[80:81], v[2:3] op_sel_hi:[1,0,0]
	v_lshl_add_u64 v[4:5], s[2:3], 0, v[180:181]
	s_mov_b64 s[2:3], 0x420000
	s_add_i32 s81, s92, 0x4000
	v_lshl_add_u64 v[4:5], v[4:5], 0, s[2:3]
	s_mov_b32 m0, s81
	v_fmamk_f32 v20, v20, 0x3e0293ee, v2
	global_load_lds_dwordx4 v[4:5], off
	v_fmamk_f32 v21, v21, 0x3e0293ee, v2
	v_fmamk_f32 v22, v22, 0x3e0293ee, v2
	v_fmamk_f32 v23, v23, 0x3e0293ee, v2
	v_fmamk_f32 v24, v24, 0x3e0293ee, v2
	v_fmamk_f32 v25, v25, 0x3e0293ee, v2
	v_fmamk_f32 v26, v26, 0x3e0293ee, v2
	v_fmamk_f32 v27, v27, 0x3e0293ee, v2
	v_fmamk_f32 v28, v28, 0x3e0293ee, v2
	v_fmamk_f32 v29, v29, 0x3e0293ee, v2
	v_fmamk_f32 v30, v30, 0x3e0293ee, v2
	v_fmamk_f32 v31, v31, 0x3e0293ee, v2
	v_fmamk_f32 v32, v32, 0x3e0293ee, v2
	v_fmamk_f32 v33, v33, 0x3e0293ee, v2
	v_fmamk_f32 v34, v34, 0x3e0293ee, v2
	v_mov_b32_e32 v36, v2
	v_subrev_co_u32_e64 v2, s[68:69], 9, v56
	v_subrev_u32_e32 v7, 28, v56
	v_cmp_gt_u32_e64 s[36:37], 16, v2
	v_subrev_u32_e32 v2, 41, v56
	v_cmp_gt_u32_e64 s[54:55], 16, v7
	v_add_u32_e32 v7, -1, v56
	v_cmp_gt_u32_e64 s[34:35], 16, v2
	v_subrev_u32_e32 v2, 42, v56
	v_cmp_gt_u32_e64 s[52:53], 16, v7
	v_subrev_u32_e32 v7, 33, v56
	v_cmp_gt_u32_e64 s[28:29], 16, v2
	v_subrev_u32_e32 v2, 43, v56
	v_cmp_gt_u32_e64 s[50:51], 16, v7
	v_add_u32_e32 v7, -2, v56
	v_cmp_gt_u32_e64 s[24:25], 16, v2
	v_subrev_u32_e32 v2, 44, v56
	v_mul_f32_e32 v39, 0x3e0293ee, v39
	v_cmp_gt_u32_e64 s[48:49], 16, v7
	v_subrev_u32_e32 v7, 34, v56
	v_cmp_gt_u32_e64 s[20:21], 16, v2
	v_subrev_u32_e32 v2, 17, v56
	v_exp_f32_e32 v39, v39
	v_cmp_gt_u32_e64 s[46:47], 16, v7
	v_add_u32_e32 v7, -3, v56
	v_cmp_gt_u32_e64 s[18:19], 16, v2
	v_subrev_u32_e32 v2, 18, v56
	v_cmp_gt_u32_e64 s[44:45], 16, v7
	v_subrev_u32_e32 v7, 35, v56
	v_cmp_gt_u32_e64 s[14:15], 16, v2
	v_subrev_u32_e32 v2, 19, v56
	v_lshl_add_u64 v[184:185], s[4:5], 0, v[182:183]
	v_cmp_lt_u32_e64 s[4:5], 50, v56
	v_fmac_f32_e32 v36, 0x3e0293ee, v35
	v_subrev_u32_e32 v4, 25, v56
	v_subrev_u32_e32 v5, 26, v56
	v_subrev_u32_e32 v6, 27, v56
	v_cmp_gt_u32_e64 s[42:43], 16, v7
	v_add_u32_e32 v7, -4, v56
	v_cmp_gt_u32_e64 s[8:9], 16, v2
	v_writelane_b32 v252, s4, 26
	v_subrev_u32_e32 v2, 20, v56
	v_exp_f32_e32 v116, v20
	v_exp_f32_e32 v117, v21
	v_exp_f32_e32 v118, v22
	v_exp_f32_e32 v119, v23
	v_exp_f32_e32 v120, v24
	v_exp_f32_e32 v121, v25
	v_exp_f32_e32 v122, v26
	v_exp_f32_e32 v123, v27
	v_exp_f32_e32 v124, v28
	v_exp_f32_e32 v125, v29
	v_exp_f32_e32 v126, v30
	v_exp_f32_e32 v127, v31
	v_exp_f32_e32 v128, v32
	v_exp_f32_e32 v129, v33
	v_exp_f32_e32 v130, v34
	v_exp_f32_e32 v131, v36
	s_waitcnt vmcnt(1)
	v_cmp_gt_u32_e64 s[66:67], 16, v4
	v_subrev_co_u32_e64 v4, s[64:65], 10, v56
	v_cmp_gt_u32_e64 s[62:63], 16, v5
	v_subrev_co_u32_e64 v5, s[60:61], 11, v56
	v_cmp_gt_u32_e64 s[58:59], 16, v6
	v_subrev_co_u32_e64 v6, s[56:57], 12, v56
	v_cmp_gt_u32_e64 s[40:41], 16, v7
	v_subrev_u32_e32 v7, 36, v56
	v_writelane_b32 v252, s5, 27
	v_cmp_gt_u32_e64 s[4:5], 16, v2
	v_mov_b32_e32 v16, v3
	v_mov_b32_e32 v17, v3
	v_cndmask_b32_e64 v132, v39, 1.0, vcc
	s_barrier
	v_lshl_add_u32 v195, v38, 2, s6
	v_cmp_gt_u32_e64 s[38:39], 16, v7
	v_cmp_gt_u32_e64 s[30:31], 16, v4
	v_cmp_gt_u32_e64 s[26:27], 16, v5
	v_cmp_gt_u32_e64 s[22:23], 16, v6
	v_cmp_lt_u32_e64 s[16:17], 48, v56
	v_cmp_lt_u32_e64 s[10:11], 49, v56
	v_lshl_add_u64 v[186:187], s[12:13], 0, v[180:181]
	v_writelane_b32 v252, s4, 28
	v_lshl_add_u32 v194, v37, 2, s6
	v_mov_b32_e32 v2, v3
	v_mov_b32_e32 v4, v3
	v_mov_b32_e32 v5, v3
	v_mov_b32_e32 v6, v3
	v_mov_b32_e32 v7, v3
	v_mov_b32_e32 v8, v3
	v_mov_b32_e32 v9, v3
	v_mov_b32_e32 v10, v3
	v_mov_b32_e32 v11, v3
	v_mov_b32_e32 v12, v3
	v_mov_b32_e32 v13, v3
	v_mov_b32_e32 v14, v3
	v_mov_b32_e32 v15, v3
	v_mov_b64_e32 v[34:35], v[16:17]
	v_cmp_lt_u32_e64 s[12:13], 51, v56
	v_mov_b64_e32 v[66:67], v[16:17]
	v_mov_b64_e32 v[50:51], v[16:17]
	v_writelane_b32 v252, s5, 29
	s_sub_i32 s4, s1, s70
	v_mov_b64_e32 v[32:33], v[14:15]
	v_mov_b64_e32 v[30:31], v[12:13]
	v_mov_b64_e32 v[28:29], v[10:11]
	v_mov_b64_e32 v[26:27], v[8:9]
	v_mov_b64_e32 v[24:25], v[6:7]
	v_mov_b64_e32 v[22:23], v[4:5]
	v_mov_b64_e32 v[20:21], v[2:3]
	v_mov_b64_e32 v[64:65], v[14:15]
	v_mov_b64_e32 v[62:63], v[12:13]
	v_mov_b64_e32 v[60:61], v[10:11]
	v_mov_b64_e32 v[58:59], v[8:9]
	v_mov_b64_e32 v[56:57], v[6:7]
	v_mov_b64_e32 v[54:55], v[4:5]
	v_mov_b64_e32 v[52:53], v[2:3]
	v_mov_b64_e32 v[48:49], v[14:15]
	v_mov_b64_e32 v[46:47], v[12:13]
	v_mov_b64_e32 v[44:45], v[10:11]
	v_mov_b64_e32 v[42:43], v[8:9]
	v_mov_b64_e32 v[40:41], v[6:7]
	v_mov_b64_e32 v[38:39], v[4:5]
	v_mov_b64_e32 v[36:37], v[2:3]
	v_mov_b64_e32 v[18:19], v[16:17]
	s_mov_b32 s97, 2
	s_add_i32 s96, s96, 4
	v_cmp_gt_u32_e64 s[2:3], 32, v189
	v_add_u32_e32 v193, 0x4000, v200
	v_add_u32_e32 v192, 0x4000, v202
	v_add_u32_e32 v191, 0x4000, v199
	v_add_u32_e32 v190, 0x4000, v201
	v_lshl_add_u32 v207, v198, 2, s72
	s_sub_i32 s75, s4, s71
	v_mov_b32_e32 v197, 0
	s_movk_i32 s93, 0x80
	v_mov_b64_e32 v[16:17], v[14:15]
	v_mov_b64_e32 v[14:15], v[12:13]
	v_mov_b64_e32 v[12:13], v[10:11]
	v_mov_b64_e32 v[10:11], v[8:9]
	v_mov_b64_e32 v[8:9], v[6:7]
	v_mov_b64_e32 v[6:7], v[4:5]
	v_mov_b64_e32 v[4:5], v[2:3]
	v_writelane_b32 v252, s6, 30
	s_branch .LBB0_585

.LBB0_587:
	s_cmp_lt_u32 s82, 5
	s_cselect_b64 vcc, -1, 0
	s_add_i32 s6, s77, -6
	s_cmp_ge_i32 s6, s94
	s_cselect_b64 s[4:5], -1, 0
	s_cmp_lt_i32 s6, s96
	s_cselect_b64 s[6:7], -1, 0
	s_and_b64 s[4:5], s[4:5], s[6:7]
	s_or_b64 s[4:5], vcc, s[4:5]
	s_andn2_b64 vcc, exec, s[4:5]
	s_cbranch_vccnz .LBB0_589
	v_add_f32_e32 v2, 0, v116
	v_add_f32_e32 v2, v117, v2
	v_add_f32_e32 v2, v118, v2
	v_add_f32_e32 v2, v119, v2
	v_add_f32_e32 v2, v120, v2
	v_add_f32_e32 v2, v121, v2
	v_add_f32_e32 v2, v122, v2
	v_add_f32_e32 v2, v123, v2
	v_add_f32_e32 v2, v124, v2
	v_add_f32_e32 v2, v125, v2
	v_add_f32_e32 v2, v126, v2
	v_add_f32_e32 v2, v127, v2
	v_exp_f32_e32 v100, v100
	v_add_f32_e32 v2, v128, v2
	v_exp_f32_e32 v101, v101
	v_add_f32_e32 v2, v129, v2
	v_exp_f32_e32 v102, v102
	v_add_f32_e32 v2, v130, v2
	v_exp_f32_e32 v103, v103
	v_add_f32_e32 v2, v131, v2
	v_exp_f32_e32 v104, v104
	v_add_f32_e32 v2, v100, v2
	v_exp_f32_e32 v105, v105
	v_add_f32_e32 v2, v101, v2
	v_exp_f32_e32 v106, v106
	v_add_f32_e32 v2, v102, v2
	v_exp_f32_e32 v107, v107
	v_add_f32_e32 v2, v103, v2
	v_exp_f32_e32 v108, v108
	v_add_f32_e32 v2, v104, v2
	v_exp_f32_e32 v109, v109
	v_add_f32_e32 v2, v105, v2
	v_exp_f32_e32 v110, v110
	v_add_f32_e32 v2, v106, v2
	v_exp_f32_e32 v111, v111
	v_add_f32_e32 v2, v107, v2
	v_exp_f32_e32 v112, v112
	v_add_f32_e32 v2, v108, v2
	v_exp_f32_e32 v113, v113
	v_add_f32_e32 v2, v109, v2
	v_exp_f32_e32 v114, v114
	v_add_f32_e32 v2, v110, v2
	v_exp_f32_e32 v115, v115
	v_add_f32_e32 v2, v111, v2
	v_add_f32_e32 v2, v112, v2
	v_add_f32_e32 v2, v113, v2
	v_add_f32_e32 v2, v114, v2
	v_add_f32_e32 v2, v115, v2
	v_mov_b32_e32 v133, v2
	s_nop 1
	v_permlane32_swap_b32_e32 v2, v133
	v_add_f32_e32 v2, v2, v133
	v_fmac_f32_e32 v2, v197, v132
	v_cvt_pk_fp8_f32 v132, v116, v117
	v_cvt_pk_fp8_f32 v136, v100, v101
	v_cvt_pk_fp8_f32 v133, v120, v121
	v_cvt_pk_fp8_f32 v137, v104, v105
	v_cvt_pk_fp8_f32 v134, v124, v125
	v_cvt_pk_fp8_f32 v138, v108, v109
	v_cvt_pk_fp8_f32 v135, v128, v129
	v_cvt_pk_fp8_f32 v139, v112, v113
	v_cvt_pk_fp8_f32 v132, v118, v119 op_sel:[0,0,1]
	v_cvt_pk_fp8_f32 v136, v102, v103 op_sel:[0,0,1]
	v_cvt_pk_fp8_f32 v133, v122, v123 op_sel:[0,0,1]
	v_cvt_pk_fp8_f32 v137, v106, v107 op_sel:[0,0,1]
	v_cvt_pk_fp8_f32 v134, v126, v127 op_sel:[0,0,1]
	v_cvt_pk_fp8_f32 v138, v110, v111 op_sel:[0,0,1]
	v_cvt_pk_fp8_f32 v135, v130, v131 op_sel:[0,0,1]
	v_cvt_pk_fp8_f32 v139, v114, v115 op_sel:[0,0,1]
	ds_read_b64_tr_b8 v[140:141], v200 offset:0
	ds_read_b64_tr_b8 v[142:143], v200 offset:0x800
	ds_read_b64_tr_b8 v[144:145], v200 offset:0x1000
	ds_read_b64_tr_b8 v[146:147], v200 offset:0x1800
	s_waitcnt lgkmcnt(0)
	s_nop 0
	v_mfma_f32_32x32x64_f8f6f4 v[20:35], v[132:139], v[140:147], v[20:35]
	ds_read_b64_tr_b8 v[140:141], v202 offset:0
	ds_read_b64_tr_b8 v[142:143], v202 offset:0x800
	ds_read_b64_tr_b8 v[144:145], v202 offset:0x1000
	ds_read_b64_tr_b8 v[146:147], v202 offset:0x1800
	s_waitcnt lgkmcnt(0)
	s_nop 0
	v_mfma_f32_32x32x64_f8f6f4 v[52:67], v[132:139], v[140:147], v[52:67]
	ds_read_b64_tr_b8 v[140:141], v199 offset:0
	ds_read_b64_tr_b8 v[142:143], v199 offset:0x800
	ds_read_b64_tr_b8 v[144:145], v199 offset:0x1000
	ds_read_b64_tr_b8 v[146:147], v199 offset:0x1800
	s_waitcnt lgkmcnt(0)
	s_nop 0
	v_mfma_f32_32x32x64_f8f6f4 v[36:51], v[132:139], v[140:147], v[36:51]
	ds_read_b64_tr_b8 v[140:141], v201 offset:0
	ds_read_b64_tr_b8 v[142:143], v201 offset:0x800
	ds_read_b64_tr_b8 v[144:145], v201 offset:0x1000
	ds_read_b64_tr_b8 v[146:147], v201 offset:0x1800
	s_waitcnt lgkmcnt(0)
	s_nop 0
	v_mfma_f32_32x32x64_f8f6f4 v[4:19], v[132:139], v[140:147], v[4:19]
	v_mov_b32_e32 v197, v2
	s_nop 15
	s_nop 7

.LBB0_656:
	v_max_f32_e32 v2, v84, v85
	v_max3_f32 v2, v2, v86, v87
	v_max3_f32 v2, v2, v88, v89
	v_max3_f32 v2, v2, v90, v91
	v_max3_f32 v2, v2, v92, v93
	v_max3_f32 v2, v2, v94, v95
	v_max3_f32 v2, v2, v96, v97
	v_max3_f32 v2, v2, v98, v99
	v_max3_f32 v2, v2, v68, v69
	v_max3_f32 v2, v2, v70, v71
	v_max3_f32 v2, v2, v72, v73
	v_max3_f32 v2, v2, v74, v75
	v_max3_f32 v2, v2, v76, v77
	v_max3_f32 v2, v2, v78, v79
	v_max3_f32 v2, v2, v80, v81
	v_max3_f32 v2, v2, v82, v83
	v_mov_b32_e32 v132, v2
	s_nop 1
	v_permlane32_swap_b32_e32 v2, v132
	v_max_f32_e32 v2, v2, v132
	v_sub_f32_e32 v132, v2, v196
	v_cmp_ge_f32_e32 vcc, s76, v132
	s_cmp_eq_u64 vcc, exec
	v_max_f32_e32 v132, v196, v196
	s_cselect_b64 vcc, -1, 0
	v_max_f32_e32 v132, v132, v2
	v_sub_f32_e32 v2, v196, v132
	v_cndmask_b32_e32 v196, v132, v196, vcc
	v_fma_f32 v132, v196, s33, 4.0
	v_mul_f32_e32 v2, 0x3e0293ee, v2
	v_mov_b32_e32 v133, v132
	v_exp_f32_e32 v2, v2
	v_fmamk_f32 v84, v84, 0x3e0293ee, v132
	v_fmamk_f32 v85, v85, 0x3e0293ee, v132
	v_fmamk_f32 v86, v86, 0x3e0293ee, v132
	v_fmamk_f32 v87, v87, 0x3e0293ee, v132
	v_fmamk_f32 v88, v88, 0x3e0293ee, v132
	v_fmamk_f32 v89, v89, 0x3e0293ee, v132
	v_fmamk_f32 v90, v90, 0x3e0293ee, v132
	v_fmamk_f32 v91, v91, 0x3e0293ee, v132
	v_fmamk_f32 v92, v92, 0x3e0293ee, v132
	v_fmamk_f32 v93, v93, 0x3e0293ee, v132
	v_fmamk_f32 v94, v94, 0x3e0293ee, v132
	v_fmamk_f32 v95, v95, 0x3e0293ee, v132
	v_fmamk_f32 v96, v96, 0x3e0293ee, v132
	v_fmamk_f32 v97, v97, 0x3e0293ee, v132
	v_fmamk_f32 v98, v98, 0x3e0293ee, v132
	v_fmac_f32_e32 v133, 0x3e0293ee, v99
	v_exp_f32_e32 v84, v84
	v_exp_f32_e32 v85, v85
	v_exp_f32_e32 v86, v86
	v_exp_f32_e32 v87, v87
	v_exp_f32_e32 v88, v88
	v_exp_f32_e32 v89, v89
	v_exp_f32_e32 v90, v90
	v_exp_f32_e32 v91, v91
	v_exp_f32_e32 v92, v92
	v_exp_f32_e32 v93, v93
	v_exp_f32_e32 v94, v94
	v_exp_f32_e32 v95, v95
	v_exp_f32_e32 v96, v96
	v_exp_f32_e32 v97, v97
	v_exp_f32_e32 v98, v98
	v_exp_f32_e32 v99, v133
	v_cndmask_b32_e64 v2, v2, 1.0, vcc
	v_pk_fma_f32 v[82:83], v[82:83], s[80:81], v[132:133] op_sel_hi:[1,0,0]
	v_pk_fma_f32 v[80:81], v[80:81], s[80:81], v[132:133] op_sel_hi:[1,0,0]
	v_pk_fma_f32 v[78:79], v[78:79], s[80:81], v[132:133] op_sel_hi:[1,0,0]
	v_pk_fma_f32 v[76:77], v[76:77], s[80:81], v[132:133] op_sel_hi:[1,0,0]
	v_pk_fma_f32 v[74:75], v[74:75], s[80:81], v[132:133] op_sel_hi:[1,0,0]
	v_pk_fma_f32 v[72:73], v[72:73], s[80:81], v[132:133] op_sel_hi:[1,0,0]
	v_pk_fma_f32 v[70:71], v[70:71], s[80:81], v[132:133] op_sel_hi:[1,0,0]
	v_pk_fma_f32 v[68:69], v[68:69], s[80:81], v[132:133] op_sel_hi:[1,0,0]

.LBB0_665:
	v_add_f32_e32 v132, 0, v84
	v_add_f32_e32 v132, v85, v132
	v_add_f32_e32 v132, v86, v132
	v_add_f32_e32 v132, v87, v132
	v_add_f32_e32 v132, v88, v132
	v_add_f32_e32 v132, v89, v132
	v_add_f32_e32 v132, v90, v132
	v_add_f32_e32 v132, v91, v132
	v_add_f32_e32 v132, v92, v132
	v_add_f32_e32 v132, v93, v132
	v_add_f32_e32 v132, v94, v132
	v_add_f32_e32 v132, v95, v132
	v_exp_f32_e32 v68, v68
	v_add_f32_e32 v132, v96, v132
	v_exp_f32_e32 v69, v69
	v_add_f32_e32 v132, v97, v132
	v_exp_f32_e32 v70, v70
	v_add_f32_e32 v132, v98, v132
	v_exp_f32_e32 v71, v71
	v_add_f32_e32 v132, v99, v132
	v_exp_f32_e32 v72, v72
	v_add_f32_e32 v132, v68, v132
	v_exp_f32_e32 v73, v73
	v_add_f32_e32 v132, v69, v132
	v_exp_f32_e32 v74, v74
	v_add_f32_e32 v132, v70, v132
	v_exp_f32_e32 v75, v75
	v_add_f32_e32 v132, v71, v132
	v_exp_f32_e32 v76, v76
	v_add_f32_e32 v132, v72, v132
	v_exp_f32_e32 v77, v77
	v_add_f32_e32 v132, v73, v132
	v_exp_f32_e32 v78, v78
	v_add_f32_e32 v132, v74, v132
	v_exp_f32_e32 v79, v79
	v_add_f32_e32 v132, v75, v132
	v_exp_f32_e32 v80, v80
	v_add_f32_e32 v132, v76, v132
	v_exp_f32_e32 v81, v81
	v_add_f32_e32 v132, v77, v132
	v_exp_f32_e32 v82, v82
	v_add_f32_e32 v132, v78, v132
	v_exp_f32_e32 v83, v83
	v_add_f32_e32 v132, v79, v132
	v_add_f32_e32 v132, v80, v132
	v_add_f32_e32 v132, v81, v132
	v_add_f32_e32 v132, v82, v132
	v_add_f32_e32 v132, v83, v132
	v_mov_b32_e32 v133, v132
	s_nop 1
	v_permlane32_swap_b32_e32 v132, v133
	v_add_f32_e32 v148, v132, v133
	v_cvt_pk_fp8_f32 v132, v84, v85
	v_cvt_pk_fp8_f32 v136, v68, v69
	v_cvt_pk_fp8_f32 v133, v88, v89
	v_cvt_pk_fp8_f32 v137, v72, v73
	v_cvt_pk_fp8_f32 v134, v92, v93
	v_cvt_pk_fp8_f32 v138, v76, v77
	v_cvt_pk_fp8_f32 v135, v96, v97
	v_cvt_pk_fp8_f32 v139, v80, v81
	v_fmac_f32_e32 v148, v197, v2
	v_cvt_pk_fp8_f32 v132, v86, v87 op_sel:[0,0,1]
	v_cvt_pk_fp8_f32 v136, v70, v71 op_sel:[0,0,1]
	v_cvt_pk_fp8_f32 v133, v90, v91 op_sel:[0,0,1]
	v_cvt_pk_fp8_f32 v137, v74, v75 op_sel:[0,0,1]
	v_cvt_pk_fp8_f32 v134, v94, v95 op_sel:[0,0,1]
	v_cvt_pk_fp8_f32 v138, v78, v79 op_sel:[0,0,1]
	v_cvt_pk_fp8_f32 v135, v98, v99 op_sel:[0,0,1]
	v_cvt_pk_fp8_f32 v139, v82, v83 op_sel:[0,0,1]
	ds_read_b64_tr_b8 v[140:141], v193 offset:0
	ds_read_b64_tr_b8 v[142:143], v193 offset:0x800
	ds_read_b64_tr_b8 v[144:145], v193 offset:0x1000
	ds_read_b64_tr_b8 v[146:147], v193 offset:0x1800
	s_waitcnt lgkmcnt(0)
	s_nop 0
	v_mfma_f32_32x32x64_f8f6f4 v[20:35], v[132:139], v[140:147], v[20:35]
	ds_read_b64_tr_b8 v[140:141], v192 offset:0
	ds_read_b64_tr_b8 v[142:143], v192 offset:0x800
	ds_read_b64_tr_b8 v[144:145], v192 offset:0x1000
	ds_read_b64_tr_b8 v[146:147], v192 offset:0x1800
	s_waitcnt lgkmcnt(0)
	s_nop 0
	v_mfma_f32_32x32x64_f8f6f4 v[52:67], v[132:139], v[140:147], v[52:67]
	ds_read_b64_tr_b8 v[140:141], v191 offset:0
	ds_read_b64_tr_b8 v[142:143], v191 offset:0x800
	ds_read_b64_tr_b8 v[144:145], v191 offset:0x1000
	ds_read_b64_tr_b8 v[146:147], v191 offset:0x1800
	s_waitcnt lgkmcnt(0)
	s_nop 0
	v_mfma_f32_32x32x64_f8f6f4 v[36:51], v[132:139], v[140:147], v[36:51]
	ds_read_b64_tr_b8 v[140:141], v190 offset:0
	ds_read_b64_tr_b8 v[142:143], v190 offset:0x800
	ds_read_b64_tr_b8 v[144:145], v190 offset:0x1000
	ds_read_b64_tr_b8 v[146:147], v190 offset:0x1800
	s_waitcnt lgkmcnt(0)
	s_nop 0
	v_mfma_f32_32x32x64_f8f6f4 v[4:19], v[132:139], v[140:147], v[4:19]
	v_mov_b32_e32 v197, v148
	s_nop 15
	s_nop 7
	s_and_b64 vcc, exec, s[72:73]
	v_mov_b32_e32 v132, 1.0
	s_cbranch_vccnz .LBB0_733

.LBB0_732:
	v_max_f32_e32 v2, v116, v117
	v_max3_f32 v2, v2, v118, v119
	v_max3_f32 v2, v2, v120, v121
	v_max3_f32 v2, v2, v122, v123
	v_max3_f32 v2, v2, v124, v125
	v_max3_f32 v2, v2, v126, v127
	v_max3_f32 v2, v2, v128, v129
	v_max3_f32 v2, v2, v130, v131
	v_max3_f32 v2, v2, v100, v101
	v_max3_f32 v2, v2, v102, v103
	v_max3_f32 v2, v2, v104, v105
	v_max3_f32 v2, v2, v106, v107
	v_max3_f32 v2, v2, v108, v109
	v_max3_f32 v2, v2, v110, v111
	v_max3_f32 v2, v2, v112, v113
	v_max3_f32 v2, v2, v114, v115
	v_mov_b32_e32 v132, v2
	s_nop 1
	v_permlane32_swap_b32_e32 v2, v132
	v_max_f32_e32 v2, v2, v132
	v_sub_f32_e32 v132, v2, v196
	v_cmp_ge_f32_e32 vcc, s76, v132
	s_cmp_eq_u64 vcc, exec
	v_max_f32_e32 v132, v196, v196
	s_cselect_b64 vcc, -1, 0
	v_max_f32_e32 v2, v132, v2
	v_sub_f32_e32 v132, v196, v2
	v_cndmask_b32_e32 v196, v2, v196, vcc
	v_fma_f32 v2, v196, s33, 4.0
	v_mul_f32_e32 v132, 0x3e0293ee, v132
	v_mov_b32_e32 v133, v2
	v_exp_f32_e32 v132, v132
	v_fmamk_f32 v116, v116, 0x3e0293ee, v2
	v_fmamk_f32 v117, v117, 0x3e0293ee, v2
	v_fmamk_f32 v118, v118, 0x3e0293ee, v2
	v_fmamk_f32 v119, v119, 0x3e0293ee, v2
	v_fmamk_f32 v120, v120, 0x3e0293ee, v2
	v_fmamk_f32 v121, v121, 0x3e0293ee, v2
	v_fmamk_f32 v122, v122, 0x3e0293ee, v2
	v_fmamk_f32 v123, v123, 0x3e0293ee, v2
	v_fmamk_f32 v124, v124, 0x3e0293ee, v2
	v_fmamk_f32 v125, v125, 0x3e0293ee, v2
	v_fmamk_f32 v126, v126, 0x3e0293ee, v2
	v_fmamk_f32 v127, v127, 0x3e0293ee, v2
	v_fmamk_f32 v128, v128, 0x3e0293ee, v2
	v_fmamk_f32 v129, v129, 0x3e0293ee, v2
	v_fmamk_f32 v130, v130, 0x3e0293ee, v2
	v_fmac_f32_e32 v133, 0x3e0293ee, v131
	v_exp_f32_e32 v116, v116
	v_exp_f32_e32 v117, v117
	v_exp_f32_e32 v118, v118
	v_exp_f32_e32 v119, v119
	v_exp_f32_e32 v120, v120
	v_exp_f32_e32 v121, v121
	v_exp_f32_e32 v122, v122
	v_exp_f32_e32 v123, v123
	v_exp_f32_e32 v124, v124
	v_exp_f32_e32 v125, v125
	v_exp_f32_e32 v126, v126
	v_exp_f32_e32 v127, v127
	v_exp_f32_e32 v128, v128
	v_exp_f32_e32 v129, v129
	v_exp_f32_e32 v130, v130
	v_exp_f32_e32 v131, v133
	v_cndmask_b32_e64 v132, v132, 1.0, vcc
	v_pk_fma_f32 v[114:115], v[114:115], s[80:81], v[2:3] op_sel_hi:[1,0,0]
	v_pk_fma_f32 v[112:113], v[112:113], s[80:81], v[2:3] op_sel_hi:[1,0,0]
	v_pk_fma_f32 v[110:111], v[110:111], s[80:81], v[2:3] op_sel_hi:[1,0,0]
	v_pk_fma_f32 v[108:109], v[108:109], s[80:81], v[2:3] op_sel_hi:[1,0,0]
	v_pk_fma_f32 v[106:107], v[106:107], s[80:81], v[2:3] op_sel_hi:[1,0,0]
	v_pk_fma_f32 v[104:105], v[104:105], s[80:81], v[2:3] op_sel_hi:[1,0,0]
	v_pk_fma_f32 v[102:103], v[102:103], s[80:81], v[2:3] op_sel_hi:[1,0,0]
	v_pk_fma_f32 v[100:101], v[100:101], s[80:81], v[2:3] op_sel_hi:[1,0,0]

.LBB0_805:
	s_or_b64 exec, exec, s[0:1]
	v_max_f32_e32 v2, v102, v84
	v_max3_f32 v2, v2, v85, v86
	v_max3_f32 v2, v2, v87, v88
	v_max3_f32 v2, v2, v89, v90
	v_max3_f32 v2, v2, v91, v92
	v_max3_f32 v2, v2, v93, v94
	v_max3_f32 v2, v2, v95, v96
	v_max3_f32 v2, v2, v97, v82
	v_max3_f32 v2, v2, v100, v101
	v_max3_f32 v2, v2, v68, v69
	v_max3_f32 v2, v2, v70, v71
	v_max3_f32 v2, v2, v72, v73
	v_max3_f32 v2, v2, v74, v75
	v_max3_f32 v2, v2, v76, v77
	v_max3_f32 v2, v2, v78, v79
	v_max3_f32 v2, v2, v80, v81
	v_mov_b32_e32 v83, v2
	s_nop 1
	v_permlane32_swap_b32_e32 v2, v83
	v_max_f32_e32 v2, v2, v83
	v_sub_f32_e32 v83, v2, v196
	v_cmp_ge_f32_e32 vcc, s76, v83
	v_max_f32_e32 v98, v196, v196
	s_cmp_eq_u64 vcc, exec
	v_max_f32_e32 v98, v98, v2
	s_cselect_b64 vcc, -1, 0
	v_cndmask_b32_e32 v83, v98, v196, vcc
	v_sub_f32_e32 v2, v196, v98
	v_fma_f32 v104, v83, s33, 4.0
	v_mul_f32_e32 v2, 0x3e0293ee, v2
	v_mov_b32_e32 v116, v104
	v_exp_f32_e32 v2, v2
	v_fmamk_f32 v98, v102, 0x3e0293ee, v104
	v_fmamk_f32 v99, v84, 0x3e0293ee, v104
	v_fmamk_f32 v102, v85, 0x3e0293ee, v104
	v_fmamk_f32 v103, v86, 0x3e0293ee, v104
	v_fmamk_f32 v105, v87, 0x3e0293ee, v104
	v_fmamk_f32 v106, v88, 0x3e0293ee, v104
	v_fmamk_f32 v107, v89, 0x3e0293ee, v104
	v_fmamk_f32 v108, v90, 0x3e0293ee, v104
	v_fmamk_f32 v109, v91, 0x3e0293ee, v104
	v_fmamk_f32 v110, v92, 0x3e0293ee, v104
	v_fmamk_f32 v111, v93, 0x3e0293ee, v104
	v_fmamk_f32 v112, v94, 0x3e0293ee, v104
	v_fmamk_f32 v113, v95, 0x3e0293ee, v104
	v_fmamk_f32 v114, v96, 0x3e0293ee, v104
	v_fmamk_f32 v115, v97, 0x3e0293ee, v104
	v_fmac_f32_e32 v116, 0x3e0293ee, v82
	v_exp_f32_e32 v84, v98
	v_exp_f32_e32 v85, v99
	v_exp_f32_e32 v86, v102
	v_exp_f32_e32 v87, v103
	v_exp_f32_e32 v88, v105
	v_exp_f32_e32 v89, v106
	v_exp_f32_e32 v90, v107
	v_exp_f32_e32 v91, v108
	v_exp_f32_e32 v92, v109
	v_exp_f32_e32 v93, v110
	v_exp_f32_e32 v94, v111
	v_exp_f32_e32 v95, v112
	v_exp_f32_e32 v96, v113
	v_exp_f32_e32 v97, v114
	v_exp_f32_e32 v98, v115
	v_exp_f32_e32 v99, v116
	v_cndmask_b32_e64 v2, v2, 1.0, vcc
	v_pk_fma_f32 v[82:83], v[80:81], s[80:81], v[104:105] op_sel_hi:[1,0,0]
	v_pk_fma_f32 v[80:81], v[78:79], s[80:81], v[104:105] op_sel_hi:[1,0,0]
	v_pk_fma_f32 v[78:79], v[76:77], s[80:81], v[104:105] op_sel_hi:[1,0,0]
	v_pk_fma_f32 v[76:77], v[74:75], s[80:81], v[104:105] op_sel_hi:[1,0,0]
	v_pk_fma_f32 v[74:75], v[72:73], s[80:81], v[104:105] op_sel_hi:[1,0,0]
	v_pk_fma_f32 v[72:73], v[70:71], s[80:81], v[104:105] op_sel_hi:[1,0,0]
	v_pk_fma_f32 v[70:71], v[68:69], s[80:81], v[104:105] op_sel_hi:[1,0,0]
	v_pk_fma_f32 v[68:69], v[100:101], s[80:81], v[104:105] op_sel_hi:[1,0,0]
	v_cmp_gt_f32_e32 vcc, 1.0, v2
	s_cbranch_vccnz .LBB0_807
	s_branch .LBB0_810

.LBB0_895:
	s_lshl_b32 s0, s63, 11
	s_ashr_i32 s1, s0, 31
	v_lshl_or_b32 v34, s64, 8, v223
	s_add_u32 s0, s46, s0
	v_ashrrev_i32_e32 v35, 31, v34
	s_addc_u32 s1, s47, s1
	v_lshl_add_u32 v36, s65, 8, v1
	v_lshl_add_u64 v[38:39], s[0:1], 0, v[34:35]
	v_mad_i64_i32 v[4:5], s[0:1], v36, s58, v[38:39]
	global_load_dwordx2 v[64:65], v[4:5], off
	v_ashrrev_i32_e32 v37, 31, v36
	v_lshl_add_u64 v[40:41], v[34:35], 1, s[10:11]
	s_cmp_lg_u32 s63, 0
	v_lshlrev_b64 v[2:3], 12, v[36:37]
	s_cselect_b64 s[0:1], -1, 0
	s_cmp_eq_u32 s63, 0
	v_lshl_add_u64 v[2:3], v[40:41], 0, v[2:3]
	s_cbranch_scc1 .LBB0_897
	global_load_dwordx4 v[30:33], v[2:3], off
	s_branch .LBB0_898

.LBB0_915:
	v_lshl_add_u64 v[30:31], s[12:13], 0, v[210:211]
	s_andn2_b64 vcc, exec, s[4:5]
	v_lshl_add_u64 v[30:31], v[30:31], 0, v[34:35]
	s_cbranch_vccnz .LBB0_917
	v_mul_f32_e32 v37, 0x41800000, v37
	v_mul_f32_e32 v189, 0x41800000, v64
	v_cvt_pk_fp8_f32 v64, v37, v189
	v_mul_f32_e32 v37, 0x41800000, v65
	v_mul_f32_e32 v187, 0x41800000, v187
	v_mul_f32_e32 v32, 0x41800000, v32
	v_cvt_pk_fp8_f32 v65, v187, v32
	v_mul_f32_e32 v186, 0x41800000, v186
	v_mul_f32_e32 v32, 0x41800000, v188
	v_mul_f32_e32 v33, 0x41800000, v33
	v_cvt_pk_fp8_f32 v64, v37, v186 op_sel:[0,0,1]
	v_cvt_pk_fp8_f32 v65, v32, v33 op_sel:[0,0,1]
	global_store_dwordx2 v[30:31], v[64:65], off

.LBB0_919:
	s_andn2_b64 vcc, exec, s[0:1]
	s_cbranch_vccnz .LBB0_921
	v_mul_f32_e32 v32, 0x41800000, v32
	v_mul_f32_e32 v61, 0x41800000, v26
	v_cvt_pk_fp8_f32 v26, v32, v61
	v_mul_f32_e32 v32, 0x41800000, v33
	v_mul_f32_e32 v33, 0x41800000, v27
	v_mul_f32_e32 v37, 0x41800000, v37
	v_mul_f32_e32 v28, 0x41800000, v28
	v_cvt_pk_fp8_f32 v27, v37, v28
	v_mul_f32_e32 v28, 0x41800000, v60
	v_mul_f32_e32 v29, 0x41800000, v29
	v_cvt_pk_fp8_f32 v26, v32, v33 op_sel:[0,0,1]
	v_cvt_pk_fp8_f32 v27, v28, v29 op_sel:[0,0,1]
	global_store_dwordx2 v[30:31], v[26:27], off offset:128

.LBB0_923:
	v_lshl_add_u64 v[22:23], s[12:13], 0, v[28:29]
	s_andn2_b64 vcc, exec, s[0:1]
	v_lshl_add_u64 v[22:23], v[22:23], 0, v[34:35]
	s_cbranch_vccnz .LBB0_925
	v_mul_f32_e32 v29, 0x41800000, v30
	v_mul_f32_e32 v30, 0x41800000, v31
	v_cvt_pk_fp8_f32 v28, v29, v30
	v_mul_f32_e32 v30, 0x41800000, v32
	v_mul_f32_e32 v32, 0x41800000, v37
	v_mul_f32_e32 v24, 0x41800000, v24
	v_cvt_pk_fp8_f32 v29, v32, v24
	v_mul_f32_e32 v31, 0x41800000, v33
	v_mul_f32_e32 v24, 0x41800000, v56
	v_mul_f32_e32 v25, 0x41800000, v25
	v_cvt_pk_fp8_f32 v28, v30, v31 op_sel:[0,0,1]
	v_cvt_pk_fp8_f32 v29, v24, v25 op_sel:[0,0,1]
	global_store_dwordx2 v[22:23], v[28:29], off

.LBB0_927:
	s_andn2_b64 vcc, exec, s[0:1]
	s_cbranch_vccnz .LBB0_929
	v_mul_f32_e32 v24, 0x41800000, v24
	v_mul_f32_e32 v26, 0x41800000, v18
	v_cvt_pk_fp8_f32 v18, v24, v26
	v_mul_f32_e32 v24, 0x41800000, v25
	v_mul_f32_e32 v25, 0x41800000, v19
	v_mul_f32_e32 v26, 0x41800000, v28
	v_mul_f32_e32 v20, 0x41800000, v20
	v_cvt_pk_fp8_f32 v19, v26, v20
	v_mul_f32_e32 v20, 0x41800000, v29
	v_mul_f32_e32 v21, 0x41800000, v21
	v_cvt_pk_fp8_f32 v18, v24, v25 op_sel:[0,0,1]
	v_cvt_pk_fp8_f32 v19, v20, v21 op_sel:[0,0,1]
	global_store_dwordx2 v[22:23], v[18:19], off offset:128

.LBB0_931:
	v_lshl_add_u64 v[14:15], s[12:13], 0, v[20:21]
	s_andn2_b64 vcc, exec, s[0:1]
	v_lshl_add_u64 v[14:15], v[14:15], 0, v[34:35]
	s_cbranch_vccnz .LBB0_933
	v_mul_f32_e32 v21, 0x41800000, v22
	v_mul_f32_e32 v22, 0x41800000, v23
	v_cvt_pk_fp8_f32 v20, v21, v22
	v_mul_f32_e32 v22, 0x41800000, v24
	v_mul_f32_e32 v24, 0x41800000, v26
	v_mul_f32_e32 v16, 0x41800000, v16
	v_cvt_pk_fp8_f32 v21, v24, v16
	v_mul_f32_e32 v23, 0x41800000, v25
	v_mul_f32_e32 v16, 0x41800000, v27
	v_mul_f32_e32 v17, 0x41800000, v17
	v_cvt_pk_fp8_f32 v20, v22, v23 op_sel:[0,0,1]
	v_cvt_pk_fp8_f32 v21, v16, v17 op_sel:[0,0,1]
	global_store_dwordx2 v[14:15], v[20:21], off

.LBB0_935:
	s_andn2_b64 vcc, exec, s[0:1]
	s_cbranch_vccnz .LBB0_937
	v_mul_f32_e32 v16, 0x41800000, v16
	v_mul_f32_e32 v18, 0x41800000, v10
	v_cvt_pk_fp8_f32 v10, v16, v18
	v_mul_f32_e32 v16, 0x41800000, v17
	v_mul_f32_e32 v17, 0x41800000, v11
	v_mul_f32_e32 v18, 0x41800000, v20
	v_mul_f32_e32 v12, 0x41800000, v12
	v_cvt_pk_fp8_f32 v11, v18, v12
	v_mul_f32_e32 v12, 0x41800000, v21
	v_mul_f32_e32 v13, 0x41800000, v13
	v_cvt_pk_fp8_f32 v10, v16, v17 op_sel:[0,0,1]
	v_cvt_pk_fp8_f32 v11, v12, v13 op_sel:[0,0,1]
	global_store_dwordx2 v[14:15], v[10:11], off offset:128

.LBB0_939:
	v_lshl_add_u64 v[6:7], s[12:13], 0, v[12:13]
	s_andn2_b64 vcc, exec, s[0:1]
	v_lshl_add_u64 v[6:7], v[6:7], 0, v[34:35]
	s_cbranch_vccnz .LBB0_941
	v_mul_f32_e32 v13, 0x41800000, v14
	v_mul_f32_e32 v14, 0x41800000, v15
	v_cvt_pk_fp8_f32 v12, v13, v14
	v_mul_f32_e32 v14, 0x41800000, v16
	v_mul_f32_e32 v16, 0x41800000, v18
	v_mul_f32_e32 v8, 0x41800000, v8
	v_cvt_pk_fp8_f32 v13, v16, v8
	v_mul_f32_e32 v15, 0x41800000, v17
	v_mul_f32_e32 v8, 0x41800000, v19
	v_mul_f32_e32 v9, 0x41800000, v9
	v_cvt_pk_fp8_f32 v12, v14, v15 op_sel:[0,0,1]
	v_cvt_pk_fp8_f32 v13, v8, v9 op_sel:[0,0,1]
	global_store_dwordx2 v[6:7], v[12:13], off

.LBB0_943:
	s_andn2_b64 vcc, exec, s[0:1]
	s_cbranch_vccnz .LBB0_945
	v_mul_f32_e32 v8, 0x41800000, v8
	v_mul_f32_e32 v10, 0x41800000, v2
	v_cvt_pk_fp8_f32 v2, v8, v10
	v_mul_f32_e32 v8, 0x41800000, v9
	v_mul_f32_e32 v9, 0x41800000, v3
	v_mul_f32_e32 v10, 0x41800000, v12
	v_mul_f32_e32 v4, 0x41800000, v4
	v_cvt_pk_fp8_f32 v3, v10, v4
	v_mul_f32_e32 v4, 0x41800000, v13
	v_mul_f32_e32 v5, 0x41800000, v5
	v_cvt_pk_fp8_f32 v2, v8, v9 op_sel:[0,0,1]
	v_cvt_pk_fp8_f32 v3, v4, v5 op_sel:[0,0,1]
	global_store_dwordx2 v[6:7], v[2:3], off offset:128

.LBB0_963:
	v_lshl_add_u64 v[30:31], s[12:13], 0, v[60:61]
	s_andn2_b64 vcc, exec, s[0:1]
	v_lshl_add_u64 v[30:31], v[30:31], 0, v[34:35]
	s_cbranch_vccnz .LBB0_965
	v_mul_f32_e32 v60, 0x41800000, v58
	v_mul_f32_e32 v59, 0x41800000, v59
	v_cvt_pk_fp8_f32 v58, v60, v59
	v_mul_f32_e32 v60, 0x41800000, v62
	v_mul_f32_e32 v62, 0x41800000, v64
	v_mul_f32_e32 v32, 0x41800000, v32
	v_cvt_pk_fp8_f32 v59, v62, v32
	v_mul_f32_e32 v61, 0x41800000, v63
	v_mul_f32_e32 v32, 0x41800000, v65
	v_mul_f32_e32 v33, 0x41800000, v33
	v_cvt_pk_fp8_f32 v58, v60, v61 op_sel:[0,0,1]
	v_cvt_pk_fp8_f32 v59, v32, v33 op_sel:[0,0,1]
	global_store_dwordx2 v[30:31], v[58:59], off

.LBB0_967:
	s_andn2_b64 vcc, exec, s[0:1]
	s_cbranch_vccnz .LBB0_969
	v_mul_f32_e32 v32, 0x41800000, v32
	v_mul_f32_e32 v40, 0x41800000, v26
	v_cvt_pk_fp8_f32 v26, v32, v40
	v_mul_f32_e32 v32, 0x41800000, v33
	v_mul_f32_e32 v33, 0x41800000, v27
	v_mul_f32_e32 v40, 0x41800000, v56
	v_mul_f32_e32 v28, 0x41800000, v28
	v_cvt_pk_fp8_f32 v27, v40, v28
	v_mul_f32_e32 v28, 0x41800000, v57
	v_mul_f32_e32 v29, 0x41800000, v29
	v_cvt_pk_fp8_f32 v26, v32, v33 op_sel:[0,0,1]
	v_cvt_pk_fp8_f32 v27, v28, v29 op_sel:[0,0,1]
	global_store_dwordx2 v[30:31], v[26:27], off offset:128

.LBB0_971:
	v_lshl_add_u64 v[22:23], s[12:13], 0, v[28:29]
	s_andn2_b64 vcc, exec, s[0:1]
	v_lshl_add_u64 v[22:23], v[22:23], 0, v[34:35]
	s_cbranch_vccnz .LBB0_973
	v_mul_f32_e32 v29, 0x41800000, v30
	v_mul_f32_e32 v30, 0x41800000, v31
	v_cvt_pk_fp8_f32 v28, v29, v30
	v_mul_f32_e32 v30, 0x41800000, v32
	v_mul_f32_e32 v32, 0x41800000, v40
	v_mul_f32_e32 v24, 0x41800000, v24
	v_cvt_pk_fp8_f32 v29, v32, v24
	v_mul_f32_e32 v31, 0x41800000, v33
	v_mul_f32_e32 v24, 0x41800000, v41
	v_mul_f32_e32 v25, 0x41800000, v25
	v_cvt_pk_fp8_f32 v28, v30, v31 op_sel:[0,0,1]
	v_cvt_pk_fp8_f32 v29, v24, v25 op_sel:[0,0,1]
	global_store_dwordx2 v[22:23], v[28:29], off

.LBB0_993:
	v_mul_f32_e32 v8, 0x41800000, v8
	v_mul_f32_e32 v10, 0x41800000, v2
	v_cvt_pk_fp8_f32 v2, v8, v10
	v_mul_f32_e32 v8, 0x41800000, v9
	v_mul_f32_e32 v9, 0x41800000, v3
	v_mul_f32_e32 v10, 0x41800000, v12
	v_mul_f32_e32 v4, 0x41800000, v4
	v_cvt_pk_fp8_f32 v3, v10, v4
	v_mul_f32_e32 v4, 0x41800000, v13
	v_mul_f32_e32 v5, 0x41800000, v5
	v_cvt_pk_fp8_f32 v2, v8, v9 op_sel:[0,0,1]
	v_cvt_pk_fp8_f32 v3, v4, v5 op_sel:[0,0,1]
	global_store_dwordx2 v[6:7], v[2:3], off offset:128
	s_and_b64 vcc, exec, s[2:3]
	s_mov_b64 s[0:1], -1
	s_cbranch_vccnz .LBB0_875

.LBB0_1072:
	v_lshl_add_u32 v8, s28, 8, v1
	v_lshl_or_b32 v2, s72, 8, v223
	v_ashrrev_i32_e32 v9, 31, v8
	v_ashrrev_i32_e32 v3, 31, v2
	v_lshlrev_b64 v[4:5], 12, v[8:9]
	v_lshl_add_u64 v[4:5], s[4:5], 0, v[4:5]
	v_lshlrev_b64 v[10:11], 1, v[2:3]
	v_lshl_add_u64 v[2:3], v[4:5], 0, v[10:11]
	v_pk_mul_f32 v[4:5], v[190:191], s[10:11] op_sel_hi:[1,0]
	v_pk_mul_f32 v[6:7], v[192:193], s[10:11] op_sel_hi:[1,0]
	v_cvt_pk_bf16_f32 v4, v4, v5
	v_pk_mul_f32 v[12:13], v[188:189], s[10:11] op_sel_hi:[1,0]
	v_cvt_pk_bf16_f32 v5, v6, v7
	v_pk_mul_f32 v[14:15], v[186:187], s[10:11] op_sel_hi:[1,0]
	v_pk_mul_f32 v[16:17], v[170:171], s[10:11] op_sel_hi:[1,0]
	v_cvt_pk_bf16_f32 v6, v14, v15
	v_cvt_pk_bf16_f32 v7, v12, v13
	global_store_dwordx4 v[2:3], v[4:7], off
	v_pk_mul_f32 v[12:13], v[176:177], s[10:11] op_sel_hi:[1,0]
	v_pk_mul_f32 v[14:15], v[174:175], s[10:11] op_sel_hi:[1,0]
	v_pk_mul_f32 v[4:5], v[182:183], s[10:11] op_sel_hi:[1,0]
	v_pk_mul_f32 v[6:7], v[184:185], s[10:11] op_sel_hi:[1,0]
	v_cvt_pk_bf16_f32 v4, v4, v5
	s_nop 0
	v_cvt_pk_bf16_f32 v5, v6, v7
	v_cvt_pk_bf16_f32 v6, v14, v15
	v_cvt_pk_bf16_f32 v7, v12, v13
	global_store_dwordx4 v[2:3], v[4:7], off offset:256
	v_pk_mul_f32 v[14:15], v[172:173], s[10:11] op_sel_hi:[1,0]
	s_nop 0
	v_or_b32_e32 v4, 16, v8
	v_ashrrev_i32_e32 v5, 31, v4
	v_lshlrev_b64 v[4:5], 12, v[4:5]
	v_lshl_add_u64 v[4:5], s[4:5], 0, v[4:5]
	v_lshl_add_u64 v[12:13], v[4:5], 0, v[10:11]
	v_pk_mul_f32 v[4:5], v[178:179], s[10:11] op_sel_hi:[1,0]
	v_pk_mul_f32 v[6:7], v[180:181], s[10:11] op_sel_hi:[1,0]
	v_cvt_pk_bf16_f32 v4, v4, v5
	s_nop 0
	v_cvt_pk_bf16_f32 v5, v6, v7
	v_cvt_pk_bf16_f32 v6, v16, v17
	v_cvt_pk_bf16_f32 v7, v14, v15
	global_store_dwordx4 v[12:13], v[4:7], off
	v_pk_mul_f32 v[14:15], v[160:161], s[10:11] op_sel_hi:[1,0]
	v_pk_mul_f32 v[16:17], v[158:159], s[10:11] op_sel_hi:[1,0]
	v_pk_mul_f32 v[4:5], v[166:167], s[10:11] op_sel_hi:[1,0]
	v_pk_mul_f32 v[6:7], v[168:169], s[10:11] op_sel_hi:[1,0]
	v_cvt_pk_bf16_f32 v4, v4, v5
	s_nop 0
	v_cvt_pk_bf16_f32 v5, v6, v7
	v_cvt_pk_bf16_f32 v6, v16, v17
	v_cvt_pk_bf16_f32 v7, v14, v15
	global_store_dwordx4 v[12:13], v[4:7], off offset:256
	v_pk_mul_f32 v[14:15], v[156:157], s[10:11] op_sel_hi:[1,0]
	v_pk_mul_f32 v[16:17], v[154:155], s[10:11] op_sel_hi:[1,0]
	v_or_b32_e32 v4, 32, v8
	v_ashrrev_i32_e32 v5, 31, v4
	v_lshlrev_b64 v[4:5], 12, v[4:5]
	v_lshl_add_u64 v[4:5], s[4:5], 0, v[4:5]
	v_lshl_add_u64 v[12:13], v[4:5], 0, v[10:11]
	v_pk_mul_f32 v[4:5], v[162:163], s[10:11] op_sel_hi:[1,0]
	v_pk_mul_f32 v[6:7], v[164:165], s[10:11] op_sel_hi:[1,0]
	v_cvt_pk_bf16_f32 v4, v4, v5
	s_nop 0
	v_cvt_pk_bf16_f32 v5, v6, v7
	v_cvt_pk_bf16_f32 v6, v16, v17
	v_cvt_pk_bf16_f32 v7, v14, v15
	global_store_dwordx4 v[12:13], v[4:7], off
	v_pk_mul_f32 v[14:15], v[144:145], s[10:11] op_sel_hi:[1,0]
	v_pk_mul_f32 v[16:17], v[142:143], s[10:11] op_sel_hi:[1,0]
	v_pk_mul_f32 v[4:5], v[150:151], s[10:11] op_sel_hi:[1,0]
	v_pk_mul_f32 v[6:7], v[152:153], s[10:11] op_sel_hi:[1,0]
	v_cvt_pk_bf16_f32 v4, v4, v5
	s_nop 0
	v_cvt_pk_bf16_f32 v5, v6, v7
	v_cvt_pk_bf16_f32 v6, v16, v17
	v_cvt_pk_bf16_f32 v7, v14, v15
	global_store_dwordx4 v[12:13], v[4:7], off offset:256
	v_pk_mul_f32 v[12:13], v[138:139], s[10:11] op_sel_hi:[1,0]
	s_nop 0
	v_or_b32_e32 v4, 48, v8
	v_ashrrev_i32_e32 v5, 31, v4
	v_lshlrev_b64 v[4:5], 12, v[4:5]
	v_lshl_add_u64 v[4:5], s[4:5], 0, v[4:5]
	v_lshl_add_u64 v[8:9], v[4:5], 0, v[10:11]
	v_pk_mul_f32 v[6:7], v[148:149], s[10:11] op_sel_hi:[1,0]
	v_pk_mul_f32 v[4:5], v[146:147], s[10:11] op_sel_hi:[1,0]
	v_pk_mul_f32 v[10:11], v[140:141], s[10:11] op_sel_hi:[1,0]
	v_cvt_pk_bf16_f32 v4, v4, v5
	v_cvt_pk_bf16_f32 v5, v6, v7
	v_cvt_pk_bf16_f32 v6, v12, v13
	v_pk_mul_f32 v[12:13], v[130:131], s[10:11] op_sel_hi:[1,0]
	v_cvt_pk_bf16_f32 v7, v10, v11
	global_store_dwordx4 v[8:9], v[4:7], off
	v_pk_mul_f32 v[10:11], v[132:133], s[10:11] op_sel_hi:[1,0]
	s_nop 0
	v_pk_mul_f32 v[6:7], v[136:137], s[10:11] op_sel_hi:[1,0]
	v_pk_mul_f32 v[4:5], v[134:135], s[10:11] op_sel_hi:[1,0]
	s_nop 0
	v_cvt_pk_bf16_f32 v4, v4, v5
	v_cvt_pk_bf16_f32 v5, v6, v7
	v_cvt_pk_bf16_f32 v6, v12, v13
	v_cvt_pk_bf16_f32 v7, v10, v11
	global_store_dwordx4 v[8:9], v[4:7], off offset:256
	v_pk_mul_f32 v[10:11], v[124:125], s[10:11] op_sel_hi:[1,0]
	v_pk_mul_f32 v[12:13], v[122:123], s[10:11] op_sel_hi:[1,0]
	v_pk_mul_f32 v[6:7], v[128:129], s[10:11] op_sel_hi:[1,0]
	v_pk_mul_f32 v[4:5], v[126:127], s[10:11] op_sel_hi:[1,0]
	v_lshl_add_u64 v[8:9], v[2:3], 0, s[12:13]
	v_cvt_pk_bf16_f32 v4, v4, v5
	v_cvt_pk_bf16_f32 v5, v6, v7
	v_cvt_pk_bf16_f32 v6, v12, v13
	v_cvt_pk_bf16_f32 v7, v10, v11
	v_add_co_u32_e32 v10, vcc, s67, v2
	v_pk_mul_f32 v[12:13], v[110:111], s[10:11] op_sel_hi:[1,0]
	s_nop 0
	v_addc_co_u32_e32 v11, vcc, 0, v3, vcc
	global_store_dwordx4 v[10:11], v[4:7], off
	v_pk_mul_f32 v[10:11], v[112:113], s[10:11] op_sel_hi:[1,0]
	s_nop 0
	v_pk_mul_f32 v[6:7], v[120:121], s[10:11] op_sel_hi:[1,0]
	v_pk_mul_f32 v[4:5], v[118:119], s[10:11] op_sel_hi:[1,0]
	s_nop 0
	v_cvt_pk_bf16_f32 v4, v4, v5
	v_cvt_pk_bf16_f32 v5, v6, v7
	v_cvt_pk_bf16_f32 v6, v12, v13
	v_cvt_pk_bf16_f32 v7, v10, v11
	global_store_dwordx4 v[8:9], v[4:7], off offset:256
	v_pk_mul_f32 v[10:11], v[108:109], s[10:11] op_sel_hi:[1,0]
	v_pk_mul_f32 v[12:13], v[106:107], s[10:11] op_sel_hi:[1,0]
	v_pk_mul_f32 v[6:7], v[116:117], s[10:11] op_sel_hi:[1,0]
	v_pk_mul_f32 v[4:5], v[114:115], s[10:11] op_sel_hi:[1,0]
	v_lshl_add_u64 v[8:9], v[2:3], 0, s[14:15]
	v_cvt_pk_bf16_f32 v4, v4, v5
	v_cvt_pk_bf16_f32 v5, v6, v7
	v_cvt_pk_bf16_f32 v6, v12, v13
	v_cvt_pk_bf16_f32 v7, v10, v11
	v_add_co_u32_e32 v10, vcc, s68, v2
	v_pk_mul_f32 v[12:13], v[94:95], s[10:11] op_sel_hi:[1,0]
	s_nop 0
	v_addc_co_u32_e32 v11, vcc, 0, v3, vcc
	global_store_dwordx4 v[10:11], v[4:7], off
	v_pk_mul_f32 v[10:11], v[96:97], s[10:11] op_sel_hi:[1,0]
	s_nop 0
	v_pk_mul_f32 v[6:7], v[104:105], s[10:11] op_sel_hi:[1,0]
	v_pk_mul_f32 v[4:5], v[102:103], s[10:11] op_sel_hi:[1,0]
	s_nop 0
	v_cvt_pk_bf16_f32 v4, v4, v5
	v_cvt_pk_bf16_f32 v5, v6, v7
	v_cvt_pk_bf16_f32 v6, v12, v13
	v_cvt_pk_bf16_f32 v7, v10, v11
	global_store_dwordx4 v[8:9], v[4:7], off offset:256
	v_pk_mul_f32 v[10:11], v[92:93], s[10:11] op_sel_hi:[1,0]
	v_pk_mul_f32 v[12:13], v[90:91], s[10:11] op_sel_hi:[1,0]
	v_pk_mul_f32 v[6:7], v[100:101], s[10:11] op_sel_hi:[1,0]
	v_pk_mul_f32 v[4:5], v[98:99], s[10:11] op_sel_hi:[1,0]
	v_lshl_add_u64 v[8:9], v[2:3], 0, s[16:17]
	v_cvt_pk_bf16_f32 v4, v4, v5
	v_cvt_pk_bf16_f32 v5, v6, v7
	v_cvt_pk_bf16_f32 v6, v12, v13
	v_cvt_pk_bf16_f32 v7, v10, v11
	v_add_co_u32_e32 v10, vcc, s69, v2
	v_pk_mul_f32 v[12:13], v[78:79], s[10:11] op_sel_hi:[1,0]
	s_nop 0
	v_addc_co_u32_e32 v11, vcc, 0, v3, vcc
	global_store_dwordx4 v[10:11], v[4:7], off
	v_pk_mul_f32 v[10:11], v[80:81], s[10:11] op_sel_hi:[1,0]
	s_nop 0
	v_pk_mul_f32 v[4:5], v[86:87], s[10:11] op_sel_hi:[1,0]
	v_pk_mul_f32 v[6:7], v[88:89], s[10:11] op_sel_hi:[1,0]
	v_cvt_pk_bf16_f32 v4, v4, v5
	s_nop 0
	v_cvt_pk_bf16_f32 v5, v6, v7
	v_cvt_pk_bf16_f32 v6, v12, v13
	v_cvt_pk_bf16_f32 v7, v10, v11
	global_store_dwordx4 v[8:9], v[4:7], off offset:256
	v_lshl_add_u64 v[8:9], v[2:3], 0, s[18:19]
	v_add_co_u32_e32 v2, vcc, s70, v2
	v_pk_mul_f32 v[4:5], v[82:83], s[10:11] op_sel_hi:[1,0]
	v_pk_mul_f32 v[6:7], v[84:85], s[10:11] op_sel_hi:[1,0]
	v_cvt_pk_bf16_f32 v4, v4, v5
	v_addc_co_u32_e32 v3, vcc, 0, v3, vcc
	v_cvt_pk_bf16_f32 v5, v6, v7
	v_pk_mul_f32 v[10:11], v[76:77], s[10:11] op_sel_hi:[1,0]
	v_pk_mul_f32 v[12:13], v[74:75], s[10:11] op_sel_hi:[1,0]
	s_andn2_b64 vcc, exec, s[2:3]
	v_cvt_pk_bf16_f32 v6, v12, v13
	v_cvt_pk_bf16_f32 v7, v10, v11
	global_store_dwordx4 v[2:3], v[4:7], off
	v_pk_mul_f32 v[2:3], v[70:71], s[10:11] op_sel_hi:[1,0]
	s_mov_b64 s[2:3], -1
	v_pk_mul_f32 v[4:5], v[72:73], s[10:11] op_sel_hi:[1,0]
	v_pk_mul_f32 v[6:7], v[68:69], s[10:11] op_sel_hi:[1,0]
	v_pk_mul_f32 v[10:11], v[66:67], s[10:11] op_sel_hi:[1,0]
	v_cvt_pk_bf16_f32 v2, v2, v3
	v_cvt_pk_bf16_f32 v3, v4, v5
	s_nop 0
	v_cvt_pk_bf16_f32 v4, v10, v11
	v_cvt_pk_bf16_f32 v5, v6, v7
	global_store_dwordx4 v[8:9], v[2:5], off offset:256
	s_cbranch_vccnz .LBB0_1054
	s_andn2_b64 vcc, exec, s[0:1]
	s_cbranch_vccnz .LBB0_1053
	s_barrier
	s_branch .LBB0_1053

.LBB0_1513:
	s_andn2_b64 vcc, exec, s[4:5]
	s_cbranch_vccnz .LBB0_1494
	s_mul_hi_i32 s2, s14, 0x6e5478ad
	s_lshr_b32 s4, s2, 31
	s_ashr_i32 s2, s2, 8
	s_add_i32 s2, s2, s4
	s_mul_i32 s5, s2, 0xffffb5c0
	s_lshl_b32 s4, s2, 6
	s_add_i32 s6, s10, s5
	v_or_b32_e32 v2, s4, v28
	s_ashr_i32 s7, s6, 31
	v_lshl_add_u64 v[42:43], s[6:7], 2, v[22:23]
	v_or_b32_e32 v27, 2, v2
	v_mad_i64_i32 v[46:47], s[84:85], v27, s83, v[42:43]
	v_or_b32_e32 v27, 4, v2
	v_mad_i64_i32 v[48:49], s[84:85], v27, s83, v[42:43]
	v_or_b32_e32 v27, 6, v2
	v_mad_i64_i32 v[50:51], s[84:85], v27, s83, v[42:43]
	v_or_b32_e32 v27, 8, v2
	v_mad_i64_i32 v[52:53], s[84:85], v27, s83, v[42:43]
	v_or_b32_e32 v27, 10, v2
	v_mad_i64_i32 v[54:55], s[84:85], v27, s83, v[42:43]
	v_or_b32_e32 v27, 12, v2
	v_mad_i64_i32 v[44:45], s[84:85], v2, s83, v[42:43]
	v_mad_i64_i32 v[56:57], s[84:85], v27, s83, v[42:43]
	v_or_b32_e32 v27, 14, v2
	v_mad_i64_i32 v[58:59], s[84:85], v27, s83, v[42:43]
	global_load_dword v27, v[44:45], off nt
	global_load_dword v60, v[46:47], off nt
	global_load_dword v61, v[48:49], off nt
	global_load_dword v62, v[50:51], off nt
	global_load_dword v63, v[52:53], off nt
	global_load_dword v64, v[54:55], off nt
	global_load_dword v65, v[56:57], off nt
	global_load_dword v66, v[58:59], off nt
	v_or_b32_e32 v44, 16, v2
	v_mad_i64_i32 v[44:45], s[84:85], v44, s83, v[42:43]
	v_or_b32_e32 v46, 18, v2
	v_or_b32_e32 v48, 20, v2
	v_or_b32_e32 v50, 22, v2
	v_or_b32_e32 v52, 24, v2
	v_or_b32_e32 v54, 26, v2
	v_or_b32_e32 v56, 28, v2
	v_or_b32_e32 v58, 30, v2
	v_mad_i64_i32 v[46:47], s[84:85], v46, s83, v[42:43]
	v_mad_i64_i32 v[48:49], s[84:85], v48, s83, v[42:43]
	v_mad_i64_i32 v[50:51], s[84:85], v50, s83, v[42:43]
	v_mad_i64_i32 v[52:53], s[84:85], v52, s83, v[42:43]
	v_mad_i64_i32 v[54:55], s[84:85], v54, s83, v[42:43]
	v_mad_i64_i32 v[56:57], s[84:85], v56, s83, v[42:43]
	v_mad_i64_i32 v[58:59], s[84:85], v58, s83, v[42:43]
	global_load_dword v67, v[44:45], off nt
	global_load_dword v68, v[46:47], off nt
	global_load_dword v69, v[48:49], off nt
	global_load_dword v70, v[50:51], off nt
	global_load_dword v71, v[52:53], off nt
	global_load_dword v72, v[54:55], off nt
	global_load_dword v73, v[56:57], off nt
	global_load_dword v74, v[58:59], off nt
	v_or_b32_e32 v44, 32, v2
	v_or_b32_e32 v46, 34, v2
	v_or_b32_e32 v48, 36, v2
	v_or_b32_e32 v50, 38, v2
	v_or_b32_e32 v56, 44, v2
	v_mad_i64_i32 v[44:45], s[84:85], v44, s83, v[42:43]
	v_mad_i64_i32 v[46:47], s[84:85], v46, s83, v[42:43]
	v_mad_i64_i32 v[48:49], s[84:85], v48, s83, v[42:43]
	v_mad_i64_i32 v[50:51], s[84:85], v50, s83, v[42:43]
	v_or_b32_e32 v52, 40, v2
	v_or_b32_e32 v54, 42, v2
	v_mad_i64_i32 v[56:57], s[84:85], v56, s83, v[42:43]
	v_or_b32_e32 v58, 46, v2
	v_mad_i64_i32 v[52:53], s[84:85], v52, s83, v[42:43]
	v_mad_i64_i32 v[54:55], s[84:85], v54, s83, v[42:43]
	v_mad_i64_i32 v[58:59], s[84:85], v58, s83, v[42:43]
	global_load_dword v75, v[44:45], off nt
	global_load_dword v76, v[46:47], off nt
	global_load_dword v77, v[48:49], off nt
	global_load_dword v78, v[50:51], off nt
	global_load_dword v79, v[52:53], off nt
	global_load_dword v80, v[54:55], off nt
	s_nop 0
	global_load_dword v56, v[56:57], off nt
	s_nop 0
	global_load_dword v57, v[58:59], off nt
	v_or_b32_e32 v44, 48, v2
	v_or_b32_e32 v46, 50, v2
	v_or_b32_e32 v48, 52, v2
	v_or_b32_e32 v50, 54, v2
	v_mad_i64_i32 v[44:45], s[84:85], v44, s83, v[42:43]
	v_mad_i64_i32 v[46:47], s[84:85], v46, s83, v[42:43]
	v_mad_i64_i32 v[48:49], s[84:85], v48, s83, v[42:43]
	v_mad_i64_i32 v[50:51], s[84:85], v50, s83, v[42:43]
	v_or_b32_e32 v52, 56, v2
	v_or_b32_e32 v54, 58, v2
	v_mad_i64_i32 v[52:53], s[84:85], v52, s83, v[42:43]
	v_mad_i64_i32 v[54:55], s[84:85], v54, s83, v[42:43]
	global_load_dword v58, v[44:45], off nt
	s_nop 0
	global_load_dword v46, v[46:47], off nt
	s_nop 0
	global_load_dword v47, v[48:49], off nt
	s_nop 0
	global_load_dword v48, v[50:51], off nt
	global_load_dword v49, v[52:53], off nt
	s_nop 0
	global_load_dword v50, v[54:55], off nt
	v_or_b32_e32 v44, 60, v2
	v_or_b32_e32 v2, 62, v2
	v_mad_i64_i32 v[44:45], s[84:85], v44, s83, v[42:43]
	v_mad_i64_i32 v[42:43], s[84:85], v2, s83, v[42:43]
	global_load_dword v2, v[44:45], off nt
	s_nop 0
	global_load_dword v42, v[42:43], off nt
	s_waitcnt vmcnt(31)
	v_mul_f32_e32 v27, 0x42800000, v27
	s_waitcnt vmcnt(30)
	v_mul_f32_e32 v43, 0x42800000, v60
	ds_write2_b32 v29, v27, v43 offset1:66
	s_waitcnt vmcnt(29)
	v_mul_f32_e32 v27, 0x42800000, v61
	s_waitcnt vmcnt(28)
	v_mul_f32_e32 v43, 0x42800000, v62
	ds_write2_b32 v29, v27, v43 offset0:132 offset1:198
	s_waitcnt vmcnt(27)
	v_mul_f32_e32 v27, 0x42800000, v63
	s_waitcnt vmcnt(26)
	v_mul_f32_e32 v43, 0x42800000, v64
	ds_write2_b32 v35, v27, v43 offset0:8 offset1:74
	s_waitcnt vmcnt(25)
	v_mul_f32_e32 v27, 0x42800000, v65
	s_waitcnt vmcnt(24)
	v_mul_f32_e32 v43, 0x42800000, v66
	ds_write2_b32 v35, v27, v43 offset0:140 offset1:206
	s_lshl_b32 s2, s2, 1
	s_sub_i32 s2, s14, s2
	v_mov_b32_e32 v51, 0
	s_and_b32 s5, s18, 4
	s_bfe_u32 s2, s2, 0x20001
	s_or_b32 s2, s5, s2
	s_lshl_b32 s2, s2, 5
	s_and_b32 s5, s6, 0xffffff00
	s_or_b32 s2, s2, s5
	s_waitcnt vmcnt(23)
	v_mul_f32_e32 v27, 0x42800000, v67
	s_waitcnt vmcnt(22)
	v_mul_f32_e32 v43, 0x42800000, v68
	ds_write2_b32 v36, v27, v43 offset0:16 offset1:82
	s_waitcnt vmcnt(21)
	v_mul_f32_e32 v27, 0x42800000, v69
	s_waitcnt vmcnt(20)
	v_mul_f32_e32 v43, 0x42800000, v70
	ds_write2_b32 v36, v27, v43 offset0:148 offset1:214
	s_waitcnt vmcnt(19)
	v_mul_f32_e32 v27, 0x42800000, v71
	s_waitcnt vmcnt(18)
	v_mul_f32_e32 v43, 0x42800000, v72
	ds_write2_b32 v37, v27, v43 offset0:24 offset1:90
	s_waitcnt vmcnt(17)
	v_mul_f32_e32 v27, 0x42800000, v73
	s_waitcnt vmcnt(16)
	v_mul_f32_e32 v43, 0x42800000, v74
	ds_write2_b32 v37, v27, v43 offset0:156 offset1:222
	v_or_b32_e32 v62, s2, v30
	s_ashr_i32 s5, s4, 31
	v_ashrrev_i32_e32 v63, 31, v62
	v_lshl_add_u64 v[60:61], v[24:25], 0, s[4:5]
	v_lshlrev_b64 v[62:63], 11, v[62:63]
	s_waitcnt vmcnt(15)
	v_mul_f32_e32 v27, 0x42800000, v75
	s_waitcnt vmcnt(14)
	v_mul_f32_e32 v43, 0x42800000, v76
	ds_write2_b32 v38, v27, v43 offset0:32 offset1:98
	s_waitcnt vmcnt(13)
	v_mul_f32_e32 v27, 0x42800000, v77
	s_waitcnt vmcnt(12)
	v_mul_f32_e32 v43, 0x42800000, v78
	ds_write2_b32 v38, v27, v43 offset0:164 offset1:230
	s_waitcnt vmcnt(11)
	v_mul_f32_e32 v27, 0x42800000, v79
	s_waitcnt vmcnt(10)
	v_mul_f32_e32 v43, 0x42800000, v80
	ds_write2_b32 v39, v27, v43 offset0:40 offset1:106
	s_waitcnt vmcnt(9)
	v_mul_f32_e32 v27, 0x42800000, v56
	s_waitcnt vmcnt(8)
	v_mul_f32_e32 v43, 0x42800000, v57
	ds_write2_b32 v39, v27, v43 offset0:172 offset1:238
	s_waitcnt vmcnt(7)
	v_mul_f32_e32 v27, 0x42800000, v58
	s_waitcnt vmcnt(6)
	v_mul_f32_e32 v43, 0x42800000, v46
	ds_write2_b32 v40, v27, v43 offset0:48 offset1:114
	s_waitcnt vmcnt(5)
	v_mul_f32_e32 v27, 0x42800000, v47
	s_waitcnt vmcnt(4)
	v_mul_f32_e32 v43, 0x42800000, v48
	ds_write2_b32 v40, v27, v43 offset0:180 offset1:246
	s_waitcnt vmcnt(3)
	v_mul_f32_e32 v27, 0x42800000, v49
	s_waitcnt vmcnt(2)
	v_mul_f32_e32 v43, 0x42800000, v50
	ds_write2_b32 v41, v27, v43 offset0:56 offset1:122
	s_waitcnt vmcnt(1)
	v_mul_f32_e32 v2, 0x42800000, v2
	s_waitcnt vmcnt(0)
	v_mul_f32_e32 v27, 0x42800000, v42
	ds_write2_b32 v41, v2, v27 offset0:188 offset1:254
	s_waitcnt lgkmcnt(0)
	ds_read2_b32 v[42:43], v31 offset0:33 offset1:41
	ds_read2_b32 v[44:45], v31 offset0:66 offset1:74
	ds_read2_b32 v[46:47], v31 offset1:8
	ds_read2_b32 v[48:49], v31 offset0:99 offset1:107
	ds_read2_b32 v[52:53], v31 offset0:132 offset1:140
	ds_read2_b32 v[54:55], v31 offset0:165 offset1:173
	ds_read2_b32 v[56:57], v31 offset0:198 offset1:206
	ds_read2_b32 v[58:59], v31 offset0:231 offset1:239
	s_waitcnt lgkmcnt(5)
	v_cvt_pk_fp8_f32 v50, v46, v42
	s_waitcnt lgkmcnt(2)
	v_cvt_pk_fp8_f32 v51, v52, v54
	v_cvt_pk_fp8_f32 v42, v47, v43
	v_cvt_pk_fp8_f32 v50, v44, v48 op_sel:[0,0,1]
	s_waitcnt lgkmcnt(0)
	v_cvt_pk_fp8_f32 v51, v56, v58 op_sel:[0,0,1]
	v_cvt_pk_fp8_f32 v43, v53, v55
	v_lshl_add_u64 v[46:47], v[60:61], 0, v[62:63]
	v_cvt_pk_fp8_f32 v42, v45, v49 op_sel:[0,0,1]
	global_store_dwordx2 v[46:47], v[50:51], off
	v_cvt_pk_fp8_f32 v43, v57, v59 op_sel:[0,0,1]
	ds_read2_b32 v[46:47], v31 offset0:49 offset1:57
	ds_read2_b32 v[48:49], v31 offset0:82 offset1:90
	ds_read2_b32 v[50:51], v31 offset0:16 offset1:24
	ds_read2_b32 v[52:53], v31 offset0:115 offset1:123
	ds_read2_b32 v[56:57], v31 offset0:148 offset1:156
	ds_read2_b32 v[58:59], v31 offset0:181 offset1:189
	v_or_b32_e32 v44, s2, v32
	ds_read2_b32 v[62:63], v31 offset0:214 offset1:222
	ds_read2_b32 v[64:65], v31 offset0:247 offset1:255
	v_ashrrev_i32_e32 v45, 31, v44
	s_waitcnt lgkmcnt(5)
	v_cvt_pk_fp8_f32 v54, v50, v46
	s_waitcnt lgkmcnt(2)
	v_cvt_pk_fp8_f32 v55, v56, v58
	v_lshlrev_b64 v[44:45], 11, v[44:45]
	v_lshl_add_u64 v[44:45], v[60:61], 0, v[44:45]
	global_store_dwordx2 v[44:45], v[42:43], off
	v_cvt_pk_fp8_f32 v54, v48, v52 op_sel:[0,0,1]
	s_waitcnt lgkmcnt(0)
	v_cvt_pk_fp8_f32 v55, v62, v64 op_sel:[0,0,1]
	v_or_b32_e32 v42, s2, v33
	v_cvt_pk_fp8_f32 v44, v51, v47
	v_cvt_pk_fp8_f32 v45, v57, v59
	v_ashrrev_i32_e32 v43, 31, v42
	v_lshlrev_b64 v[42:43], 11, v[42:43]
	v_lshl_add_u64 v[42:43], v[60:61], 0, v[42:43]
	global_store_dwordx2 v[42:43], v[54:55], off
	v_cvt_pk_fp8_f32 v44, v49, v53 op_sel:[0,0,1]
	v_cvt_pk_fp8_f32 v45, v63, v65 op_sel:[0,0,1]
	v_or_b32_e32 v42, s2, v34
	v_ashrrev_i32_e32 v43, 31, v42
	v_lshlrev_b64 v[42:43], 11, v[42:43]
	v_lshl_add_u64 v[42:43], v[60:61], 0, v[42:43]
	global_store_dwordx2 v[42:43], v[44:45], off
	s_waitcnt lgkmcnt(0)
	s_branch .LBB0_1494

.LBB0_1848:
	s_waitcnt vmcnt(0)
	v_lshlrev_b32_e32 v58, 16, v46
	v_and_b32_e32 v46, 0xffff0000, v46
	v_mov_b32_e32 v146, v171
	v_cvt_pk_fp8_f32 v146, v58, v46
	v_lshlrev_b32_e32 v58, 16, v48
	v_and_b32_e32 v48, 0xffff0000, v48
	v_mov_b32_e32 v147, v171
	v_cvt_pk_fp8_f32 v147, v58, v48
	v_lshlrev_b32_e32 v46, 16, v47
	v_and_b32_e32 v47, 0xffff0000, v47
	v_cvt_pk_fp8_f32 v146, v46, v47 op_sel:[0,0,1]
	v_lshlrev_b32_e32 v46, 16, v49
	v_and_b32_e32 v47, 0xffff0000, v49
	v_cvt_pk_fp8_f32 v147, v46, v47 op_sel:[0,0,1]
	v_lshlrev_b32_e32 v46, 16, v42
	v_and_b32_e32 v42, 0xffff0000, v42
	v_mov_b32_e32 v148, v171
	v_cvt_pk_fp8_f32 v148, v46, v42
	v_lshlrev_b32_e32 v46, 16, v44
	v_and_b32_e32 v44, 0xffff0000, v44
	v_mov_b32_e32 v149, v171
	v_cvt_pk_fp8_f32 v149, v46, v44
	v_lshlrev_b32_e32 v42, 16, v43
	v_and_b32_e32 v43, 0xffff0000, v43
	v_cvt_pk_fp8_f32 v148, v42, v43 op_sel:[0,0,1]
	v_lshlrev_b32_e32 v42, 16, v45
	v_and_b32_e32 v43, 0xffff0000, v45
	v_cvt_pk_fp8_f32 v149, v42, v43 op_sel:[0,0,1]
	v_lshlrev_b32_e32 v42, 16, v38
	v_and_b32_e32 v38, 0xffff0000, v38
	v_mov_b32_e32 v150, v171
	v_cvt_pk_fp8_f32 v150, v42, v38
	v_lshlrev_b32_e32 v42, 16, v40
	v_and_b32_e32 v40, 0xffff0000, v40
	v_mov_b32_e32 v151, v171
	v_cvt_pk_fp8_f32 v151, v42, v40
	v_lshlrev_b32_e32 v38, 16, v39
	v_and_b32_e32 v39, 0xffff0000, v39
	v_cvt_pk_fp8_f32 v150, v38, v39 op_sel:[0,0,1]
	v_lshlrev_b32_e32 v38, 16, v41
	v_and_b32_e32 v39, 0xffff0000, v41
	v_cvt_pk_fp8_f32 v151, v38, v39 op_sel:[0,0,1]
	v_lshlrev_b32_e32 v38, 16, v34
	v_and_b32_e32 v34, 0xffff0000, v34
	v_mov_b32_e32 v152, v171
	v_cvt_pk_fp8_f32 v152, v38, v34
	v_lshlrev_b32_e32 v38, 16, v36
	v_and_b32_e32 v36, 0xffff0000, v36
	v_mov_b32_e32 v153, v171
	v_cvt_pk_fp8_f32 v153, v38, v36
	v_lshlrev_b32_e32 v34, 16, v35
	v_and_b32_e32 v35, 0xffff0000, v35
	v_cvt_pk_fp8_f32 v152, v34, v35 op_sel:[0,0,1]
	v_lshlrev_b32_e32 v34, 16, v37
	v_and_b32_e32 v35, 0xffff0000, v37
	v_cvt_pk_fp8_f32 v153, v34, v35 op_sel:[0,0,1]
	v_lshlrev_b32_e32 v34, 16, v30
	v_and_b32_e32 v30, 0xffff0000, v30
	v_mov_b32_e32 v154, v171
	v_cvt_pk_fp8_f32 v154, v34, v30
	v_lshlrev_b32_e32 v34, 16, v32
	v_and_b32_e32 v32, 0xffff0000, v32
	v_mov_b32_e32 v155, v171
	v_cvt_pk_fp8_f32 v155, v34, v32
	v_lshlrev_b32_e32 v30, 16, v31
	v_and_b32_e32 v31, 0xffff0000, v31
	v_cvt_pk_fp8_f32 v154, v30, v31 op_sel:[0,0,1]
	v_lshlrev_b32_e32 v30, 16, v33
	v_and_b32_e32 v31, 0xffff0000, v33
	v_cvt_pk_fp8_f32 v155, v30, v31 op_sel:[0,0,1]
	v_lshlrev_b32_e32 v30, 16, v26
	v_and_b32_e32 v26, 0xffff0000, v26
	v_mov_b32_e32 v156, v171
	v_cvt_pk_fp8_f32 v156, v30, v26
	v_lshlrev_b32_e32 v30, 16, v28
	v_and_b32_e32 v28, 0xffff0000, v28
	v_mov_b32_e32 v157, v171
	v_cvt_pk_fp8_f32 v157, v30, v28
	v_lshlrev_b32_e32 v26, 16, v27
	v_and_b32_e32 v27, 0xffff0000, v27
	v_cvt_pk_fp8_f32 v156, v26, v27 op_sel:[0,0,1]
	v_lshlrev_b32_e32 v26, 16, v29
	v_and_b32_e32 v27, 0xffff0000, v29
	v_cvt_pk_fp8_f32 v157, v26, v27 op_sel:[0,0,1]
	v_lshlrev_b32_e32 v26, 16, v22
	v_and_b32_e32 v22, 0xffff0000, v22
	v_mov_b32_e32 v158, v171
	v_cvt_pk_fp8_f32 v158, v26, v22
	v_lshlrev_b32_e32 v26, 16, v24
	v_and_b32_e32 v24, 0xffff0000, v24
	v_mov_b32_e32 v159, v171
	v_cvt_pk_fp8_f32 v159, v26, v24
	v_lshlrev_b32_e32 v22, 16, v23
	v_and_b32_e32 v23, 0xffff0000, v23
	v_cvt_pk_fp8_f32 v158, v22, v23 op_sel:[0,0,1]
	v_lshlrev_b32_e32 v22, 16, v25
	v_and_b32_e32 v23, 0xffff0000, v25
	v_cvt_pk_fp8_f32 v159, v22, v23 op_sel:[0,0,1]
	v_lshlrev_b32_e32 v22, 16, v18
	v_and_b32_e32 v18, 0xffff0000, v18
	v_mov_b32_e32 v160, v171
	v_cvt_pk_fp8_f32 v160, v22, v18
	v_lshlrev_b32_e32 v22, 16, v20
	v_and_b32_e32 v20, 0xffff0000, v20
	v_mov_b32_e32 v161, v171
	v_cvt_pk_fp8_f32 v161, v22, v20
	v_lshlrev_b32_e32 v18, 16, v19
	v_and_b32_e32 v19, 0xffff0000, v19
	v_cvt_pk_fp8_f32 v160, v18, v19 op_sel:[0,0,1]
	v_lshlrev_b32_e32 v18, 16, v21
	v_and_b32_e32 v19, 0xffff0000, v21
	v_cvt_pk_fp8_f32 v161, v18, v19 op_sel:[0,0,1]
	v_lshlrev_b32_e32 v18, 16, v14
	v_and_b32_e32 v14, 0xffff0000, v14
	v_mov_b32_e32 v162, v171
	v_cvt_pk_fp8_f32 v162, v18, v14
	v_lshlrev_b32_e32 v18, 16, v16
	v_and_b32_e32 v16, 0xffff0000, v16
	v_mov_b32_e32 v163, v171
	v_cvt_pk_fp8_f32 v163, v18, v16
	v_lshlrev_b32_e32 v14, 16, v15
	v_and_b32_e32 v15, 0xffff0000, v15
	v_cvt_pk_fp8_f32 v162, v14, v15 op_sel:[0,0,1]
	v_lshlrev_b32_e32 v14, 16, v17
	v_and_b32_e32 v15, 0xffff0000, v17
	v_cvt_pk_fp8_f32 v163, v14, v15 op_sel:[0,0,1]
	v_lshlrev_b32_e32 v14, 16, v10
	v_and_b32_e32 v10, 0xffff0000, v10
	v_mov_b32_e32 v164, v171
	v_cvt_pk_fp8_f32 v164, v14, v10
	v_lshlrev_b32_e32 v14, 16, v12
	v_and_b32_e32 v12, 0xffff0000, v12
	v_mov_b32_e32 v165, v171
	v_cvt_pk_fp8_f32 v165, v14, v12
	v_lshlrev_b32_e32 v10, 16, v11
	v_and_b32_e32 v11, 0xffff0000, v11
	v_cvt_pk_fp8_f32 v164, v10, v11 op_sel:[0,0,1]
	v_lshlrev_b32_e32 v10, 16, v13
	v_and_b32_e32 v11, 0xffff0000, v13
	v_cvt_pk_fp8_f32 v165, v10, v11 op_sel:[0,0,1]
	v_lshlrev_b32_e32 v10, 16, v6
	v_and_b32_e32 v6, 0xffff0000, v6
	v_mov_b32_e32 v166, v171
	v_cvt_pk_fp8_f32 v166, v10, v6
	v_lshlrev_b32_e32 v10, 16, v8
	v_and_b32_e32 v8, 0xffff0000, v8
	v_mov_b32_e32 v167, v171
	v_cvt_pk_fp8_f32 v167, v10, v8
	v_lshlrev_b32_e32 v6, 16, v7
	v_and_b32_e32 v7, 0xffff0000, v7
	v_cvt_pk_fp8_f32 v166, v6, v7 op_sel:[0,0,1]
	v_lshlrev_b32_e32 v6, 16, v9
	v_and_b32_e32 v7, 0xffff0000, v9
	v_cvt_pk_fp8_f32 v167, v6, v7 op_sel:[0,0,1]
	v_lshlrev_b32_e32 v6, 16, v2
	v_and_b32_e32 v2, 0xffff0000, v2
	v_mov_b32_e32 v168, v171
	v_cvt_pk_fp8_f32 v168, v6, v2
	v_lshlrev_b32_e32 v6, 16, v4
	v_and_b32_e32 v4, 0xffff0000, v4
	v_mov_b32_e32 v169, v171
	v_cvt_pk_fp8_f32 v169, v6, v4
	v_lshlrev_b32_e32 v2, 16, v3
	v_and_b32_e32 v3, 0xffff0000, v3
	v_cvt_pk_fp8_f32 v168, v2, v3 op_sel:[0,0,1]
	v_lshlrev_b32_e32 v2, 16, v5
	v_and_b32_e32 v3, 0xffff0000, v5
	v_cvt_pk_fp8_f32 v169, v2, v3 op_sel:[0,0,1]
	v_lshrrev_b32_e32 v2, 1, v55
	v_and_b32_e32 v3, 8, v55
	v_and_or_b32 v2, v2, 3, v3
	v_bfe_u32 v58, v55, 5, 1
	v_bfe_u32 v59, v55, 1, 3
	v_lshlrev_b32_e32 v2, 7, v2
	v_lshlrev_b32_e32 v3, 3, v55
	v_and_b32_e32 v60, 1, v57
	v_lshl_or_b32 v2, v58, 9, v2
	v_and_b32_e32 v3, 8, v3
	v_bitop3_b32 v10, v57, v59, 1 bitop3:0x6c
	v_lshlrev_b32_e32 v42, 3, v52
	v_or_b32_e32 v57, 32, v52
	v_add3_u32 v61, v3, s67, v2
	s_waitcnt lgkmcnt(0)
	v_bitop3_b32 v11, v42, v56, s45 bitop3:0x6c
	v_lshl_add_u32 v43, v52, 7, s67
	v_or_b32_e32 v2, 16, v56
	v_lshl_add_u32 v44, v57, 7, s67
	s_barrier
	v_add_u32_e32 v209, v43, v11
	v_bitop3_b32 v12, v42, v2, s45 bitop3:0x6c
	v_add_u32_e32 v211, v44, v11
	v_add_u32_e32 v210, v43, v12
	ds_read_b128 v[2:5], v209 offset:32768
	ds_read_b128 v[6:9], v210 offset:32768
	v_add_u32_e32 v212, v44, v12
	ds_read_b128 v[34:37], v211 offset:32768
	ds_read_b128 v[38:41], v212 offset:32768
	v_lshl_add_u32 v206, v10, 4, v61
	v_bitop3_b32 v10, v60, v59, 2 bitop3:0x36
	v_lshl_add_u32 v205, v10, 4, v61
	s_waitcnt lgkmcnt(0)
	v_mfma_f32_32x32x64_f8f6f4 v[18:33], v[2:9], v[146:153], 0
	v_mfma_f32_32x32x64_f8f6f4 v[2:17], v[34:41], v[146:153], 0
	v_or_b32_e32 v34, 64, v56
	v_bitop3_b32 v45, v42, v34, s45 bitop3:0x6c
	v_or_b32_e32 v34, 0x50, v56
	v_add_u32_e32 v213, v43, v45
	v_bitop3_b32 v42, v42, v34, s45 bitop3:0x6c
	v_add_u32_e32 v214, v43, v42
	ds_read_b128 v[34:37], v213 offset:32768
	ds_read_b128 v[38:41], v214 offset:32768
	v_add_u32_e32 v207, v44, v45
	v_add_u32_e32 v208, v44, v42
	ds_read_b128 v[42:45], v207 offset:32768
	ds_read_b128 v[46:49], v208 offset:32768
	v_bitop3_b32 v56, v60, v59, 4 bitop3:0x36
	s_waitcnt lgkmcnt(2)
	v_mfma_f32_32x32x64_f8f6f4 v[18:33], v[34:41], v[154:161], v[18:33]
	v_lshlrev_b32_e32 v34, 1, v58
	v_lshrrev_b32_e32 v35, 2, v55
	v_and_b32_e32 v195, 63, v55
	v_lshl_add_u32 v203, v56, 4, v61
	v_bitop3_b32 v56, v60, v59, 6 bitop3:0x36
	v_lshlrev_b32_e32 v59, 6, v52
	v_bfe_u32 v36, v55, 2, 2
	v_bitop3_b32 v35, v34, v35, 3 bitop3:0x78
	v_lshlrev_b32_e32 v55, 6, v57
	s_waitcnt lgkmcnt(0)
	v_mfma_f32_32x32x64_f8f6f4 v[2:17], v[42:49], v[154:161], v[2:17]
	v_lshlrev_b32_e32 v215, 4, v35
	v_add_u32_e32 v35, s42, v59
	v_bitop3_b32 v34, v34, v36, 1 bitop3:0x36
	v_add_u32_e32 v42, s42, v55
	v_add_u32_e32 v216, v35, v215
	v_lshlrev_b32_e32 v217, 4, v34
	v_add_u32_e32 v219, v42, v215
	v_add_u32_e32 v218, v35, v217
	ds_read_b128 v[34:37], v216
	ds_read_b128 v[38:41], v218
	v_add_u32_e32 v220, v42, v217
	ds_read_b128 v[42:45], v219
	ds_read_b128 v[46:49], v220
	s_waitcnt lgkmcnt(2)
	v_mfma_f32_32x32x64_f8f6f4 v[18:33], v[34:41], v[162:169], v[18:33]
	s_waitcnt lgkmcnt(0)
	v_mfma_f32_32x32x64_f8f6f4 v[2:17], v[42:49], v[162:169], v[2:17]
	s_nop 0
	s_nop 15
	s_nop 7
	s_lshr_b32 s2, s58, 3
	v_max_f32_e32 v34, v18, v19
	v_max3_f32 v34, v34, v20, v21
	v_max3_f32 v34, v34, v22, v23
	v_max3_f32 v34, v34, v24, v25
	v_max3_f32 v34, v34, v26, v27
	v_max3_f32 v34, v34, v28, v29
	v_max3_f32 v34, v34, v30, v31
	v_max3_f32 v34, v34, v32, v33
	v_max3_f32 v34, v34, v2, v3
	v_max3_f32 v34, v34, v4, v5
	v_max3_f32 v34, v34, v6, v7
	v_max3_f32 v34, v34, v8, v9
	v_max3_f32 v34, v34, v10, v11
	v_max3_f32 v34, v34, v12, v13
	v_max3_f32 v34, v34, v14, v15
	v_max3_f32 v34, v34, v16, v17
	v_mov_b32_e32 v35, v34
	s_nop 1
	v_permlane32_swap_b32_e32 v34, v35
	v_max_f32_e32 v35, v35, v35
	v_max_f32_e32 v34, v34, v34
	s_and_b32 s3, s59, 0x3fffffc0
	v_max_f32_e32 v34, v34, v35
	s_lshl_b32 s3, s3, 2
	s_and_b32 s2, s2, 15
	v_add_f32_e32 v35, 0x7149f2ca, v34
	s_add_i32 s36, s71, s3
	s_lshl_b32 s58, s2, 7
	v_cmp_ge_f32_e32 vcc, s46, v35
	s_cmp_eq_u64 vcc, exec
	v_max_f32_e32 v34, 0xf149f2ca, v34
	s_cselect_b64 vcc, -1, 0
	v_cndmask_b32_e32 v228, v34, v194, vcc
	v_sub_f32_e32 v36, 0xf149f2ca, v34
	v_fma_f32 v34, v228, s47, 4.0
	v_mov_b32_e32 v35, v34
	s_add_u32 s2, s54, s34
	v_fmac_f32_e32 v35, 0x3dd53b94, v33
	s_addc_u32 s3, s55, s35
	s_add_i32 s37, s67, s57
	v_pk_fma_f32 v[66:67], v[2:3], s[4:5], v[34:35] op_sel_hi:[1,0,0]
	v_lshl_add_u64 v[2:3], s[2:3], 0, v[174:175]
	s_add_i32 s57, s37, 0x4000
	v_lshl_add_u64 v[2:3], v[2:3], 0, s[6:7]
	s_mov_b32 m0, s57
	v_mul_f32_e32 v36, 0x3dd53b94, v36
	global_load_lds_dwordx4 v[2:3], off
	v_exp_f32_e32 v36, v36
	v_fmamk_f32 v18, v18, 0x3dd53b94, v34
	v_fmamk_f32 v19, v19, 0x3dd53b94, v34
	v_fmamk_f32 v20, v20, 0x3dd53b94, v34
	v_fmamk_f32 v21, v21, 0x3dd53b94, v34
	v_fmamk_f32 v22, v22, 0x3dd53b94, v34
	v_fmamk_f32 v23, v23, 0x3dd53b94, v34
	v_fmamk_f32 v24, v24, 0x3dd53b94, v34
	v_fmamk_f32 v25, v25, 0x3dd53b94, v34
	v_fmamk_f32 v26, v26, 0x3dd53b94, v34
	v_fmamk_f32 v27, v27, 0x3dd53b94, v34
	v_fmamk_f32 v28, v28, 0x3dd53b94, v34
	v_fmamk_f32 v29, v29, 0x3dd53b94, v34
	v_fmamk_f32 v30, v30, 0x3dd53b94, v34
	v_fmamk_f32 v31, v31, 0x3dd53b94, v34
	v_fmamk_f32 v32, v32, 0x3dd53b94, v34
	v_exp_f32_e32 v82, v18
	v_exp_f32_e32 v83, v19
	v_exp_f32_e32 v84, v20
	v_exp_f32_e32 v85, v21
	v_exp_f32_e32 v184, v22
	v_exp_f32_e32 v185, v23
	v_exp_f32_e32 v182, v24
	v_exp_f32_e32 v183, v25
	v_exp_f32_e32 v144, v26
	v_exp_f32_e32 v145, v27
	v_exp_f32_e32 v138, v28
	v_exp_f32_e32 v139, v29
	v_exp_f32_e32 v142, v30
	v_exp_f32_e32 v143, v31
	v_exp_f32_e32 v140, v32
	v_exp_f32_e32 v141, v35
	s_waitcnt vmcnt(1)
	s_barrier
	s_add_u32 s34, s34, s58
	v_add_u32_e32 v2, v54, v53
	v_lshl_add_u32 v202, v56, 4, v61
	s_addc_u32 s35, s35, 0
	v_ashrrev_i32_e32 v3, 31, v2
	v_mov_b32_e32 v196, 0
	v_cndmask_b32_e64 v221, v36, 1.0, vcc
	v_pk_fma_f32 v[80:81], v[16:17], s[4:5], v[34:35] op_sel_hi:[1,0,0]
	v_pk_fma_f32 v[78:79], v[14:15], s[4:5], v[34:35] op_sel_hi:[1,0,0]
	v_pk_fma_f32 v[76:77], v[12:13], s[4:5], v[34:35] op_sel_hi:[1,0,0]
	v_pk_fma_f32 v[74:75], v[10:11], s[4:5], v[34:35] op_sel_hi:[1,0,0]
	v_pk_fma_f32 v[72:73], v[8:9], s[4:5], v[34:35] op_sel_hi:[1,0,0]
	v_pk_fma_f32 v[70:71], v[6:7], s[4:5], v[34:35] op_sel_hi:[1,0,0]
	v_pk_fma_f32 v[68:69], v[4:5], s[4:5], v[34:35] op_sel_hi:[1,0,0]
	v_add_u32_e32 v222, s43, v59
	v_add_u32_e32 v223, s43, v55
	v_cmp_gt_u32_e64 s[2:3], 32, v195
	v_lshl_add_u32 v204, v52, 2, s36
	v_lshl_add_u32 v201, v58, 4, s36
	v_add_u32_e32 v200, 0x4000, v206
	v_add_u32_e32 v199, 0x4000, v205
	v_add_u32_e32 v198, 0x4000, v203
	v_add_u32_e32 v197, 0x4000, v202
	v_lshl_add_u64 v[176:177], v[170:171], 0, v[50:51]
	v_lshl_add_u64 v[178:179], s[34:35], 0, v[174:175]
	v_lshl_add_u64 v[180:181], s[34:35], 0, v[2:3]
	s_mov_b32 s58, -1
	v_mov_b32_e32 v2, 0
	v_mov_b32_e32 v3, v196
	v_mov_b32_e32 v4, v196
	v_mov_b32_e32 v5, v196
	v_mov_b32_e32 v6, v196
	v_mov_b32_e32 v7, v196
	v_mov_b32_e32 v8, v196
	v_mov_b32_e32 v9, v196
	v_mov_b32_e32 v10, v196
	v_mov_b32_e32 v11, v196
	v_mov_b32_e32 v12, v196
	v_mov_b32_e32 v13, v196
	v_mov_b32_e32 v14, v196
	v_mov_b32_e32 v15, v196
	v_mov_b32_e32 v16, v196
	v_mov_b32_e32 v17, v196
	v_mov_b32_e32 v18, 0
	v_mov_b32_e32 v19, v196
	v_mov_b32_e32 v20, v196
	v_mov_b32_e32 v21, v196
	v_mov_b32_e32 v22, v196
	v_mov_b32_e32 v23, v196
	v_mov_b32_e32 v24, v196
	v_mov_b32_e32 v25, v196
	v_mov_b32_e32 v26, v196
	v_mov_b32_e32 v27, v196
	v_mov_b32_e32 v28, v196
	v_mov_b32_e32 v29, v196
	v_mov_b32_e32 v30, v196
	v_mov_b32_e32 v31, v196
	v_mov_b32_e32 v32, v196
	v_mov_b32_e32 v33, v196
	v_mov_b32_e32 v34, 0
	v_mov_b32_e32 v35, v196
	v_mov_b32_e32 v36, v196
	v_mov_b32_e32 v37, v196
	v_mov_b32_e32 v38, v196
	v_mov_b32_e32 v39, v196
	v_mov_b32_e32 v40, v196
	v_mov_b32_e32 v41, v196
	v_mov_b32_e32 v42, v196
	v_mov_b32_e32 v43, v196
	v_mov_b32_e32 v44, v196
	v_mov_b32_e32 v45, v196
	v_mov_b32_e32 v46, v196
	v_mov_b32_e32 v47, v196
	v_mov_b32_e32 v48, v196
	v_mov_b32_e32 v49, v196
	v_mov_b32_e32 v50, 0
	v_mov_b32_e32 v51, v196
	v_mov_b32_e32 v52, v196
	v_mov_b32_e32 v53, v196
	v_mov_b32_e32 v54, v196
	v_mov_b32_e32 v55, v196
	v_mov_b32_e32 v56, v196
	v_mov_b32_e32 v57, v196
	v_mov_b32_e32 v58, v196
	v_mov_b32_e32 v59, v196
	v_mov_b32_e32 v60, v196
	v_mov_b32_e32 v61, v196
	v_mov_b32_e32 v62, v196
	v_mov_b32_e32 v63, v196
	v_mov_b32_e32 v64, v196
	v_mov_b32_e32 v65, v196
.LBB0_1849:
	ds_read_b128 v[102:105], v209 offset:49152
	ds_read_b128 v[106:109], v210 offset:49152
	ds_read_b128 v[130:133], v211 offset:49152
	ds_read_b128 v[134:137], v212 offset:49152
	v_lshl_add_u64 v[186:187], s[0:1], 0, v[180:181]
	s_add_i32 s55, s37, 0x8000
	v_lshl_add_u64 v[86:87], v[186:187], 0, s[8:9]
	s_mov_b32 m0, s55
	v_lshl_add_u64 v[188:189], s[0:1], 0, v[176:177]
	s_add_i32 s54, s42, s56
	global_load_lds_dwordx4 v[86:87], off
	v_lshl_add_u64 v[86:87], v[188:189], 0, s[10:11]
	s_mov_b32 m0, s54
	s_nop 0
	global_load_lds_dwordx4 v[86:87], off
	v_add_u32_e32 v224, v222, v215
	v_add_u32_e32 v225, v222, v217
	s_waitcnt lgkmcnt(2)
	v_mfma_f32_32x32x64_f8f6f4 v[86:101], v[102:109], v[146:153], 0
	ds_read_b128 v[102:105], v213 offset:49152
	ds_read_b128 v[106:109], v214 offset:49152
	v_exp_f32_e32 v66, v66
	v_exp_f32_e32 v67, v67
	v_exp_f32_e32 v68, v68
	s_waitcnt lgkmcnt(2)
	v_mfma_f32_32x32x64_f8f6f4 v[114:129], v[130:137], v[146:153], 0
	ds_read_b128 v[232:235], v207 offset:49152
	ds_read_b128 v[236:239], v208 offset:49152
	v_exp_f32_e32 v69, v69
	v_exp_f32_e32 v70, v70
	v_exp_f32_e32 v71, v71
	s_waitcnt lgkmcnt(2)
	v_mfma_f32_32x32x64_f8f6f4 v[86:101], v[102:109], v[154:161], v[86:101]
	ds_read_b128 v[102:105], v224
	ds_read_b128 v[106:109], v225
	v_exp_f32_e32 v72, v72
	v_exp_f32_e32 v73, v73
	v_exp_f32_e32 v74, v74
	v_add_u32_e32 v226, v223, v215
	s_waitcnt lgkmcnt(2)
	v_mfma_f32_32x32x64_f8f6f4 v[114:129], v[232:239], v[154:161], v[114:129]
	v_add_u32_e32 v227, v223, v217
	ds_read_b128 v[232:235], v226
	ds_read_b128 v[236:239], v227
	v_exp_f32_e32 v75, v75
	v_exp_f32_e32 v76, v76
	v_exp_f32_e32 v77, v77
	s_waitcnt lgkmcnt(2)
	v_mfma_f32_32x32x64_f8f6f4 v[86:101], v[102:109], v[162:169], v[86:101]
	v_exp_f32_e32 v78, v78
	v_exp_f32_e32 v79, v79
	s_waitcnt lgkmcnt(0)
	v_mfma_f32_32x32x64_f8f6f4 v[114:129], v[232:239], v[162:169], v[114:129]
	ds_read_b64_tr_b8 v[102:103], v206 offset:0
	ds_read_b64_tr_b8 v[104:105], v206 offset:0x800
	ds_read_b64_tr_b8 v[106:107], v206 offset:0x1000
	ds_read_b64_tr_b8 v[108:109], v206 offset:0x1800
	v_cvt_pk_fp8_f32 v130, v82, v83
	v_cvt_pk_fp8_f32 v131, v184, v185
	v_cvt_pk_fp8_f32 v132, v144, v145
	v_cvt_pk_fp8_f32 v134, v66, v67
	v_cvt_pk_fp8_f32 v135, v70, v71
	v_exp_f32_e32 v80, v80
	v_exp_f32_e32 v81, v81
	v_cvt_pk_fp8_f32 v136, v74, v75
	v_cvt_pk_fp8_f32 v133, v142, v143
	v_cvt_pk_fp8_f32 v137, v78, v79
	ds_read_b64_tr_b8 v[232:233], v205 offset:0
	ds_read_b64_tr_b8 v[234:235], v205 offset:0x800
	ds_read_b64_tr_b8 v[236:237], v205 offset:0x1000
	ds_read_b64_tr_b8 v[238:239], v205 offset:0x1800
	v_cvt_pk_fp8_f32 v130, v84, v85 op_sel:[0,0,1]
	v_cvt_pk_fp8_f32 v131, v182, v183 op_sel:[0,0,1]
	v_cvt_pk_fp8_f32 v134, v68, v69 op_sel:[0,0,1]
	v_cvt_pk_fp8_f32 v135, v72, v73 op_sel:[0,0,1]
	v_cvt_pk_fp8_f32 v132, v138, v139 op_sel:[0,0,1]
	v_cvt_pk_fp8_f32 v136, v76, v77 op_sel:[0,0,1]
	v_cvt_pk_fp8_f32 v133, v140, v141 op_sel:[0,0,1]
	v_cvt_pk_fp8_f32 v137, v80, v81 op_sel:[0,0,1]
	s_waitcnt lgkmcnt(4)
	s_mov_b32 m0, s37
	v_mfma_f32_32x32x64_f8f6f4 v[2:17], v[130:137], v[102:109], v[2:17]
	ds_read_b64_tr_b8 v[240:241], v203 offset:0
	ds_read_b64_tr_b8 v[242:243], v203 offset:0x800
	ds_read_b64_tr_b8 v[244:245], v203 offset:0x1000
	ds_read_b64_tr_b8 v[246:247], v203 offset:0x1800
	s_waitcnt lgkmcnt(4)
	s_nop 0
	v_max_f32_e32 v102, v86, v87
	v_max3_f32 v102, v102, v88, v89
	v_max3_f32 v102, v102, v90, v91
	v_max3_f32 v102, v102, v92, v93
	v_max3_f32 v102, v102, v94, v95
	v_max3_f32 v102, v102, v96, v97
	v_max3_f32 v102, v102, v98, v99
	v_max3_f32 v102, v102, v100, v101
	v_max3_f32 v102, v102, v114, v115
	v_max3_f32 v102, v102, v116, v117
	v_max3_f32 v102, v102, v118, v119
	v_max3_f32 v102, v102, v120, v121
	v_max3_f32 v102, v102, v122, v123
	v_max3_f32 v102, v102, v124, v125
	v_max3_f32 v102, v102, v126, v127
	v_max3_f32 v102, v102, v128, v129
	v_mov_b32_e32 v103, v102
	s_nop 1
	v_permlane32_swap_b32_e32 v102, v103
	v_max_f32_e32 v102, v102, v103
	v_sub_f32_e32 v103, v102, v228
	v_cmp_ge_f32_e32 vcc, s46, v103
	s_cmp_eq_u64 vcc, exec
	v_max_f32_e32 v103, v228, v228
	v_max_f32_e32 v192, v103, v102
	s_cselect_b64 vcc, -1, 0
	v_cndmask_b32_e32 v231, v192, v228, vcc
	v_fma_f32 v190, v231, s47, 4.0
	v_mfma_f32_32x32x64_f8f6f4 v[18:33], v[130:137], v[232:239], v[18:33]
	v_pk_add_f32 v[82:83], v[82:83], v[84:85]
	v_pk_fma_f32 v[110:111], v[98:99], s[4:5], v[190:191] op_sel_hi:[1,0,0]
	v_pk_fma_f32 v[98:99], v[86:87], s[4:5], v[190:191] op_sel_hi:[1,0,0]
	ds_read_b64_tr_b8 v[86:87], v202 offset:0
	v_pk_fma_f32 v[112:113], v[100:101], s[4:5], v[190:191] op_sel_hi:[1,0,0]
	v_pk_fma_f32 v[100:101], v[88:89], s[4:5], v[190:191] op_sel_hi:[1,0,0]
	ds_read_b64_tr_b8 v[88:89], v202 offset:0x800
	v_pk_fma_f32 v[102:103], v[90:91], s[4:5], v[190:191] op_sel_hi:[1,0,0]
	ds_read_b64_tr_b8 v[90:91], v202 offset:0x1000
	v_pk_fma_f32 v[108:109], v[96:97], s[4:5], v[190:191] op_sel_hi:[1,0,0]
	v_pk_fma_f32 v[106:107], v[94:95], s[4:5], v[190:191] op_sel_hi:[1,0,0]
	v_pk_fma_f32 v[104:105], v[92:93], s[4:5], v[190:191] op_sel_hi:[1,0,0]
	v_pk_fma_f32 v[128:129], v[128:129], s[4:5], v[190:191] op_sel_hi:[1,0,0]
	v_pk_fma_f32 v[126:127], v[126:127], s[4:5], v[190:191] op_sel_hi:[1,0,0]
	v_pk_fma_f32 v[124:125], v[124:125], s[4:5], v[190:191] op_sel_hi:[1,0,0]
	v_pk_fma_f32 v[122:123], v[122:123], s[4:5], v[190:191] op_sel_hi:[1,0,0]
	v_pk_fma_f32 v[120:121], v[120:121], s[4:5], v[190:191] op_sel_hi:[1,0,0]
	v_pk_fma_f32 v[118:119], v[118:119], s[4:5], v[190:191] op_sel_hi:[1,0,0]
	v_pk_fma_f32 v[116:117], v[116:117], s[4:5], v[190:191] op_sel_hi:[1,0,0]
	v_pk_fma_f32 v[114:115], v[114:115], s[4:5], v[190:191] op_sel_hi:[1,0,0]
	ds_read_b64_tr_b8 v[92:93], v202 offset:0x1800
	s_waitcnt lgkmcnt(4)
	v_lshl_add_u64 v[190:191], s[0:1], 0, v[178:179]
	v_mfma_f32_32x32x64_f8f6f4 v[34:49], v[130:137], v[240:247], v[34:49]
	s_waitcnt lgkmcnt(0)
	v_pk_add_f32 v[82:83], v[184:185], v[82:83]
	v_exp_f32_e32 v98, v98
	v_exp_f32_e32 v99, v99
	v_exp_f32_e32 v100, v100
	v_exp_f32_e32 v101, v101
	v_mfma_f32_32x32x64_f8f6f4 v[50:65], v[130:137], v[86:93], v[50:65]
	s_barrier
	v_lshl_add_u64 v[86:87], v[190:191], 0, s[12:13]
	global_load_lds_dwordx4 v[86:87], off
	v_pk_add_f32 v[82:83], v[182:183], v[82:83]
	s_nop 0
	v_pk_add_f32 v[82:83], v[144:145], v[82:83]
	s_nop 0
	v_pk_add_f32 v[82:83], v[138:139], v[82:83]
	s_nop 0
	v_pk_add_f32 v[82:83], v[142:143], v[82:83]
	s_nop 0
	v_pk_add_f32 v[82:83], v[140:141], v[82:83]
	s_nop 0
	v_pk_add_f32 v[66:67], v[82:83], v[66:67]
	s_nop 0
	v_pk_add_f32 v[66:67], v[68:69], v[66:67]
	s_nop 0
	v_pk_add_f32 v[66:67], v[70:71], v[66:67]
	s_nop 0
	v_pk_add_f32 v[66:67], v[72:73], v[66:67]
	s_nop 0
	v_pk_add_f32 v[66:67], v[74:75], v[66:67]
	s_nop 0
	v_pk_add_f32 v[66:67], v[76:77], v[66:67]
	s_nop 0
	v_pk_add_f32 v[66:67], v[78:79], v[66:67]
	s_nop 0
	v_pk_add_f32 v[66:67], v[80:81], v[66:67]
	s_nop 0
	v_pk_add_f32 v[182:183], v[66:67], v[66:67] op_sel:[0,1] op_sel_hi:[1,0]
	v_sub_f32_e32 v66, v228, v192
	v_mul_f32_e32 v66, 0x3dd53b94, v66
	v_exp_f32_e32 v66, v66
	v_mov_b32_e32 v229, v182
	s_nop 1
	v_permlane32_swap_b32_e32 v182, v229
	v_cndmask_b32_e64 v183, v66, 1.0, vcc
	v_cmp_gt_f32_e32 vcc, 1.0, v183
	s_cbranch_vccz .LBB0_1853
	s_and_saveexec_b64 s[34:35], s[2:3]
	ds_write_b32 v204, v183 offset:128
	s_or_b64 exec, exec, s[34:35]
	s_waitcnt lgkmcnt(0)
	s_nop 15
	s_nop 7
	ds_read2_b32 v[66:67], v201 offset0:32 offset1:33
	ds_read2_b32 v[68:69], v201 offset0:34 offset1:35
	ds_read2_b32 v[70:71], v201 offset0:40 offset1:41
	ds_read2_b32 v[72:73], v201 offset0:42 offset1:43
	s_waitcnt lgkmcnt(0)
	v_pk_mul_f32 v[2:3], v[66:67], v[2:3]
	v_pk_mul_f32 v[18:19], v[66:67], v[18:19]
	v_pk_mul_f32 v[34:35], v[66:67], v[34:35]
	v_pk_mul_f32 v[50:51], v[66:67], v[50:51]
	v_pk_mul_f32 v[4:5], v[4:5], v[68:69]
	v_pk_mul_f32 v[20:21], v[20:21], v[68:69]
	v_pk_mul_f32 v[36:37], v[36:37], v[68:69]
	v_pk_mul_f32 v[52:53], v[52:53], v[68:69]
	v_pk_mul_f32 v[6:7], v[6:7], v[70:71]
	v_pk_mul_f32 v[22:23], v[22:23], v[70:71]
	v_pk_mul_f32 v[38:39], v[38:39], v[70:71]
	v_pk_mul_f32 v[54:55], v[54:55], v[70:71]
	v_pk_mul_f32 v[8:9], v[8:9], v[72:73]
	v_pk_mul_f32 v[24:25], v[24:25], v[72:73]
	v_pk_mul_f32 v[40:41], v[40:41], v[72:73]
	ds_read2_b32 v[66:67], v201 offset0:48 offset1:49
	v_pk_mul_f32 v[56:57], v[56:57], v[72:73]
	ds_read2_b32 v[68:69], v201 offset0:50 offset1:51
	ds_read2_b32 v[70:71], v201 offset0:56 offset1:57
	ds_read2_b32 v[72:73], v201 offset0:58 offset1:59
	s_waitcnt lgkmcnt(0)
	v_pk_mul_f32 v[10:11], v[10:11], v[66:67]
	v_pk_mul_f32 v[26:27], v[26:27], v[66:67]
	v_pk_mul_f32 v[42:43], v[42:43], v[66:67]
	v_pk_mul_f32 v[58:59], v[58:59], v[66:67]
	v_pk_mul_f32 v[12:13], v[12:13], v[68:69]
	v_pk_mul_f32 v[28:29], v[28:29], v[68:69]
	v_pk_mul_f32 v[44:45], v[44:45], v[68:69]
	v_pk_mul_f32 v[60:61], v[60:61], v[68:69]
	v_pk_mul_f32 v[14:15], v[14:15], v[70:71]
	v_pk_mul_f32 v[30:31], v[30:31], v[70:71]
	v_pk_mul_f32 v[46:47], v[46:47], v[70:71]
	v_pk_mul_f32 v[62:63], v[62:63], v[70:71]
	v_pk_mul_f32 v[16:17], v[16:17], v[72:73]
	v_pk_mul_f32 v[32:33], v[32:33], v[72:73]
	v_pk_mul_f32 v[48:49], v[48:49], v[72:73]
	v_pk_mul_f32 v[64:65], v[64:65], v[72:73]
.LBB0_1853:
	s_waitcnt vmcnt(1)
	s_add_i32 s60, s37, 0xc000
	s_barrier
	ds_read_b128 v[82:85], v209 offset:32768
	ds_read_b128 v[86:89], v210 offset:32768
	ds_read_b128 v[90:93], v211 offset:32768
	ds_read_b128 v[94:97], v212 offset:32768
	v_lshl_add_u64 v[66:67], v[186:187], 0, s[14:15]
	s_mov_b32 m0, s60
	s_add_i32 s59, s43, s56
	global_load_lds_dwordx4 v[66:67], off
	v_lshl_add_u64 v[66:67], v[188:189], 0, s[16:17]
	s_mov_b32 m0, s59
	v_exp_f32_e32 v184, v102
	global_load_lds_dwordx4 v[66:67], off
	v_exp_f32_e32 v185, v103
	v_exp_f32_e32 v186, v104
	v_exp_f32_e32 v187, v105
	v_exp_f32_e32 v188, v106
	v_exp_f32_e32 v189, v107
	v_exp_f32_e32 v192, v108
	v_exp_f32_e32 v193, v109
	v_exp_f32_e32 v110, v110
	v_exp_f32_e32 v111, v111
	v_exp_f32_e32 v112, v112
	v_exp_f32_e32 v113, v113
	v_mov_b32_e32 v102, 0
	v_mov_b32_e32 v103, 0
	s_waitcnt lgkmcnt(2)
	v_mfma_f32_32x32x64_f8f6f4 v[66:81], v[82:89], v[146:153], 0
	ds_read_b128 v[82:85], v213 offset:32768
	ds_read_b128 v[86:89], v214 offset:32768
	v_exp_f32_e32 v114, v114
	v_exp_f32_e32 v115, v115
	v_exp_f32_e32 v116, v116
	s_waitcnt lgkmcnt(2)
	v_mfma_f32_32x32x64_f8f6f4 v[130:145], v[90:97], v[146:153], 0
	ds_read_b128 v[90:93], v207 offset:32768
	ds_read_b128 v[94:97], v208 offset:32768
	v_exp_f32_e32 v117, v117
	v_exp_f32_e32 v118, v118
	v_exp_f32_e32 v119, v119
	s_waitcnt lgkmcnt(2)
	v_mfma_f32_32x32x64_f8f6f4 v[66:81], v[82:89], v[154:161], v[66:81]
	ds_read_b128 v[82:85], v216
	ds_read_b128 v[86:89], v218
	v_exp_f32_e32 v120, v120
	v_exp_f32_e32 v121, v121
	v_exp_f32_e32 v122, v122
	s_waitcnt lgkmcnt(2)
	v_mfma_f32_32x32x64_f8f6f4 v[130:145], v[90:97], v[154:161], v[130:145]
	ds_read_b128 v[90:93], v219
	ds_read_b128 v[94:97], v220
	v_exp_f32_e32 v123, v123
	v_exp_f32_e32 v124, v124
	v_exp_f32_e32 v125, v125
	s_waitcnt lgkmcnt(2)
	v_mfma_f32_32x32x64_f8f6f4 v[66:81], v[82:89], v[162:169], v[66:81]
	v_exp_f32_e32 v126, v126
	v_exp_f32_e32 v127, v127
	s_waitcnt lgkmcnt(0)
	v_mfma_f32_32x32x64_f8f6f4 v[130:145], v[90:97], v[162:169], v[130:145]
	ds_read_b64_tr_b8 v[82:83], v200 offset:0
	ds_read_b64_tr_b8 v[84:85], v200 offset:0x800
	ds_read_b64_tr_b8 v[86:87], v200 offset:0x1000
	ds_read_b64_tr_b8 v[88:89], v200 offset:0x1800
	v_cvt_pk_fp8_f32 v102, v98, v99
	v_cvt_pk_fp8_f32 v103, v184, v185
	v_cvt_pk_fp8_f32 v104, v188, v189
	v_cvt_pk_fp8_f32 v105, v110, v111
	v_exp_f32_e32 v128, v128
	v_cvt_pk_fp8_f32 v106, v114, v115
	v_cvt_pk_fp8_f32 v107, v118, v119
	v_exp_f32_e32 v129, v129
	v_cvt_pk_fp8_f32 v108, v122, v123
	v_cvt_pk_fp8_f32 v109, v126, v127
	ds_read_b64_tr_b8 v[90:91], v199 offset:0
	ds_read_b64_tr_b8 v[92:93], v199 offset:0x800
	ds_read_b64_tr_b8 v[94:95], v199 offset:0x1000
	ds_read_b64_tr_b8 v[96:97], v199 offset:0x1800
	v_cvt_pk_fp8_f32 v102, v100, v101 op_sel:[0,0,1]
	v_cvt_pk_fp8_f32 v103, v186, v187 op_sel:[0,0,1]
	v_cvt_pk_fp8_f32 v106, v116, v117 op_sel:[0,0,1]
	v_cvt_pk_fp8_f32 v107, v120, v121 op_sel:[0,0,1]
	v_cvt_pk_fp8_f32 v104, v192, v193 op_sel:[0,0,1]
	v_cvt_pk_fp8_f32 v108, v124, v125 op_sel:[0,0,1]
	v_cvt_pk_fp8_f32 v105, v112, v113 op_sel:[0,0,1]
	v_cvt_pk_fp8_f32 v109, v128, v129 op_sel:[0,0,1]
	s_waitcnt lgkmcnt(4)
	s_mov_b32 m0, s57
	v_mfma_f32_32x32x64_f8f6f4 v[2:17], v[102:109], v[82:89], v[2:17]
	ds_read_b64_tr_b8 v[232:233], v198 offset:0
	ds_read_b64_tr_b8 v[234:235], v198 offset:0x800
	ds_read_b64_tr_b8 v[236:237], v198 offset:0x1000
	ds_read_b64_tr_b8 v[238:239], v198 offset:0x1800
	s_waitcnt lgkmcnt(4)
	s_nop 0
	v_max_f32_e32 v82, v66, v67
	v_max3_f32 v82, v82, v68, v69
	v_max3_f32 v82, v82, v70, v71
	v_max3_f32 v82, v82, v72, v73
	v_max3_f32 v82, v82, v74, v75
	v_max3_f32 v82, v82, v76, v77
	v_max3_f32 v82, v82, v78, v79
	v_max3_f32 v82, v82, v80, v81
	v_max3_f32 v82, v82, v130, v131
	v_max3_f32 v82, v82, v132, v133
	v_max3_f32 v82, v82, v134, v135
	v_max3_f32 v82, v82, v136, v137
	v_max3_f32 v82, v82, v138, v139
	v_max3_f32 v82, v82, v140, v141
	v_max3_f32 v82, v82, v142, v143
	v_max3_f32 v82, v82, v144, v145
	v_mov_b32_e32 v83, v82
	s_nop 1
	v_permlane32_swap_b32_e32 v82, v83
	v_max_f32_e32 v82, v82, v83
	v_sub_f32_e32 v83, v82, v231
	v_cmp_ge_f32_e32 vcc, s46, v83
	s_cmp_eq_u64 vcc, exec
	v_max_f32_e32 v83, v231, v231
	v_max_f32_e32 v241, v83, v82
	s_cselect_b64 vcc, -1, 0
	v_cndmask_b32_e32 v228, v241, v231, vcc
	v_fma_f32 v240, v228, s47, 4.0
	v_mfma_f32_32x32x64_f8f6f4 v[18:33], v[102:109], v[90:97], v[18:33]
	v_pk_add_f32 v[98:99], v[98:99], v[100:101]
	v_pk_fma_f32 v[82:83], v[66:67], s[4:5], v[240:241] op_sel_hi:[1,0,0]
	v_pk_fma_f32 v[66:67], v[130:131], s[4:5], v[240:241] op_sel_hi:[1,0,0]
	ds_read_b64_tr_b8 v[130:131], v197 offset:0
	v_pk_fma_f32 v[84:85], v[68:69], s[4:5], v[240:241] op_sel_hi:[1,0,0]
	v_pk_fma_f32 v[68:69], v[132:133], s[4:5], v[240:241] op_sel_hi:[1,0,0]
	ds_read_b64_tr_b8 v[132:133], v197 offset:0x800
	v_pk_fma_f32 v[86:87], v[70:71], s[4:5], v[240:241] op_sel_hi:[1,0,0]
	v_pk_fma_f32 v[70:71], v[134:135], s[4:5], v[240:241] op_sel_hi:[1,0,0]
	ds_read_b64_tr_b8 v[134:135], v197 offset:0x1000
	v_pk_fma_f32 v[96:97], v[80:81], s[4:5], v[240:241] op_sel_hi:[1,0,0]
	v_pk_fma_f32 v[94:95], v[78:79], s[4:5], v[240:241] op_sel_hi:[1,0,0]
	v_pk_fma_f32 v[92:93], v[76:77], s[4:5], v[240:241] op_sel_hi:[1,0,0]
	v_pk_fma_f32 v[90:91], v[74:75], s[4:5], v[240:241] op_sel_hi:[1,0,0]
	v_pk_fma_f32 v[88:89], v[72:73], s[4:5], v[240:241] op_sel_hi:[1,0,0]
	v_pk_fma_f32 v[80:81], v[144:145], s[4:5], v[240:241] op_sel_hi:[1,0,0]
	v_pk_fma_f32 v[78:79], v[142:143], s[4:5], v[240:241] op_sel_hi:[1,0,0]
	v_pk_fma_f32 v[76:77], v[140:141], s[4:5], v[240:241] op_sel_hi:[1,0,0]
	v_pk_fma_f32 v[74:75], v[138:139], s[4:5], v[240:241] op_sel_hi:[1,0,0]
	v_pk_fma_f32 v[72:73], v[136:137], s[4:5], v[240:241] op_sel_hi:[1,0,0]
	ds_read_b64_tr_b8 v[136:137], v197 offset:0x1800
	s_waitcnt lgkmcnt(4)
	v_pk_add_f32 v[98:99], v[98:99], v[184:185]
	v_mfma_f32_32x32x64_f8f6f4 v[34:49], v[102:109], v[232:239], v[34:49]
	s_waitcnt lgkmcnt(0)
	s_nop 0
	v_exp_f32_e32 v82, v82
	v_exp_f32_e32 v83, v83
	v_exp_f32_e32 v84, v84
	v_exp_f32_e32 v85, v85
	v_mfma_f32_32x32x64_f8f6f4 v[50:65], v[102:109], v[130:137], v[50:65]
	s_barrier
	v_lshl_add_u64 v[102:103], v[190:191], 0, s[18:19]
	global_load_lds_dwordx4 v[102:103], off
	v_pk_add_f32 v[98:99], v[186:187], v[98:99]
	s_nop 0
	v_pk_add_f32 v[98:99], v[188:189], v[98:99]
	s_nop 0
	v_pk_add_f32 v[98:99], v[192:193], v[98:99]
	s_nop 0
	v_pk_add_f32 v[98:99], v[110:111], v[98:99]
	s_nop 0
	v_pk_add_f32 v[98:99], v[112:113], v[98:99]
	s_nop 0
	v_pk_add_f32 v[98:99], v[98:99], v[114:115]
	s_nop 0
	v_pk_add_f32 v[98:99], v[116:117], v[98:99]
	s_nop 0
	v_pk_add_f32 v[98:99], v[118:119], v[98:99]
	s_nop 0
	v_pk_add_f32 v[98:99], v[120:121], v[98:99]
	s_nop 0
	v_pk_add_f32 v[98:99], v[122:123], v[98:99]
	s_nop 0
	v_pk_add_f32 v[98:99], v[124:125], v[98:99]
	s_nop 0
	v_pk_add_f32 v[98:99], v[126:127], v[98:99]
	s_nop 0
	v_pk_add_f32 v[98:99], v[128:129], v[98:99]
	s_nop 0
	v_pk_add_f32 v[98:99], v[98:99], v[98:99] op_sel:[0,1] op_sel_hi:[1,0]
	s_nop 0
	v_sub_f32_e32 v99, v231, v241
	v_mul_f32_e32 v99, 0x3dd53b94, v99
	v_exp_f32_e32 v100, v99
	v_mov_b32_e32 v99, v98
	s_nop 1
	v_permlane32_swap_b32_e32 v98, v99
	v_cndmask_b32_e64 v128, v100, 1.0, vcc
	v_cmp_gt_f32_e32 vcc, 1.0, v128
	s_cbranch_vccz .LBB0_1857
	s_and_saveexec_b64 s[34:35], s[2:3]
	ds_write_b32 v204, v128 offset:128
	s_or_b64 exec, exec, s[34:35]
	s_waitcnt lgkmcnt(0)
	s_nop 15
	s_nop 7
	ds_read2_b32 v[100:101], v201 offset0:32 offset1:33
	ds_read2_b32 v[102:103], v201 offset0:34 offset1:35
	ds_read2_b32 v[104:105], v201 offset0:40 offset1:41
	ds_read2_b32 v[106:107], v201 offset0:42 offset1:43
	s_waitcnt lgkmcnt(0)
	v_pk_mul_f32 v[2:3], v[100:101], v[2:3]
	v_pk_mul_f32 v[18:19], v[100:101], v[18:19]
	v_pk_mul_f32 v[34:35], v[100:101], v[34:35]
	v_pk_mul_f32 v[50:51], v[100:101], v[50:51]
	v_pk_mul_f32 v[4:5], v[4:5], v[102:103]
	v_pk_mul_f32 v[20:21], v[20:21], v[102:103]
	v_pk_mul_f32 v[36:37], v[36:37], v[102:103]
	v_pk_mul_f32 v[52:53], v[52:53], v[102:103]
	v_pk_mul_f32 v[6:7], v[6:7], v[104:105]
	v_pk_mul_f32 v[22:23], v[22:23], v[104:105]
	v_pk_mul_f32 v[38:39], v[38:39], v[104:105]
	v_pk_mul_f32 v[54:55], v[54:55], v[104:105]
	v_pk_mul_f32 v[8:9], v[8:9], v[106:107]
	v_pk_mul_f32 v[24:25], v[24:25], v[106:107]
	v_pk_mul_f32 v[40:41], v[40:41], v[106:107]
	ds_read2_b32 v[100:101], v201 offset0:48 offset1:49
	v_pk_mul_f32 v[56:57], v[56:57], v[106:107]
	ds_read2_b32 v[102:103], v201 offset0:50 offset1:51
	ds_read2_b32 v[104:105], v201 offset0:56 offset1:57
	ds_read2_b32 v[106:107], v201 offset0:58 offset1:59
	s_waitcnt lgkmcnt(0)
	v_pk_mul_f32 v[10:11], v[10:11], v[100:101]
	v_pk_mul_f32 v[26:27], v[26:27], v[100:101]
	v_pk_mul_f32 v[42:43], v[42:43], v[100:101]
	v_pk_mul_f32 v[58:59], v[58:59], v[100:101]
	v_pk_mul_f32 v[12:13], v[12:13], v[102:103]
	v_pk_mul_f32 v[28:29], v[28:29], v[102:103]
	v_pk_mul_f32 v[44:45], v[44:45], v[102:103]
	v_pk_mul_f32 v[60:61], v[60:61], v[102:103]
	v_pk_mul_f32 v[14:15], v[14:15], v[104:105]
	v_pk_mul_f32 v[30:31], v[30:31], v[104:105]
	v_pk_mul_f32 v[46:47], v[46:47], v[104:105]
	v_pk_mul_f32 v[62:63], v[62:63], v[104:105]
	v_pk_mul_f32 v[16:17], v[16:17], v[106:107]
	v_pk_mul_f32 v[32:33], v[32:33], v[106:107]
	v_pk_mul_f32 v[48:49], v[48:49], v[106:107]
	v_pk_mul_f32 v[64:65], v[64:65], v[106:107]

.LBB0_1859:
	ds_read_b128 v[102:105], v209 offset:49152
	ds_read_b128 v[106:109], v210 offset:49152
	ds_read_b128 v[120:123], v211 offset:49152
	ds_read_b128 v[124:127], v212 offset:49152
	v_mov_b32_e32 v118, v171
	v_cvt_pk_fp8_f32 v118, v82, v83
	s_waitcnt lgkmcnt(2)
	v_mfma_f32_32x32x64_f8f6f4 v[86:101], v[102:109], v[146:153], 0
	ds_read_b128 v[130:133], v213 offset:49152
	ds_read_b128 v[134:137], v214 offset:49152
	v_exp_f32_e32 v66, v66
	v_exp_f32_e32 v67, v67
	v_exp_f32_e32 v68, v68
	v_pk_add_f32 v[102:103], v[82:83], v[84:85]
	v_mov_b32_e32 v119, v171
	v_pk_add_f32 v[176:177], v[102:103], v[184:185]
	s_waitcnt lgkmcnt(2)
	v_mfma_f32_32x32x64_f8f6f4 v[102:117], v[120:127], v[146:153], 0
	ds_read_b128 v[120:123], v207 offset:49152
	ds_read_b128 v[124:127], v208 offset:49152
	v_exp_f32_e32 v69, v69
	v_exp_f32_e32 v70, v70
	v_exp_f32_e32 v71, v71
	s_waitcnt lgkmcnt(2)
	v_mfma_f32_32x32x64_f8f6f4 v[86:101], v[130:137], v[154:161], v[86:101]
	ds_read_b128 v[130:133], v224
	ds_read_b128 v[134:137], v225
	v_exp_f32_e32 v72, v72
	v_exp_f32_e32 v73, v73
	v_exp_f32_e32 v74, v74
	s_waitcnt lgkmcnt(2)
	v_mfma_f32_32x32x64_f8f6f4 v[102:117], v[120:127], v[154:161], v[102:117]
	v_pk_add_f32 v[82:83], v[176:177], v[182:183]
	ds_read_b128 v[146:149], v226
	ds_read_b128 v[150:153], v227
	v_pk_add_f32 v[82:83], v[82:83], v[144:145]
	v_exp_f32_e32 v75, v75
	v_exp_f32_e32 v76, v76
	v_exp_f32_e32 v77, v77
	v_pk_add_f32 v[82:83], v[82:83], v[138:139]
	s_waitcnt lgkmcnt(2)
	v_mfma_f32_32x32x64_f8f6f4 v[86:101], v[130:137], v[162:169], v[86:101]
	v_mov_b32_e32 v122, v171
	v_pk_add_f32 v[82:83], v[82:83], v[142:143]
	v_exp_f32_e32 v78, v78
	v_exp_f32_e32 v79, v79
	v_pk_add_f32 v[82:83], v[82:83], v[140:141]
	s_waitcnt lgkmcnt(0)
	v_mfma_f32_32x32x64_f8f6f4 v[102:117], v[146:153], v[162:169], v[102:117]
	v_mov_b32_e32 v123, v171
	v_pk_add_f32 v[82:83], v[82:83], v[66:67]
	v_cvt_pk_fp8_f32 v122, v66, v67
	v_pk_add_f32 v[66:67], v[68:69], v[82:83]
	v_exp_f32_e32 v80, v80
	v_pk_add_f32 v[66:67], v[70:71], v[66:67]
	v_exp_f32_e32 v81, v81
	v_pk_add_f32 v[66:67], v[72:73], v[66:67]
	v_cvt_pk_fp8_f32 v123, v70, v71
	v_pk_add_f32 v[66:67], v[74:75], v[66:67]
	v_mov_b32_e32 v124, v171
	v_pk_add_f32 v[66:67], v[76:77], v[66:67]
	v_cvt_pk_fp8_f32 v122, v68, v69 op_sel:[0,0,1]
	v_pk_add_f32 v[66:67], v[78:79], v[66:67]
	v_cvt_pk_fp8_f32 v124, v74, v75
	v_pk_add_f32 v[66:67], v[80:81], v[66:67]
	v_mov_b32_e32 v125, v171
	v_pk_add_f32 v[126:127], v[66:67], v[66:67] op_sel:[0,1] op_sel_hi:[1,0]
	ds_read_b64_tr_b8 v[66:67], v206 offset:0
	ds_read_b64_tr_b8 v[68:69], v206 offset:0x800
	ds_read_b64_tr_b8 v[70:71], v206 offset:0x1000
	v_cvt_pk_fp8_f32 v123, v72, v73 op_sel:[0,0,1]
	v_mov_b32_e32 v120, v171
	v_mov_b32_e32 v121, v171
	v_cvt_pk_fp8_f32 v125, v78, v79
	ds_read_b64_tr_b8 v[72:73], v206 offset:0x1800
	v_cvt_pk_fp8_f32 v119, v184, v185
	v_cvt_pk_fp8_f32 v120, v144, v145
	v_cvt_pk_fp8_f32 v121, v142, v143
	ds_read_b64_tr_b8 v[74:75], v205 offset:0
	v_cvt_pk_fp8_f32 v124, v76, v77 op_sel:[0,0,1]
	ds_read_b64_tr_b8 v[76:77], v205 offset:0x800
	ds_read_b64_tr_b8 v[78:79], v205 offset:0x1000
	v_cvt_pk_fp8_f32 v125, v80, v81 op_sel:[0,0,1]
	ds_read_b64_tr_b8 v[80:81], v205 offset:0x1800
	v_cvt_pk_fp8_f32 v118, v84, v85 op_sel:[0,0,1]
	v_cvt_pk_fp8_f32 v119, v182, v183 op_sel:[0,0,1]
	v_cvt_pk_fp8_f32 v120, v138, v139 op_sel:[0,0,1]
	v_cvt_pk_fp8_f32 v121, v140, v141 op_sel:[0,0,1]
	s_waitcnt lgkmcnt(4)
	v_mov_b32_e32 v127, v126
	v_mfma_f32_32x32x64_f8f6f4 v[2:17], v[118:125], v[66:73], v[2:17]
	ds_read_b64_tr_b8 v[130:131], v203 offset:0
	ds_read_b64_tr_b8 v[132:133], v203 offset:0x800
	ds_read_b64_tr_b8 v[134:135], v203 offset:0x1000
	ds_read_b64_tr_b8 v[136:137], v203 offset:0x1800
	s_waitcnt lgkmcnt(4)
	s_nop 0
	v_max_f32_e32 v66, v86, v87
	v_max3_f32 v66, v66, v88, v89
	v_max3_f32 v66, v66, v90, v91
	v_max3_f32 v66, v66, v92, v93
	v_max3_f32 v66, v66, v94, v95
	v_max3_f32 v66, v66, v96, v97
	v_max3_f32 v66, v66, v98, v99
	v_max3_f32 v66, v66, v100, v101
	v_max3_f32 v66, v66, v102, v103
	v_max3_f32 v66, v66, v104, v105
	v_max3_f32 v66, v66, v106, v107
	v_max3_f32 v66, v66, v108, v109
	v_max3_f32 v66, v66, v110, v111
	v_max3_f32 v66, v66, v112, v113
	v_max3_f32 v66, v66, v114, v115
	v_max3_f32 v66, v66, v116, v117
	v_mov_b32_e32 v67, v66
	s_nop 1
	v_permlane32_swap_b32_e32 v66, v67
	v_max_f32_e32 v66, v66, v67
	v_sub_f32_e32 v67, v66, v228
	v_cmp_ge_f32_e32 vcc, s46, v67
	s_cmp_eq_u64 vcc, exec
	v_max_f32_e32 v66, v228, v66
	s_cselect_b64 vcc, -1, 0
	v_sub_f32_e32 v67, v228, v66
	v_cndmask_b32_e32 v66, v66, v228, vcc
	v_mul_f32_e32 v83, 0x3dd53b94, v67
	v_fma_f32 v82, v66, s47, 4.0
	v_mfma_f32_32x32x64_f8f6f4 v[18:33], v[118:125], v[74:81], v[18:33]
	v_permlane32_swap_b32_e32 v126, v127
	v_pk_fma_f32 v[80:81], v[100:101], s[4:5], v[82:83] op_sel_hi:[1,0,0]
	ds_read_b64_tr_b8 v[100:101], v202 offset:0
	v_pk_fma_f32 v[78:79], v[98:99], s[4:5], v[82:83] op_sel_hi:[1,0,0]
	v_pk_fma_f32 v[76:77], v[96:97], s[4:5], v[82:83] op_sel_hi:[1,0,0]
	v_pk_fma_f32 v[74:75], v[94:95], s[4:5], v[82:83] op_sel_hi:[1,0,0]
	v_pk_fma_f32 v[72:73], v[92:93], s[4:5], v[82:83] op_sel_hi:[1,0,0]
	v_pk_fma_f32 v[70:71], v[90:91], s[4:5], v[82:83] op_sel_hi:[1,0,0]
	v_pk_fma_f32 v[68:69], v[88:89], s[4:5], v[82:83] op_sel_hi:[1,0,0]
	v_pk_fma_f32 v[66:67], v[86:87], s[4:5], v[82:83] op_sel_hi:[1,0,0]
	v_exp_f32_e32 v98, v83
	v_pk_fma_f32 v[96:97], v[116:117], s[4:5], v[82:83] op_sel_hi:[1,0,0]
	v_pk_fma_f32 v[94:95], v[114:115], s[4:5], v[82:83] op_sel_hi:[1,0,0]
	v_pk_fma_f32 v[92:93], v[112:113], s[4:5], v[82:83] op_sel_hi:[1,0,0]
	v_pk_fma_f32 v[90:91], v[110:111], s[4:5], v[82:83] op_sel_hi:[1,0,0]
	v_pk_fma_f32 v[88:89], v[108:109], s[4:5], v[82:83] op_sel_hi:[1,0,0]
	v_pk_fma_f32 v[86:87], v[106:107], s[4:5], v[82:83] op_sel_hi:[1,0,0]
	v_pk_fma_f32 v[84:85], v[104:105], s[4:5], v[82:83] op_sel_hi:[1,0,0]
	v_pk_fma_f32 v[82:83], v[102:103], s[4:5], v[82:83] op_sel_hi:[1,0,0]
	ds_read_b64_tr_b8 v[102:103], v202 offset:0x800
	ds_read_b64_tr_b8 v[104:105], v202 offset:0x1000
	ds_read_b64_tr_b8 v[106:107], v202 offset:0x1800
	s_waitcnt lgkmcnt(4)
	v_cndmask_b32_e64 v98, v98, 1.0, vcc
	v_mfma_f32_32x32x64_f8f6f4 v[34:49], v[118:125], v[130:137], v[34:49]
	s_waitcnt lgkmcnt(0)
	v_cmp_gt_f32_e32 vcc, 1.0, v98
	v_exp_f32_e32 v66, v66
	v_exp_f32_e32 v67, v67
	v_exp_f32_e32 v68, v68
	v_exp_f32_e32 v69, v69
	v_mfma_f32_32x32x64_f8f6f4 v[50:65], v[118:125], v[100:107], v[50:65]
	s_cbranch_vccz .LBB0_1863
	s_and_saveexec_b64 s[34:35], s[2:3]
	ds_write_b32 v204, v98 offset:128
	s_or_b64 exec, exec, s[34:35]
	s_waitcnt lgkmcnt(0)
	s_nop 15
	s_nop 7
	ds_read2_b32 v[100:101], v201 offset0:32 offset1:33
	ds_read2_b32 v[102:103], v201 offset0:34 offset1:35
	ds_read2_b32 v[104:105], v201 offset0:40 offset1:41
	ds_read2_b32 v[106:107], v201 offset0:42 offset1:43
	s_waitcnt lgkmcnt(0)
	v_pk_mul_f32 v[2:3], v[100:101], v[2:3]
	v_pk_mul_f32 v[18:19], v[100:101], v[18:19]
	v_pk_mul_f32 v[34:35], v[100:101], v[34:35]
	v_pk_mul_f32 v[50:51], v[100:101], v[50:51]
	v_pk_mul_f32 v[4:5], v[4:5], v[102:103]
	v_pk_mul_f32 v[20:21], v[20:21], v[102:103]
	v_pk_mul_f32 v[36:37], v[36:37], v[102:103]
	v_pk_mul_f32 v[52:53], v[52:53], v[102:103]
	v_pk_mul_f32 v[6:7], v[6:7], v[104:105]
	v_pk_mul_f32 v[22:23], v[22:23], v[104:105]
	v_pk_mul_f32 v[38:39], v[38:39], v[104:105]
	v_pk_mul_f32 v[54:55], v[54:55], v[104:105]
	v_pk_mul_f32 v[8:9], v[8:9], v[106:107]
	v_pk_mul_f32 v[24:25], v[24:25], v[106:107]
	v_pk_mul_f32 v[40:41], v[40:41], v[106:107]
	ds_read2_b32 v[100:101], v201 offset0:48 offset1:49
	v_pk_mul_f32 v[56:57], v[56:57], v[106:107]
	ds_read2_b32 v[102:103], v201 offset0:50 offset1:51
	ds_read2_b32 v[104:105], v201 offset0:56 offset1:57
	ds_read2_b32 v[106:107], v201 offset0:58 offset1:59
	s_waitcnt lgkmcnt(0)
	v_pk_mul_f32 v[10:11], v[10:11], v[100:101]
	v_pk_mul_f32 v[26:27], v[26:27], v[100:101]
	v_pk_mul_f32 v[42:43], v[42:43], v[100:101]
	v_pk_mul_f32 v[58:59], v[58:59], v[100:101]
	v_pk_mul_f32 v[12:13], v[12:13], v[102:103]
	v_pk_mul_f32 v[28:29], v[28:29], v[102:103]
	v_pk_mul_f32 v[44:45], v[44:45], v[102:103]
	v_pk_mul_f32 v[60:61], v[60:61], v[102:103]
	v_pk_mul_f32 v[14:15], v[14:15], v[104:105]
	v_pk_mul_f32 v[30:31], v[30:31], v[104:105]
	v_pk_mul_f32 v[46:47], v[46:47], v[104:105]
	v_pk_mul_f32 v[62:63], v[62:63], v[104:105]
	v_pk_mul_f32 v[16:17], v[16:17], v[106:107]
	v_pk_mul_f32 v[32:33], v[32:33], v[106:107]
	v_pk_mul_f32 v[48:49], v[48:49], v[106:107]
	v_pk_mul_f32 v[64:65], v[64:65], v[106:107]

.LBB0_1882:
	v_lshrrev_b32_e32 v4, 3, v39
	v_and_b32_e32 v3, 8, v39
	v_and_b32_e32 v56, 4, v4
	v_bfe_u32 v4, v39, 1, 2
	v_or3_b32 v3, v4, v3, v56
	v_lshlrev_b32_e32 v4, 3, v39
	v_bfe_u32 v10, v39, 1, 3
	v_lshlrev_b32_e32 v3, 7, v3
	v_and_b32_e32 v4, 8, v4
	v_and_b32_e32 v11, 1, v2
	v_add3_u32 v12, v4, s67, v3
	v_bitop3_b32 v2, v2, v10, 1 bitop3:0x6c
	v_lshl_add_u32 v194, v2, 4, v12
	v_bitop3_b32 v2, v11, v10, 2 bitop3:0x36
	v_lshlrev_b32_e32 v48, 3, v38
	v_lshl_add_u32 v193, v2, 4, v12
	v_bitop3_b32 v2, v48, v162, s37 bitop3:0x6c
	v_lshl_add_u32 v49, v38, 7, s67
	s_waitcnt lgkmcnt(0)
	v_add_u32_e32 v197, v49, v2
	v_or_b32_e32 v2, 16, v162
	s_barrier
	v_bitop3_b32 v2, v48, v2, s37 bitop3:0x6c
	v_add_u32_e32 v198, v49, v2
	ds_read_b128 v[2:5], v197 offset:32768
	ds_read_b128 v[40:43], v197 offset:36864
	ds_read_b128 v[6:9], v198 offset:32768
	ds_read_b128 v[44:47], v198 offset:36864
	v_bitop3_b32 v13, v11, v10, 4 bitop3:0x36
	v_bitop3_b32 v10, v11, v10, 6 bitop3:0x36
	v_lshl_add_u32 v192, v13, 4, v12
	v_lshl_add_u32 v190, v10, 4, v12
	s_waitcnt vmcnt(0) lgkmcnt(0)
	v_mfma_f32_32x32x64_f8f6f4 v[18:33], v[2:9], v[154:161], 0
	v_mfma_f32_32x32x64_f8f6f4 v[2:17], v[40:47], v[154:161], 0
	v_or_b32_e32 v40, 64, v162
	v_bitop3_b32 v40, v48, v40, s37 bitop3:0x6c
	v_add_u32_e32 v195, v49, v40
	v_or_b32_e32 v40, 0x50, v162
	v_bitop3_b32 v40, v48, v40, s37 bitop3:0x6c
	v_add_u32_e32 v196, v49, v40
	ds_read_b128 v[40:43], v195 offset:32768
	ds_read_b128 v[48:51], v195 offset:36864
	ds_read_b128 v[44:47], v196 offset:32768
	ds_read_b128 v[52:55], v196 offset:36864
	s_waitcnt lgkmcnt(1)
	v_mfma_f32_32x32x64_f8f6f4 v[18:33], v[40:47], v[146:153], v[18:33]
	s_waitcnt lgkmcnt(0)
	v_mfma_f32_32x32x64_f8f6f4 v[2:17], v[48:55], v[146:153], v[2:17]
	v_and_b32_e32 v181, 63, v39
	s_nop 15
	s_nop 7
	s_lshr_b32 s4, s4, 3
	v_max_f32_e32 v39, v18, v19
	v_max3_f32 v39, v39, v20, v21
	v_max3_f32 v39, v39, v22, v23
	v_max3_f32 v39, v39, v24, v25
	v_max3_f32 v39, v39, v26, v27
	v_max3_f32 v39, v39, v28, v29
	v_max3_f32 v39, v39, v30, v31
	v_max3_f32 v39, v39, v32, v33
	v_max3_f32 v39, v39, v2, v3
	v_max3_f32 v39, v39, v4, v5
	v_max3_f32 v39, v39, v6, v7
	v_max3_f32 v39, v39, v8, v9
	v_max3_f32 v39, v39, v10, v11
	v_max3_f32 v39, v39, v12, v13
	v_max3_f32 v39, v39, v14, v15
	v_max3_f32 v39, v39, v16, v17
	v_mov_b32_e32 v40, v39
	s_nop 1
	v_permlane32_swap_b32_e32 v39, v40
	v_max_f32_e32 v39, v39, v40
	s_and_b32 s30, s49, 0x3fffffc0
	v_add_f32_e32 v40, 0x7149f2ca, v39
	v_max_f32_e32 v39, 0xf149f2ca, v39
	s_lshl_b32 s30, s30, 2
	s_lshl_b32 s4, s4, 5
	v_sub_f32_e32 v41, 0xf149f2ca, v39
	s_add_i32 s30, s71, s30
	s_and_b32 s4, s4, 0x180
	v_mul_f32_e32 v41, 0x3e0293ee, v41
	v_cmp_ge_f32_e32 vcc, s38, v40
	v_exp_f32_e32 v41, v41
	s_cmp_eq_u64 vcc, exec
	s_cselect_b64 vcc, -1, 0
	s_add_u32 s2, s46, s2
	v_cndmask_b32_e32 v200, v39, v180, vcc
	s_addc_u32 s3, s47, s3
	s_add_i32 s31, s67, s48
	v_fma_f32 v40, v200, s39, 4.0
	s_add_i32 s47, s31, 0x4000
	v_pk_fma_f32 v[66:67], v[2:3], s[6:7], v[40:41] op_sel_hi:[1,0,0]
	v_lshl_add_u64 v[2:3], s[2:3], 0, v[36:37]
	s_mov_b32 m0, s47
	v_mov_b32_e32 v39, v40
	global_load_lds_dwordx4 v[2:3], off
	v_fmamk_f32 v18, v18, 0x3e0293ee, v40
	v_fmamk_f32 v19, v19, 0x3e0293ee, v40
	v_fmamk_f32 v20, v20, 0x3e0293ee, v40
	v_fmamk_f32 v21, v21, 0x3e0293ee, v40
	v_fmamk_f32 v22, v22, 0x3e0293ee, v40
	v_fmamk_f32 v23, v23, 0x3e0293ee, v40
	v_fmamk_f32 v24, v24, 0x3e0293ee, v40
	v_fmamk_f32 v25, v25, 0x3e0293ee, v40
	v_fmamk_f32 v26, v26, 0x3e0293ee, v40
	v_fmamk_f32 v27, v27, 0x3e0293ee, v40
	v_fmamk_f32 v28, v28, 0x3e0293ee, v40
	v_fmamk_f32 v29, v29, 0x3e0293ee, v40
	v_fmamk_f32 v30, v30, 0x3e0293ee, v40
	v_fmamk_f32 v31, v31, 0x3e0293ee, v40
	v_fmamk_f32 v32, v32, 0x3e0293ee, v40
	v_fmac_f32_e32 v39, 0x3e0293ee, v33
	v_exp_f32_e32 v82, v18
	v_exp_f32_e32 v83, v19
	v_exp_f32_e32 v84, v20
	v_exp_f32_e32 v85, v21
	v_exp_f32_e32 v172, v22
	v_exp_f32_e32 v173, v23
	v_exp_f32_e32 v170, v24
	v_exp_f32_e32 v171, v25
	v_exp_f32_e32 v168, v26
	v_exp_f32_e32 v169, v27
	v_exp_f32_e32 v140, v28
	v_exp_f32_e32 v141, v29
	v_exp_f32_e32 v144, v30
	v_exp_f32_e32 v145, v31
	v_exp_f32_e32 v142, v32
	v_exp_f32_e32 v143, v39
	s_waitcnt vmcnt(1)
	s_barrier
	s_add_u32 s28, s0, s28
	s_addc_u32 s29, s1, s29
	v_mov_b32_e32 v162, 0
	v_cndmask_b32_e64 v199, v41, 1.0, vcc
	v_pk_fma_f32 v[80:81], v[16:17], s[6:7], v[40:41] op_sel_hi:[1,0,0]
	v_pk_fma_f32 v[78:79], v[14:15], s[6:7], v[40:41] op_sel_hi:[1,0,0]
	v_pk_fma_f32 v[76:77], v[12:13], s[6:7], v[40:41] op_sel_hi:[1,0,0]
	v_pk_fma_f32 v[74:75], v[10:11], s[6:7], v[40:41] op_sel_hi:[1,0,0]
	v_pk_fma_f32 v[72:73], v[8:9], s[6:7], v[40:41] op_sel_hi:[1,0,0]
	v_pk_fma_f32 v[70:71], v[6:7], s[6:7], v[40:41] op_sel_hi:[1,0,0]
	v_pk_fma_f32 v[68:69], v[4:5], s[6:7], v[40:41] op_sel_hi:[1,0,0]
	v_cmp_gt_u32_e64 s[2:3], 32, v181
	v_lshl_add_u32 v191, v38, 2, s30
	v_lshl_add_u32 v189, v56, 2, s30
	v_add_u32_e32 v188, 0x4000, v194
	v_add_u32_e32 v187, 0x4000, v193
	v_add_u32_e32 v186, 0x4000, v192
	v_add_u32_e32 v185, 0x4000, v190
	v_lshl_add_u64 v[164:165], s[28:29], 0, v[36:37]
	v_lshl_add_u64 v[166:167], s[28:29], 0, v[34:35]
	s_mov_b32 s48, -1
	v_mov_b32_e32 v2, 0
	v_mov_b32_e32 v3, v162
	v_mov_b32_e32 v4, v162
	v_mov_b32_e32 v5, v162
	v_mov_b32_e32 v6, v162
	v_mov_b32_e32 v7, v162
	v_mov_b32_e32 v8, v162
	v_mov_b32_e32 v9, v162
	v_mov_b32_e32 v10, v162
	v_mov_b32_e32 v11, v162
	v_mov_b32_e32 v12, v162
	v_mov_b32_e32 v13, v162
	v_mov_b32_e32 v14, v162
	v_mov_b32_e32 v15, v162
	v_mov_b32_e32 v16, v162
	v_mov_b32_e32 v17, v162
	v_mov_b32_e32 v18, 0
	v_mov_b32_e32 v19, v162
	v_mov_b32_e32 v20, v162
	v_mov_b32_e32 v21, v162
	v_mov_b32_e32 v22, v162
	v_mov_b32_e32 v23, v162
	v_mov_b32_e32 v24, v162
	v_mov_b32_e32 v25, v162
	v_mov_b32_e32 v26, v162
	v_mov_b32_e32 v27, v162
	v_mov_b32_e32 v28, v162
	v_mov_b32_e32 v29, v162
	v_mov_b32_e32 v30, v162
	v_mov_b32_e32 v31, v162
	v_mov_b32_e32 v32, v162
	v_mov_b32_e32 v33, v162
	v_mov_b32_e32 v34, 0
	v_mov_b32_e32 v35, v162
	v_mov_b32_e32 v36, v162
	v_mov_b32_e32 v37, v162
	v_mov_b32_e32 v38, v162
	v_mov_b32_e32 v39, v162
	v_mov_b32_e32 v40, v162
	v_mov_b32_e32 v41, v162
	v_mov_b32_e32 v42, v162
	v_mov_b32_e32 v43, v162
	v_mov_b32_e32 v44, v162
	v_mov_b32_e32 v45, v162
	v_mov_b32_e32 v46, v162
	v_mov_b32_e32 v47, v162
	v_mov_b32_e32 v48, v162
	v_mov_b32_e32 v49, v162
	v_mov_b32_e32 v50, 0
	v_mov_b32_e32 v51, v162
	v_mov_b32_e32 v52, v162
	v_mov_b32_e32 v53, v162
	v_mov_b32_e32 v54, v162
	v_mov_b32_e32 v55, v162
	v_mov_b32_e32 v56, v162
	v_mov_b32_e32 v57, v162
	v_mov_b32_e32 v58, v162
	v_mov_b32_e32 v59, v162
	v_mov_b32_e32 v60, v162
	v_mov_b32_e32 v61, v162
	v_mov_b32_e32 v62, v162
	v_mov_b32_e32 v63, v162
	v_mov_b32_e32 v64, v162
	v_mov_b32_e32 v65, v162
.LBB0_1883:
	ds_read_b128 v[106:109], v198 offset:49152
	ds_read_b128 v[102:105], v197 offset:49152
	ds_read_b128 v[130:133], v197 offset:53248
	ds_read_b128 v[134:137], v198 offset:53248
	v_lshl_add_u64 v[138:139], v[166:167], 0, s[4:5]
	s_add_i32 s46, s31, 0x8000
	v_lshl_add_u64 v[86:87], v[138:139], 0, s[8:9]
	s_mov_b32 m0, s46
	s_nop 0
	global_load_lds_dwordx4 v[86:87], off
	s_mov_b32 m0, s31
	s_waitcnt lgkmcnt(2)
	v_mfma_f32_32x32x64_f8f6f4 v[86:101], v[102:109], v[154:161], 0
	s_nop 0
	v_exp_f32_e32 v66, v66
	v_exp_f32_e32 v67, v67
	v_exp_f32_e32 v68, v68
	v_exp_f32_e32 v69, v69
	ds_read_b128 v[102:105], v195 offset:49152
	ds_read_b128 v[106:109], v196 offset:49152
	s_waitcnt lgkmcnt(2)
	v_mfma_f32_32x32x64_f8f6f4 v[114:129], v[130:137], v[154:161], 0
	ds_read_b128 v[202:205], v195 offset:53248
	ds_read_b128 v[206:209], v196 offset:53248
	v_exp_f32_e32 v70, v70
	v_exp_f32_e32 v71, v71
	v_exp_f32_e32 v72, v72
	v_exp_f32_e32 v73, v73
	s_waitcnt lgkmcnt(2)
	v_mfma_f32_32x32x64_f8f6f4 v[86:101], v[102:109], v[146:153], v[86:101]
	v_exp_f32_e32 v74, v74
	v_exp_f32_e32 v75, v75
	v_exp_f32_e32 v76, v76
	v_exp_f32_e32 v77, v77
	s_waitcnt lgkmcnt(0)
	v_mfma_f32_32x32x64_f8f6f4 v[114:129], v[202:209], v[146:153], v[114:129]
	ds_read_b64_tr_b8 v[102:103], v194 offset:0
	ds_read_b64_tr_b8 v[104:105], v194 offset:0x800
	ds_read_b64_tr_b8 v[106:107], v194 offset:0x1000
	v_exp_f32_e32 v78, v78
	v_exp_f32_e32 v79, v79
	ds_read_b64_tr_b8 v[108:109], v194 offset:0x1800
	v_cvt_pk_fp8_f32 v130, v82, v83
	v_exp_f32_e32 v80, v80
	v_exp_f32_e32 v81, v81
	v_cvt_pk_fp8_f32 v134, v66, v67
	v_cvt_pk_fp8_f32 v131, v172, v173
	v_cvt_pk_fp8_f32 v135, v70, v71
	v_cvt_pk_fp8_f32 v132, v168, v169
	v_cvt_pk_fp8_f32 v136, v74, v75
	v_cvt_pk_fp8_f32 v133, v144, v145
	v_cvt_pk_fp8_f32 v137, v78, v79
	ds_read_b64_tr_b8 v[204:205], v193 offset:0
	ds_read_b64_tr_b8 v[206:207], v193 offset:0x800
	ds_read_b64_tr_b8 v[208:209], v193 offset:0x1000
	ds_read_b64_tr_b8 v[210:211], v193 offset:0x1800
	v_cvt_pk_fp8_f32 v130, v84, v85 op_sel:[0,0,1]
	v_cvt_pk_fp8_f32 v134, v68, v69 op_sel:[0,0,1]
	v_cvt_pk_fp8_f32 v131, v170, v171 op_sel:[0,0,1]
	v_cvt_pk_fp8_f32 v135, v72, v73 op_sel:[0,0,1]
	v_cvt_pk_fp8_f32 v132, v140, v141 op_sel:[0,0,1]
	v_cvt_pk_fp8_f32 v136, v76, v77 op_sel:[0,0,1]
	v_cvt_pk_fp8_f32 v133, v142, v143 op_sel:[0,0,1]
	v_cvt_pk_fp8_f32 v137, v80, v81 op_sel:[0,0,1]
	s_waitcnt lgkmcnt(4)
	v_pk_add_f32 v[82:83], v[82:83], v[84:85]
	v_mfma_f32_32x32x64_f8f6f4 v[2:17], v[130:137], v[102:109], v[2:17]
	ds_read_b64_tr_b8 v[212:213], v192 offset:0
	ds_read_b64_tr_b8 v[214:215], v192 offset:0x800
	ds_read_b64_tr_b8 v[216:217], v192 offset:0x1000
	ds_read_b64_tr_b8 v[218:219], v192 offset:0x1800
	s_waitcnt lgkmcnt(4)
	s_nop 0
	v_max_f32_e32 v102, v86, v87
	v_max3_f32 v102, v102, v88, v89
	v_max3_f32 v102, v102, v90, v91
	v_max3_f32 v102, v102, v92, v93
	v_max3_f32 v102, v102, v94, v95
	v_max3_f32 v102, v102, v96, v97
	v_max3_f32 v102, v102, v98, v99
	v_max3_f32 v102, v102, v100, v101
	v_max3_f32 v102, v102, v114, v115
	v_max3_f32 v102, v102, v116, v117
	v_max3_f32 v102, v102, v118, v119
	v_max3_f32 v102, v102, v120, v121
	v_max3_f32 v102, v102, v122, v123
	v_max3_f32 v102, v102, v124, v125
	v_max3_f32 v102, v102, v126, v127
	v_max3_f32 v102, v102, v128, v129
	v_mov_b32_e32 v103, v102
	s_nop 1
	v_permlane32_swap_b32_e32 v102, v103
	v_max_f32_e32 v102, v102, v103
	v_sub_f32_e32 v103, v102, v200
	v_cmp_ge_f32_e32 vcc, s38, v103
	s_cmp_eq_u64 vcc, exec
	v_max_f32_e32 v103, v200, v200
	v_max_f32_e32 v176, v103, v102
	s_cselect_b64 vcc, -1, 0
	v_cndmask_b32_e32 v202, v176, v200, vcc
	v_fma_f32 v174, v202, s39, 4.0
	v_mfma_f32_32x32x64_f8f6f4 v[18:33], v[130:137], v[204:211], v[18:33]
	v_pk_add_f32 v[82:83], v[172:173], v[82:83]
	v_pk_fma_f32 v[110:111], v[98:99], s[6:7], v[174:175] op_sel_hi:[1,0,0]
	v_pk_fma_f32 v[98:99], v[86:87], s[6:7], v[174:175] op_sel_hi:[1,0,0]
	ds_read_b64_tr_b8 v[86:87], v190 offset:0
	v_pk_fma_f32 v[112:113], v[100:101], s[6:7], v[174:175] op_sel_hi:[1,0,0]
	v_pk_fma_f32 v[100:101], v[88:89], s[6:7], v[174:175] op_sel_hi:[1,0,0]
	ds_read_b64_tr_b8 v[88:89], v190 offset:0x800
	v_pk_fma_f32 v[102:103], v[90:91], s[6:7], v[174:175] op_sel_hi:[1,0,0]
	ds_read_b64_tr_b8 v[90:91], v190 offset:0x1000
	v_pk_fma_f32 v[108:109], v[96:97], s[6:7], v[174:175] op_sel_hi:[1,0,0]
	v_pk_fma_f32 v[106:107], v[94:95], s[6:7], v[174:175] op_sel_hi:[1,0,0]
	v_pk_fma_f32 v[104:105], v[92:93], s[6:7], v[174:175] op_sel_hi:[1,0,0]
	v_pk_fma_f32 v[128:129], v[128:129], s[6:7], v[174:175] op_sel_hi:[1,0,0]
	v_pk_fma_f32 v[126:127], v[126:127], s[6:7], v[174:175] op_sel_hi:[1,0,0]
	v_pk_fma_f32 v[124:125], v[124:125], s[6:7], v[174:175] op_sel_hi:[1,0,0]
	v_pk_fma_f32 v[122:123], v[122:123], s[6:7], v[174:175] op_sel_hi:[1,0,0]
	v_pk_fma_f32 v[120:121], v[120:121], s[6:7], v[174:175] op_sel_hi:[1,0,0]
	v_pk_fma_f32 v[118:119], v[118:119], s[6:7], v[174:175] op_sel_hi:[1,0,0]
	v_pk_fma_f32 v[116:117], v[116:117], s[6:7], v[174:175] op_sel_hi:[1,0,0]
	v_pk_fma_f32 v[114:115], v[114:115], s[6:7], v[174:175] op_sel_hi:[1,0,0]
	ds_read_b64_tr_b8 v[92:93], v190 offset:0x1800
	s_waitcnt lgkmcnt(4)
	v_lshl_add_u64 v[174:175], v[164:165], 0, s[4:5]
	v_mfma_f32_32x32x64_f8f6f4 v[34:49], v[130:137], v[212:219], v[34:49]
	s_waitcnt lgkmcnt(0)
	v_pk_add_f32 v[82:83], v[170:171], v[82:83]
	v_exp_f32_e32 v98, v98
	v_exp_f32_e32 v99, v99
	v_exp_f32_e32 v100, v100
	v_exp_f32_e32 v101, v101
	v_mfma_f32_32x32x64_f8f6f4 v[50:65], v[130:137], v[86:93], v[50:65]
	s_barrier
	v_lshl_add_u64 v[86:87], v[174:175], 0, s[10:11]
	global_load_lds_dwordx4 v[86:87], off
	v_pk_add_f32 v[82:83], v[168:169], v[82:83]
	s_nop 0
	v_pk_add_f32 v[82:83], v[140:141], v[82:83]
	s_nop 0
	v_pk_add_f32 v[82:83], v[144:145], v[82:83]
	s_nop 0
	v_pk_add_f32 v[82:83], v[142:143], v[82:83]
	s_nop 0
	v_pk_add_f32 v[66:67], v[82:83], v[66:67]
	s_nop 0
	v_pk_add_f32 v[66:67], v[68:69], v[66:67]
	s_nop 0
	v_pk_add_f32 v[66:67], v[70:71], v[66:67]
	s_nop 0
	v_pk_add_f32 v[66:67], v[72:73], v[66:67]
	s_nop 0
	v_pk_add_f32 v[66:67], v[74:75], v[66:67]
	s_nop 0
	v_pk_add_f32 v[66:67], v[76:77], v[66:67]
	s_nop 0
	v_pk_add_f32 v[66:67], v[78:79], v[66:67]
	s_nop 0
	v_pk_add_f32 v[66:67], v[80:81], v[66:67]
	s_nop 0
	v_pk_add_f32 v[168:169], v[66:67], v[66:67] op_sel:[0,1] op_sel_hi:[1,0]
	v_sub_f32_e32 v66, v200, v176
	v_mul_f32_e32 v66, 0x3e0293ee, v66
	v_exp_f32_e32 v66, v66
	v_mov_b32_e32 v201, v168
	s_nop 1
	v_permlane32_swap_b32_e32 v168, v201
	v_cndmask_b32_e64 v169, v66, 1.0, vcc
	v_cmp_gt_f32_e32 vcc, 1.0, v169
	s_cbranch_vccz .LBB0_1887
	s_and_saveexec_b64 s[28:29], s[2:3]
	ds_write_b32 v191, v169 offset:128
	s_or_b64 exec, exec, s[28:29]
	s_waitcnt lgkmcnt(0)
	s_nop 15
	s_nop 7
	ds_read2_b32 v[66:67], v189 offset0:32 offset1:33
	ds_read2_b32 v[68:69], v189 offset0:34 offset1:35
	ds_read2_b32 v[70:71], v189 offset0:40 offset1:41
	ds_read2_b32 v[72:73], v189 offset0:42 offset1:43
	s_waitcnt lgkmcnt(0)
	v_pk_mul_f32 v[2:3], v[66:67], v[2:3]
	v_pk_mul_f32 v[18:19], v[66:67], v[18:19]
	v_pk_mul_f32 v[34:35], v[66:67], v[34:35]
	v_pk_mul_f32 v[50:51], v[66:67], v[50:51]
	v_pk_mul_f32 v[4:5], v[4:5], v[68:69]
	v_pk_mul_f32 v[20:21], v[20:21], v[68:69]
	v_pk_mul_f32 v[36:37], v[36:37], v[68:69]
	v_pk_mul_f32 v[52:53], v[52:53], v[68:69]
	v_pk_mul_f32 v[6:7], v[6:7], v[70:71]
	v_pk_mul_f32 v[22:23], v[22:23], v[70:71]
	v_pk_mul_f32 v[38:39], v[38:39], v[70:71]
	v_pk_mul_f32 v[54:55], v[54:55], v[70:71]
	v_pk_mul_f32 v[8:9], v[8:9], v[72:73]
	v_pk_mul_f32 v[24:25], v[24:25], v[72:73]
	v_pk_mul_f32 v[40:41], v[40:41], v[72:73]
	ds_read2_b32 v[66:67], v189 offset0:48 offset1:49
	v_pk_mul_f32 v[56:57], v[56:57], v[72:73]
	ds_read2_b32 v[68:69], v189 offset0:50 offset1:51
	ds_read2_b32 v[70:71], v189 offset0:56 offset1:57
	ds_read2_b32 v[72:73], v189 offset0:58 offset1:59
	s_waitcnt lgkmcnt(0)
	v_pk_mul_f32 v[10:11], v[10:11], v[66:67]
	v_pk_mul_f32 v[26:27], v[26:27], v[66:67]
	v_pk_mul_f32 v[42:43], v[42:43], v[66:67]
	v_pk_mul_f32 v[58:59], v[58:59], v[66:67]
	v_pk_mul_f32 v[12:13], v[12:13], v[68:69]
	v_pk_mul_f32 v[28:29], v[28:29], v[68:69]
	v_pk_mul_f32 v[44:45], v[44:45], v[68:69]
	v_pk_mul_f32 v[60:61], v[60:61], v[68:69]
	v_pk_mul_f32 v[14:15], v[14:15], v[70:71]
	v_pk_mul_f32 v[30:31], v[30:31], v[70:71]
	v_pk_mul_f32 v[46:47], v[46:47], v[70:71]
	v_pk_mul_f32 v[62:63], v[62:63], v[70:71]
	v_pk_mul_f32 v[16:17], v[16:17], v[72:73]
	v_pk_mul_f32 v[32:33], v[32:33], v[72:73]
	v_pk_mul_f32 v[48:49], v[48:49], v[72:73]
	v_pk_mul_f32 v[64:65], v[64:65], v[72:73]
.LBB0_1887:
	s_waitcnt vmcnt(1)
	s_add_i32 s49, s31, 0xc000
	s_barrier
	ds_read_b128 v[86:89], v198 offset:32768
	ds_read_b128 v[82:85], v197 offset:32768
	ds_read_b128 v[90:93], v197 offset:36864
	ds_read_b128 v[94:97], v198 offset:36864
	v_lshl_add_u64 v[66:67], v[138:139], 0, s[12:13]
	s_mov_b32 m0, s49
	v_exp_f32_e32 v170, v102
	global_load_lds_dwordx4 v[66:67], off
	v_exp_f32_e32 v171, v103
	v_exp_f32_e32 v172, v104
	v_exp_f32_e32 v173, v105
	v_exp_f32_e32 v176, v106
	v_exp_f32_e32 v177, v107
	v_exp_f32_e32 v178, v108
	v_exp_f32_e32 v179, v109
	v_exp_f32_e32 v110, v110
	v_exp_f32_e32 v111, v111
	v_exp_f32_e32 v112, v112
	v_exp_f32_e32 v113, v113
	s_waitcnt lgkmcnt(2)
	v_mfma_f32_32x32x64_f8f6f4 v[66:81], v[82:89], v[154:161], 0
	ds_read_b128 v[82:85], v195 offset:32768
	ds_read_b128 v[86:89], v196 offset:32768
	v_exp_f32_e32 v114, v114
	v_exp_f32_e32 v115, v115
	v_exp_f32_e32 v116, v116
	v_exp_f32_e32 v117, v117
	s_waitcnt lgkmcnt(2)
	v_mfma_f32_32x32x64_f8f6f4 v[130:145], v[90:97], v[154:161], 0
	ds_read_b128 v[90:93], v195 offset:36864
	ds_read_b128 v[94:97], v196 offset:36864
	v_exp_f32_e32 v118, v118
	v_exp_f32_e32 v119, v119
	v_exp_f32_e32 v120, v120
	v_exp_f32_e32 v121, v121
	s_waitcnt lgkmcnt(2)
	v_mfma_f32_32x32x64_f8f6f4 v[66:81], v[82:89], v[146:153], v[66:81]
	v_exp_f32_e32 v122, v122
	v_exp_f32_e32 v123, v123
	v_exp_f32_e32 v124, v124
	v_exp_f32_e32 v125, v125
	s_waitcnt lgkmcnt(0)
	v_mfma_f32_32x32x64_f8f6f4 v[130:145], v[90:97], v[146:153], v[130:145]
	ds_read_b64_tr_b8 v[82:83], v188 offset:0
	ds_read_b64_tr_b8 v[84:85], v188 offset:0x800
	ds_read_b64_tr_b8 v[86:87], v188 offset:0x1000
	v_exp_f32_e32 v126, v126
	v_exp_f32_e32 v127, v127
	ds_read_b64_tr_b8 v[88:89], v188 offset:0x1800
	v_cvt_pk_fp8_f32 v102, v98, v99
	v_exp_f32_e32 v128, v128
	v_exp_f32_e32 v129, v129
	v_cvt_pk_fp8_f32 v106, v114, v115
	v_cvt_pk_fp8_f32 v103, v170, v171
	v_cvt_pk_fp8_f32 v107, v118, v119
	v_cvt_pk_fp8_f32 v104, v176, v177
	v_cvt_pk_fp8_f32 v108, v122, v123
	v_cvt_pk_fp8_f32 v105, v110, v111
	v_cvt_pk_fp8_f32 v109, v126, v127
	ds_read_b64_tr_b8 v[90:91], v187 offset:0
	ds_read_b64_tr_b8 v[92:93], v187 offset:0x800
	ds_read_b64_tr_b8 v[94:95], v187 offset:0x1000
	ds_read_b64_tr_b8 v[96:97], v187 offset:0x1800
	v_cvt_pk_fp8_f32 v102, v100, v101 op_sel:[0,0,1]
	v_cvt_pk_fp8_f32 v106, v116, v117 op_sel:[0,0,1]
	v_cvt_pk_fp8_f32 v103, v172, v173 op_sel:[0,0,1]
	v_cvt_pk_fp8_f32 v107, v120, v121 op_sel:[0,0,1]
	v_cvt_pk_fp8_f32 v104, v178, v179 op_sel:[0,0,1]
	v_cvt_pk_fp8_f32 v108, v124, v125 op_sel:[0,0,1]
	v_cvt_pk_fp8_f32 v105, v112, v113 op_sel:[0,0,1]
	v_cvt_pk_fp8_f32 v109, v128, v129 op_sel:[0,0,1]
	s_waitcnt lgkmcnt(4)
	s_mov_b32 m0, s47
	v_mfma_f32_32x32x64_f8f6f4 v[2:17], v[102:109], v[82:89], v[2:17]
	ds_read_b64_tr_b8 v[204:205], v186 offset:0
	ds_read_b64_tr_b8 v[206:207], v186 offset:0x800
	ds_read_b64_tr_b8 v[208:209], v186 offset:0x1000
	ds_read_b64_tr_b8 v[210:211], v186 offset:0x1800
	s_waitcnt lgkmcnt(4)
	s_nop 0
	v_max_f32_e32 v82, v66, v67
	v_max3_f32 v82, v82, v68, v69
	v_max3_f32 v82, v82, v70, v71
	v_max3_f32 v82, v82, v72, v73
	v_max3_f32 v82, v82, v74, v75
	v_max3_f32 v82, v82, v76, v77
	v_max3_f32 v82, v82, v78, v79
	v_max3_f32 v82, v82, v80, v81
	v_max3_f32 v82, v82, v130, v131
	v_max3_f32 v82, v82, v132, v133
	v_max3_f32 v82, v82, v134, v135
	v_max3_f32 v82, v82, v136, v137
	v_max3_f32 v82, v82, v138, v139
	v_max3_f32 v82, v82, v140, v141
	v_max3_f32 v82, v82, v142, v143
	v_max3_f32 v82, v82, v144, v145
	v_mov_b32_e32 v83, v82
	s_nop 1
	v_permlane32_swap_b32_e32 v82, v83
	v_max_f32_e32 v82, v82, v83
	v_sub_f32_e32 v83, v82, v202
	v_cmp_ge_f32_e32 vcc, s38, v83
	s_cmp_eq_u64 vcc, exec
	v_max_f32_e32 v83, v202, v202
	v_max_f32_e32 v203, v83, v82
	s_cselect_b64 vcc, -1, 0
	v_cndmask_b32_e32 v200, v203, v202, vcc
	v_fma_f32 v212, v200, s39, 4.0
	v_mfma_f32_32x32x64_f8f6f4 v[18:33], v[102:109], v[90:97], v[18:33]
	v_pk_add_f32 v[98:99], v[98:99], v[100:101]
	v_pk_fma_f32 v[82:83], v[66:67], s[6:7], v[212:213] op_sel_hi:[1,0,0]
	v_pk_fma_f32 v[66:67], v[130:131], s[6:7], v[212:213] op_sel_hi:[1,0,0]
	ds_read_b64_tr_b8 v[130:131], v185 offset:0
	v_pk_fma_f32 v[84:85], v[68:69], s[6:7], v[212:213] op_sel_hi:[1,0,0]
	v_pk_fma_f32 v[68:69], v[132:133], s[6:7], v[212:213] op_sel_hi:[1,0,0]
	ds_read_b64_tr_b8 v[132:133], v185 offset:0x800
	v_pk_fma_f32 v[86:87], v[70:71], s[6:7], v[212:213] op_sel_hi:[1,0,0]
	v_pk_fma_f32 v[70:71], v[134:135], s[6:7], v[212:213] op_sel_hi:[1,0,0]
	ds_read_b64_tr_b8 v[134:135], v185 offset:0x1000
	v_pk_fma_f32 v[96:97], v[80:81], s[6:7], v[212:213] op_sel_hi:[1,0,0]
	v_pk_fma_f32 v[94:95], v[78:79], s[6:7], v[212:213] op_sel_hi:[1,0,0]
	v_pk_fma_f32 v[92:93], v[76:77], s[6:7], v[212:213] op_sel_hi:[1,0,0]
	v_pk_fma_f32 v[90:91], v[74:75], s[6:7], v[212:213] op_sel_hi:[1,0,0]
	v_pk_fma_f32 v[88:89], v[72:73], s[6:7], v[212:213] op_sel_hi:[1,0,0]
	v_pk_fma_f32 v[80:81], v[144:145], s[6:7], v[212:213] op_sel_hi:[1,0,0]
	v_pk_fma_f32 v[78:79], v[142:143], s[6:7], v[212:213] op_sel_hi:[1,0,0]
	v_pk_fma_f32 v[76:77], v[140:141], s[6:7], v[212:213] op_sel_hi:[1,0,0]
	v_pk_fma_f32 v[74:75], v[138:139], s[6:7], v[212:213] op_sel_hi:[1,0,0]
	v_pk_fma_f32 v[72:73], v[136:137], s[6:7], v[212:213] op_sel_hi:[1,0,0]
	ds_read_b64_tr_b8 v[136:137], v185 offset:0x1800
	s_waitcnt lgkmcnt(4)
	v_pk_add_f32 v[98:99], v[98:99], v[170:171]
	v_mfma_f32_32x32x64_f8f6f4 v[34:49], v[102:109], v[204:211], v[34:49]
	s_waitcnt lgkmcnt(0)
	s_nop 0
	v_exp_f32_e32 v82, v82
	v_exp_f32_e32 v83, v83
	v_exp_f32_e32 v84, v84
	v_exp_f32_e32 v85, v85
	v_mfma_f32_32x32x64_f8f6f4 v[50:65], v[102:109], v[130:137], v[50:65]
	s_barrier
	v_lshl_add_u64 v[102:103], v[174:175], 0, s[14:15]
	global_load_lds_dwordx4 v[102:103], off
	v_pk_add_f32 v[98:99], v[172:173], v[98:99]
	s_nop 0
	v_pk_add_f32 v[98:99], v[176:177], v[98:99]
	s_nop 0
	v_pk_add_f32 v[98:99], v[178:179], v[98:99]
	s_nop 0
	v_pk_add_f32 v[98:99], v[110:111], v[98:99]
	s_nop 0
	v_pk_add_f32 v[98:99], v[112:113], v[98:99]
	s_nop 0
	v_pk_add_f32 v[98:99], v[98:99], v[114:115]
	s_nop 0
	v_pk_add_f32 v[98:99], v[116:117], v[98:99]
	s_nop 0
	v_pk_add_f32 v[98:99], v[118:119], v[98:99]
	s_nop 0
	v_pk_add_f32 v[98:99], v[120:121], v[98:99]
	s_nop 0
	v_pk_add_f32 v[98:99], v[122:123], v[98:99]
	s_nop 0
	v_pk_add_f32 v[98:99], v[124:125], v[98:99]
	s_nop 0
	v_pk_add_f32 v[98:99], v[126:127], v[98:99]
	s_nop 0
	v_pk_add_f32 v[98:99], v[128:129], v[98:99]
	s_nop 0
	v_pk_add_f32 v[98:99], v[98:99], v[98:99] op_sel:[0,1] op_sel_hi:[1,0]
	s_nop 0
	v_sub_f32_e32 v99, v202, v203
	v_mul_f32_e32 v99, 0x3e0293ee, v99
	v_exp_f32_e32 v100, v99
	v_mov_b32_e32 v99, v98
	s_nop 1
	v_permlane32_swap_b32_e32 v98, v99
	v_cndmask_b32_e64 v174, v100, 1.0, vcc
	v_cmp_gt_f32_e32 vcc, 1.0, v174
	s_cbranch_vccz .LBB0_1891
	s_and_saveexec_b64 s[28:29], s[2:3]
	ds_write_b32 v191, v174 offset:128
	s_or_b64 exec, exec, s[28:29]
	s_waitcnt lgkmcnt(0)
	s_nop 15
	s_nop 7
	ds_read2_b32 v[100:101], v189 offset0:32 offset1:33
	ds_read2_b32 v[102:103], v189 offset0:34 offset1:35
	ds_read2_b32 v[104:105], v189 offset0:40 offset1:41
	ds_read2_b32 v[106:107], v189 offset0:42 offset1:43
	s_waitcnt lgkmcnt(0)
	v_pk_mul_f32 v[2:3], v[100:101], v[2:3]
	v_pk_mul_f32 v[18:19], v[100:101], v[18:19]
	v_pk_mul_f32 v[34:35], v[100:101], v[34:35]
	v_pk_mul_f32 v[50:51], v[100:101], v[50:51]
	v_pk_mul_f32 v[4:5], v[4:5], v[102:103]
	v_pk_mul_f32 v[20:21], v[20:21], v[102:103]
	v_pk_mul_f32 v[36:37], v[36:37], v[102:103]
	v_pk_mul_f32 v[52:53], v[52:53], v[102:103]
	v_pk_mul_f32 v[6:7], v[6:7], v[104:105]
	v_pk_mul_f32 v[22:23], v[22:23], v[104:105]
	v_pk_mul_f32 v[38:39], v[38:39], v[104:105]
	v_pk_mul_f32 v[54:55], v[54:55], v[104:105]
	v_pk_mul_f32 v[8:9], v[8:9], v[106:107]
	v_pk_mul_f32 v[24:25], v[24:25], v[106:107]
	v_pk_mul_f32 v[40:41], v[40:41], v[106:107]
	ds_read2_b32 v[100:101], v189 offset0:48 offset1:49
	v_pk_mul_f32 v[56:57], v[56:57], v[106:107]
	ds_read2_b32 v[102:103], v189 offset0:50 offset1:51
	ds_read2_b32 v[104:105], v189 offset0:56 offset1:57
	ds_read2_b32 v[106:107], v189 offset0:58 offset1:59
	s_waitcnt lgkmcnt(0)
	v_pk_mul_f32 v[10:11], v[10:11], v[100:101]
	v_pk_mul_f32 v[26:27], v[26:27], v[100:101]
	v_pk_mul_f32 v[42:43], v[42:43], v[100:101]
	v_pk_mul_f32 v[58:59], v[58:59], v[100:101]
	v_pk_mul_f32 v[12:13], v[12:13], v[102:103]
	v_pk_mul_f32 v[28:29], v[28:29], v[102:103]
	v_pk_mul_f32 v[44:45], v[44:45], v[102:103]
	v_pk_mul_f32 v[60:61], v[60:61], v[102:103]
	v_pk_mul_f32 v[14:15], v[14:15], v[104:105]
	v_pk_mul_f32 v[30:31], v[30:31], v[104:105]
	v_pk_mul_f32 v[46:47], v[46:47], v[104:105]
	v_pk_mul_f32 v[62:63], v[62:63], v[104:105]
	v_pk_mul_f32 v[16:17], v[16:17], v[106:107]
	v_pk_mul_f32 v[32:33], v[32:33], v[106:107]
	v_pk_mul_f32 v[48:49], v[48:49], v[106:107]
	v_pk_mul_f32 v[64:65], v[64:65], v[106:107]

.LBB0_1893:
	ds_read_b128 v[90:93], v198 offset:49152
	ds_read_b128 v[86:89], v197 offset:49152
	ds_read_b128 v[130:133], v197 offset:53248
	ds_read_b128 v[134:137], v198 offset:53248
	v_pk_add_f32 v[94:95], v[82:83], v[84:85]
	s_waitcnt lgkmcnt(2)
	v_mfma_f32_32x32x64_f8f6f4 v[114:129], v[86:93], v[154:161], 0
	s_nop 0
	v_exp_f32_e32 v66, v66
	v_exp_f32_e32 v67, v67
	v_exp_f32_e32 v68, v68
	v_exp_f32_e32 v69, v69
	ds_read_b128 v[86:89], v195 offset:49152
	ds_read_b128 v[90:93], v196 offset:49152
	s_waitcnt lgkmcnt(2)
	v_mfma_f32_32x32x64_f8f6f4 v[98:113], v[130:137], v[154:161], 0
	ds_read_b128 v[130:133], v195 offset:53248
	ds_read_b128 v[134:137], v196 offset:53248
	v_exp_f32_e32 v70, v70
	v_exp_f32_e32 v71, v71
	v_exp_f32_e32 v72, v72
	v_exp_f32_e32 v73, v73
	v_pk_add_f32 v[94:95], v[94:95], v[172:173]
	s_waitcnt lgkmcnt(2)
	v_mfma_f32_32x32x64_f8f6f4 v[114:129], v[86:93], v[146:153], v[114:129]
	v_pk_add_f32 v[94:95], v[94:95], v[170:171]
	v_exp_f32_e32 v74, v74
	v_exp_f32_e32 v75, v75
	v_exp_f32_e32 v76, v76
	v_exp_f32_e32 v77, v77
	v_pk_add_f32 v[86:87], v[94:95], v[168:169]
	s_waitcnt lgkmcnt(0)
	v_mfma_f32_32x32x64_f8f6f4 v[98:113], v[130:137], v[146:153], v[98:113]
	v_mov_b32_e32 v134, v163
	v_pk_add_f32 v[86:87], v[86:87], v[140:141]
	v_cvt_pk_fp8_f32 v134, v66, v67
	v_pk_add_f32 v[86:87], v[86:87], v[144:145]
	v_mov_b32_e32 v135, v163
	v_exp_f32_e32 v78, v78
	v_exp_f32_e32 v79, v79
	v_pk_add_f32 v[86:87], v[86:87], v[142:143]
	v_cvt_pk_fp8_f32 v135, v70, v71
	v_pk_add_f32 v[86:87], v[86:87], v[66:67]
	v_mov_b32_e32 v136, v163
	ds_read_b64_tr_b8 v[66:67], v194 offset:0
	v_pk_add_f32 v[86:87], v[68:69], v[86:87]
	v_cvt_pk_fp8_f32 v134, v68, v69 op_sel:[0,0,1]
	v_cvt_pk_fp8_f32 v136, v74, v75
	ds_read_b64_tr_b8 v[68:69], v194 offset:0x800
	v_pk_add_f32 v[86:87], v[70:71], v[86:87]
	v_mov_b32_e32 v137, v163
	ds_read_b64_tr_b8 v[70:71], v194 offset:0x1000
	v_exp_f32_e32 v80, v80
	v_exp_f32_e32 v81, v81
	v_pk_add_f32 v[86:87], v[72:73], v[86:87]
	v_mov_b32_e32 v130, v163
	v_mov_b32_e32 v131, v163
	v_cvt_pk_fp8_f32 v135, v72, v73 op_sel:[0,0,1]
	v_mov_b32_e32 v132, v163
	v_mov_b32_e32 v133, v163
	v_cvt_pk_fp8_f32 v137, v78, v79
	ds_read_b64_tr_b8 v[72:73], v194 offset:0x1800
	v_pk_add_f32 v[86:87], v[74:75], v[86:87]
	v_cvt_pk_fp8_f32 v130, v82, v83
	v_cvt_pk_fp8_f32 v131, v172, v173
	v_cvt_pk_fp8_f32 v132, v168, v169
	v_cvt_pk_fp8_f32 v133, v144, v145
	ds_read_b64_tr_b8 v[74:75], v193 offset:0
	v_pk_add_f32 v[86:87], v[76:77], v[86:87]
	v_cvt_pk_fp8_f32 v136, v76, v77 op_sel:[0,0,1]
	ds_read_b64_tr_b8 v[76:77], v193 offset:0x800
	v_pk_add_f32 v[86:87], v[78:79], v[86:87]
	ds_read_b64_tr_b8 v[78:79], v193 offset:0x1000
	v_cvt_pk_fp8_f32 v137, v80, v81 op_sel:[0,0,1]
	v_pk_add_f32 v[86:87], v[80:81], v[86:87]
	ds_read_b64_tr_b8 v[80:81], v193 offset:0x1800
	v_cvt_pk_fp8_f32 v130, v84, v85 op_sel:[0,0,1]
	v_cvt_pk_fp8_f32 v131, v170, v171 op_sel:[0,0,1]
	v_cvt_pk_fp8_f32 v132, v140, v141 op_sel:[0,0,1]
	v_cvt_pk_fp8_f32 v133, v142, v143 op_sel:[0,0,1]
	s_waitcnt lgkmcnt(4)
	v_pk_add_f32 v[138:139], v[86:87], v[86:87] op_sel:[0,1] op_sel_hi:[1,0]
	v_mfma_f32_32x32x64_f8f6f4 v[2:17], v[130:137], v[66:73], v[2:17]
	ds_read_b64_tr_b8 v[140:141], v192 offset:0
	ds_read_b64_tr_b8 v[142:143], v192 offset:0x800
	ds_read_b64_tr_b8 v[144:145], v192 offset:0x1000
	ds_read_b64_tr_b8 v[146:147], v192 offset:0x1800
	s_waitcnt lgkmcnt(4)
	s_nop 0
	v_max_f32_e32 v66, v114, v115
	v_max3_f32 v66, v66, v116, v117
	v_max3_f32 v66, v66, v118, v119
	v_max3_f32 v66, v66, v120, v121
	v_max3_f32 v66, v66, v122, v123
	v_max3_f32 v66, v66, v124, v125
	v_max3_f32 v66, v66, v126, v127
	v_max3_f32 v66, v66, v128, v129
	v_max3_f32 v66, v66, v98, v99
	v_max3_f32 v66, v66, v100, v101
	v_max3_f32 v66, v66, v102, v103
	v_max3_f32 v66, v66, v104, v105
	v_max3_f32 v66, v66, v106, v107
	v_max3_f32 v66, v66, v108, v109
	v_max3_f32 v66, v66, v110, v111
	v_max3_f32 v66, v66, v112, v113
	v_mov_b32_e32 v67, v66
	s_nop 1
	v_permlane32_swap_b32_e32 v66, v67
	v_max_f32_e32 v66, v66, v67
	v_sub_f32_e32 v67, v66, v200
	v_cmp_ge_f32_e32 vcc, s38, v67
	s_cmp_eq_u64 vcc, exec
	v_max_f32_e32 v66, v200, v66
	s_cselect_b64 vcc, -1, 0
	v_sub_f32_e32 v67, v200, v66
	v_cndmask_b32_e32 v66, v66, v200, vcc
	v_mul_f32_e32 v83, 0x3e0293ee, v67
	v_fma_f32 v82, v66, s39, 4.0
	v_mfma_f32_32x32x64_f8f6f4 v[18:33], v[130:137], v[74:81], v[18:33]
	v_mov_b32_e32 v139, v138
	v_pk_fma_f32 v[84:85], v[100:101], s[6:7], v[82:83] op_sel_hi:[1,0,0]
	ds_read_b64_tr_b8 v[100:101], v190 offset:0
	v_pk_fma_f32 v[66:67], v[114:115], s[6:7], v[82:83] op_sel_hi:[1,0,0]
	v_exp_f32_e32 v114, v83
	v_pk_fma_f32 v[86:87], v[102:103], s[6:7], v[82:83] op_sel_hi:[1,0,0]
	ds_read_b64_tr_b8 v[102:103], v190 offset:0x800
	v_pk_fma_f32 v[88:89], v[104:105], s[6:7], v[82:83] op_sel_hi:[1,0,0]
	ds_read_b64_tr_b8 v[104:105], v190 offset:0x1000
	v_pk_fma_f32 v[80:81], v[128:129], s[6:7], v[82:83] op_sel_hi:[1,0,0]
	v_pk_fma_f32 v[78:79], v[126:127], s[6:7], v[82:83] op_sel_hi:[1,0,0]
	v_pk_fma_f32 v[76:77], v[124:125], s[6:7], v[82:83] op_sel_hi:[1,0,0]
	v_pk_fma_f32 v[74:75], v[122:123], s[6:7], v[82:83] op_sel_hi:[1,0,0]
	v_pk_fma_f32 v[72:73], v[120:121], s[6:7], v[82:83] op_sel_hi:[1,0,0]
	v_pk_fma_f32 v[70:71], v[118:119], s[6:7], v[82:83] op_sel_hi:[1,0,0]
	v_pk_fma_f32 v[68:69], v[116:117], s[6:7], v[82:83] op_sel_hi:[1,0,0]
	v_pk_fma_f32 v[96:97], v[112:113], s[6:7], v[82:83] op_sel_hi:[1,0,0]
	v_pk_fma_f32 v[94:95], v[110:111], s[6:7], v[82:83] op_sel_hi:[1,0,0]
	v_pk_fma_f32 v[92:93], v[108:109], s[6:7], v[82:83] op_sel_hi:[1,0,0]
	v_pk_fma_f32 v[90:91], v[106:107], s[6:7], v[82:83] op_sel_hi:[1,0,0]
	v_pk_fma_f32 v[82:83], v[98:99], s[6:7], v[82:83] op_sel_hi:[1,0,0]
	ds_read_b64_tr_b8 v[106:107], v190 offset:0x1800
	s_waitcnt lgkmcnt(4)
	v_cndmask_b32_e64 v98, v114, 1.0, vcc
	v_mfma_f32_32x32x64_f8f6f4 v[34:49], v[130:137], v[140:147], v[34:49]
	s_waitcnt lgkmcnt(0)
	v_permlane32_swap_b32_e32 v138, v139
	v_exp_f32_e32 v66, v66
	v_exp_f32_e32 v67, v67
	v_exp_f32_e32 v68, v68
	v_exp_f32_e32 v69, v69
	v_cmp_gt_f32_e32 vcc, 1.0, v98
	v_mfma_f32_32x32x64_f8f6f4 v[50:65], v[130:137], v[100:107], v[50:65]
	s_cbranch_vccz .LBB0_1897
	s_and_saveexec_b64 s[28:29], s[2:3]
	ds_write_b32 v191, v98 offset:128
	s_or_b64 exec, exec, s[28:29]
	s_waitcnt lgkmcnt(0)
	s_nop 15
	s_nop 7
	ds_read2_b32 v[100:101], v189 offset0:32 offset1:33
	ds_read2_b32 v[102:103], v189 offset0:34 offset1:35
	ds_read2_b32 v[104:105], v189 offset0:40 offset1:41
	ds_read2_b32 v[106:107], v189 offset0:42 offset1:43
	s_waitcnt lgkmcnt(0)
	v_pk_mul_f32 v[2:3], v[100:101], v[2:3]
	v_pk_mul_f32 v[18:19], v[100:101], v[18:19]
	v_pk_mul_f32 v[34:35], v[100:101], v[34:35]
	v_pk_mul_f32 v[50:51], v[100:101], v[50:51]
	v_pk_mul_f32 v[4:5], v[4:5], v[102:103]
	v_pk_mul_f32 v[20:21], v[20:21], v[102:103]
	v_pk_mul_f32 v[36:37], v[36:37], v[102:103]
	v_pk_mul_f32 v[52:53], v[52:53], v[102:103]
	v_pk_mul_f32 v[6:7], v[6:7], v[104:105]
	v_pk_mul_f32 v[22:23], v[22:23], v[104:105]
	v_pk_mul_f32 v[38:39], v[38:39], v[104:105]
	v_pk_mul_f32 v[54:55], v[54:55], v[104:105]
	v_pk_mul_f32 v[8:9], v[8:9], v[106:107]
	v_pk_mul_f32 v[24:25], v[24:25], v[106:107]
	v_pk_mul_f32 v[40:41], v[40:41], v[106:107]
	ds_read2_b32 v[100:101], v189 offset0:48 offset1:49
	v_pk_mul_f32 v[56:57], v[56:57], v[106:107]
	ds_read2_b32 v[102:103], v189 offset0:50 offset1:51
	ds_read2_b32 v[104:105], v189 offset0:56 offset1:57
	ds_read2_b32 v[106:107], v189 offset0:58 offset1:59
	s_waitcnt lgkmcnt(0)
	v_pk_mul_f32 v[10:11], v[10:11], v[100:101]
	v_pk_mul_f32 v[26:27], v[26:27], v[100:101]
	v_pk_mul_f32 v[42:43], v[42:43], v[100:101]
	v_pk_mul_f32 v[58:59], v[58:59], v[100:101]
	v_pk_mul_f32 v[12:13], v[12:13], v[102:103]
	v_pk_mul_f32 v[28:29], v[28:29], v[102:103]
	v_pk_mul_f32 v[44:45], v[44:45], v[102:103]
	v_pk_mul_f32 v[60:61], v[60:61], v[102:103]
	v_pk_mul_f32 v[14:15], v[14:15], v[104:105]
	v_pk_mul_f32 v[30:31], v[30:31], v[104:105]
	v_pk_mul_f32 v[46:47], v[46:47], v[104:105]
	v_pk_mul_f32 v[62:63], v[62:63], v[104:105]
	v_pk_mul_f32 v[16:17], v[16:17], v[106:107]
	v_pk_mul_f32 v[32:33], v[32:33], v[106:107]
	v_pk_mul_f32 v[48:49], v[48:49], v[106:107]
	v_pk_mul_f32 v[64:65], v[64:65], v[106:107]

.LBB0_1913:
	v_lshrrev_b32_e32 v5, 3, v37
	v_and_b32_e32 v54, 4, v5
	v_and_or_b32 v5, s17, 32, v36
	v_med3_i32 v6, v5, 8, 56
	v_sub_u32_e32 v133, v6, v54
	v_xad_u32 v198, v5, 63, v54
	v_and_b32_e32 v5, 8, v37
	v_bfe_u32 v6, v37, 1, 2
	v_or3_b32 v5, v6, v5, v54
	v_lshlrev_b32_e32 v6, 3, v37
	v_bfe_u32 v55, v37, 1, 3
	v_lshlrev_b32_e32 v5, 7, v5
	v_and_b32_e32 v6, 8, v6
	v_and_b32_e32 v56, 1, v4
	v_add3_u32 v57, v6, s67, v5
	v_bitop3_b32 v4, v4, v55, 1 bitop3:0x6c
	v_lshlrev_b32_e32 v46, 3, v36
	s_lshl_b32 s1, s14, 2
	s_ashr_i32 s33, s15, 7
	v_lshl_add_u32 v200, v4, 4, v57
	v_bitop3_b32 v4, v46, v2, s18 bitop3:0x6c
	v_lshl_add_u32 v47, v36, 7, s67
	s_add_i32 s7, s33, s1
	s_waitcnt lgkmcnt(0)
	v_add_u32_e32 v203, v47, v4
	v_or_b32_e32 v4, 16, v2
	v_med3_i32 v7, s7, 4, 28
	s_barrier
	v_bitop3_b32 v4, v46, v4, s18 bitop3:0x6c
	v_readfirstlane_b32 s74, v7
	v_add_u32_e32 v204, v47, v4
	ds_read_b128 v[4:7], v203 offset:32768
	ds_read_b128 v[38:41], v203 offset:36864
	ds_read_b128 v[8:11], v204 offset:32768
	ds_read_b128 v[42:45], v204 offset:36864
	v_bitop3_b32 v12, v56, v55, 2 bitop3:0x36
	v_lshl_add_u32 v202, v12, 4, v57
	v_bitop3_b32 v12, v56, v55, 4 bitop3:0x36
	v_lshl_add_u32 v199, v12, 4, v57
	s_waitcnt vmcnt(0) lgkmcnt(0)
	v_mfma_f32_32x32x64_f8f6f4 v[20:35], v[4:11], v[172:179], 0
	v_mfma_f32_32x32x64_f8f6f4 v[4:19], v[38:45], v[172:179], 0
	v_or_b32_e32 v38, 64, v2
	v_bitop3_b32 v38, v46, v38, s18 bitop3:0x6c
	v_or_b32_e32 v2, 0x50, v2
	v_add_u32_e32 v205, v47, v38
	v_bitop3_b32 v2, v46, v2, s18 bitop3:0x6c
	v_add_u32_e32 v206, v47, v2
	ds_read_b128 v[38:41], v205 offset:32768
	ds_read_b128 v[46:49], v205 offset:36864
	ds_read_b128 v[42:45], v206 offset:32768
	ds_read_b128 v[50:53], v206 offset:36864
	v_bitop3_b32 v2, v56, v55, 6 bitop3:0x36
	s_waitcnt lgkmcnt(1)
	v_mfma_f32_32x32x64_f8f6f4 v[20:35], v[38:45], v[164:171], v[20:35]
	s_waitcnt lgkmcnt(0)
	v_mfma_f32_32x32x64_f8f6f4 v[4:19], v[46:53], v[164:171], v[4:19]
	v_lshl_add_u32 v201, v2, 4, v57
	v_and_b32_e32 v189, 63, v37
	s_nop 15
	s_nop 7
	v_writelane_b32 v252, s17, 24
	v_max_f32_e32 v2, v20, v21
	v_max3_f32 v2, v2, v22, v23
	v_max3_f32 v2, v2, v24, v25
	v_max3_f32 v2, v2, v26, v27
	v_max3_f32 v2, v2, v28, v29
	v_max3_f32 v2, v2, v30, v31
	v_max3_f32 v2, v2, v32, v33
	v_max3_f32 v2, v2, v34, v35
	v_max3_f32 v2, v2, v4, v5
	v_writelane_b32 v252, s7, 25
	s_and_b32 s7, s16, 7
	v_max3_f32 v2, v2, v6, v7
	s_add_i32 s93, s74, -4
	s_lshl_b32 s70, s7, 2
	s_add_i32 s1, s1, -4
	v_max3_f32 v2, v2, v8, v9
	s_cmp_eq_u32 s14, 0
	v_max3_f32 v2, v2, v10, v11
	s_cselect_b64 s[8:9], -1, 0
	v_max3_f32 v2, v2, v12, v13
	v_writelane_b32 v252, s16, 23
	s_and_b64 s[16:17], s[8:9], exec
	v_max3_f32 v2, v2, v14, v15
	s_cselect_b32 s1, 0, s1
	s_cmp_eq_u32 s14, 7
	v_max3_f32 v2, v2, v16, v17
	s_cselect_b64 s[16:17], -1, 0
	v_max3_f32 v2, v2, v18, v19
	s_or_b64 s[8:9], s[8:9], s[16:17]
	v_mov_b32_e32 v37, v2
	s_and_b64 s[8:9], s[8:9], exec
	s_nop 0
	v_permlane32_swap_b32_e32 v2, v37
	s_cselect_b32 s78, 12, 16
	s_lshl_b32 s79, s1, 6
	v_max_f32_e32 v37, v37, v37
	v_max_f32_e32 v2, v2, v2
	s_add_i32 s79, s79, s6
	s_and_b32 s6, s15, 0x3fffffc0
	v_max_f32_e32 v2, v2, v37
	s_lshl_b32 s6, s6, 2
	v_add_f32_e32 v37, 0x7149f2ca, v2
	s_add_i32 s71, s71, s6
	v_cmp_ge_f32_e32 vcc, s92, v37
	s_cmp_eq_u64 vcc, exec
	v_max_f32_e32 v2, 0xf149f2ca, v2
	s_cselect_b64 vcc, -1, 0
	v_cndmask_b32_e32 v196, v2, v188, vcc
	s_mov_b32 s6, 0xbe0293ee
	s_add_u32 s2, s12, s2
	v_sub_f32_e32 v38, 0xf149f2ca, v2
	v_fma_f32 v2, v196, s6, 4.0
	s_addc_u32 s3, s13, s3
	s_add_i32 s76, s67, s10
	v_pk_fma_f32 v[100:101], v[4:5], s[80:81], v[2:3] op_sel_hi:[1,0,0]
	v_lshl_add_u64 v[4:5], s[2:3], 0, v[180:181]
	s_mov_b64 s[2:3], 0x420000
	s_add_i32 s95, s76, 0x4000
	v_lshl_add_u64 v[4:5], v[4:5], 0, s[2:3]
	s_mov_b32 m0, s95
	v_fmamk_f32 v20, v20, 0x3e0293ee, v2
	global_load_lds_dwordx4 v[4:5], off
	v_fmamk_f32 v21, v21, 0x3e0293ee, v2
	v_fmamk_f32 v22, v22, 0x3e0293ee, v2
	v_fmamk_f32 v23, v23, 0x3e0293ee, v2
	v_fmamk_f32 v24, v24, 0x3e0293ee, v2
	v_fmamk_f32 v25, v25, 0x3e0293ee, v2
	v_fmamk_f32 v26, v26, 0x3e0293ee, v2
	v_fmamk_f32 v27, v27, 0x3e0293ee, v2
	v_fmamk_f32 v28, v28, 0x3e0293ee, v2
	v_fmamk_f32 v29, v29, 0x3e0293ee, v2
	v_fmamk_f32 v30, v30, 0x3e0293ee, v2
	v_fmamk_f32 v31, v31, 0x3e0293ee, v2
	v_fmamk_f32 v32, v32, 0x3e0293ee, v2
	v_fmamk_f32 v33, v33, 0x3e0293ee, v2
	v_fmamk_f32 v34, v34, 0x3e0293ee, v2
	v_mov_b32_e32 v37, v2
	v_pk_fma_f32 v[114:115], v[18:19], s[80:81], v[2:3] op_sel_hi:[1,0,0]
	v_pk_fma_f32 v[112:113], v[16:17], s[80:81], v[2:3] op_sel_hi:[1,0,0]
	v_pk_fma_f32 v[110:111], v[14:15], s[80:81], v[2:3] op_sel_hi:[1,0,0]
	v_pk_fma_f32 v[108:109], v[12:13], s[80:81], v[2:3] op_sel_hi:[1,0,0]
	v_pk_fma_f32 v[106:107], v[10:11], s[80:81], v[2:3] op_sel_hi:[1,0,0]
	v_pk_fma_f32 v[104:105], v[8:9], s[80:81], v[2:3] op_sel_hi:[1,0,0]
	v_pk_fma_f32 v[102:103], v[6:7], s[80:81], v[2:3] op_sel_hi:[1,0,0]
	v_subrev_co_u32_e64 v2, s[68:69], 9, v133
	v_subrev_u32_e32 v7, 28, v133
	v_cmp_gt_u32_e64 s[36:37], 16, v2
	v_subrev_u32_e32 v2, 41, v133
	v_cmp_gt_u32_e64 s[54:55], 16, v7
	v_add_u32_e32 v7, -1, v133
	v_cmp_gt_u32_e64 s[34:35], 16, v2
	v_subrev_u32_e32 v2, 42, v133
	v_cmp_gt_u32_e64 s[52:53], 16, v7
	v_subrev_u32_e32 v7, 33, v133
	v_cmp_gt_u32_e64 s[28:29], 16, v2
	v_subrev_u32_e32 v2, 43, v133
	v_cmp_gt_u32_e64 s[50:51], 16, v7
	v_add_u32_e32 v7, -2, v133
	v_cmp_gt_u32_e64 s[24:25], 16, v2
	v_subrev_u32_e32 v2, 44, v133
	v_mul_f32_e32 v38, 0x3e0293ee, v38
	v_cmp_gt_u32_e64 s[48:49], 16, v7
	v_subrev_u32_e32 v7, 34, v133
	v_cmp_gt_u32_e64 s[20:21], 16, v2
	v_subrev_u32_e32 v2, 17, v133
	v_exp_f32_e32 v38, v38
	v_cmp_gt_u32_e64 s[46:47], 16, v7
	v_add_u32_e32 v7, -3, v133
	v_cmp_gt_u32_e64 s[18:19], 16, v2
	v_subrev_u32_e32 v2, 18, v133
	v_cmp_gt_u32_e64 s[44:45], 16, v7
	v_subrev_u32_e32 v7, 35, v133
	v_cmp_gt_u32_e64 s[14:15], 16, v2
	v_subrev_u32_e32 v2, 19, v133
	v_fmac_f32_e32 v37, 0x3e0293ee, v35
	v_subrev_u32_e32 v4, 25, v133
	v_subrev_u32_e32 v5, 26, v133
	v_subrev_u32_e32 v6, 27, v133
	v_cmp_gt_u32_e64 s[42:43], 16, v7
	v_add_u32_e32 v7, -4, v133
	v_cmp_gt_u32_e64 s[8:9], 16, v2
	v_subrev_u32_e32 v2, 20, v133
	v_exp_f32_e32 v116, v20
	v_exp_f32_e32 v117, v21
	v_exp_f32_e32 v118, v22
	v_exp_f32_e32 v119, v23
	v_exp_f32_e32 v120, v24
	v_exp_f32_e32 v121, v25
	v_exp_f32_e32 v122, v26
	v_exp_f32_e32 v123, v27
	v_exp_f32_e32 v124, v28
	v_exp_f32_e32 v125, v29
	v_exp_f32_e32 v126, v30
	v_exp_f32_e32 v127, v31
	v_exp_f32_e32 v128, v32
	v_exp_f32_e32 v129, v33
	v_exp_f32_e32 v130, v34
	v_exp_f32_e32 v131, v37
	s_waitcnt vmcnt(1)
	v_cmp_gt_u32_e64 s[66:67], 16, v4
	v_subrev_co_u32_e64 v4, s[64:65], 10, v133
	v_cmp_gt_u32_e64 s[62:63], 16, v5
	v_subrev_co_u32_e64 v5, s[60:61], 11, v133
	v_cmp_gt_u32_e64 s[58:59], 16, v6
	v_subrev_co_u32_e64 v6, s[56:57], 12, v133
	v_cmp_gt_u32_e64 s[40:41], 16, v7
	v_subrev_u32_e32 v7, 36, v133
	v_lshl_add_u64 v[184:185], s[4:5], 0, v[182:183]
	v_cmp_gt_u32_e64 s[4:5], 16, v2
	v_mov_b32_e32 v16, v3
	v_mov_b32_e32 v17, v3
	v_cndmask_b32_e64 v132, v38, 1.0, vcc
	s_barrier
	v_lshl_add_u32 v195, v36, 2, s71
	v_cmp_gt_u32_e64 s[38:39], 16, v7
	v_cmp_gt_u32_e64 s[30:31], 16, v4
	v_cmp_gt_u32_e64 s[26:27], 16, v5
	v_cmp_gt_u32_e64 s[22:23], 16, v6
	v_writelane_b32 v252, s4, 28
	v_lshl_add_u32 v194, v54, 2, s71
	v_mov_b32_e32 v2, v3
	v_mov_b32_e32 v4, v3
	v_mov_b32_e32 v5, v3
	v_mov_b32_e32 v6, v3
	v_mov_b32_e32 v7, v3
	v_mov_b32_e32 v8, v3
	v_mov_b32_e32 v9, v3
	v_mov_b32_e32 v10, v3
	v_mov_b32_e32 v11, v3
	v_mov_b32_e32 v12, v3
	v_mov_b32_e32 v13, v3
	v_mov_b32_e32 v14, v3
	v_mov_b32_e32 v15, v3
	v_mov_b64_e32 v[66:67], v[16:17]
	v_mov_b64_e32 v[50:51], v[16:17]
	v_mov_b64_e32 v[34:35], v[16:17]
	v_writelane_b32 v252, s5, 29
	s_sub_i32 s4, s1, s33
	v_mov_b64_e32 v[64:65], v[14:15]
	v_mov_b64_e32 v[62:63], v[12:13]
	v_mov_b64_e32 v[60:61], v[10:11]
	v_mov_b64_e32 v[58:59], v[8:9]
	v_mov_b64_e32 v[56:57], v[6:7]
	v_mov_b64_e32 v[54:55], v[4:5]
	v_mov_b64_e32 v[52:53], v[2:3]
	v_mov_b64_e32 v[48:49], v[14:15]
	v_mov_b64_e32 v[46:47], v[12:13]
	v_mov_b64_e32 v[44:45], v[10:11]
	v_mov_b64_e32 v[42:43], v[8:9]
	v_mov_b64_e32 v[40:41], v[6:7]
	v_mov_b64_e32 v[38:39], v[4:5]
	v_mov_b64_e32 v[36:37], v[2:3]
	v_mov_b64_e32 v[32:33], v[14:15]
	v_mov_b64_e32 v[30:31], v[12:13]
	v_mov_b64_e32 v[28:29], v[10:11]
	v_mov_b64_e32 v[26:27], v[8:9]
	v_mov_b64_e32 v[24:25], v[6:7]
	v_mov_b64_e32 v[22:23], v[4:5]
	v_mov_b64_e32 v[20:21], v[2:3]
	v_mov_b64_e32 v[18:19], v[16:17]
	s_mov_b32 s75, 2
	s_add_i32 s74, s74, 4
	v_cmp_gt_u32_e64 s[2:3], 32, v189
	v_cmp_lt_u32_e64 s[16:17], 48, v133
	v_cmp_lt_u32_e64 s[10:11], 49, v133
	v_cmp_lt_u32_e64 s[6:7], 50, v133
	v_lshl_add_u64 v[186:187], s[12:13], 0, v[180:181]
	v_add_u32_e32 v193, 0x4000, v200
	v_add_u32_e32 v192, 0x4000, v202
	v_add_u32_e32 v191, 0x4000, v199
	v_add_u32_e32 v190, 0x4000, v201
	v_lshl_add_u32 v207, v198, 2, s77
	s_sub_i32 s33, s4, s70
	v_mov_b32_e32 v197, 0
	s_movk_i32 s77, 0x80
	v_mov_b64_e32 v[16:17], v[14:15]
	v_mov_b64_e32 v[14:15], v[12:13]
	v_mov_b64_e32 v[12:13], v[10:11]
	v_mov_b64_e32 v[10:11], v[8:9]
	v_mov_b64_e32 v[8:9], v[6:7]
	v_mov_b64_e32 v[6:7], v[4:5]
	v_mov_b64_e32 v[4:5], v[2:3]
	v_cmp_lt_u32_e64 s[12:13], 51, v133
	v_writelane_b32 v252, s71, 30
	s_branch .LBB0_1916

.LBB0_1918:
	s_cmp_lt_u32 s82, 5
	s_cselect_b64 vcc, -1, 0
	s_add_i32 s4, s81, -6
	s_cmp_ge_i32 s4, s93
	s_cselect_b64 s[96:97], -1, 0
	s_cmp_lt_i32 s4, s74
	s_cselect_b64 s[4:5], -1, 0
	s_and_b64 s[4:5], s[96:97], s[4:5]
	s_or_b64 s[4:5], vcc, s[4:5]
	s_andn2_b64 vcc, exec, s[4:5]
	s_cbranch_vccnz .LBB0_1920
	v_add_f32_e32 v2, 0, v116
	v_add_f32_e32 v2, v117, v2
	v_add_f32_e32 v2, v118, v2
	v_add_f32_e32 v2, v119, v2
	v_add_f32_e32 v2, v120, v2
	v_add_f32_e32 v2, v121, v2
	v_add_f32_e32 v2, v122, v2
	v_add_f32_e32 v2, v123, v2
	v_add_f32_e32 v2, v124, v2
	v_add_f32_e32 v2, v125, v2
	v_add_f32_e32 v2, v126, v2
	v_add_f32_e32 v2, v127, v2
	v_exp_f32_e32 v100, v100
	v_add_f32_e32 v2, v128, v2
	v_exp_f32_e32 v101, v101
	v_add_f32_e32 v2, v129, v2
	v_exp_f32_e32 v102, v102
	v_add_f32_e32 v2, v130, v2
	v_exp_f32_e32 v103, v103
	v_add_f32_e32 v2, v131, v2
	v_exp_f32_e32 v104, v104
	v_add_f32_e32 v2, v100, v2
	v_exp_f32_e32 v105, v105
	v_add_f32_e32 v2, v101, v2
	v_exp_f32_e32 v106, v106
	v_add_f32_e32 v2, v102, v2
	v_exp_f32_e32 v107, v107
	v_add_f32_e32 v2, v103, v2
	v_exp_f32_e32 v108, v108
	v_add_f32_e32 v2, v104, v2
	v_exp_f32_e32 v109, v109
	v_add_f32_e32 v2, v105, v2
	v_exp_f32_e32 v110, v110
	v_add_f32_e32 v2, v106, v2
	v_exp_f32_e32 v111, v111
	v_add_f32_e32 v2, v107, v2
	v_exp_f32_e32 v112, v112
	v_add_f32_e32 v2, v108, v2
	v_exp_f32_e32 v113, v113
	v_add_f32_e32 v2, v109, v2
	v_exp_f32_e32 v114, v114
	v_add_f32_e32 v2, v110, v2
	v_exp_f32_e32 v115, v115
	v_add_f32_e32 v2, v111, v2
	v_add_f32_e32 v2, v112, v2
	v_add_f32_e32 v2, v113, v2
	v_add_f32_e32 v2, v114, v2
	v_add_f32_e32 v2, v115, v2
	v_mov_b32_e32 v133, v2
	s_nop 1
	v_permlane32_swap_b32_e32 v2, v133
	v_add_f32_e32 v2, v2, v133
	v_fmac_f32_e32 v2, v197, v132
	v_cvt_pk_fp8_f32 v132, v116, v117
	v_cvt_pk_fp8_f32 v136, v100, v101
	v_cvt_pk_fp8_f32 v133, v120, v121
	v_cvt_pk_fp8_f32 v137, v104, v105
	v_cvt_pk_fp8_f32 v134, v124, v125
	v_cvt_pk_fp8_f32 v138, v108, v109
	v_cvt_pk_fp8_f32 v135, v128, v129
	v_cvt_pk_fp8_f32 v139, v112, v113
	v_cvt_pk_fp8_f32 v132, v118, v119 op_sel:[0,0,1]
	v_cvt_pk_fp8_f32 v136, v102, v103 op_sel:[0,0,1]
	v_cvt_pk_fp8_f32 v133, v122, v123 op_sel:[0,0,1]
	v_cvt_pk_fp8_f32 v137, v106, v107 op_sel:[0,0,1]
	v_cvt_pk_fp8_f32 v134, v126, v127 op_sel:[0,0,1]
	v_cvt_pk_fp8_f32 v138, v110, v111 op_sel:[0,0,1]
	v_cvt_pk_fp8_f32 v135, v130, v131 op_sel:[0,0,1]
	v_cvt_pk_fp8_f32 v139, v114, v115 op_sel:[0,0,1]
	ds_read_b64_tr_b8 v[140:141], v200 offset:0
	ds_read_b64_tr_b8 v[142:143], v200 offset:0x800
	ds_read_b64_tr_b8 v[144:145], v200 offset:0x1000
	ds_read_b64_tr_b8 v[146:147], v200 offset:0x1800
	s_waitcnt lgkmcnt(0)
	s_nop 0
	v_mfma_f32_32x32x64_f8f6f4 v[52:67], v[132:139], v[140:147], v[52:67]
	ds_read_b64_tr_b8 v[140:141], v202 offset:0
	ds_read_b64_tr_b8 v[142:143], v202 offset:0x800
	ds_read_b64_tr_b8 v[144:145], v202 offset:0x1000
	ds_read_b64_tr_b8 v[146:147], v202 offset:0x1800
	s_waitcnt lgkmcnt(0)
	s_nop 0
	v_mfma_f32_32x32x64_f8f6f4 v[36:51], v[132:139], v[140:147], v[36:51]
	ds_read_b64_tr_b8 v[140:141], v199 offset:0
	ds_read_b64_tr_b8 v[142:143], v199 offset:0x800
	ds_read_b64_tr_b8 v[144:145], v199 offset:0x1000
	ds_read_b64_tr_b8 v[146:147], v199 offset:0x1800
	s_waitcnt lgkmcnt(0)
	s_nop 0
	v_mfma_f32_32x32x64_f8f6f4 v[20:35], v[132:139], v[140:147], v[20:35]
	ds_read_b64_tr_b8 v[140:141], v201 offset:0
	ds_read_b64_tr_b8 v[142:143], v201 offset:0x800
	ds_read_b64_tr_b8 v[144:145], v201 offset:0x1000
	ds_read_b64_tr_b8 v[146:147], v201 offset:0x1800
	s_waitcnt lgkmcnt(0)
	s_nop 0
	v_mfma_f32_32x32x64_f8f6f4 v[4:19], v[132:139], v[140:147], v[4:19]
	v_mov_b32_e32 v197, v2
	s_nop 15
	s_nop 7

.LBB0_1987:
	v_max_f32_e32 v2, v84, v85
	v_max3_f32 v2, v2, v86, v87
	v_max3_f32 v2, v2, v88, v89
	v_max3_f32 v2, v2, v90, v91
	v_max3_f32 v2, v2, v92, v93
	v_max3_f32 v2, v2, v94, v95
	v_max3_f32 v2, v2, v96, v97
	v_max3_f32 v2, v2, v98, v99
	v_max3_f32 v2, v2, v68, v69
	v_max3_f32 v2, v2, v70, v71
	v_max3_f32 v2, v2, v72, v73
	v_max3_f32 v2, v2, v74, v75
	v_max3_f32 v2, v2, v76, v77
	v_max3_f32 v2, v2, v78, v79
	v_max3_f32 v2, v2, v80, v81
	v_max3_f32 v2, v2, v82, v83
	v_mov_b32_e32 v132, v2
	s_nop 1
	v_permlane32_swap_b32_e32 v2, v132
	v_max_f32_e32 v2, v2, v132
	v_sub_f32_e32 v132, v2, v196
	v_cmp_ge_f32_e32 vcc, s92, v132
	s_cmp_eq_u64 vcc, exec
	v_max_f32_e32 v132, v196, v196
	s_cselect_b64 vcc, -1, 0
	v_max_f32_e32 v132, v132, v2
	v_sub_f32_e32 v2, v196, v132
	v_cndmask_b32_e32 v196, v132, v196, vcc
	s_mov_b32 s4, 0xbe0293ee
	v_fma_f32 v132, v196, s4, 4.0
	v_mul_f32_e32 v2, 0x3e0293ee, v2
	v_mov_b32_e32 v133, v132
	v_exp_f32_e32 v2, v2
	v_fmamk_f32 v84, v84, 0x3e0293ee, v132
	v_fmamk_f32 v85, v85, 0x3e0293ee, v132
	v_fmamk_f32 v86, v86, 0x3e0293ee, v132
	v_fmamk_f32 v87, v87, 0x3e0293ee, v132
	v_fmamk_f32 v88, v88, 0x3e0293ee, v132
	v_fmamk_f32 v89, v89, 0x3e0293ee, v132
	v_fmamk_f32 v90, v90, 0x3e0293ee, v132
	v_fmamk_f32 v91, v91, 0x3e0293ee, v132
	v_fmamk_f32 v92, v92, 0x3e0293ee, v132
	v_fmamk_f32 v93, v93, 0x3e0293ee, v132
	v_fmamk_f32 v94, v94, 0x3e0293ee, v132
	v_fmamk_f32 v95, v95, 0x3e0293ee, v132
	v_fmamk_f32 v96, v96, 0x3e0293ee, v132
	v_fmamk_f32 v97, v97, 0x3e0293ee, v132
	v_fmamk_f32 v98, v98, 0x3e0293ee, v132
	v_fmac_f32_e32 v133, 0x3e0293ee, v99
	v_exp_f32_e32 v84, v84
	v_exp_f32_e32 v85, v85
	v_exp_f32_e32 v86, v86
	v_exp_f32_e32 v87, v87
	v_exp_f32_e32 v88, v88
	v_exp_f32_e32 v89, v89
	v_exp_f32_e32 v90, v90
	v_exp_f32_e32 v91, v91
	v_exp_f32_e32 v92, v92
	v_exp_f32_e32 v93, v93
	v_exp_f32_e32 v94, v94
	v_exp_f32_e32 v95, v95
	v_exp_f32_e32 v96, v96
	v_exp_f32_e32 v97, v97
	v_exp_f32_e32 v98, v98
	v_exp_f32_e32 v99, v133
	v_cndmask_b32_e64 v2, v2, 1.0, vcc
	v_pk_fma_f32 v[82:83], v[82:83], s[80:81], v[132:133] op_sel_hi:[1,0,0]
	v_pk_fma_f32 v[80:81], v[80:81], s[80:81], v[132:133] op_sel_hi:[1,0,0]
	v_pk_fma_f32 v[78:79], v[78:79], s[80:81], v[132:133] op_sel_hi:[1,0,0]
	v_pk_fma_f32 v[76:77], v[76:77], s[80:81], v[132:133] op_sel_hi:[1,0,0]
	v_pk_fma_f32 v[74:75], v[74:75], s[80:81], v[132:133] op_sel_hi:[1,0,0]
	v_pk_fma_f32 v[72:73], v[72:73], s[80:81], v[132:133] op_sel_hi:[1,0,0]
	v_pk_fma_f32 v[70:71], v[70:71], s[80:81], v[132:133] op_sel_hi:[1,0,0]
	v_pk_fma_f32 v[68:69], v[68:69], s[80:81], v[132:133] op_sel_hi:[1,0,0]

.LBB0_1996:
	v_add_f32_e32 v132, 0, v84
	v_add_f32_e32 v132, v85, v132
	v_add_f32_e32 v132, v86, v132
	v_add_f32_e32 v132, v87, v132
	v_add_f32_e32 v132, v88, v132
	v_add_f32_e32 v132, v89, v132
	v_add_f32_e32 v132, v90, v132
	v_add_f32_e32 v132, v91, v132
	v_add_f32_e32 v132, v92, v132
	v_add_f32_e32 v132, v93, v132
	v_add_f32_e32 v132, v94, v132
	v_add_f32_e32 v132, v95, v132
	v_exp_f32_e32 v68, v68
	v_add_f32_e32 v132, v96, v132
	v_exp_f32_e32 v69, v69
	v_add_f32_e32 v132, v97, v132
	v_exp_f32_e32 v70, v70
	v_add_f32_e32 v132, v98, v132
	v_exp_f32_e32 v71, v71
	v_add_f32_e32 v132, v99, v132
	v_exp_f32_e32 v72, v72
	v_add_f32_e32 v132, v68, v132
	v_exp_f32_e32 v73, v73
	v_add_f32_e32 v132, v69, v132
	v_exp_f32_e32 v74, v74
	v_add_f32_e32 v132, v70, v132
	v_exp_f32_e32 v75, v75
	v_add_f32_e32 v132, v71, v132
	v_exp_f32_e32 v76, v76
	v_add_f32_e32 v132, v72, v132
	v_exp_f32_e32 v77, v77
	v_add_f32_e32 v132, v73, v132
	v_exp_f32_e32 v78, v78
	v_add_f32_e32 v132, v74, v132
	v_exp_f32_e32 v79, v79
	v_add_f32_e32 v132, v75, v132
	v_exp_f32_e32 v80, v80
	v_add_f32_e32 v132, v76, v132
	v_exp_f32_e32 v81, v81
	v_add_f32_e32 v132, v77, v132
	v_exp_f32_e32 v82, v82
	v_add_f32_e32 v132, v78, v132
	v_exp_f32_e32 v83, v83
	v_add_f32_e32 v132, v79, v132
	v_add_f32_e32 v132, v80, v132
	v_add_f32_e32 v132, v81, v132
	v_add_f32_e32 v132, v82, v132
	v_add_f32_e32 v132, v83, v132
	v_mov_b32_e32 v133, v132
	s_nop 1
	v_permlane32_swap_b32_e32 v132, v133
	v_add_f32_e32 v148, v132, v133
	v_cvt_pk_fp8_f32 v132, v84, v85
	v_cvt_pk_fp8_f32 v136, v68, v69
	v_cvt_pk_fp8_f32 v133, v88, v89
	v_cvt_pk_fp8_f32 v137, v72, v73
	v_cvt_pk_fp8_f32 v134, v92, v93
	v_cvt_pk_fp8_f32 v138, v76, v77
	v_cvt_pk_fp8_f32 v135, v96, v97
	v_cvt_pk_fp8_f32 v139, v80, v81
	v_fmac_f32_e32 v148, v197, v2
	v_cvt_pk_fp8_f32 v132, v86, v87 op_sel:[0,0,1]
	v_cvt_pk_fp8_f32 v136, v70, v71 op_sel:[0,0,1]
	v_cvt_pk_fp8_f32 v133, v90, v91 op_sel:[0,0,1]
	v_cvt_pk_fp8_f32 v137, v74, v75 op_sel:[0,0,1]
	v_cvt_pk_fp8_f32 v134, v94, v95 op_sel:[0,0,1]
	v_cvt_pk_fp8_f32 v138, v78, v79 op_sel:[0,0,1]
	v_cvt_pk_fp8_f32 v135, v98, v99 op_sel:[0,0,1]
	v_cvt_pk_fp8_f32 v139, v82, v83 op_sel:[0,0,1]
	ds_read_b64_tr_b8 v[140:141], v193 offset:0
	ds_read_b64_tr_b8 v[142:143], v193 offset:0x800
	ds_read_b64_tr_b8 v[144:145], v193 offset:0x1000
	ds_read_b64_tr_b8 v[146:147], v193 offset:0x1800
	s_waitcnt lgkmcnt(0)
	s_nop 0
	v_mfma_f32_32x32x64_f8f6f4 v[52:67], v[132:139], v[140:147], v[52:67]
	ds_read_b64_tr_b8 v[140:141], v192 offset:0
	ds_read_b64_tr_b8 v[142:143], v192 offset:0x800
	ds_read_b64_tr_b8 v[144:145], v192 offset:0x1000
	ds_read_b64_tr_b8 v[146:147], v192 offset:0x1800
	s_waitcnt lgkmcnt(0)
	s_nop 0
	v_mfma_f32_32x32x64_f8f6f4 v[36:51], v[132:139], v[140:147], v[36:51]
	ds_read_b64_tr_b8 v[140:141], v191 offset:0
	ds_read_b64_tr_b8 v[142:143], v191 offset:0x800
	ds_read_b64_tr_b8 v[144:145], v191 offset:0x1000
	ds_read_b64_tr_b8 v[146:147], v191 offset:0x1800
	s_waitcnt lgkmcnt(0)
	s_nop 0
	v_mfma_f32_32x32x64_f8f6f4 v[20:35], v[132:139], v[140:147], v[20:35]
	ds_read_b64_tr_b8 v[140:141], v190 offset:0
	ds_read_b64_tr_b8 v[142:143], v190 offset:0x800
	ds_read_b64_tr_b8 v[144:145], v190 offset:0x1000
	ds_read_b64_tr_b8 v[146:147], v190 offset:0x1800
	s_waitcnt lgkmcnt(0)
	s_nop 0
	v_mfma_f32_32x32x64_f8f6f4 v[4:19], v[132:139], v[140:147], v[4:19]
	v_mov_b32_e32 v197, v148
	s_nop 15
	s_nop 7
	s_and_b64 vcc, exec, s[72:73]
	v_mov_b32_e32 v132, 1.0
	s_cbranch_vccnz .LBB0_2064

.LBB0_2063:
	v_max_f32_e32 v2, v116, v117
	v_max3_f32 v2, v2, v118, v119
	v_max3_f32 v2, v2, v120, v121
	v_max3_f32 v2, v2, v122, v123
	v_max3_f32 v2, v2, v124, v125
	v_max3_f32 v2, v2, v126, v127
	v_max3_f32 v2, v2, v128, v129
	v_max3_f32 v2, v2, v130, v131
	v_max3_f32 v2, v2, v100, v101
	v_max3_f32 v2, v2, v102, v103
	v_max3_f32 v2, v2, v104, v105
	v_max3_f32 v2, v2, v106, v107
	v_max3_f32 v2, v2, v108, v109
	v_max3_f32 v2, v2, v110, v111
	v_max3_f32 v2, v2, v112, v113
	v_max3_f32 v2, v2, v114, v115
	v_mov_b32_e32 v132, v2
	s_nop 1
	v_permlane32_swap_b32_e32 v2, v132
	v_max_f32_e32 v2, v2, v132
	v_sub_f32_e32 v132, v2, v196
	v_cmp_ge_f32_e32 vcc, s92, v132
	s_cmp_eq_u64 vcc, exec
	v_max_f32_e32 v132, v196, v196
	s_cselect_b64 vcc, -1, 0
	v_max_f32_e32 v2, v132, v2
	v_sub_f32_e32 v132, v196, v2
	v_cndmask_b32_e32 v196, v2, v196, vcc
	s_mov_b32 s4, 0xbe0293ee
	v_fma_f32 v2, v196, s4, 4.0
	v_mul_f32_e32 v132, 0x3e0293ee, v132
	v_mov_b32_e32 v133, v2
	v_exp_f32_e32 v132, v132
	v_fmamk_f32 v116, v116, 0x3e0293ee, v2
	v_fmamk_f32 v117, v117, 0x3e0293ee, v2
	v_fmamk_f32 v118, v118, 0x3e0293ee, v2
	v_fmamk_f32 v119, v119, 0x3e0293ee, v2
	v_fmamk_f32 v120, v120, 0x3e0293ee, v2
	v_fmamk_f32 v121, v121, 0x3e0293ee, v2
	v_fmamk_f32 v122, v122, 0x3e0293ee, v2
	v_fmamk_f32 v123, v123, 0x3e0293ee, v2
	v_fmamk_f32 v124, v124, 0x3e0293ee, v2
	v_fmamk_f32 v125, v125, 0x3e0293ee, v2
	v_fmamk_f32 v126, v126, 0x3e0293ee, v2
	v_fmamk_f32 v127, v127, 0x3e0293ee, v2
	v_fmamk_f32 v128, v128, 0x3e0293ee, v2
	v_fmamk_f32 v129, v129, 0x3e0293ee, v2
	v_fmamk_f32 v130, v130, 0x3e0293ee, v2
	v_fmac_f32_e32 v133, 0x3e0293ee, v131
	v_exp_f32_e32 v116, v116
	v_exp_f32_e32 v117, v117
	v_exp_f32_e32 v118, v118
	v_exp_f32_e32 v119, v119
	v_exp_f32_e32 v120, v120
	v_exp_f32_e32 v121, v121
	v_exp_f32_e32 v122, v122
	v_exp_f32_e32 v123, v123
	v_exp_f32_e32 v124, v124
	v_exp_f32_e32 v125, v125
	v_exp_f32_e32 v126, v126
	v_exp_f32_e32 v127, v127
	v_exp_f32_e32 v128, v128
	v_exp_f32_e32 v129, v129
	v_exp_f32_e32 v130, v130
	v_exp_f32_e32 v131, v133
	v_cndmask_b32_e64 v132, v132, 1.0, vcc
	v_pk_fma_f32 v[114:115], v[114:115], s[80:81], v[2:3] op_sel_hi:[1,0,0]
	v_pk_fma_f32 v[112:113], v[112:113], s[80:81], v[2:3] op_sel_hi:[1,0,0]
	v_pk_fma_f32 v[110:111], v[110:111], s[80:81], v[2:3] op_sel_hi:[1,0,0]
	v_pk_fma_f32 v[108:109], v[108:109], s[80:81], v[2:3] op_sel_hi:[1,0,0]
	v_pk_fma_f32 v[106:107], v[106:107], s[80:81], v[2:3] op_sel_hi:[1,0,0]
	v_pk_fma_f32 v[104:105], v[104:105], s[80:81], v[2:3] op_sel_hi:[1,0,0]
	v_pk_fma_f32 v[102:103], v[102:103], s[80:81], v[2:3] op_sel_hi:[1,0,0]
	v_pk_fma_f32 v[100:101], v[100:101], s[80:81], v[2:3] op_sel_hi:[1,0,0]

.LBB0_2136:
	s_or_b64 exec, exec, s[0:1]
	v_max_f32_e32 v2, v102, v84
	v_max3_f32 v2, v2, v85, v86
	v_max3_f32 v2, v2, v87, v88
	v_max3_f32 v2, v2, v89, v90
	v_max3_f32 v2, v2, v91, v92
	v_max3_f32 v2, v2, v93, v94
	v_max3_f32 v2, v2, v95, v96
	v_max3_f32 v2, v2, v97, v82
	v_max3_f32 v2, v2, v100, v101
	v_max3_f32 v2, v2, v68, v69
	v_max3_f32 v2, v2, v70, v71
	v_max3_f32 v2, v2, v72, v73
	v_max3_f32 v2, v2, v74, v75
	v_max3_f32 v2, v2, v76, v77
	v_max3_f32 v2, v2, v78, v79
	v_max3_f32 v2, v2, v80, v81
	v_mov_b32_e32 v83, v2
	s_nop 1
	v_permlane32_swap_b32_e32 v2, v83
	v_max_f32_e32 v2, v2, v83
	v_sub_f32_e32 v83, v2, v196
	v_cmp_ge_f32_e32 vcc, s92, v83
	v_max_f32_e32 v98, v196, v196
	s_cmp_eq_u64 vcc, exec
	v_max_f32_e32 v98, v98, v2
	s_cselect_b64 vcc, -1, 0
	v_cndmask_b32_e32 v83, v98, v196, vcc
	s_mov_b32 s0, 0xbe0293ee
	v_sub_f32_e32 v2, v196, v98
	v_fma_f32 v104, v83, s0, 4.0
	v_mul_f32_e32 v2, 0x3e0293ee, v2
	v_mov_b32_e32 v116, v104
	v_exp_f32_e32 v2, v2
	v_fmamk_f32 v98, v102, 0x3e0293ee, v104
	v_fmamk_f32 v99, v84, 0x3e0293ee, v104
	v_fmamk_f32 v102, v85, 0x3e0293ee, v104
	v_fmamk_f32 v103, v86, 0x3e0293ee, v104
	v_fmamk_f32 v105, v87, 0x3e0293ee, v104
	v_fmamk_f32 v106, v88, 0x3e0293ee, v104
	v_fmamk_f32 v107, v89, 0x3e0293ee, v104
	v_fmamk_f32 v108, v90, 0x3e0293ee, v104
	v_fmamk_f32 v109, v91, 0x3e0293ee, v104
	v_fmamk_f32 v110, v92, 0x3e0293ee, v104
	v_fmamk_f32 v111, v93, 0x3e0293ee, v104
	v_fmamk_f32 v112, v94, 0x3e0293ee, v104
	v_fmamk_f32 v113, v95, 0x3e0293ee, v104
	v_fmamk_f32 v114, v96, 0x3e0293ee, v104
	v_fmamk_f32 v115, v97, 0x3e0293ee, v104
	v_fmac_f32_e32 v116, 0x3e0293ee, v82
	v_exp_f32_e32 v84, v98
	v_exp_f32_e32 v85, v99
	v_exp_f32_e32 v86, v102
	v_exp_f32_e32 v87, v103
	v_exp_f32_e32 v88, v105
	v_exp_f32_e32 v89, v106
	v_exp_f32_e32 v90, v107
	v_exp_f32_e32 v91, v108
	v_exp_f32_e32 v92, v109
	v_exp_f32_e32 v93, v110
	v_exp_f32_e32 v94, v111
	v_exp_f32_e32 v95, v112
	v_exp_f32_e32 v96, v113
	v_exp_f32_e32 v97, v114
	v_exp_f32_e32 v98, v115
	v_exp_f32_e32 v99, v116
	v_cndmask_b32_e64 v2, v2, 1.0, vcc
	v_pk_fma_f32 v[82:83], v[80:81], s[80:81], v[104:105] op_sel_hi:[1,0,0]
	v_pk_fma_f32 v[80:81], v[78:79], s[80:81], v[104:105] op_sel_hi:[1,0,0]
	v_pk_fma_f32 v[78:79], v[76:77], s[80:81], v[104:105] op_sel_hi:[1,0,0]
	v_pk_fma_f32 v[76:77], v[74:75], s[80:81], v[104:105] op_sel_hi:[1,0,0]
	v_pk_fma_f32 v[74:75], v[72:73], s[80:81], v[104:105] op_sel_hi:[1,0,0]
	v_pk_fma_f32 v[72:73], v[70:71], s[80:81], v[104:105] op_sel_hi:[1,0,0]
	v_pk_fma_f32 v[70:71], v[68:69], s[80:81], v[104:105] op_sel_hi:[1,0,0]
	v_pk_fma_f32 v[68:69], v[100:101], s[80:81], v[104:105] op_sel_hi:[1,0,0]
	v_cmp_gt_f32_e32 vcc, 1.0, v2
	s_cbranch_vccnz .LBB0_2138
	s_branch .LBB0_2141

.LBB0_2234:
	s_lshl_b32 s0, s62, 11
	s_ashr_i32 s1, s0, 31
	v_lshl_or_b32 v34, s63, 8, v223
	s_add_u32 s0, s46, s0
	v_ashrrev_i32_e32 v35, 31, v34
	s_addc_u32 s1, s47, s1
	v_lshl_add_u32 v36, s64, 8, v1
	v_lshl_add_u64 v[38:39], s[0:1], 0, v[34:35]
	v_mad_i64_i32 v[4:5], s[0:1], v36, s57, v[38:39]
	global_load_dwordx2 v[64:65], v[4:5], off
	v_ashrrev_i32_e32 v37, 31, v36
	v_lshl_add_u64 v[40:41], v[34:35], 1, s[10:11]
	s_cmp_lg_u32 s62, 0
	v_lshlrev_b64 v[2:3], 12, v[36:37]
	s_cselect_b64 s[0:1], -1, 0
	s_cmp_eq_u32 s62, 0
	v_lshl_add_u64 v[2:3], v[40:41], 0, v[2:3]
	s_cbranch_scc1 .LBB0_2236
	global_load_dwordx4 v[30:33], v[2:3], off
	s_branch .LBB0_2237

.LBB0_2419:
	v_lshl_add_u32 v8, s28, 8, v1
	v_lshl_or_b32 v2, s71, 8, v223
	v_ashrrev_i32_e32 v9, 31, v8
	v_ashrrev_i32_e32 v3, 31, v2
	v_lshlrev_b64 v[4:5], 12, v[8:9]
	v_lshl_add_u64 v[4:5], s[4:5], 0, v[4:5]
	v_lshlrev_b64 v[10:11], 1, v[2:3]
	v_lshl_add_u64 v[2:3], v[4:5], 0, v[10:11]
	v_pk_mul_f32 v[4:5], v[190:191], s[10:11] op_sel_hi:[1,0]
	v_pk_mul_f32 v[6:7], v[192:193], s[10:11] op_sel_hi:[1,0]
	v_cvt_pk_bf16_f32 v4, v4, v5
	v_pk_mul_f32 v[12:13], v[188:189], s[10:11] op_sel_hi:[1,0]
	v_cvt_pk_bf16_f32 v5, v6, v7
	v_pk_mul_f32 v[14:15], v[186:187], s[10:11] op_sel_hi:[1,0]
	v_pk_mul_f32 v[16:17], v[170:171], s[10:11] op_sel_hi:[1,0]
	v_cvt_pk_bf16_f32 v6, v14, v15
	v_cvt_pk_bf16_f32 v7, v12, v13
	global_store_dwordx4 v[2:3], v[4:7], off
	v_pk_mul_f32 v[12:13], v[176:177], s[10:11] op_sel_hi:[1,0]
	v_pk_mul_f32 v[14:15], v[174:175], s[10:11] op_sel_hi:[1,0]
	v_pk_mul_f32 v[4:5], v[182:183], s[10:11] op_sel_hi:[1,0]
	v_pk_mul_f32 v[6:7], v[184:185], s[10:11] op_sel_hi:[1,0]
	v_cvt_pk_bf16_f32 v4, v4, v5
	s_nop 0
	v_cvt_pk_bf16_f32 v5, v6, v7
	v_cvt_pk_bf16_f32 v6, v14, v15
	v_cvt_pk_bf16_f32 v7, v12, v13
	global_store_dwordx4 v[2:3], v[4:7], off offset:256
	v_pk_mul_f32 v[14:15], v[172:173], s[10:11] op_sel_hi:[1,0]
	s_nop 0
	v_or_b32_e32 v4, 16, v8
	v_ashrrev_i32_e32 v5, 31, v4
	v_lshlrev_b64 v[4:5], 12, v[4:5]
	v_lshl_add_u64 v[4:5], s[4:5], 0, v[4:5]
	v_lshl_add_u64 v[12:13], v[4:5], 0, v[10:11]
	v_pk_mul_f32 v[4:5], v[178:179], s[10:11] op_sel_hi:[1,0]
	v_pk_mul_f32 v[6:7], v[180:181], s[10:11] op_sel_hi:[1,0]
	v_cvt_pk_bf16_f32 v4, v4, v5
	s_nop 0
	v_cvt_pk_bf16_f32 v5, v6, v7
	v_cvt_pk_bf16_f32 v6, v16, v17
	v_cvt_pk_bf16_f32 v7, v14, v15
	global_store_dwordx4 v[12:13], v[4:7], off
	v_pk_mul_f32 v[14:15], v[160:161], s[10:11] op_sel_hi:[1,0]
	v_pk_mul_f32 v[16:17], v[158:159], s[10:11] op_sel_hi:[1,0]
	v_pk_mul_f32 v[4:5], v[166:167], s[10:11] op_sel_hi:[1,0]
	v_pk_mul_f32 v[6:7], v[168:169], s[10:11] op_sel_hi:[1,0]
	v_cvt_pk_bf16_f32 v4, v4, v5
	s_nop 0
	v_cvt_pk_bf16_f32 v5, v6, v7
	v_cvt_pk_bf16_f32 v6, v16, v17
	v_cvt_pk_bf16_f32 v7, v14, v15
	global_store_dwordx4 v[12:13], v[4:7], off offset:256
	v_pk_mul_f32 v[14:15], v[156:157], s[10:11] op_sel_hi:[1,0]
	v_pk_mul_f32 v[16:17], v[154:155], s[10:11] op_sel_hi:[1,0]
	v_or_b32_e32 v4, 32, v8
	v_ashrrev_i32_e32 v5, 31, v4
	v_lshlrev_b64 v[4:5], 12, v[4:5]
	v_lshl_add_u64 v[4:5], s[4:5], 0, v[4:5]
	v_lshl_add_u64 v[12:13], v[4:5], 0, v[10:11]
	v_pk_mul_f32 v[4:5], v[162:163], s[10:11] op_sel_hi:[1,0]
	v_pk_mul_f32 v[6:7], v[164:165], s[10:11] op_sel_hi:[1,0]
	v_cvt_pk_bf16_f32 v4, v4, v5
	s_nop 0
	v_cvt_pk_bf16_f32 v5, v6, v7
	v_cvt_pk_bf16_f32 v6, v16, v17
	v_cvt_pk_bf16_f32 v7, v14, v15
	global_store_dwordx4 v[12:13], v[4:7], off
	v_pk_mul_f32 v[14:15], v[144:145], s[10:11] op_sel_hi:[1,0]
	v_pk_mul_f32 v[16:17], v[142:143], s[10:11] op_sel_hi:[1,0]
	v_pk_mul_f32 v[4:5], v[150:151], s[10:11] op_sel_hi:[1,0]
	v_pk_mul_f32 v[6:7], v[152:153], s[10:11] op_sel_hi:[1,0]
	v_cvt_pk_bf16_f32 v4, v4, v5
	s_nop 0
	v_cvt_pk_bf16_f32 v5, v6, v7
	v_cvt_pk_bf16_f32 v6, v16, v17
	v_cvt_pk_bf16_f32 v7, v14, v15
	global_store_dwordx4 v[12:13], v[4:7], off offset:256
	v_pk_mul_f32 v[12:13], v[138:139], s[10:11] op_sel_hi:[1,0]
	s_nop 0
	v_or_b32_e32 v4, 48, v8
	v_ashrrev_i32_e32 v5, 31, v4
	v_lshlrev_b64 v[4:5], 12, v[4:5]
	v_lshl_add_u64 v[4:5], s[4:5], 0, v[4:5]
	v_lshl_add_u64 v[8:9], v[4:5], 0, v[10:11]
	v_pk_mul_f32 v[6:7], v[148:149], s[10:11] op_sel_hi:[1,0]
	v_pk_mul_f32 v[4:5], v[146:147], s[10:11] op_sel_hi:[1,0]
	v_pk_mul_f32 v[10:11], v[140:141], s[10:11] op_sel_hi:[1,0]
	v_cvt_pk_bf16_f32 v4, v4, v5
	v_cvt_pk_bf16_f32 v5, v6, v7
	v_cvt_pk_bf16_f32 v6, v12, v13
	v_pk_mul_f32 v[12:13], v[130:131], s[10:11] op_sel_hi:[1,0]
	v_cvt_pk_bf16_f32 v7, v10, v11
	global_store_dwordx4 v[8:9], v[4:7], off
	v_pk_mul_f32 v[10:11], v[132:133], s[10:11] op_sel_hi:[1,0]
	s_nop 0
	v_pk_mul_f32 v[6:7], v[136:137], s[10:11] op_sel_hi:[1,0]
	v_pk_mul_f32 v[4:5], v[134:135], s[10:11] op_sel_hi:[1,0]
	s_nop 0
	v_cvt_pk_bf16_f32 v4, v4, v5
	v_cvt_pk_bf16_f32 v5, v6, v7
	v_cvt_pk_bf16_f32 v6, v12, v13
	v_cvt_pk_bf16_f32 v7, v10, v11
	global_store_dwordx4 v[8:9], v[4:7], off offset:256
	v_pk_mul_f32 v[10:11], v[124:125], s[10:11] op_sel_hi:[1,0]
	v_pk_mul_f32 v[12:13], v[122:123], s[10:11] op_sel_hi:[1,0]
	v_pk_mul_f32 v[6:7], v[128:129], s[10:11] op_sel_hi:[1,0]
	v_pk_mul_f32 v[4:5], v[126:127], s[10:11] op_sel_hi:[1,0]
	v_lshl_add_u64 v[8:9], v[2:3], 0, s[12:13]
	v_cvt_pk_bf16_f32 v4, v4, v5
	v_cvt_pk_bf16_f32 v5, v6, v7
	v_cvt_pk_bf16_f32 v6, v12, v13
	v_cvt_pk_bf16_f32 v7, v10, v11
	v_add_co_u32_e32 v10, vcc, s66, v2
	v_pk_mul_f32 v[12:13], v[110:111], s[10:11] op_sel_hi:[1,0]
	s_nop 0
	v_addc_co_u32_e32 v11, vcc, 0, v3, vcc
	global_store_dwordx4 v[10:11], v[4:7], off
	v_pk_mul_f32 v[10:11], v[112:113], s[10:11] op_sel_hi:[1,0]
	s_nop 0
	v_pk_mul_f32 v[6:7], v[120:121], s[10:11] op_sel_hi:[1,0]
	v_pk_mul_f32 v[4:5], v[118:119], s[10:11] op_sel_hi:[1,0]
	s_nop 0
	v_cvt_pk_bf16_f32 v4, v4, v5
	v_cvt_pk_bf16_f32 v5, v6, v7
	v_cvt_pk_bf16_f32 v6, v12, v13
	v_cvt_pk_bf16_f32 v7, v10, v11
	global_store_dwordx4 v[8:9], v[4:7], off offset:256
	v_pk_mul_f32 v[10:11], v[108:109], s[10:11] op_sel_hi:[1,0]
	v_pk_mul_f32 v[12:13], v[106:107], s[10:11] op_sel_hi:[1,0]
	v_pk_mul_f32 v[6:7], v[116:117], s[10:11] op_sel_hi:[1,0]
	v_pk_mul_f32 v[4:5], v[114:115], s[10:11] op_sel_hi:[1,0]
	v_lshl_add_u64 v[8:9], v[2:3], 0, s[14:15]
	v_cvt_pk_bf16_f32 v4, v4, v5
	v_cvt_pk_bf16_f32 v5, v6, v7
	v_cvt_pk_bf16_f32 v6, v12, v13
	v_cvt_pk_bf16_f32 v7, v10, v11
	v_add_co_u32_e32 v10, vcc, s67, v2
	v_pk_mul_f32 v[12:13], v[94:95], s[10:11] op_sel_hi:[1,0]
	s_nop 0
	v_addc_co_u32_e32 v11, vcc, 0, v3, vcc
	global_store_dwordx4 v[10:11], v[4:7], off
	v_pk_mul_f32 v[10:11], v[96:97], s[10:11] op_sel_hi:[1,0]
	s_nop 0
	v_pk_mul_f32 v[6:7], v[104:105], s[10:11] op_sel_hi:[1,0]
	v_pk_mul_f32 v[4:5], v[102:103], s[10:11] op_sel_hi:[1,0]
	s_nop 0
	v_cvt_pk_bf16_f32 v4, v4, v5
	v_cvt_pk_bf16_f32 v5, v6, v7
	v_cvt_pk_bf16_f32 v6, v12, v13
	v_cvt_pk_bf16_f32 v7, v10, v11
	global_store_dwordx4 v[8:9], v[4:7], off offset:256
	v_pk_mul_f32 v[10:11], v[92:93], s[10:11] op_sel_hi:[1,0]
	v_pk_mul_f32 v[12:13], v[90:91], s[10:11] op_sel_hi:[1,0]
	v_pk_mul_f32 v[6:7], v[100:101], s[10:11] op_sel_hi:[1,0]
	v_pk_mul_f32 v[4:5], v[98:99], s[10:11] op_sel_hi:[1,0]
	v_lshl_add_u64 v[8:9], v[2:3], 0, s[16:17]
	v_cvt_pk_bf16_f32 v4, v4, v5
	v_cvt_pk_bf16_f32 v5, v6, v7
	v_cvt_pk_bf16_f32 v6, v12, v13
	v_cvt_pk_bf16_f32 v7, v10, v11
	v_add_co_u32_e32 v10, vcc, s68, v2
	v_pk_mul_f32 v[12:13], v[78:79], s[10:11] op_sel_hi:[1,0]
	s_nop 0
	v_addc_co_u32_e32 v11, vcc, 0, v3, vcc
	global_store_dwordx4 v[10:11], v[4:7], off
	v_pk_mul_f32 v[10:11], v[80:81], s[10:11] op_sel_hi:[1,0]
	s_nop 0
	v_pk_mul_f32 v[4:5], v[86:87], s[10:11] op_sel_hi:[1,0]
	v_pk_mul_f32 v[6:7], v[88:89], s[10:11] op_sel_hi:[1,0]
	v_cvt_pk_bf16_f32 v4, v4, v5
	s_nop 0
	v_cvt_pk_bf16_f32 v5, v6, v7
	v_cvt_pk_bf16_f32 v6, v12, v13
	v_cvt_pk_bf16_f32 v7, v10, v11
	global_store_dwordx4 v[8:9], v[4:7], off offset:256
	v_lshl_add_u64 v[8:9], v[2:3], 0, s[18:19]
	v_add_co_u32_e32 v2, vcc, s69, v2
	v_pk_mul_f32 v[4:5], v[82:83], s[10:11] op_sel_hi:[1,0]
	v_pk_mul_f32 v[6:7], v[84:85], s[10:11] op_sel_hi:[1,0]
	v_cvt_pk_bf16_f32 v4, v4, v5
	v_addc_co_u32_e32 v3, vcc, 0, v3, vcc
	v_cvt_pk_bf16_f32 v5, v6, v7
	v_pk_mul_f32 v[10:11], v[76:77], s[10:11] op_sel_hi:[1,0]
	v_pk_mul_f32 v[12:13], v[74:75], s[10:11] op_sel_hi:[1,0]
	s_andn2_b64 vcc, exec, s[2:3]
	v_cvt_pk_bf16_f32 v6, v12, v13
	v_cvt_pk_bf16_f32 v7, v10, v11
	global_store_dwordx4 v[2:3], v[4:7], off
	v_pk_mul_f32 v[2:3], v[70:71], s[10:11] op_sel_hi:[1,0]
	s_mov_b64 s[2:3], -1
	v_pk_mul_f32 v[4:5], v[72:73], s[10:11] op_sel_hi:[1,0]
	v_pk_mul_f32 v[6:7], v[68:69], s[10:11] op_sel_hi:[1,0]
	v_pk_mul_f32 v[10:11], v[66:67], s[10:11] op_sel_hi:[1,0]
	v_cvt_pk_bf16_f32 v2, v2, v3
	v_cvt_pk_bf16_f32 v3, v4, v5
	s_nop 0
	v_cvt_pk_bf16_f32 v4, v10, v11
	v_cvt_pk_bf16_f32 v5, v6, v7
	global_store_dwordx4 v[8:9], v[2:5], off offset:256
	s_cbranch_vccnz .LBB0_2397
	s_andn2_b64 vcc, exec, s[0:1]
	s_cbranch_vccnz .LBB0_2396
	s_barrier
	s_branch .LBB0_2396
